# v35 + first K-loop iteration of all 28 GEMM loops peeled with C=0 on each accumulator's first MFMA; the 128 accumulator-zeroing v_mov per tile deleted
# baseline (speedup 1.0000x reference)
.LBB0_273:
	s_ashr_i32 s69, s68, 31
	s_lshl_b64 s[0:1], s[68:69], 20
	v_readlane_b32 s62, v247, 45
	s_add_u32 s70, s62, s0
	v_readlane_b32 s0, v247, 47
	s_addc_u32 s71, s0, s1
	s_and_b64 s[0:1], s[2:3], exec
	s_cselect_b32 s0, s71, s35
	s_cselect_b32 s1, s70, s34
	s_ashr_i32 s67, s66, 31
	s_lshl_b64 s[62:63], s[66:67], 20
	s_add_u32 s72, s30, s62
	s_addc_u32 s73, s31, s63
	s_and_b64 s[62:63], s[2:3], exec
	s_cselect_b32 s67, s73, s79
	s_cselect_b32 s69, s72, s78
	s_add_u32 s76, s34, 0x80080
	s_addc_u32 s77, s35, 0
	s_add_u32 s83, s78, 0x100
	s_addc_u32 s84, s79, 0
	s_mov_b32 s85, -2
	ds_read_b128 v[146:149], v153
	ds_read_b128 v[156:159], v153 offset:1024
	ds_read_b128 v[160:163], v153 offset:2048
	ds_read_b128 v[164:167], v153 offset:3072
	ds_read_b128 v[168:171], v154
	ds_read_b128 v[172:175], v154 offset:1024
	ds_read_b128 v[176:179], v154 offset:2048
	ds_read_b128 v[180:183], v154 offset:3072
	s_add_u32 s34, s76, 0xfff80080
	s_addc_u32 s35, s77, -1
	s_cmp_eq_u32 s85, 28
	s_cselect_b32 s79, s0, s35
	s_cselect_b32 s78, s1, s34
	s_cselect_b32 s35, s67, s84
	s_cselect_b32 s34, s69, s83
	v_lshl_add_u64 v[218:219], s[76:77], 0, v[138:139]
	s_add_i32 m0, s54, 0xc000
	ds_read_b128 v[184:187], v155
	ds_read_b128 v[188:191], v155 offset:1024
	ds_read_b128 v[192:195], v155 offset:2048
	ds_read_b128 v[196:199], v155 offset:3072
	ds_read_b128 v[200:203], v155 offset:4096
	ds_read_b128 v[204:207], v155 offset:5120
	ds_read_b128 v[208:211], v155 offset:6144
	ds_read_b128 v[212:215], v155 offset:7168
	global_load_lds_dwordx4 v[218:219], off
	v_lshl_add_u64 v[218:219], s[76:77], 0, v[140:141]
	s_add_i32 m0, s54, 0xe000
	s_nop 0
	global_load_lds_dwordx4 v[218:219], off
	s_waitcnt vmcnt(8)
	s_waitcnt lgkmcnt(0)
	s_barrier
	s_setprio 1
	s_waitcnt lgkmcnt(0)
	v_mfma_f32_16x16x32_bf16 v[126:129], v[146:149], v[184:187], 0
	v_mfma_f32_16x16x32_bf16 v[118:121], v[160:163], v[184:187], 0
	v_mfma_f32_16x16x32_bf16 v[110:113], v[146:149], v[192:195], 0
	v_mfma_f32_16x16x32_bf16 v[102:105], v[160:163], v[192:195], 0
	v_mfma_f32_16x16x32_bf16 v[94:97], v[146:149], v[200:203], 0
	v_mfma_f32_16x16x32_bf16 v[86:89], v[160:163], v[200:203], 0
	v_mfma_f32_16x16x32_bf16 v[78:81], v[146:149], v[208:211], 0
	v_mfma_f32_16x16x32_bf16 v[70:73], v[160:163], v[208:211], 0
	v_mfma_f32_16x16x32_bf16 v[126:129], v[156:159], v[188:191], v[126:129]
	v_mfma_f32_16x16x32_bf16 v[118:121], v[164:167], v[188:191], v[118:121]
	v_mfma_f32_16x16x32_bf16 v[110:113], v[156:159], v[196:199], v[110:113]
	v_mfma_f32_16x16x32_bf16 v[102:105], v[164:167], v[196:199], v[102:105]
	v_mfma_f32_16x16x32_bf16 v[94:97], v[156:159], v[204:207], v[94:97]
	v_mfma_f32_16x16x32_bf16 v[86:89], v[164:167], v[204:207], v[86:89]
	v_mfma_f32_16x16x32_bf16 v[78:81], v[156:159], v[212:215], v[78:81]
	v_mfma_f32_16x16x32_bf16 v[70:73], v[164:167], v[212:215], v[70:73]
	s_setprio 0
	s_setprio 1
	v_mfma_f32_16x16x32_bf16 v[122:125], v[168:171], v[184:187], 0
	v_mfma_f32_16x16x32_bf16 v[114:117], v[176:179], v[184:187], 0
	v_mfma_f32_16x16x32_bf16 v[106:109], v[168:171], v[192:195], 0
	v_mfma_f32_16x16x32_bf16 v[98:101], v[176:179], v[192:195], 0
	v_mfma_f32_16x16x32_bf16 v[90:93], v[168:171], v[200:203], 0
	v_mfma_f32_16x16x32_bf16 v[82:85], v[176:179], v[200:203], 0
	v_mfma_f32_16x16x32_bf16 v[74:77], v[168:171], v[208:211], 0
	v_mfma_f32_16x16x32_bf16 v[66:69], v[176:179], v[208:211], 0
	v_mfma_f32_16x16x32_bf16 v[122:125], v[172:175], v[188:191], v[122:125]
	v_mfma_f32_16x16x32_bf16 v[114:117], v[180:183], v[188:191], v[114:117]
	v_mfma_f32_16x16x32_bf16 v[106:109], v[172:175], v[196:199], v[106:109]
	v_mfma_f32_16x16x32_bf16 v[98:101], v[180:183], v[196:199], v[98:101]
	v_mfma_f32_16x16x32_bf16 v[90:93], v[172:175], v[204:207], v[90:93]
	v_mfma_f32_16x16x32_bf16 v[82:85], v[180:183], v[204:207], v[82:85]
	v_mfma_f32_16x16x32_bf16 v[74:77], v[172:175], v[212:215], v[74:77]
	v_mfma_f32_16x16x32_bf16 v[66:69], v[180:183], v[212:215], v[66:69]
	s_setprio 0
	s_barrier
	s_add_i32 s62, s75, s33
	v_lshl_add_u64 v[218:219], s[34:35], 0, v[134:135]
	s_mov_b32 m0, s62
	ds_read_b128 v[184:187], v155 offset:16384
	ds_read_b128 v[188:191], v155 offset:17408
	ds_read_b128 v[192:195], v155 offset:18432
	ds_read_b128 v[196:199], v155 offset:19456
	ds_read_b128 v[200:203], v155 offset:20480
	ds_read_b128 v[204:207], v155 offset:21504
	ds_read_b128 v[208:211], v155 offset:22528
	ds_read_b128 v[212:215], v155 offset:23552
	global_load_lds_dwordx4 v[218:219], off
	s_add_i32 m0, s62, 0x2000
	s_add_u32 s62, s34, 0x80000
	v_lshl_add_u64 v[220:221], s[34:35], 0, v[130:131]
	s_addc_u32 s63, s35, 0
	s_add_i32 s86, s80, s33
	global_load_lds_dwordx4 v[220:221], off
	v_lshl_add_u64 v[222:223], s[62:63], 0, v[134:135]
	s_mov_b32 m0, s86
	v_lshl_add_u64 v[224:225], s[78:79], 0, v[132:133]
	global_load_lds_dwordx4 v[222:223], off
	v_lshl_add_u64 v[222:223], s[62:63], 0, v[130:131]
	s_add_i32 m0, s86, 0x2000
	s_nop 0
	global_load_lds_dwordx4 v[222:223], off
	v_lshl_add_u64 v[222:223], s[78:79], 0, v[136:137]
	s_mov_b32 m0, s54
	s_nop 0
	global_load_lds_dwordx4 v[222:223], off
	s_mov_b32 m0, s55
	s_nop 0
	global_load_lds_dwordx4 v[224:225], off
	s_waitcnt vmcnt(8)
	s_waitcnt lgkmcnt(0)
	s_barrier
	s_setprio 1
	s_waitcnt lgkmcnt(0)
	v_mfma_f32_16x16x32_bf16 v[62:65], v[146:149], v[184:187], 0
	v_mfma_f32_16x16x32_bf16 v[54:57], v[160:163], v[184:187], 0
	v_mfma_f32_16x16x32_bf16 v[46:49], v[146:149], v[192:195], 0
	v_mfma_f32_16x16x32_bf16 v[38:41], v[160:163], v[192:195], 0
	v_mfma_f32_16x16x32_bf16 v[30:33], v[146:149], v[200:203], 0
	v_mfma_f32_16x16x32_bf16 v[22:25], v[160:163], v[200:203], 0
	v_mfma_f32_16x16x32_bf16 v[14:17], v[146:149], v[208:211], 0
	v_mfma_f32_16x16x32_bf16 v[6:9], v[160:163], v[208:211], 0
	v_mfma_f32_16x16x32_bf16 v[62:65], v[156:159], v[188:191], v[62:65]
	v_mfma_f32_16x16x32_bf16 v[54:57], v[164:167], v[188:191], v[54:57]
	v_mfma_f32_16x16x32_bf16 v[46:49], v[156:159], v[196:199], v[46:49]
	v_mfma_f32_16x16x32_bf16 v[38:41], v[164:167], v[196:199], v[38:41]
	v_mfma_f32_16x16x32_bf16 v[30:33], v[156:159], v[204:207], v[30:33]
	v_mfma_f32_16x16x32_bf16 v[22:25], v[164:167], v[204:207], v[22:25]
	v_mfma_f32_16x16x32_bf16 v[14:17], v[156:159], v[212:215], v[14:17]
	v_mfma_f32_16x16x32_bf16 v[6:9], v[164:167], v[212:215], v[6:9]
	s_setprio 0
	s_setprio 1
	v_mfma_f32_16x16x32_bf16 v[58:61], v[168:171], v[184:187], 0
	v_mfma_f32_16x16x32_bf16 v[50:53], v[176:179], v[184:187], 0
	v_mfma_f32_16x16x32_bf16 v[42:45], v[168:171], v[192:195], 0
	v_mfma_f32_16x16x32_bf16 v[34:37], v[176:179], v[192:195], 0
	v_mfma_f32_16x16x32_bf16 v[26:29], v[168:171], v[200:203], 0
	v_mfma_f32_16x16x32_bf16 v[18:21], v[176:179], v[200:203], 0
	v_mfma_f32_16x16x32_bf16 v[10:13], v[168:171], v[208:211], 0
	v_mfma_f32_16x16x32_bf16 v[2:5], v[176:179], v[208:211], 0
	v_mfma_f32_16x16x32_bf16 v[58:61], v[172:175], v[188:191], v[58:61]
	v_mfma_f32_16x16x32_bf16 v[50:53], v[180:183], v[188:191], v[50:53]
	v_mfma_f32_16x16x32_bf16 v[42:45], v[172:175], v[196:199], v[42:45]
	v_mfma_f32_16x16x32_bf16 v[34:37], v[180:183], v[196:199], v[34:37]
	v_mfma_f32_16x16x32_bf16 v[26:29], v[172:175], v[204:207], v[26:29]
	v_mfma_f32_16x16x32_bf16 v[18:21], v[180:183], v[204:207], v[18:21]
	v_mfma_f32_16x16x32_bf16 v[10:13], v[172:175], v[212:215], v[10:13]
	v_mfma_f32_16x16x32_bf16 v[2:5], v[180:183], v[212:215], v[2:5]
	s_setprio 0
	s_barrier
	s_add_i32 s86, 0, 0x18000
	s_add_i32 s87, 0, 0x1c000
	v_add_u32_e32 v164, s86, v151
	v_add_u32_e32 v180, s87, v151
	ds_read_b128 v[146:149], v164
	ds_read_b128 v[156:159], v164 offset:1024
	ds_read_b128 v[160:163], v164 offset:2048
	ds_read_b128 v[164:167], v164 offset:3072
	ds_read_b128 v[168:171], v180
	ds_read_b128 v[172:175], v180 offset:1024
	ds_read_b128 v[176:179], v180 offset:2048
	ds_read_b128 v[180:183], v180 offset:3072
	s_add_u32 s62, s78, 0x80000
	s_addc_u32 s63, s79, 0
	s_mov_b32 m0, s56
	v_lshl_add_u64 v[226:227], s[62:63], 0, v[136:137]
	ds_read_b128 v[184:187], v155 offset:32768
	ds_read_b128 v[188:191], v155 offset:33792
	ds_read_b128 v[192:195], v155 offset:34816
	ds_read_b128 v[196:199], v155 offset:35840
	ds_read_b128 v[200:203], v155 offset:36864
	ds_read_b128 v[204:207], v155 offset:37888
	ds_read_b128 v[208:211], v155 offset:38912
	ds_read_b128 v[212:215], v155 offset:39936
	global_load_lds_dwordx4 v[226:227], off
	v_lshl_add_u64 v[226:227], s[62:63], 0, v[132:133]
	s_mov_b32 m0, s57
	s_nop 0
	global_load_lds_dwordx4 v[226:227], off
	s_waitcnt vmcnt(8)
	s_waitcnt lgkmcnt(0)
	s_barrier
	s_setprio 1
	s_waitcnt lgkmcnt(0)
	v_mfma_f32_16x16x32_bf16 v[126:129], v[146:149], v[184:187], v[126:129]
	v_mfma_f32_16x16x32_bf16 v[118:121], v[160:163], v[184:187], v[118:121]
	v_mfma_f32_16x16x32_bf16 v[110:113], v[146:149], v[192:195], v[110:113]
	v_mfma_f32_16x16x32_bf16 v[102:105], v[160:163], v[192:195], v[102:105]
	v_mfma_f32_16x16x32_bf16 v[94:97], v[146:149], v[200:203], v[94:97]
	v_mfma_f32_16x16x32_bf16 v[86:89], v[160:163], v[200:203], v[86:89]
	v_mfma_f32_16x16x32_bf16 v[78:81], v[146:149], v[208:211], v[78:81]
	v_mfma_f32_16x16x32_bf16 v[70:73], v[160:163], v[208:211], v[70:73]
	v_mfma_f32_16x16x32_bf16 v[126:129], v[156:159], v[188:191], v[126:129]
	v_mfma_f32_16x16x32_bf16 v[118:121], v[164:167], v[188:191], v[118:121]
	v_mfma_f32_16x16x32_bf16 v[110:113], v[156:159], v[196:199], v[110:113]
	v_mfma_f32_16x16x32_bf16 v[102:105], v[164:167], v[196:199], v[102:105]
	v_mfma_f32_16x16x32_bf16 v[94:97], v[156:159], v[204:207], v[94:97]
	v_mfma_f32_16x16x32_bf16 v[86:89], v[164:167], v[204:207], v[86:89]
	v_mfma_f32_16x16x32_bf16 v[78:81], v[156:159], v[212:215], v[78:81]
	v_mfma_f32_16x16x32_bf16 v[70:73], v[164:167], v[212:215], v[70:73]
	s_setprio 0
	s_setprio 1
	v_mfma_f32_16x16x32_bf16 v[122:125], v[168:171], v[184:187], v[122:125]
	v_mfma_f32_16x16x32_bf16 v[114:117], v[176:179], v[184:187], v[114:117]
	v_mfma_f32_16x16x32_bf16 v[106:109], v[168:171], v[192:195], v[106:109]
	v_mfma_f32_16x16x32_bf16 v[98:101], v[176:179], v[192:195], v[98:101]
	v_mfma_f32_16x16x32_bf16 v[90:93], v[168:171], v[200:203], v[90:93]
	v_mfma_f32_16x16x32_bf16 v[82:85], v[176:179], v[200:203], v[82:85]
	v_mfma_f32_16x16x32_bf16 v[74:77], v[168:171], v[208:211], v[74:77]
	v_mfma_f32_16x16x32_bf16 v[66:69], v[176:179], v[208:211], v[66:69]
	v_mfma_f32_16x16x32_bf16 v[122:125], v[172:175], v[188:191], v[122:125]
	v_mfma_f32_16x16x32_bf16 v[114:117], v[180:183], v[188:191], v[114:117]
	v_mfma_f32_16x16x32_bf16 v[106:109], v[172:175], v[196:199], v[106:109]
	v_mfma_f32_16x16x32_bf16 v[98:101], v[180:183], v[196:199], v[98:101]
	v_mfma_f32_16x16x32_bf16 v[90:93], v[172:175], v[204:207], v[90:93]
	v_mfma_f32_16x16x32_bf16 v[82:85], v[180:183], v[204:207], v[82:85]
	v_mfma_f32_16x16x32_bf16 v[74:77], v[172:175], v[212:215], v[74:77]
	v_mfma_f32_16x16x32_bf16 v[66:69], v[180:183], v[212:215], v[66:69]
	s_setprio 0
	s_barrier
	s_add_i32 s62, s86, s33
	v_lshl_add_u64 v[218:219], v[218:219], 0, s[8:9]
	s_mov_b32 m0, s62
	ds_read_b128 v[184:187], v155 offset:49152
	ds_read_b128 v[188:191], v155 offset:50176
	ds_read_b128 v[192:195], v155 offset:51200
	ds_read_b128 v[196:199], v155 offset:52224
	ds_read_b128 v[200:203], v155 offset:53248
	ds_read_b128 v[204:207], v155 offset:54272
	ds_read_b128 v[208:211], v155 offset:55296
	ds_read_b128 v[212:215], v155 offset:56320
	global_load_lds_dwordx4 v[218:219], off
	s_add_i32 m0, s62, 0x2000
	s_add_u32 s34, s34, 0x80080
	v_lshl_add_u64 v[218:219], v[220:221], 0, s[8:9]
	s_addc_u32 s35, s35, 0
	s_add_i32 s62, s87, s33
	global_load_lds_dwordx4 v[218:219], off
	v_lshl_add_u64 v[218:219], s[34:35], 0, v[134:135]
	s_mov_b32 m0, s62
	s_nop 0
	global_load_lds_dwordx4 v[218:219], off
	v_lshl_add_u64 v[218:219], s[34:35], 0, v[130:131]
	s_add_i32 m0, s62, 0x2000
	s_nop 0
	global_load_lds_dwordx4 v[218:219], off
	v_lshl_add_u64 v[218:219], v[222:223], 0, s[8:9]
	s_mov_b32 m0, s59
	s_nop 0
	global_load_lds_dwordx4 v[218:219], off
	v_lshl_add_u64 v[218:219], v[224:225], 0, s[8:9]
	s_mov_b32 m0, s60
	s_nop 0
	global_load_lds_dwordx4 v[218:219], off
	s_waitcnt vmcnt(8)
	s_waitcnt lgkmcnt(0)
	s_barrier
	s_setprio 1
	s_waitcnt lgkmcnt(0)
	v_mfma_f32_16x16x32_bf16 v[62:65], v[146:149], v[184:187], v[62:65]
	v_mfma_f32_16x16x32_bf16 v[54:57], v[160:163], v[184:187], v[54:57]
	v_mfma_f32_16x16x32_bf16 v[46:49], v[146:149], v[192:195], v[46:49]
	v_mfma_f32_16x16x32_bf16 v[38:41], v[160:163], v[192:195], v[38:41]
	v_mfma_f32_16x16x32_bf16 v[30:33], v[146:149], v[200:203], v[30:33]
	v_mfma_f32_16x16x32_bf16 v[22:25], v[160:163], v[200:203], v[22:25]
	v_mfma_f32_16x16x32_bf16 v[14:17], v[146:149], v[208:211], v[14:17]
	v_mfma_f32_16x16x32_bf16 v[6:9], v[160:163], v[208:211], v[6:9]
	v_mfma_f32_16x16x32_bf16 v[62:65], v[156:159], v[188:191], v[62:65]
	v_mfma_f32_16x16x32_bf16 v[54:57], v[164:167], v[188:191], v[54:57]
	v_mfma_f32_16x16x32_bf16 v[46:49], v[156:159], v[196:199], v[46:49]
	v_mfma_f32_16x16x32_bf16 v[38:41], v[164:167], v[196:199], v[38:41]
	v_mfma_f32_16x16x32_bf16 v[30:33], v[156:159], v[204:207], v[30:33]
	v_mfma_f32_16x16x32_bf16 v[22:25], v[164:167], v[204:207], v[22:25]
	v_mfma_f32_16x16x32_bf16 v[14:17], v[156:159], v[212:215], v[14:17]
	v_mfma_f32_16x16x32_bf16 v[6:9], v[164:167], v[212:215], v[6:9]
	s_setprio 0
	s_setprio 1
	v_mfma_f32_16x16x32_bf16 v[58:61], v[168:171], v[184:187], v[58:61]
	v_mfma_f32_16x16x32_bf16 v[50:53], v[176:179], v[184:187], v[50:53]
	v_mfma_f32_16x16x32_bf16 v[42:45], v[168:171], v[192:195], v[42:45]
	v_mfma_f32_16x16x32_bf16 v[34:37], v[176:179], v[192:195], v[34:37]
	v_mfma_f32_16x16x32_bf16 v[26:29], v[168:171], v[200:203], v[26:29]
	v_mfma_f32_16x16x32_bf16 v[18:21], v[176:179], v[200:203], v[18:21]
	v_mfma_f32_16x16x32_bf16 v[10:13], v[168:171], v[208:211], v[10:13]
	v_mfma_f32_16x16x32_bf16 v[2:5], v[176:179], v[208:211], v[2:5]
	v_mfma_f32_16x16x32_bf16 v[58:61], v[172:175], v[188:191], v[58:61]
	v_mfma_f32_16x16x32_bf16 v[50:53], v[180:183], v[188:191], v[50:53]
	v_mfma_f32_16x16x32_bf16 v[42:45], v[172:175], v[196:199], v[42:45]
	v_mfma_f32_16x16x32_bf16 v[34:37], v[180:183], v[196:199], v[34:37]
	v_mfma_f32_16x16x32_bf16 v[26:29], v[172:175], v[204:207], v[26:29]
	v_mfma_f32_16x16x32_bf16 v[18:21], v[180:183], v[204:207], v[18:21]
	v_mfma_f32_16x16x32_bf16 v[10:13], v[172:175], v[212:215], v[10:13]
	v_mfma_f32_16x16x32_bf16 v[2:5], v[180:183], v[212:215], v[2:5]
	s_setprio 0
	s_barrier
	s_add_i32 s85, s85, 2
	s_add_u32 s76, s76, 0x100
	s_addc_u32 s77, s77, 0
	s_add_u32 s83, s83, 0x100
	s_addc_u32 s84, s84, 0

.LBB0_386:
	s_add_u32 s72, s72, 0x160080
	s_addc_u32 s73, s73, 0
	s_add_u32 s0, s74, 0x100
	s_addc_u32 s1, s75, 0
	s_mov_b32 s81, -2
	s_waitcnt vmcnt(0)
	ds_read_b128 v[146:149], v154
	ds_read_b128 v[158:161], v154 offset:1024
	ds_read_b128 v[162:165], v154 offset:2048
	ds_read_b128 v[166:169], v154 offset:3072
	ds_read_b128 v[170:173], v155
	ds_read_b128 v[174:177], v155 offset:1024
	ds_read_b128 v[178:181], v155 offset:2048
	ds_read_b128 v[182:185], v155 offset:3072
	s_add_u32 s34, s72, 0xffea0080
	s_addc_u32 s35, s73, -1
	s_cmpk_eq_i32 s81, 0x54
	s_cselect_b32 s75, s5, s35
	s_cselect_b32 s74, s4, s34
	s_cselect_b32 s35, s71, s1
	s_cselect_b32 s34, s70, s0
	v_lshl_add_u64 v[150:151], s[72:73], 0, v[138:139]
	s_add_i32 m0, s53, 0xc000
	ds_read_b128 v[186:189], v156
	ds_read_b128 v[190:193], v156 offset:1024
	ds_read_b128 v[194:197], v156 offset:2048
	ds_read_b128 v[198:201], v156 offset:3072
	ds_read_b128 v[202:205], v156 offset:4096
	ds_read_b128 v[206:209], v156 offset:5120
	ds_read_b128 v[210:213], v156 offset:6144
	ds_read_b128 v[218:221], v156 offset:7168
	global_load_lds_dwordx4 v[150:151], off
	v_lshl_add_u64 v[150:151], s[72:73], 0, v[140:141]
	s_add_i32 m0, s53, 0xe000
	s_nop 0
	global_load_lds_dwordx4 v[150:151], off
	s_waitcnt vmcnt(8)
	s_waitcnt lgkmcnt(0)
	s_barrier
	s_setprio 1
	s_waitcnt lgkmcnt(0)
	v_mfma_f32_16x16x32_bf16 v[126:129], v[146:149], v[186:189], 0
	v_mfma_f32_16x16x32_bf16 v[122:125], v[162:165], v[186:189], 0
	v_mfma_f32_16x16x32_bf16 v[118:121], v[146:149], v[194:197], 0
	v_mfma_f32_16x16x32_bf16 v[114:117], v[162:165], v[194:197], 0
	v_mfma_f32_16x16x32_bf16 v[94:97], v[146:149], v[202:205], 0
	v_mfma_f32_16x16x32_bf16 v[90:93], v[162:165], v[202:205], 0
	v_mfma_f32_16x16x32_bf16 v[86:89], v[146:149], v[210:213], 0
	v_mfma_f32_16x16x32_bf16 v[82:85], v[162:165], v[210:213], 0
	v_mfma_f32_16x16x32_bf16 v[126:129], v[158:161], v[190:193], v[126:129]
	v_mfma_f32_16x16x32_bf16 v[122:125], v[166:169], v[190:193], v[122:125]
	v_mfma_f32_16x16x32_bf16 v[118:121], v[158:161], v[198:201], v[118:121]
	v_mfma_f32_16x16x32_bf16 v[114:117], v[166:169], v[198:201], v[114:117]
	v_mfma_f32_16x16x32_bf16 v[94:97], v[158:161], v[206:209], v[94:97]
	v_mfma_f32_16x16x32_bf16 v[90:93], v[166:169], v[206:209], v[90:93]
	v_mfma_f32_16x16x32_bf16 v[86:89], v[158:161], v[218:221], v[86:89]
	v_mfma_f32_16x16x32_bf16 v[82:85], v[166:169], v[218:221], v[82:85]
	s_setprio 0
	s_setprio 1
	v_mfma_f32_16x16x32_bf16 v[110:113], v[170:173], v[186:189], 0
	v_mfma_f32_16x16x32_bf16 v[106:109], v[178:181], v[186:189], 0
	v_mfma_f32_16x16x32_bf16 v[102:105], v[170:173], v[194:197], 0
	v_mfma_f32_16x16x32_bf16 v[98:101], v[178:181], v[194:197], 0
	v_mfma_f32_16x16x32_bf16 v[78:81], v[170:173], v[202:205], 0
	v_mfma_f32_16x16x32_bf16 v[74:77], v[178:181], v[202:205], 0
	v_mfma_f32_16x16x32_bf16 v[70:73], v[170:173], v[210:213], 0
	v_mfma_f32_16x16x32_bf16 v[66:69], v[178:181], v[210:213], 0
	v_mfma_f32_16x16x32_bf16 v[110:113], v[174:177], v[190:193], v[110:113]
	v_mfma_f32_16x16x32_bf16 v[106:109], v[182:185], v[190:193], v[106:109]
	v_mfma_f32_16x16x32_bf16 v[102:105], v[174:177], v[198:201], v[102:105]
	v_mfma_f32_16x16x32_bf16 v[98:101], v[182:185], v[198:201], v[98:101]
	v_mfma_f32_16x16x32_bf16 v[78:81], v[174:177], v[206:209], v[78:81]
	v_mfma_f32_16x16x32_bf16 v[74:77], v[182:185], v[206:209], v[74:77]
	v_mfma_f32_16x16x32_bf16 v[70:73], v[174:177], v[218:221], v[70:73]
	v_mfma_f32_16x16x32_bf16 v[66:69], v[182:185], v[218:221], v[66:69]
	s_setprio 0
	s_barrier
	s_add_i32 s62, s61, s52
	v_lshl_add_u64 v[150:151], s[34:35], 0, v[132:133]
	s_mov_b32 m0, s62
	ds_read_b128 v[186:189], v156 offset:16384
	ds_read_b128 v[190:193], v156 offset:17408
	ds_read_b128 v[194:197], v156 offset:18432
	ds_read_b128 v[198:201], v156 offset:19456
	ds_read_b128 v[202:205], v156 offset:20480
	ds_read_b128 v[206:209], v156 offset:21504
	ds_read_b128 v[210:213], v156 offset:22528
	ds_read_b128 v[218:221], v156 offset:23552
	global_load_lds_dwordx4 v[150:151], off
	s_add_i32 m0, s62, 0x2000
	s_add_u32 s62, s34, 0x160000
	v_lshl_add_u64 v[214:215], s[34:35], 0, v[136:137]
	s_addc_u32 s63, s35, 0
	s_add_i32 s82, s76, s52
	global_load_lds_dwordx4 v[214:215], off
	v_lshl_add_u64 v[222:223], s[62:63], 0, v[132:133]
	s_mov_b32 m0, s82
	v_lshl_add_u64 v[224:225], s[74:75], 0, v[134:135]
	global_load_lds_dwordx4 v[222:223], off
	v_lshl_add_u64 v[222:223], s[62:63], 0, v[136:137]
	s_add_i32 m0, s82, 0x2000
	s_nop 0
	global_load_lds_dwordx4 v[222:223], off
	v_lshl_add_u64 v[222:223], s[74:75], 0, v[130:131]
	s_mov_b32 m0, s53
	s_nop 0
	global_load_lds_dwordx4 v[222:223], off
	s_mov_b32 m0, s54
	s_nop 0
	global_load_lds_dwordx4 v[224:225], off
	s_waitcnt vmcnt(8)
	s_waitcnt lgkmcnt(0)
	s_barrier
	s_setprio 1
	s_waitcnt lgkmcnt(0)
	v_mfma_f32_16x16x32_bf16 v[62:65], v[146:149], v[186:189], 0
	v_mfma_f32_16x16x32_bf16 v[58:61], v[162:165], v[186:189], 0
	v_mfma_f32_16x16x32_bf16 v[54:57], v[146:149], v[194:197], 0
	v_mfma_f32_16x16x32_bf16 v[50:53], v[162:165], v[194:197], 0
	v_mfma_f32_16x16x32_bf16 v[30:33], v[146:149], v[202:205], 0
	v_mfma_f32_16x16x32_bf16 v[26:29], v[162:165], v[202:205], 0
	v_mfma_f32_16x16x32_bf16 v[22:25], v[146:149], v[210:213], 0
	v_mfma_f32_16x16x32_bf16 v[18:21], v[162:165], v[210:213], 0
	v_mfma_f32_16x16x32_bf16 v[62:65], v[158:161], v[190:193], v[62:65]
	v_mfma_f32_16x16x32_bf16 v[58:61], v[166:169], v[190:193], v[58:61]
	v_mfma_f32_16x16x32_bf16 v[54:57], v[158:161], v[198:201], v[54:57]
	v_mfma_f32_16x16x32_bf16 v[50:53], v[166:169], v[198:201], v[50:53]
	v_mfma_f32_16x16x32_bf16 v[30:33], v[158:161], v[206:209], v[30:33]
	v_mfma_f32_16x16x32_bf16 v[26:29], v[166:169], v[206:209], v[26:29]
	v_mfma_f32_16x16x32_bf16 v[22:25], v[158:161], v[218:221], v[22:25]
	v_mfma_f32_16x16x32_bf16 v[18:21], v[166:169], v[218:221], v[18:21]
	s_setprio 0
	s_setprio 1
	v_mfma_f32_16x16x32_bf16 v[46:49], v[170:173], v[186:189], 0
	v_mfma_f32_16x16x32_bf16 v[42:45], v[178:181], v[186:189], 0
	v_mfma_f32_16x16x32_bf16 v[38:41], v[170:173], v[194:197], 0
	v_mfma_f32_16x16x32_bf16 v[34:37], v[178:181], v[194:197], 0
	v_mfma_f32_16x16x32_bf16 v[14:17], v[170:173], v[202:205], 0
	v_mfma_f32_16x16x32_bf16 v[10:13], v[178:181], v[202:205], 0
	v_mfma_f32_16x16x32_bf16 v[6:9], v[170:173], v[210:213], 0
	v_mfma_f32_16x16x32_bf16 v[2:5], v[178:181], v[210:213], 0
	v_mfma_f32_16x16x32_bf16 v[46:49], v[174:177], v[190:193], v[46:49]
	v_mfma_f32_16x16x32_bf16 v[42:45], v[182:185], v[190:193], v[42:45]
	v_mfma_f32_16x16x32_bf16 v[38:41], v[174:177], v[198:201], v[38:41]
	v_mfma_f32_16x16x32_bf16 v[34:37], v[182:185], v[198:201], v[34:37]
	v_mfma_f32_16x16x32_bf16 v[14:17], v[174:177], v[206:209], v[14:17]
	v_mfma_f32_16x16x32_bf16 v[10:13], v[182:185], v[206:209], v[10:13]
	v_mfma_f32_16x16x32_bf16 v[6:9], v[174:177], v[218:221], v[6:9]
	v_mfma_f32_16x16x32_bf16 v[2:5], v[182:185], v[218:221], v[2:5]
	s_setprio 0
	s_barrier
	s_add_i32 s82, 0, 0x18000
	v_add_u32_e32 v157, s82, v152
	s_add_i32 s83, 0, 0x1c000
	ds_read_b128 v[146:149], v157
	ds_read_b128 v[158:161], v157 offset:1024
	ds_read_b128 v[162:165], v157 offset:2048
	ds_read_b128 v[166:169], v157 offset:3072
	v_add_u32_e32 v157, s83, v152
	ds_read_b128 v[170:173], v157
	ds_read_b128 v[174:177], v157 offset:1024
	ds_read_b128 v[178:181], v157 offset:2048
	ds_read_b128 v[182:185], v157 offset:3072
	s_add_u32 s62, s74, 0x160000
	s_addc_u32 s63, s75, 0
	s_mov_b32 m0, s55
	v_lshl_add_u64 v[226:227], s[62:63], 0, v[130:131]
	ds_read_b128 v[186:189], v156 offset:32768
	ds_read_b128 v[190:193], v156 offset:33792
	ds_read_b128 v[194:197], v156 offset:34816
	ds_read_b128 v[198:201], v156 offset:35840
	ds_read_b128 v[202:205], v156 offset:36864
	ds_read_b128 v[206:209], v156 offset:37888
	ds_read_b128 v[210:213], v156 offset:38912
	ds_read_b128 v[218:221], v156 offset:39936
	global_load_lds_dwordx4 v[226:227], off
	v_lshl_add_u64 v[226:227], s[62:63], 0, v[134:135]
	s_mov_b32 m0, s56
	s_nop 0
	global_load_lds_dwordx4 v[226:227], off
	s_waitcnt vmcnt(8)
	s_waitcnt lgkmcnt(0)
	s_barrier
	s_setprio 1
	s_waitcnt lgkmcnt(0)
	v_mfma_f32_16x16x32_bf16 v[126:129], v[146:149], v[186:189], v[126:129]
	v_mfma_f32_16x16x32_bf16 v[122:125], v[162:165], v[186:189], v[122:125]
	v_mfma_f32_16x16x32_bf16 v[118:121], v[146:149], v[194:197], v[118:121]
	v_mfma_f32_16x16x32_bf16 v[114:117], v[162:165], v[194:197], v[114:117]
	v_mfma_f32_16x16x32_bf16 v[94:97], v[146:149], v[202:205], v[94:97]
	v_mfma_f32_16x16x32_bf16 v[90:93], v[162:165], v[202:205], v[90:93]
	v_mfma_f32_16x16x32_bf16 v[86:89], v[146:149], v[210:213], v[86:89]
	v_mfma_f32_16x16x32_bf16 v[82:85], v[162:165], v[210:213], v[82:85]
	v_mfma_f32_16x16x32_bf16 v[126:129], v[158:161], v[190:193], v[126:129]
	v_mfma_f32_16x16x32_bf16 v[122:125], v[166:169], v[190:193], v[122:125]
	v_mfma_f32_16x16x32_bf16 v[118:121], v[158:161], v[198:201], v[118:121]
	v_mfma_f32_16x16x32_bf16 v[114:117], v[166:169], v[198:201], v[114:117]
	v_mfma_f32_16x16x32_bf16 v[94:97], v[158:161], v[206:209], v[94:97]
	v_mfma_f32_16x16x32_bf16 v[90:93], v[166:169], v[206:209], v[90:93]
	v_mfma_f32_16x16x32_bf16 v[86:89], v[158:161], v[218:221], v[86:89]
	v_mfma_f32_16x16x32_bf16 v[82:85], v[166:169], v[218:221], v[82:85]
	s_setprio 0
	s_setprio 1
	v_mfma_f32_16x16x32_bf16 v[110:113], v[170:173], v[186:189], v[110:113]
	v_mfma_f32_16x16x32_bf16 v[106:109], v[178:181], v[186:189], v[106:109]
	v_mfma_f32_16x16x32_bf16 v[102:105], v[170:173], v[194:197], v[102:105]
	v_mfma_f32_16x16x32_bf16 v[98:101], v[178:181], v[194:197], v[98:101]
	v_mfma_f32_16x16x32_bf16 v[78:81], v[170:173], v[202:205], v[78:81]
	v_mfma_f32_16x16x32_bf16 v[74:77], v[178:181], v[202:205], v[74:77]
	v_mfma_f32_16x16x32_bf16 v[70:73], v[170:173], v[210:213], v[70:73]
	v_mfma_f32_16x16x32_bf16 v[66:69], v[178:181], v[210:213], v[66:69]
	v_mfma_f32_16x16x32_bf16 v[110:113], v[174:177], v[190:193], v[110:113]
	v_mfma_f32_16x16x32_bf16 v[106:109], v[182:185], v[190:193], v[106:109]
	v_mfma_f32_16x16x32_bf16 v[102:105], v[174:177], v[198:201], v[102:105]
	v_mfma_f32_16x16x32_bf16 v[98:101], v[182:185], v[198:201], v[98:101]
	v_mfma_f32_16x16x32_bf16 v[78:81], v[174:177], v[206:209], v[78:81]
	v_mfma_f32_16x16x32_bf16 v[74:77], v[182:185], v[206:209], v[74:77]
	v_mfma_f32_16x16x32_bf16 v[70:73], v[174:177], v[218:221], v[70:73]
	v_mfma_f32_16x16x32_bf16 v[66:69], v[182:185], v[218:221], v[66:69]
	s_setprio 0
	s_barrier
	s_add_i32 s62, s82, s52
	v_lshl_add_u64 v[150:151], v[150:151], 0, s[66:67]
	s_mov_b32 m0, s62
	ds_read_b128 v[186:189], v156 offset:49152
	ds_read_b128 v[190:193], v156 offset:50176
	ds_read_b128 v[194:197], v156 offset:51200
	ds_read_b128 v[198:201], v156 offset:52224
	ds_read_b128 v[202:205], v156 offset:53248
	ds_read_b128 v[206:209], v156 offset:54272
	ds_read_b128 v[210:213], v156 offset:55296
	ds_read_b128 v[218:221], v156 offset:56320
	global_load_lds_dwordx4 v[150:151], off
	s_add_i32 m0, s62, 0x2000
	s_add_u32 s34, s34, 0x160080
	v_lshl_add_u64 v[150:151], v[214:215], 0, s[66:67]
	s_addc_u32 s35, s35, 0
	s_add_i32 s62, s83, s52
	global_load_lds_dwordx4 v[150:151], off
	v_lshl_add_u64 v[150:151], s[34:35], 0, v[132:133]
	s_mov_b32 m0, s62
	s_nop 0
	global_load_lds_dwordx4 v[150:151], off
	v_lshl_add_u64 v[150:151], s[34:35], 0, v[136:137]
	s_add_i32 m0, s62, 0x2000
	s_nop 0
	global_load_lds_dwordx4 v[150:151], off
	v_lshl_add_u64 v[150:151], v[222:223], 0, s[66:67]
	s_mov_b32 m0, s58
	s_nop 0
	global_load_lds_dwordx4 v[150:151], off
	v_lshl_add_u64 v[150:151], v[224:225], 0, s[66:67]
	s_mov_b32 m0, s59
	s_nop 0
	global_load_lds_dwordx4 v[150:151], off
	s_waitcnt vmcnt(8)
	s_waitcnt lgkmcnt(0)
	s_barrier
	s_setprio 1
	s_waitcnt lgkmcnt(0)
	v_mfma_f32_16x16x32_bf16 v[62:65], v[146:149], v[186:189], v[62:65]
	v_mfma_f32_16x16x32_bf16 v[58:61], v[162:165], v[186:189], v[58:61]
	v_mfma_f32_16x16x32_bf16 v[54:57], v[146:149], v[194:197], v[54:57]
	v_mfma_f32_16x16x32_bf16 v[50:53], v[162:165], v[194:197], v[50:53]
	v_mfma_f32_16x16x32_bf16 v[30:33], v[146:149], v[202:205], v[30:33]
	v_mfma_f32_16x16x32_bf16 v[26:29], v[162:165], v[202:205], v[26:29]
	v_mfma_f32_16x16x32_bf16 v[22:25], v[146:149], v[210:213], v[22:25]
	v_mfma_f32_16x16x32_bf16 v[18:21], v[162:165], v[210:213], v[18:21]
	v_mfma_f32_16x16x32_bf16 v[62:65], v[158:161], v[190:193], v[62:65]
	v_mfma_f32_16x16x32_bf16 v[58:61], v[166:169], v[190:193], v[58:61]
	v_mfma_f32_16x16x32_bf16 v[54:57], v[158:161], v[198:201], v[54:57]
	v_mfma_f32_16x16x32_bf16 v[50:53], v[166:169], v[198:201], v[50:53]
	v_mfma_f32_16x16x32_bf16 v[30:33], v[158:161], v[206:209], v[30:33]
	v_mfma_f32_16x16x32_bf16 v[26:29], v[166:169], v[206:209], v[26:29]
	v_mfma_f32_16x16x32_bf16 v[22:25], v[158:161], v[218:221], v[22:25]
	v_mfma_f32_16x16x32_bf16 v[18:21], v[166:169], v[218:221], v[18:21]
	s_setprio 0
	s_setprio 1
	v_mfma_f32_16x16x32_bf16 v[46:49], v[170:173], v[186:189], v[46:49]
	v_mfma_f32_16x16x32_bf16 v[42:45], v[178:181], v[186:189], v[42:45]
	v_mfma_f32_16x16x32_bf16 v[38:41], v[170:173], v[194:197], v[38:41]
	v_mfma_f32_16x16x32_bf16 v[34:37], v[178:181], v[194:197], v[34:37]
	v_mfma_f32_16x16x32_bf16 v[14:17], v[170:173], v[202:205], v[14:17]
	v_mfma_f32_16x16x32_bf16 v[10:13], v[178:181], v[202:205], v[10:13]
	v_mfma_f32_16x16x32_bf16 v[6:9], v[170:173], v[210:213], v[6:9]
	v_mfma_f32_16x16x32_bf16 v[2:5], v[178:181], v[210:213], v[2:5]
	v_mfma_f32_16x16x32_bf16 v[46:49], v[174:177], v[190:193], v[46:49]
	v_mfma_f32_16x16x32_bf16 v[42:45], v[182:185], v[190:193], v[42:45]
	v_mfma_f32_16x16x32_bf16 v[38:41], v[174:177], v[198:201], v[38:41]
	v_mfma_f32_16x16x32_bf16 v[34:37], v[182:185], v[198:201], v[34:37]
	v_mfma_f32_16x16x32_bf16 v[14:17], v[174:177], v[206:209], v[14:17]
	v_mfma_f32_16x16x32_bf16 v[10:13], v[182:185], v[206:209], v[10:13]
	v_mfma_f32_16x16x32_bf16 v[6:9], v[174:177], v[218:221], v[6:9]
	v_mfma_f32_16x16x32_bf16 v[2:5], v[182:185], v[218:221], v[2:5]
	s_setprio 0
	s_barrier
	s_add_i32 s81, s81, 2
	s_add_u32 s72, s72, 0x100
	s_addc_u32 s73, s73, 0
	s_add_u32 s0, s0, 0x100
	s_addc_u32 s1, s1, 0

.LBB0_517:
	s_ashr_i32 s85, s84, 31
	s_lshl_b64 s[0:1], s[84:85], 20
	v_readlane_b32 s7, v247, 45
	s_add_u32 s86, s7, s0
	v_readlane_b32 s0, v247, 47
	s_addc_u32 s87, s0, s1
	s_and_b64 s[0:1], s[4:5], exec
	s_cselect_b32 s0, s87, s91
	s_cselect_b32 s1, s86, s90
	s_ashr_i32 s83, s82, 31
	s_lshl_b64 s[34:35], s[82:83], 20
	s_add_u32 s88, s31, s34
	s_addc_u32 s89, s33, s35
	s_and_b64 s[34:35], s[4:5], exec
	s_cselect_b32 s7, s89, s93
	s_cselect_b32 s9, s88, s92
	s_add_u32 s90, s90, 0x80080
	s_addc_u32 s91, s91, 0
	s_add_u32 s52, s92, 0x100
	s_addc_u32 s68, s93, 0
	s_mov_b32 s83, -2
	s_waitcnt lgkmcnt(0)
	ds_read_b128 v[160:163], v155
	ds_read_b128 v[164:167], v155 offset:1024
	ds_read_b128 v[168:171], v155 offset:2048
	ds_read_b128 v[172:175], v155 offset:3072
	ds_read_b128 v[176:179], v156
	ds_read_b128 v[180:183], v156 offset:1024
	ds_read_b128 v[184:187], v156 offset:2048
	ds_read_b128 v[188:191], v156 offset:3072
	s_add_u32 s34, s90, 0xfff80080
	s_addc_u32 s35, s91, -1
	s_cmp_eq_u32 s83, 28
	s_cselect_b32 s93, s0, s35
	s_cselect_b32 s92, s1, s34
	s_cselect_b32 s35, s7, s68
	s_cselect_b32 s34, s9, s52
	v_lshl_add_u64 v[152:153], s[90:91], 0, v[144:145]
	s_add_i32 m0, s56, 0xc000
	ds_read_b128 v[192:195], v157
	ds_read_b128 v[196:199], v157 offset:1024
	ds_read_b128 v[200:203], v157 offset:2048
	ds_read_b128 v[204:207], v157 offset:3072
	ds_read_b128 v[208:211], v157 offset:4096
	ds_read_b128 v[212:215], v157 offset:5120
	ds_read_b128 v[218:221], v157 offset:6144
	ds_read_b128 v[222:225], v157 offset:7168
	global_load_lds_dwordx4 v[152:153], off
	v_lshl_add_u64 v[152:153], s[90:91], 0, v[146:147]
	s_add_i32 m0, s56, 0xe000
	s_nop 0
	global_load_lds_dwordx4 v[152:153], off
	s_waitcnt vmcnt(8)
	s_waitcnt lgkmcnt(0)
	s_barrier
	s_setprio 1
	s_waitcnt lgkmcnt(0)
	v_mfma_f32_16x16x32_bf16 v[126:129], v[160:163], v[192:195], 0
	v_mfma_f32_16x16x32_bf16 v[122:125], v[168:171], v[192:195], 0
	v_mfma_f32_16x16x32_bf16 v[110:113], v[160:163], v[200:203], 0
	v_mfma_f32_16x16x32_bf16 v[106:109], v[168:171], v[200:203], 0
	v_mfma_f32_16x16x32_bf16 v[94:97], v[160:163], v[208:211], 0
	v_mfma_f32_16x16x32_bf16 v[90:93], v[168:171], v[208:211], 0
	v_mfma_f32_16x16x32_bf16 v[78:81], v[160:163], v[218:221], 0
	v_mfma_f32_16x16x32_bf16 v[74:77], v[168:171], v[218:221], 0
	v_mfma_f32_16x16x32_bf16 v[126:129], v[164:167], v[196:199], v[126:129]
	v_mfma_f32_16x16x32_bf16 v[122:125], v[172:175], v[196:199], v[122:125]
	v_mfma_f32_16x16x32_bf16 v[110:113], v[164:167], v[204:207], v[110:113]
	v_mfma_f32_16x16x32_bf16 v[106:109], v[172:175], v[204:207], v[106:109]
	v_mfma_f32_16x16x32_bf16 v[94:97], v[164:167], v[212:215], v[94:97]
	v_mfma_f32_16x16x32_bf16 v[90:93], v[172:175], v[212:215], v[90:93]
	v_mfma_f32_16x16x32_bf16 v[78:81], v[164:167], v[222:225], v[78:81]
	v_mfma_f32_16x16x32_bf16 v[74:77], v[172:175], v[222:225], v[74:77]
	s_setprio 0
	s_setprio 1
	v_mfma_f32_16x16x32_bf16 v[118:121], v[176:179], v[192:195], 0
	v_mfma_f32_16x16x32_bf16 v[114:117], v[184:187], v[192:195], 0
	v_mfma_f32_16x16x32_bf16 v[102:105], v[176:179], v[200:203], 0
	v_mfma_f32_16x16x32_bf16 v[98:101], v[184:187], v[200:203], 0
	v_mfma_f32_16x16x32_bf16 v[86:89], v[176:179], v[208:211], 0
	v_mfma_f32_16x16x32_bf16 v[82:85], v[184:187], v[208:211], 0
	v_mfma_f32_16x16x32_bf16 v[70:73], v[176:179], v[218:221], 0
	v_mfma_f32_16x16x32_bf16 v[66:69], v[184:187], v[218:221], 0
	v_mfma_f32_16x16x32_bf16 v[118:121], v[180:183], v[196:199], v[118:121]
	v_mfma_f32_16x16x32_bf16 v[114:117], v[188:191], v[196:199], v[114:117]
	v_mfma_f32_16x16x32_bf16 v[102:105], v[180:183], v[204:207], v[102:105]
	v_mfma_f32_16x16x32_bf16 v[98:101], v[188:191], v[204:207], v[98:101]
	v_mfma_f32_16x16x32_bf16 v[86:89], v[180:183], v[212:215], v[86:89]
	v_mfma_f32_16x16x32_bf16 v[82:85], v[188:191], v[212:215], v[82:85]
	v_mfma_f32_16x16x32_bf16 v[70:73], v[180:183], v[222:225], v[70:73]
	v_mfma_f32_16x16x32_bf16 v[66:69], v[188:191], v[222:225], v[66:69]
	s_setprio 0
	s_barrier
	s_add_i32 s53, s75, s30
	v_lshl_add_u64 v[152:153], s[34:35], 0, v[132:133]
	s_mov_b32 m0, s53
	ds_read_b128 v[192:195], v157 offset:16384
	ds_read_b128 v[196:199], v157 offset:17408
	ds_read_b128 v[200:203], v157 offset:18432
	ds_read_b128 v[204:207], v157 offset:19456
	ds_read_b128 v[208:211], v157 offset:20480
	ds_read_b128 v[212:215], v157 offset:21504
	ds_read_b128 v[218:221], v157 offset:22528
	ds_read_b128 v[222:225], v157 offset:23552
	global_load_lds_dwordx4 v[152:153], off
	s_add_i32 m0, s53, 0x2000
	s_add_u32 s54, s34, 0x80000
	v_lshl_add_u64 v[226:227], s[34:35], 0, v[136:137]
	s_addc_u32 s55, s35, 0
	s_add_i32 s53, s94, s30
	global_load_lds_dwordx4 v[226:227], off
	v_lshl_add_u64 v[228:229], s[54:55], 0, v[132:133]
	s_mov_b32 m0, s53
	v_lshl_add_u64 v[230:231], s[92:93], 0, v[134:135]
	global_load_lds_dwordx4 v[228:229], off
	v_lshl_add_u64 v[228:229], s[54:55], 0, v[136:137]
	s_add_i32 m0, s53, 0x2000
	s_nop 0
	global_load_lds_dwordx4 v[228:229], off
	v_lshl_add_u64 v[228:229], s[92:93], 0, v[130:131]
	s_mov_b32 m0, s56
	s_nop 0
	global_load_lds_dwordx4 v[228:229], off
	s_mov_b32 m0, s57
	s_nop 0
	global_load_lds_dwordx4 v[230:231], off
	s_waitcnt vmcnt(8)
	s_waitcnt lgkmcnt(0)
	s_barrier
	s_setprio 1
	s_waitcnt lgkmcnt(0)
	v_mfma_f32_16x16x32_bf16 v[62:65], v[160:163], v[192:195], 0
	v_mfma_f32_16x16x32_bf16 v[58:61], v[168:171], v[192:195], 0
	v_mfma_f32_16x16x32_bf16 v[46:49], v[160:163], v[200:203], 0
	v_mfma_f32_16x16x32_bf16 v[42:45], v[168:171], v[200:203], 0
	v_mfma_f32_16x16x32_bf16 v[30:33], v[160:163], v[208:211], 0
	v_mfma_f32_16x16x32_bf16 v[26:29], v[168:171], v[208:211], 0
	v_mfma_f32_16x16x32_bf16 v[14:17], v[160:163], v[218:221], 0
	v_mfma_f32_16x16x32_bf16 v[10:13], v[168:171], v[218:221], 0
	v_mfma_f32_16x16x32_bf16 v[62:65], v[164:167], v[196:199], v[62:65]
	v_mfma_f32_16x16x32_bf16 v[58:61], v[172:175], v[196:199], v[58:61]
	v_mfma_f32_16x16x32_bf16 v[46:49], v[164:167], v[204:207], v[46:49]
	v_mfma_f32_16x16x32_bf16 v[42:45], v[172:175], v[204:207], v[42:45]
	v_mfma_f32_16x16x32_bf16 v[30:33], v[164:167], v[212:215], v[30:33]
	v_mfma_f32_16x16x32_bf16 v[26:29], v[172:175], v[212:215], v[26:29]
	v_mfma_f32_16x16x32_bf16 v[14:17], v[164:167], v[222:225], v[14:17]
	v_mfma_f32_16x16x32_bf16 v[10:13], v[172:175], v[222:225], v[10:13]
	s_setprio 0
	s_setprio 1
	v_mfma_f32_16x16x32_bf16 v[54:57], v[176:179], v[192:195], 0
	v_mfma_f32_16x16x32_bf16 v[50:53], v[184:187], v[192:195], 0
	v_mfma_f32_16x16x32_bf16 v[38:41], v[176:179], v[200:203], 0
	v_mfma_f32_16x16x32_bf16 v[34:37], v[184:187], v[200:203], 0
	v_mfma_f32_16x16x32_bf16 v[22:25], v[176:179], v[208:211], 0
	v_mfma_f32_16x16x32_bf16 v[18:21], v[184:187], v[208:211], 0
	v_mfma_f32_16x16x32_bf16 v[6:9], v[176:179], v[218:221], 0
	v_mfma_f32_16x16x32_bf16 v[2:5], v[184:187], v[218:221], 0
	v_mfma_f32_16x16x32_bf16 v[54:57], v[180:183], v[196:199], v[54:57]
	v_mfma_f32_16x16x32_bf16 v[50:53], v[188:191], v[196:199], v[50:53]
	v_mfma_f32_16x16x32_bf16 v[38:41], v[180:183], v[204:207], v[38:41]
	v_mfma_f32_16x16x32_bf16 v[34:37], v[188:191], v[204:207], v[34:37]
	v_mfma_f32_16x16x32_bf16 v[22:25], v[180:183], v[212:215], v[22:25]
	v_mfma_f32_16x16x32_bf16 v[18:21], v[188:191], v[212:215], v[18:21]
	v_mfma_f32_16x16x32_bf16 v[6:9], v[180:183], v[222:225], v[6:9]
	v_mfma_f32_16x16x32_bf16 v[2:5], v[188:191], v[222:225], v[2:5]
	s_setprio 0
	s_barrier
	s_add_i32 s53, 0, 0x18000
	v_add_u32_e32 v138, s53, v154
	s_add_i32 s62, 0, 0x1c000
	ds_read_b128 v[160:163], v138
	ds_read_b128 v[164:167], v138 offset:1024
	ds_read_b128 v[168:171], v138 offset:2048
	ds_read_b128 v[172:175], v138 offset:3072
	v_add_u32_e32 v138, s62, v154
	ds_read_b128 v[176:179], v138
	ds_read_b128 v[180:183], v138 offset:1024
	ds_read_b128 v[184:187], v138 offset:2048
	ds_read_b128 v[188:191], v138 offset:3072
	s_add_u32 s54, s92, 0x80000
	s_addc_u32 s55, s93, 0
	s_mov_b32 m0, s58
	v_lshl_add_u64 v[232:233], s[54:55], 0, v[130:131]
	ds_read_b128 v[192:195], v157 offset:32768
	ds_read_b128 v[196:199], v157 offset:33792
	ds_read_b128 v[200:203], v157 offset:34816
	ds_read_b128 v[204:207], v157 offset:35840
	ds_read_b128 v[208:211], v157 offset:36864
	ds_read_b128 v[212:215], v157 offset:37888
	ds_read_b128 v[218:221], v157 offset:38912
	ds_read_b128 v[222:225], v157 offset:39936
	global_load_lds_dwordx4 v[232:233], off
	v_lshl_add_u64 v[232:233], s[54:55], 0, v[134:135]
	s_mov_b32 m0, s59
	s_nop 0
	global_load_lds_dwordx4 v[232:233], off
	s_waitcnt vmcnt(8)
	s_waitcnt lgkmcnt(0)
	s_barrier
	s_setprio 1
	s_waitcnt lgkmcnt(0)
	v_mfma_f32_16x16x32_bf16 v[126:129], v[160:163], v[192:195], v[126:129]
	v_mfma_f32_16x16x32_bf16 v[122:125], v[168:171], v[192:195], v[122:125]
	v_mfma_f32_16x16x32_bf16 v[110:113], v[160:163], v[200:203], v[110:113]
	v_mfma_f32_16x16x32_bf16 v[106:109], v[168:171], v[200:203], v[106:109]
	v_mfma_f32_16x16x32_bf16 v[94:97], v[160:163], v[208:211], v[94:97]
	v_mfma_f32_16x16x32_bf16 v[90:93], v[168:171], v[208:211], v[90:93]
	v_mfma_f32_16x16x32_bf16 v[78:81], v[160:163], v[218:221], v[78:81]
	v_mfma_f32_16x16x32_bf16 v[74:77], v[168:171], v[218:221], v[74:77]
	v_mfma_f32_16x16x32_bf16 v[126:129], v[164:167], v[196:199], v[126:129]
	v_mfma_f32_16x16x32_bf16 v[122:125], v[172:175], v[196:199], v[122:125]
	v_mfma_f32_16x16x32_bf16 v[110:113], v[164:167], v[204:207], v[110:113]
	v_mfma_f32_16x16x32_bf16 v[106:109], v[172:175], v[204:207], v[106:109]
	v_mfma_f32_16x16x32_bf16 v[94:97], v[164:167], v[212:215], v[94:97]
	v_mfma_f32_16x16x32_bf16 v[90:93], v[172:175], v[212:215], v[90:93]
	v_mfma_f32_16x16x32_bf16 v[78:81], v[164:167], v[222:225], v[78:81]
	v_mfma_f32_16x16x32_bf16 v[74:77], v[172:175], v[222:225], v[74:77]
	s_setprio 0
	s_setprio 1
	v_mfma_f32_16x16x32_bf16 v[118:121], v[176:179], v[192:195], v[118:121]
	v_mfma_f32_16x16x32_bf16 v[114:117], v[184:187], v[192:195], v[114:117]
	v_mfma_f32_16x16x32_bf16 v[102:105], v[176:179], v[200:203], v[102:105]
	v_mfma_f32_16x16x32_bf16 v[98:101], v[184:187], v[200:203], v[98:101]
	v_mfma_f32_16x16x32_bf16 v[86:89], v[176:179], v[208:211], v[86:89]
	v_mfma_f32_16x16x32_bf16 v[82:85], v[184:187], v[208:211], v[82:85]
	v_mfma_f32_16x16x32_bf16 v[70:73], v[176:179], v[218:221], v[70:73]
	v_mfma_f32_16x16x32_bf16 v[66:69], v[184:187], v[218:221], v[66:69]
	v_mfma_f32_16x16x32_bf16 v[118:121], v[180:183], v[196:199], v[118:121]
	v_mfma_f32_16x16x32_bf16 v[114:117], v[188:191], v[196:199], v[114:117]
	v_mfma_f32_16x16x32_bf16 v[102:105], v[180:183], v[204:207], v[102:105]
	v_mfma_f32_16x16x32_bf16 v[98:101], v[188:191], v[204:207], v[98:101]
	v_mfma_f32_16x16x32_bf16 v[86:89], v[180:183], v[212:215], v[86:89]
	v_mfma_f32_16x16x32_bf16 v[82:85], v[188:191], v[212:215], v[82:85]
	v_mfma_f32_16x16x32_bf16 v[70:73], v[180:183], v[222:225], v[70:73]
	v_mfma_f32_16x16x32_bf16 v[66:69], v[188:191], v[222:225], v[66:69]
	s_setprio 0
	s_barrier
	s_add_i32 s53, s53, s30
	v_lshl_add_u64 v[152:153], v[152:153], 0, s[76:77]
	s_mov_b32 m0, s53
	ds_read_b128 v[192:195], v157 offset:49152
	ds_read_b128 v[196:199], v157 offset:50176
	ds_read_b128 v[200:203], v157 offset:51200
	ds_read_b128 v[204:207], v157 offset:52224
	ds_read_b128 v[208:211], v157 offset:53248
	ds_read_b128 v[212:215], v157 offset:54272
	ds_read_b128 v[218:221], v157 offset:55296
	ds_read_b128 v[222:225], v157 offset:56320
	global_load_lds_dwordx4 v[152:153], off
	s_add_i32 m0, s53, 0x2000
	s_add_u32 s34, s34, 0x80080
	v_lshl_add_u64 v[152:153], v[226:227], 0, s[76:77]
	s_addc_u32 s35, s35, 0
	s_add_i32 s53, s62, s30
	global_load_lds_dwordx4 v[152:153], off
	v_lshl_add_u64 v[152:153], s[34:35], 0, v[132:133]
	s_mov_b32 m0, s53
	s_nop 0
	global_load_lds_dwordx4 v[152:153], off
	v_lshl_add_u64 v[152:153], s[34:35], 0, v[136:137]
	s_add_i32 m0, s53, 0x2000
	s_nop 0
	global_load_lds_dwordx4 v[152:153], off
	v_lshl_add_u64 v[152:153], v[228:229], 0, s[76:77]
	s_mov_b32 m0, s61
	s_nop 0
	global_load_lds_dwordx4 v[152:153], off
	v_lshl_add_u64 v[152:153], v[230:231], 0, s[76:77]
	s_mov_b32 m0, s72
	s_nop 0
	global_load_lds_dwordx4 v[152:153], off
	s_waitcnt vmcnt(8)
	s_waitcnt lgkmcnt(0)
	s_barrier
	s_setprio 1
	s_waitcnt lgkmcnt(0)
	v_mfma_f32_16x16x32_bf16 v[62:65], v[160:163], v[192:195], v[62:65]
	v_mfma_f32_16x16x32_bf16 v[58:61], v[168:171], v[192:195], v[58:61]
	v_mfma_f32_16x16x32_bf16 v[46:49], v[160:163], v[200:203], v[46:49]
	v_mfma_f32_16x16x32_bf16 v[42:45], v[168:171], v[200:203], v[42:45]
	v_mfma_f32_16x16x32_bf16 v[30:33], v[160:163], v[208:211], v[30:33]
	v_mfma_f32_16x16x32_bf16 v[26:29], v[168:171], v[208:211], v[26:29]
	v_mfma_f32_16x16x32_bf16 v[14:17], v[160:163], v[218:221], v[14:17]
	v_mfma_f32_16x16x32_bf16 v[10:13], v[168:171], v[218:221], v[10:13]
	v_mfma_f32_16x16x32_bf16 v[62:65], v[164:167], v[196:199], v[62:65]
	v_mfma_f32_16x16x32_bf16 v[58:61], v[172:175], v[196:199], v[58:61]
	v_mfma_f32_16x16x32_bf16 v[46:49], v[164:167], v[204:207], v[46:49]
	v_mfma_f32_16x16x32_bf16 v[42:45], v[172:175], v[204:207], v[42:45]
	v_mfma_f32_16x16x32_bf16 v[30:33], v[164:167], v[212:215], v[30:33]
	v_mfma_f32_16x16x32_bf16 v[26:29], v[172:175], v[212:215], v[26:29]
	v_mfma_f32_16x16x32_bf16 v[14:17], v[164:167], v[222:225], v[14:17]
	v_mfma_f32_16x16x32_bf16 v[10:13], v[172:175], v[222:225], v[10:13]
	s_setprio 0
	s_setprio 1
	v_mfma_f32_16x16x32_bf16 v[54:57], v[176:179], v[192:195], v[54:57]
	v_mfma_f32_16x16x32_bf16 v[50:53], v[184:187], v[192:195], v[50:53]
	v_mfma_f32_16x16x32_bf16 v[38:41], v[176:179], v[200:203], v[38:41]
	v_mfma_f32_16x16x32_bf16 v[34:37], v[184:187], v[200:203], v[34:37]
	v_mfma_f32_16x16x32_bf16 v[22:25], v[176:179], v[208:211], v[22:25]
	v_mfma_f32_16x16x32_bf16 v[18:21], v[184:187], v[208:211], v[18:21]
	v_mfma_f32_16x16x32_bf16 v[6:9], v[176:179], v[218:221], v[6:9]
	v_mfma_f32_16x16x32_bf16 v[2:5], v[184:187], v[218:221], v[2:5]
	v_mfma_f32_16x16x32_bf16 v[54:57], v[180:183], v[196:199], v[54:57]
	v_mfma_f32_16x16x32_bf16 v[50:53], v[188:191], v[196:199], v[50:53]
	v_mfma_f32_16x16x32_bf16 v[38:41], v[180:183], v[204:207], v[38:41]
	v_mfma_f32_16x16x32_bf16 v[34:37], v[188:191], v[204:207], v[34:37]
	v_mfma_f32_16x16x32_bf16 v[22:25], v[180:183], v[212:215], v[22:25]
	v_mfma_f32_16x16x32_bf16 v[18:21], v[188:191], v[212:215], v[18:21]
	v_mfma_f32_16x16x32_bf16 v[6:9], v[180:183], v[222:225], v[6:9]
	v_mfma_f32_16x16x32_bf16 v[2:5], v[188:191], v[222:225], v[2:5]
	s_setprio 0
	s_barrier
	s_add_i32 s83, s83, 2
	s_add_u32 s90, s90, 0x100
	s_addc_u32 s91, s91, 0
	s_add_u32 s52, s52, 0x100
	s_addc_u32 s68, s68, 0

.LBB0_684:
	s_ashr_i32 s77, s76, 31
	s_lshl_b64 s[0:1], s[76:77], 18
	v_readlane_b32 s52, v247, 27
	s_add_u32 s78, s52, s0
	v_readlane_b32 s0, v247, 29
	s_addc_u32 s79, s0, s1
	s_and_b64 s[0:1], s[2:3], exec
	s_cselect_b32 s0, s79, s35
	s_cselect_b32 s1, s78, s34
	s_ashr_i32 s71, s70, 31
	s_lshl_b64 s[52:53], s[70:71], 18
	s_add_u32 s80, s13, s52
	s_addc_u32 s81, s30, s53
	s_and_b64 s[52:53], s[2:3], exec
	s_cselect_b32 s52, s81, s87
	s_cselect_b32 s71, s80, s86
	s_add_u32 s84, s34, 0x20080
	s_addc_u32 s85, s35, 0
	s_add_u32 s77, s86, 0x100
	s_addc_u32 s88, s87, 0
	s_mov_b32 s89, -2
	ds_read_b128 v[146:149], v165
	ds_read_b128 v[150:153], v165 offset:1024
	ds_read_b128 v[168:171], v165 offset:2048
	ds_read_b128 v[172:175], v165 offset:3072
	ds_read_b128 v[176:179], v166
	ds_read_b128 v[180:183], v166 offset:1024
	ds_read_b128 v[184:187], v166 offset:2048
	ds_read_b128 v[188:191], v166 offset:3072
	s_add_u32 s34, s84, 0xfffe0080
	s_addc_u32 s35, s85, -1
	s_cmp_eq_u32 s89, 4
	s_cselect_b32 s87, s0, s35
	s_cselect_b32 s86, s1, s34
	s_cselect_b32 s35, s52, s88
	s_cselect_b32 s34, s71, s77
	v_lshl_add_u64 v[226:227], s[84:85], 0, v[138:139]
	s_add_i32 m0, s33, 0xc000
	ds_read_b128 v[192:195], v167
	ds_read_b128 v[196:199], v167 offset:1024
	ds_read_b128 v[200:203], v167 offset:2048
	ds_read_b128 v[204:207], v167 offset:3072
	ds_read_b128 v[208:211], v167 offset:4096
	ds_read_b128 v[212:215], v167 offset:5120
	ds_read_b128 v[218:221], v167 offset:6144
	ds_read_b128 v[222:225], v167 offset:7168
	global_load_lds_dwordx4 v[226:227], off
	v_lshl_add_u64 v[226:227], s[84:85], 0, v[140:141]
	s_add_i32 m0, s33, 0xe000
	s_nop 0
	global_load_lds_dwordx4 v[226:227], off
	s_waitcnt vmcnt(8)
	s_waitcnt lgkmcnt(0)
	s_barrier
	s_setprio 1
	s_waitcnt lgkmcnt(0)
	v_mfma_f32_16x16x32_bf16 v[126:129], v[146:149], v[192:195], 0
	v_mfma_f32_16x16x32_bf16 v[122:125], v[168:171], v[192:195], 0
	v_mfma_f32_16x16x32_bf16 v[114:117], v[146:149], v[200:203], 0
	v_mfma_f32_16x16x32_bf16 v[106:109], v[168:171], v[200:203], 0
	v_mfma_f32_16x16x32_bf16 v[98:101], v[146:149], v[208:211], 0
	v_mfma_f32_16x16x32_bf16 v[90:93], v[168:171], v[208:211], 0
	v_mfma_f32_16x16x32_bf16 v[82:85], v[146:149], v[218:221], 0
	v_mfma_f32_16x16x32_bf16 v[74:77], v[168:171], v[218:221], 0
	v_mfma_f32_16x16x32_bf16 v[126:129], v[150:153], v[196:199], v[126:129]
	v_mfma_f32_16x16x32_bf16 v[122:125], v[172:175], v[196:199], v[122:125]
	v_mfma_f32_16x16x32_bf16 v[114:117], v[150:153], v[204:207], v[114:117]
	v_mfma_f32_16x16x32_bf16 v[106:109], v[172:175], v[204:207], v[106:109]
	v_mfma_f32_16x16x32_bf16 v[98:101], v[150:153], v[212:215], v[98:101]
	v_mfma_f32_16x16x32_bf16 v[90:93], v[172:175], v[212:215], v[90:93]
	v_mfma_f32_16x16x32_bf16 v[82:85], v[150:153], v[222:225], v[82:85]
	v_mfma_f32_16x16x32_bf16 v[74:77], v[172:175], v[222:225], v[74:77]
	s_setprio 0
	s_setprio 1
	v_mfma_f32_16x16x32_bf16 v[118:121], v[176:179], v[192:195], 0
	v_mfma_f32_16x16x32_bf16 v[110:113], v[184:187], v[192:195], 0
	v_mfma_f32_16x16x32_bf16 v[102:105], v[176:179], v[200:203], 0
	v_mfma_f32_16x16x32_bf16 v[94:97], v[184:187], v[200:203], 0
	v_mfma_f32_16x16x32_bf16 v[86:89], v[176:179], v[208:211], 0
	v_mfma_f32_16x16x32_bf16 v[78:81], v[184:187], v[208:211], 0
	v_mfma_f32_16x16x32_bf16 v[70:73], v[176:179], v[218:221], 0
	v_mfma_f32_16x16x32_bf16 v[66:69], v[184:187], v[218:221], 0
	v_mfma_f32_16x16x32_bf16 v[118:121], v[180:183], v[196:199], v[118:121]
	v_mfma_f32_16x16x32_bf16 v[110:113], v[188:191], v[196:199], v[110:113]
	v_mfma_f32_16x16x32_bf16 v[102:105], v[180:183], v[204:207], v[102:105]
	v_mfma_f32_16x16x32_bf16 v[94:97], v[188:191], v[204:207], v[94:97]
	v_mfma_f32_16x16x32_bf16 v[86:89], v[180:183], v[212:215], v[86:89]
	v_mfma_f32_16x16x32_bf16 v[78:81], v[188:191], v[212:215], v[78:81]
	v_mfma_f32_16x16x32_bf16 v[70:73], v[180:183], v[222:225], v[70:73]
	v_mfma_f32_16x16x32_bf16 v[66:69], v[188:191], v[222:225], v[66:69]
	s_setprio 0
	s_barrier
	s_add_i32 s53, s73, s12
	v_lshl_add_u64 v[226:227], s[34:35], 0, v[132:133]
	s_mov_b32 m0, s53
	ds_read_b128 v[192:195], v167 offset:16384
	ds_read_b128 v[196:199], v167 offset:17408
	ds_read_b128 v[200:203], v167 offset:18432
	ds_read_b128 v[204:207], v167 offset:19456
	ds_read_b128 v[208:211], v167 offset:20480
	ds_read_b128 v[212:215], v167 offset:21504
	ds_read_b128 v[218:221], v167 offset:22528
	ds_read_b128 v[222:225], v167 offset:23552
	global_load_lds_dwordx4 v[226:227], off
	s_add_i32 m0, s53, 0x2000
	s_add_u32 s54, s34, 0x20000
	v_lshl_add_u64 v[228:229], s[34:35], 0, v[136:137]
	s_addc_u32 s55, s35, 0
	s_add_i32 s53, s74, s12
	global_load_lds_dwordx4 v[228:229], off
	v_lshl_add_u64 v[230:231], s[54:55], 0, v[132:133]
	s_mov_b32 m0, s53
	v_lshl_add_u64 v[232:233], s[86:87], 0, v[134:135]
	global_load_lds_dwordx4 v[230:231], off
	v_lshl_add_u64 v[230:231], s[54:55], 0, v[136:137]
	s_add_i32 m0, s53, 0x2000
	s_nop 0
	global_load_lds_dwordx4 v[230:231], off
	v_lshl_add_u64 v[230:231], s[86:87], 0, v[130:131]
	s_mov_b32 m0, s33
	s_nop 0
	global_load_lds_dwordx4 v[230:231], off
	s_mov_b32 m0, s56
	s_nop 0
	global_load_lds_dwordx4 v[232:233], off
	s_waitcnt vmcnt(8)
	s_waitcnt lgkmcnt(0)
	s_barrier
	s_setprio 1
	s_waitcnt lgkmcnt(0)
	v_mfma_f32_16x16x32_bf16 v[62:65], v[146:149], v[192:195], 0
	v_mfma_f32_16x16x32_bf16 v[58:61], v[168:171], v[192:195], 0
	v_mfma_f32_16x16x32_bf16 v[50:53], v[146:149], v[200:203], 0
	v_mfma_f32_16x16x32_bf16 v[42:45], v[168:171], v[200:203], 0
	v_mfma_f32_16x16x32_bf16 v[34:37], v[146:149], v[208:211], 0
	v_mfma_f32_16x16x32_bf16 v[26:29], v[168:171], v[208:211], 0
	v_mfma_f32_16x16x32_bf16 v[18:21], v[146:149], v[218:221], 0
	v_mfma_f32_16x16x32_bf16 v[10:13], v[168:171], v[218:221], 0
	v_mfma_f32_16x16x32_bf16 v[62:65], v[150:153], v[196:199], v[62:65]
	v_mfma_f32_16x16x32_bf16 v[58:61], v[172:175], v[196:199], v[58:61]
	v_mfma_f32_16x16x32_bf16 v[50:53], v[150:153], v[204:207], v[50:53]
	v_mfma_f32_16x16x32_bf16 v[42:45], v[172:175], v[204:207], v[42:45]
	v_mfma_f32_16x16x32_bf16 v[34:37], v[150:153], v[212:215], v[34:37]
	v_mfma_f32_16x16x32_bf16 v[26:29], v[172:175], v[212:215], v[26:29]
	v_mfma_f32_16x16x32_bf16 v[18:21], v[150:153], v[222:225], v[18:21]
	v_mfma_f32_16x16x32_bf16 v[10:13], v[172:175], v[222:225], v[10:13]
	s_setprio 0
	s_setprio 1
	v_mfma_f32_16x16x32_bf16 v[54:57], v[176:179], v[192:195], 0
	v_mfma_f32_16x16x32_bf16 v[46:49], v[184:187], v[192:195], 0
	v_mfma_f32_16x16x32_bf16 v[38:41], v[176:179], v[200:203], 0
	v_mfma_f32_16x16x32_bf16 v[30:33], v[184:187], v[200:203], 0
	v_mfma_f32_16x16x32_bf16 v[22:25], v[176:179], v[208:211], 0
	v_mfma_f32_16x16x32_bf16 v[14:17], v[184:187], v[208:211], 0
	v_mfma_f32_16x16x32_bf16 v[6:9], v[176:179], v[218:221], 0
	v_mfma_f32_16x16x32_bf16 v[2:5], v[184:187], v[218:221], 0
	v_mfma_f32_16x16x32_bf16 v[54:57], v[180:183], v[196:199], v[54:57]
	v_mfma_f32_16x16x32_bf16 v[46:49], v[188:191], v[196:199], v[46:49]
	v_mfma_f32_16x16x32_bf16 v[38:41], v[180:183], v[204:207], v[38:41]
	v_mfma_f32_16x16x32_bf16 v[30:33], v[188:191], v[204:207], v[30:33]
	v_mfma_f32_16x16x32_bf16 v[22:25], v[180:183], v[212:215], v[22:25]
	v_mfma_f32_16x16x32_bf16 v[14:17], v[188:191], v[212:215], v[14:17]
	v_mfma_f32_16x16x32_bf16 v[6:9], v[180:183], v[222:225], v[6:9]
	v_mfma_f32_16x16x32_bf16 v[2:5], v[188:191], v[222:225], v[2:5]
	s_setprio 0
	s_barrier
	s_add_i32 s53, 0, 0x18000
	s_add_i32 s62, 0, 0x1c000
	v_add_u32_e32 v172, s53, v162
	v_add_u32_e32 v188, s62, v162
	ds_read_b128 v[146:149], v172
	ds_read_b128 v[150:153], v172 offset:1024
	ds_read_b128 v[168:171], v172 offset:2048
	ds_read_b128 v[172:175], v172 offset:3072
	ds_read_b128 v[176:179], v188
	ds_read_b128 v[180:183], v188 offset:1024
	ds_read_b128 v[184:187], v188 offset:2048
	ds_read_b128 v[188:191], v188 offset:3072
	s_add_u32 s54, s86, 0x20000
	s_addc_u32 s55, s87, 0
	s_mov_b32 m0, s57
	v_lshl_add_u64 v[234:235], s[54:55], 0, v[130:131]
	ds_read_b128 v[192:195], v167 offset:32768
	ds_read_b128 v[196:199], v167 offset:33792
	ds_read_b128 v[200:203], v167 offset:34816
	ds_read_b128 v[204:207], v167 offset:35840
	ds_read_b128 v[208:211], v167 offset:36864
	ds_read_b128 v[212:215], v167 offset:37888
	ds_read_b128 v[218:221], v167 offset:38912
	ds_read_b128 v[222:225], v167 offset:39936
	global_load_lds_dwordx4 v[234:235], off
	v_lshl_add_u64 v[234:235], s[54:55], 0, v[134:135]
	s_mov_b32 m0, s58
	s_nop 0
	global_load_lds_dwordx4 v[234:235], off
	s_waitcnt vmcnt(8)
	s_waitcnt lgkmcnt(0)
	s_barrier
	s_setprio 1
	s_waitcnt lgkmcnt(0)
	v_mfma_f32_16x16x32_bf16 v[126:129], v[146:149], v[192:195], v[126:129]
	v_mfma_f32_16x16x32_bf16 v[122:125], v[168:171], v[192:195], v[122:125]
	v_mfma_f32_16x16x32_bf16 v[114:117], v[146:149], v[200:203], v[114:117]
	v_mfma_f32_16x16x32_bf16 v[106:109], v[168:171], v[200:203], v[106:109]
	v_mfma_f32_16x16x32_bf16 v[98:101], v[146:149], v[208:211], v[98:101]
	v_mfma_f32_16x16x32_bf16 v[90:93], v[168:171], v[208:211], v[90:93]
	v_mfma_f32_16x16x32_bf16 v[82:85], v[146:149], v[218:221], v[82:85]
	v_mfma_f32_16x16x32_bf16 v[74:77], v[168:171], v[218:221], v[74:77]
	v_mfma_f32_16x16x32_bf16 v[126:129], v[150:153], v[196:199], v[126:129]
	v_mfma_f32_16x16x32_bf16 v[122:125], v[172:175], v[196:199], v[122:125]
	v_mfma_f32_16x16x32_bf16 v[114:117], v[150:153], v[204:207], v[114:117]
	v_mfma_f32_16x16x32_bf16 v[106:109], v[172:175], v[204:207], v[106:109]
	v_mfma_f32_16x16x32_bf16 v[98:101], v[150:153], v[212:215], v[98:101]
	v_mfma_f32_16x16x32_bf16 v[90:93], v[172:175], v[212:215], v[90:93]
	v_mfma_f32_16x16x32_bf16 v[82:85], v[150:153], v[222:225], v[82:85]
	v_mfma_f32_16x16x32_bf16 v[74:77], v[172:175], v[222:225], v[74:77]
	s_setprio 0
	s_setprio 1
	v_mfma_f32_16x16x32_bf16 v[118:121], v[176:179], v[192:195], v[118:121]
	v_mfma_f32_16x16x32_bf16 v[110:113], v[184:187], v[192:195], v[110:113]
	v_mfma_f32_16x16x32_bf16 v[102:105], v[176:179], v[200:203], v[102:105]
	v_mfma_f32_16x16x32_bf16 v[94:97], v[184:187], v[200:203], v[94:97]
	v_mfma_f32_16x16x32_bf16 v[86:89], v[176:179], v[208:211], v[86:89]
	v_mfma_f32_16x16x32_bf16 v[78:81], v[184:187], v[208:211], v[78:81]
	v_mfma_f32_16x16x32_bf16 v[70:73], v[176:179], v[218:221], v[70:73]
	v_mfma_f32_16x16x32_bf16 v[66:69], v[184:187], v[218:221], v[66:69]
	v_mfma_f32_16x16x32_bf16 v[118:121], v[180:183], v[196:199], v[118:121]
	v_mfma_f32_16x16x32_bf16 v[110:113], v[188:191], v[196:199], v[110:113]
	v_mfma_f32_16x16x32_bf16 v[102:105], v[180:183], v[204:207], v[102:105]
	v_mfma_f32_16x16x32_bf16 v[94:97], v[188:191], v[204:207], v[94:97]
	v_mfma_f32_16x16x32_bf16 v[86:89], v[180:183], v[212:215], v[86:89]
	v_mfma_f32_16x16x32_bf16 v[78:81], v[188:191], v[212:215], v[78:81]
	v_mfma_f32_16x16x32_bf16 v[70:73], v[180:183], v[222:225], v[70:73]
	v_mfma_f32_16x16x32_bf16 v[66:69], v[188:191], v[222:225], v[66:69]
	s_setprio 0
	s_barrier
	s_add_i32 s53, s53, s12
	v_lshl_add_u64 v[226:227], v[226:227], 0, s[8:9]
	s_mov_b32 m0, s53
	ds_read_b128 v[192:195], v167 offset:49152
	ds_read_b128 v[196:199], v167 offset:50176
	ds_read_b128 v[200:203], v167 offset:51200
	ds_read_b128 v[204:207], v167 offset:52224
	ds_read_b128 v[208:211], v167 offset:53248
	ds_read_b128 v[212:215], v167 offset:54272
	ds_read_b128 v[218:221], v167 offset:55296
	ds_read_b128 v[222:225], v167 offset:56320
	global_load_lds_dwordx4 v[226:227], off
	s_add_i32 m0, s53, 0x2000
	s_add_u32 s34, s34, 0x20080
	v_lshl_add_u64 v[226:227], v[228:229], 0, s[8:9]
	s_addc_u32 s35, s35, 0
	s_add_i32 s53, s62, s12
	global_load_lds_dwordx4 v[226:227], off
	v_lshl_add_u64 v[226:227], s[34:35], 0, v[132:133]
	s_mov_b32 m0, s53
	s_nop 0
	global_load_lds_dwordx4 v[226:227], off
	v_lshl_add_u64 v[226:227], s[34:35], 0, v[136:137]
	s_add_i32 m0, s53, 0x2000
	s_nop 0
	global_load_lds_dwordx4 v[226:227], off
	v_lshl_add_u64 v[226:227], v[230:231], 0, s[8:9]
	s_mov_b32 m0, s60
	s_nop 0
	global_load_lds_dwordx4 v[226:227], off
	v_lshl_add_u64 v[226:227], v[232:233], 0, s[8:9]
	s_mov_b32 m0, s61
	s_nop 0
	global_load_lds_dwordx4 v[226:227], off
	s_waitcnt vmcnt(8)
	s_waitcnt lgkmcnt(0)
	s_barrier
	s_setprio 1
	s_waitcnt lgkmcnt(0)
	v_mfma_f32_16x16x32_bf16 v[62:65], v[146:149], v[192:195], v[62:65]
	v_mfma_f32_16x16x32_bf16 v[58:61], v[168:171], v[192:195], v[58:61]
	v_mfma_f32_16x16x32_bf16 v[50:53], v[146:149], v[200:203], v[50:53]
	v_mfma_f32_16x16x32_bf16 v[42:45], v[168:171], v[200:203], v[42:45]
	v_mfma_f32_16x16x32_bf16 v[34:37], v[146:149], v[208:211], v[34:37]
	v_mfma_f32_16x16x32_bf16 v[26:29], v[168:171], v[208:211], v[26:29]
	v_mfma_f32_16x16x32_bf16 v[18:21], v[146:149], v[218:221], v[18:21]
	v_mfma_f32_16x16x32_bf16 v[10:13], v[168:171], v[218:221], v[10:13]
	v_mfma_f32_16x16x32_bf16 v[62:65], v[150:153], v[196:199], v[62:65]
	v_mfma_f32_16x16x32_bf16 v[58:61], v[172:175], v[196:199], v[58:61]
	v_mfma_f32_16x16x32_bf16 v[50:53], v[150:153], v[204:207], v[50:53]
	v_mfma_f32_16x16x32_bf16 v[42:45], v[172:175], v[204:207], v[42:45]
	v_mfma_f32_16x16x32_bf16 v[34:37], v[150:153], v[212:215], v[34:37]
	v_mfma_f32_16x16x32_bf16 v[26:29], v[172:175], v[212:215], v[26:29]
	v_mfma_f32_16x16x32_bf16 v[18:21], v[150:153], v[222:225], v[18:21]
	v_mfma_f32_16x16x32_bf16 v[10:13], v[172:175], v[222:225], v[10:13]
	s_setprio 0
	s_setprio 1
	v_mfma_f32_16x16x32_bf16 v[54:57], v[176:179], v[192:195], v[54:57]
	v_mfma_f32_16x16x32_bf16 v[46:49], v[184:187], v[192:195], v[46:49]
	v_mfma_f32_16x16x32_bf16 v[38:41], v[176:179], v[200:203], v[38:41]
	v_mfma_f32_16x16x32_bf16 v[30:33], v[184:187], v[200:203], v[30:33]
	v_mfma_f32_16x16x32_bf16 v[22:25], v[176:179], v[208:211], v[22:25]
	v_mfma_f32_16x16x32_bf16 v[14:17], v[184:187], v[208:211], v[14:17]
	v_mfma_f32_16x16x32_bf16 v[6:9], v[176:179], v[218:221], v[6:9]
	v_mfma_f32_16x16x32_bf16 v[2:5], v[184:187], v[218:221], v[2:5]
	v_mfma_f32_16x16x32_bf16 v[54:57], v[180:183], v[196:199], v[54:57]
	v_mfma_f32_16x16x32_bf16 v[46:49], v[188:191], v[196:199], v[46:49]
	v_mfma_f32_16x16x32_bf16 v[38:41], v[180:183], v[204:207], v[38:41]
	v_mfma_f32_16x16x32_bf16 v[30:33], v[188:191], v[204:207], v[30:33]
	v_mfma_f32_16x16x32_bf16 v[22:25], v[180:183], v[212:215], v[22:25]
	v_mfma_f32_16x16x32_bf16 v[14:17], v[188:191], v[212:215], v[14:17]
	v_mfma_f32_16x16x32_bf16 v[6:9], v[180:183], v[222:225], v[6:9]
	v_mfma_f32_16x16x32_bf16 v[2:5], v[188:191], v[222:225], v[2:5]
	s_setprio 0
	s_barrier
	s_add_i32 s89, s89, 2
	s_add_u32 s84, s84, 0x100
	s_addc_u32 s85, s85, 0
	s_add_u32 s77, s77, 0x100
	s_addc_u32 s88, s88, 0

.LBB0_714:
	s_ashr_i32 s77, s76, 31
	s_lshl_b64 s[0:1], s[76:77], 18
	v_readlane_b32 s34, v247, 43
	s_add_u32 s78, s34, s0
	v_readlane_b32 s0, v247, 25
	s_addc_u32 s79, s0, s1
	s_and_b64 s[0:1], s[2:3], exec
	s_cselect_b32 s0, s79, s85
	s_cselect_b32 s1, s78, s84
	s_ashr_i32 s71, s70, 31
	s_lshl_b64 s[34:35], s[70:71], 18
	s_add_u32 s80, s30, s34
	s_addc_u32 s81, s31, s35
	s_and_b64 s[34:35], s[2:3], exec
	s_cselect_b32 s52, s81, s87
	s_cselect_b32 s71, s80, s86
	s_add_u32 s84, s84, 0x20080
	s_addc_u32 s85, s85, 0
	s_add_u32 s77, s86, 0x100
	s_addc_u32 s83, s87, 0
	s_mov_b32 s88, -2
	ds_read_b128 v[146:149], v1
	ds_read_b128 v[160:163], v1 offset:1024
	ds_read_b128 v[164:167], v1 offset:2048
	ds_read_b128 v[168:171], v1 offset:3072
	ds_read_b128 v[172:175], v154
	ds_read_b128 v[176:179], v154 offset:1024
	ds_read_b128 v[180:183], v154 offset:2048
	ds_read_b128 v[184:187], v154 offset:3072
	s_add_u32 s34, s84, 0xfffe0080
	s_addc_u32 s35, s85, -1
	s_cmp_eq_u32 s88, 4
	s_cselect_b32 s87, s0, s35
	s_cselect_b32 s86, s1, s34
	s_cselect_b32 s35, s52, s83
	s_cselect_b32 s34, s71, s77
	v_lshl_add_u64 v[150:151], s[84:85], 0, v[138:139]
	s_add_i32 m0, s33, 0xc000
	ds_read_b128 v[188:191], v155
	ds_read_b128 v[192:195], v155 offset:1024
	ds_read_b128 v[196:199], v155 offset:2048
	ds_read_b128 v[200:203], v155 offset:3072
	ds_read_b128 v[204:207], v155 offset:4096
	ds_read_b128 v[208:211], v155 offset:5120
	ds_read_b128 v[212:215], v155 offset:6144
	ds_read_b128 v[218:221], v155 offset:7168
	global_load_lds_dwordx4 v[150:151], off
	v_lshl_add_u64 v[150:151], s[84:85], 0, v[140:141]
	s_add_i32 m0, s33, 0xe000
	s_nop 0
	global_load_lds_dwordx4 v[150:151], off
	s_waitcnt vmcnt(8)
	s_waitcnt lgkmcnt(0)
	s_barrier
	s_setprio 1
	s_waitcnt lgkmcnt(0)
	v_mfma_f32_16x16x32_bf16 v[126:129], v[146:149], v[188:191], 0
	v_mfma_f32_16x16x32_bf16 v[122:125], v[164:167], v[188:191], 0
	v_mfma_f32_16x16x32_bf16 v[110:113], v[146:149], v[196:199], 0
	v_mfma_f32_16x16x32_bf16 v[106:109], v[164:167], v[196:199], 0
	v_mfma_f32_16x16x32_bf16 v[94:97], v[146:149], v[204:207], 0
	v_mfma_f32_16x16x32_bf16 v[90:93], v[164:167], v[204:207], 0
	v_mfma_f32_16x16x32_bf16 v[78:81], v[146:149], v[212:215], 0
	v_mfma_f32_16x16x32_bf16 v[74:77], v[164:167], v[212:215], 0
	v_mfma_f32_16x16x32_bf16 v[126:129], v[160:163], v[192:195], v[126:129]
	v_mfma_f32_16x16x32_bf16 v[122:125], v[168:171], v[192:195], v[122:125]
	v_mfma_f32_16x16x32_bf16 v[110:113], v[160:163], v[200:203], v[110:113]
	v_mfma_f32_16x16x32_bf16 v[106:109], v[168:171], v[200:203], v[106:109]
	v_mfma_f32_16x16x32_bf16 v[94:97], v[160:163], v[208:211], v[94:97]
	v_mfma_f32_16x16x32_bf16 v[90:93], v[168:171], v[208:211], v[90:93]
	v_mfma_f32_16x16x32_bf16 v[78:81], v[160:163], v[218:221], v[78:81]
	v_mfma_f32_16x16x32_bf16 v[74:77], v[168:171], v[218:221], v[74:77]
	s_setprio 0
	s_setprio 1
	v_mfma_f32_16x16x32_bf16 v[118:121], v[172:175], v[188:191], 0
	v_mfma_f32_16x16x32_bf16 v[114:117], v[180:183], v[188:191], 0
	v_mfma_f32_16x16x32_bf16 v[102:105], v[172:175], v[196:199], 0
	v_mfma_f32_16x16x32_bf16 v[98:101], v[180:183], v[196:199], 0
	v_mfma_f32_16x16x32_bf16 v[86:89], v[172:175], v[204:207], 0
	v_mfma_f32_16x16x32_bf16 v[82:85], v[180:183], v[204:207], 0
	v_mfma_f32_16x16x32_bf16 v[70:73], v[172:175], v[212:215], 0
	v_mfma_f32_16x16x32_bf16 v[66:69], v[180:183], v[212:215], 0
	v_mfma_f32_16x16x32_bf16 v[118:121], v[176:179], v[192:195], v[118:121]
	v_mfma_f32_16x16x32_bf16 v[114:117], v[184:187], v[192:195], v[114:117]
	v_mfma_f32_16x16x32_bf16 v[102:105], v[176:179], v[200:203], v[102:105]
	v_mfma_f32_16x16x32_bf16 v[98:101], v[184:187], v[200:203], v[98:101]
	v_mfma_f32_16x16x32_bf16 v[86:89], v[176:179], v[208:211], v[86:89]
	v_mfma_f32_16x16x32_bf16 v[82:85], v[184:187], v[208:211], v[82:85]
	v_mfma_f32_16x16x32_bf16 v[70:73], v[176:179], v[218:221], v[70:73]
	v_mfma_f32_16x16x32_bf16 v[66:69], v[184:187], v[218:221], v[66:69]
	s_setprio 0
	s_barrier
	s_add_i32 s53, s73, s13
	v_lshl_add_u64 v[150:151], s[34:35], 0, v[132:133]
	s_mov_b32 m0, s53
	ds_read_b128 v[188:191], v155 offset:16384
	ds_read_b128 v[192:195], v155 offset:17408
	ds_read_b128 v[196:199], v155 offset:18432
	ds_read_b128 v[200:203], v155 offset:19456
	ds_read_b128 v[204:207], v155 offset:20480
	ds_read_b128 v[208:211], v155 offset:21504
	ds_read_b128 v[212:215], v155 offset:22528
	ds_read_b128 v[218:221], v155 offset:23552
	global_load_lds_dwordx4 v[150:151], off
	s_add_i32 m0, s53, 0x2000
	s_add_u32 s54, s34, 0x20000
	v_lshl_add_u64 v[222:223], s[34:35], 0, v[136:137]
	s_addc_u32 s55, s35, 0
	s_add_i32 s53, s74, s13
	global_load_lds_dwordx4 v[222:223], off
	v_lshl_add_u64 v[224:225], s[54:55], 0, v[132:133]
	s_mov_b32 m0, s53
	v_lshl_add_u64 v[226:227], s[86:87], 0, v[134:135]
	global_load_lds_dwordx4 v[224:225], off
	v_lshl_add_u64 v[224:225], s[54:55], 0, v[136:137]
	s_add_i32 m0, s53, 0x2000
	s_nop 0
	global_load_lds_dwordx4 v[224:225], off
	v_lshl_add_u64 v[224:225], s[86:87], 0, v[130:131]
	s_mov_b32 m0, s33
	s_nop 0
	global_load_lds_dwordx4 v[224:225], off
	s_mov_b32 m0, s56
	s_nop 0
	global_load_lds_dwordx4 v[226:227], off
	s_waitcnt vmcnt(8)
	s_waitcnt lgkmcnt(0)
	s_barrier
	s_setprio 1
	s_waitcnt lgkmcnt(0)
	v_mfma_f32_16x16x32_bf16 v[62:65], v[146:149], v[188:191], 0
	v_mfma_f32_16x16x32_bf16 v[58:61], v[164:167], v[188:191], 0
	v_mfma_f32_16x16x32_bf16 v[50:53], v[146:149], v[196:199], 0
	v_mfma_f32_16x16x32_bf16 v[42:45], v[164:167], v[196:199], 0
	v_mfma_f32_16x16x32_bf16 v[34:37], v[146:149], v[204:207], 0
	v_mfma_f32_16x16x32_bf16 v[26:29], v[164:167], v[204:207], 0
	v_mfma_f32_16x16x32_bf16 v[18:21], v[146:149], v[212:215], 0
	v_mfma_f32_16x16x32_bf16 v[10:13], v[164:167], v[212:215], 0
	v_mfma_f32_16x16x32_bf16 v[62:65], v[160:163], v[192:195], v[62:65]
	v_mfma_f32_16x16x32_bf16 v[58:61], v[168:171], v[192:195], v[58:61]
	v_mfma_f32_16x16x32_bf16 v[50:53], v[160:163], v[200:203], v[50:53]
	v_mfma_f32_16x16x32_bf16 v[42:45], v[168:171], v[200:203], v[42:45]
	v_mfma_f32_16x16x32_bf16 v[34:37], v[160:163], v[208:211], v[34:37]
	v_mfma_f32_16x16x32_bf16 v[26:29], v[168:171], v[208:211], v[26:29]
	v_mfma_f32_16x16x32_bf16 v[18:21], v[160:163], v[218:221], v[18:21]
	v_mfma_f32_16x16x32_bf16 v[10:13], v[168:171], v[218:221], v[10:13]
	s_setprio 0
	s_setprio 1
	v_mfma_f32_16x16x32_bf16 v[54:57], v[172:175], v[188:191], 0
	v_mfma_f32_16x16x32_bf16 v[46:49], v[180:183], v[188:191], 0
	v_mfma_f32_16x16x32_bf16 v[38:41], v[172:175], v[196:199], 0
	v_mfma_f32_16x16x32_bf16 v[30:33], v[180:183], v[196:199], 0
	v_mfma_f32_16x16x32_bf16 v[22:25], v[172:175], v[204:207], 0
	v_mfma_f32_16x16x32_bf16 v[14:17], v[180:183], v[204:207], 0
	v_mfma_f32_16x16x32_bf16 v[6:9], v[172:175], v[212:215], 0
	v_mfma_f32_16x16x32_bf16 v[2:5], v[180:183], v[212:215], 0
	v_mfma_f32_16x16x32_bf16 v[54:57], v[176:179], v[192:195], v[54:57]
	v_mfma_f32_16x16x32_bf16 v[46:49], v[184:187], v[192:195], v[46:49]
	v_mfma_f32_16x16x32_bf16 v[38:41], v[176:179], v[200:203], v[38:41]
	v_mfma_f32_16x16x32_bf16 v[30:33], v[184:187], v[200:203], v[30:33]
	v_mfma_f32_16x16x32_bf16 v[22:25], v[176:179], v[208:211], v[22:25]
	v_mfma_f32_16x16x32_bf16 v[14:17], v[184:187], v[208:211], v[14:17]
	v_mfma_f32_16x16x32_bf16 v[6:9], v[176:179], v[218:221], v[6:9]
	v_mfma_f32_16x16x32_bf16 v[2:5], v[184:187], v[218:221], v[2:5]
	s_setprio 0
	s_barrier
	s_add_i32 s53, 0, 0x18000
	v_add_u32_e32 v156, s53, v153
	s_add_i32 s62, 0, 0x1c000
	ds_read_b128 v[146:149], v156
	ds_read_b128 v[160:163], v156 offset:1024
	ds_read_b128 v[164:167], v156 offset:2048
	ds_read_b128 v[168:171], v156 offset:3072
	v_add_u32_e32 v156, s62, v153
	ds_read_b128 v[172:175], v156
	ds_read_b128 v[176:179], v156 offset:1024
	ds_read_b128 v[180:183], v156 offset:2048
	ds_read_b128 v[184:187], v156 offset:3072
	s_add_u32 s54, s86, 0x20000
	s_addc_u32 s55, s87, 0
	s_mov_b32 m0, s57
	v_lshl_add_u64 v[228:229], s[54:55], 0, v[130:131]
	ds_read_b128 v[188:191], v155 offset:32768
	ds_read_b128 v[192:195], v155 offset:33792
	ds_read_b128 v[196:199], v155 offset:34816
	ds_read_b128 v[200:203], v155 offset:35840
	ds_read_b128 v[204:207], v155 offset:36864
	ds_read_b128 v[208:211], v155 offset:37888
	ds_read_b128 v[212:215], v155 offset:38912
	ds_read_b128 v[218:221], v155 offset:39936
	global_load_lds_dwordx4 v[228:229], off
	v_lshl_add_u64 v[228:229], s[54:55], 0, v[134:135]
	s_mov_b32 m0, s58
	s_nop 0
	global_load_lds_dwordx4 v[228:229], off
	s_waitcnt vmcnt(8)
	s_waitcnt lgkmcnt(0)
	s_barrier
	s_setprio 1
	s_waitcnt lgkmcnt(0)
	v_mfma_f32_16x16x32_bf16 v[126:129], v[146:149], v[188:191], v[126:129]
	v_mfma_f32_16x16x32_bf16 v[122:125], v[164:167], v[188:191], v[122:125]
	v_mfma_f32_16x16x32_bf16 v[110:113], v[146:149], v[196:199], v[110:113]
	v_mfma_f32_16x16x32_bf16 v[106:109], v[164:167], v[196:199], v[106:109]
	v_mfma_f32_16x16x32_bf16 v[94:97], v[146:149], v[204:207], v[94:97]
	v_mfma_f32_16x16x32_bf16 v[90:93], v[164:167], v[204:207], v[90:93]
	v_mfma_f32_16x16x32_bf16 v[78:81], v[146:149], v[212:215], v[78:81]
	v_mfma_f32_16x16x32_bf16 v[74:77], v[164:167], v[212:215], v[74:77]
	v_mfma_f32_16x16x32_bf16 v[126:129], v[160:163], v[192:195], v[126:129]
	v_mfma_f32_16x16x32_bf16 v[122:125], v[168:171], v[192:195], v[122:125]
	v_mfma_f32_16x16x32_bf16 v[110:113], v[160:163], v[200:203], v[110:113]
	v_mfma_f32_16x16x32_bf16 v[106:109], v[168:171], v[200:203], v[106:109]
	v_mfma_f32_16x16x32_bf16 v[94:97], v[160:163], v[208:211], v[94:97]
	v_mfma_f32_16x16x32_bf16 v[90:93], v[168:171], v[208:211], v[90:93]
	v_mfma_f32_16x16x32_bf16 v[78:81], v[160:163], v[218:221], v[78:81]
	v_mfma_f32_16x16x32_bf16 v[74:77], v[168:171], v[218:221], v[74:77]
	s_setprio 0
	s_setprio 1
	v_mfma_f32_16x16x32_bf16 v[118:121], v[172:175], v[188:191], v[118:121]
	v_mfma_f32_16x16x32_bf16 v[114:117], v[180:183], v[188:191], v[114:117]
	v_mfma_f32_16x16x32_bf16 v[102:105], v[172:175], v[196:199], v[102:105]
	v_mfma_f32_16x16x32_bf16 v[98:101], v[180:183], v[196:199], v[98:101]
	v_mfma_f32_16x16x32_bf16 v[86:89], v[172:175], v[204:207], v[86:89]
	v_mfma_f32_16x16x32_bf16 v[82:85], v[180:183], v[204:207], v[82:85]
	v_mfma_f32_16x16x32_bf16 v[70:73], v[172:175], v[212:215], v[70:73]
	v_mfma_f32_16x16x32_bf16 v[66:69], v[180:183], v[212:215], v[66:69]
	v_mfma_f32_16x16x32_bf16 v[118:121], v[176:179], v[192:195], v[118:121]
	v_mfma_f32_16x16x32_bf16 v[114:117], v[184:187], v[192:195], v[114:117]
	v_mfma_f32_16x16x32_bf16 v[102:105], v[176:179], v[200:203], v[102:105]
	v_mfma_f32_16x16x32_bf16 v[98:101], v[184:187], v[200:203], v[98:101]
	v_mfma_f32_16x16x32_bf16 v[86:89], v[176:179], v[208:211], v[86:89]
	v_mfma_f32_16x16x32_bf16 v[82:85], v[184:187], v[208:211], v[82:85]
	v_mfma_f32_16x16x32_bf16 v[70:73], v[176:179], v[218:221], v[70:73]
	v_mfma_f32_16x16x32_bf16 v[66:69], v[184:187], v[218:221], v[66:69]
	s_setprio 0
	s_barrier
	s_add_i32 s53, s53, s13
	v_lshl_add_u64 v[150:151], v[150:151], 0, s[8:9]
	s_mov_b32 m0, s53
	ds_read_b128 v[188:191], v155 offset:49152
	ds_read_b128 v[192:195], v155 offset:50176
	ds_read_b128 v[196:199], v155 offset:51200
	ds_read_b128 v[200:203], v155 offset:52224
	ds_read_b128 v[204:207], v155 offset:53248
	ds_read_b128 v[208:211], v155 offset:54272
	ds_read_b128 v[212:215], v155 offset:55296
	ds_read_b128 v[218:221], v155 offset:56320
	global_load_lds_dwordx4 v[150:151], off
	s_add_i32 m0, s53, 0x2000
	s_add_u32 s34, s34, 0x20080
	v_lshl_add_u64 v[150:151], v[222:223], 0, s[8:9]
	s_addc_u32 s35, s35, 0
	s_add_i32 s53, s62, s13
	global_load_lds_dwordx4 v[150:151], off
	v_lshl_add_u64 v[150:151], s[34:35], 0, v[132:133]
	s_mov_b32 m0, s53
	s_nop 0
	global_load_lds_dwordx4 v[150:151], off
	v_lshl_add_u64 v[150:151], s[34:35], 0, v[136:137]
	s_add_i32 m0, s53, 0x2000
	s_nop 0
	global_load_lds_dwordx4 v[150:151], off
	v_lshl_add_u64 v[150:151], v[224:225], 0, s[8:9]
	s_mov_b32 m0, s60
	s_nop 0
	global_load_lds_dwordx4 v[150:151], off
	v_lshl_add_u64 v[150:151], v[226:227], 0, s[8:9]
	s_mov_b32 m0, s61
	s_nop 0
	global_load_lds_dwordx4 v[150:151], off
	s_waitcnt vmcnt(8)
	s_waitcnt lgkmcnt(0)
	s_barrier
	s_setprio 1
	s_waitcnt lgkmcnt(0)
	v_mfma_f32_16x16x32_bf16 v[62:65], v[146:149], v[188:191], v[62:65]
	v_mfma_f32_16x16x32_bf16 v[58:61], v[164:167], v[188:191], v[58:61]
	v_mfma_f32_16x16x32_bf16 v[50:53], v[146:149], v[196:199], v[50:53]
	v_mfma_f32_16x16x32_bf16 v[42:45], v[164:167], v[196:199], v[42:45]
	v_mfma_f32_16x16x32_bf16 v[34:37], v[146:149], v[204:207], v[34:37]
	v_mfma_f32_16x16x32_bf16 v[26:29], v[164:167], v[204:207], v[26:29]
	v_mfma_f32_16x16x32_bf16 v[18:21], v[146:149], v[212:215], v[18:21]
	v_mfma_f32_16x16x32_bf16 v[10:13], v[164:167], v[212:215], v[10:13]
	v_mfma_f32_16x16x32_bf16 v[62:65], v[160:163], v[192:195], v[62:65]
	v_mfma_f32_16x16x32_bf16 v[58:61], v[168:171], v[192:195], v[58:61]
	v_mfma_f32_16x16x32_bf16 v[50:53], v[160:163], v[200:203], v[50:53]
	v_mfma_f32_16x16x32_bf16 v[42:45], v[168:171], v[200:203], v[42:45]
	v_mfma_f32_16x16x32_bf16 v[34:37], v[160:163], v[208:211], v[34:37]
	v_mfma_f32_16x16x32_bf16 v[26:29], v[168:171], v[208:211], v[26:29]
	v_mfma_f32_16x16x32_bf16 v[18:21], v[160:163], v[218:221], v[18:21]
	v_mfma_f32_16x16x32_bf16 v[10:13], v[168:171], v[218:221], v[10:13]
	s_setprio 0
	s_setprio 1
	v_mfma_f32_16x16x32_bf16 v[54:57], v[172:175], v[188:191], v[54:57]
	v_mfma_f32_16x16x32_bf16 v[46:49], v[180:183], v[188:191], v[46:49]
	v_mfma_f32_16x16x32_bf16 v[38:41], v[172:175], v[196:199], v[38:41]
	v_mfma_f32_16x16x32_bf16 v[30:33], v[180:183], v[196:199], v[30:33]
	v_mfma_f32_16x16x32_bf16 v[22:25], v[172:175], v[204:207], v[22:25]
	v_mfma_f32_16x16x32_bf16 v[14:17], v[180:183], v[204:207], v[14:17]
	v_mfma_f32_16x16x32_bf16 v[6:9], v[172:175], v[212:215], v[6:9]
	v_mfma_f32_16x16x32_bf16 v[2:5], v[180:183], v[212:215], v[2:5]
	v_mfma_f32_16x16x32_bf16 v[54:57], v[176:179], v[192:195], v[54:57]
	v_mfma_f32_16x16x32_bf16 v[46:49], v[184:187], v[192:195], v[46:49]
	v_mfma_f32_16x16x32_bf16 v[38:41], v[176:179], v[200:203], v[38:41]
	v_mfma_f32_16x16x32_bf16 v[30:33], v[184:187], v[200:203], v[30:33]
	v_mfma_f32_16x16x32_bf16 v[22:25], v[176:179], v[208:211], v[22:25]
	v_mfma_f32_16x16x32_bf16 v[14:17], v[184:187], v[208:211], v[14:17]
	v_mfma_f32_16x16x32_bf16 v[6:9], v[176:179], v[218:221], v[6:9]
	v_mfma_f32_16x16x32_bf16 v[2:5], v[184:187], v[218:221], v[2:5]
	s_setprio 0
	s_barrier
	s_add_i32 s88, s88, 2
	s_add_u32 s84, s84, 0x100
	s_addc_u32 s85, s85, 0
	s_add_u32 s77, s77, 0x100
	s_addc_u32 s83, s83, 0

.LBB0_994:
	s_ashr_i32 s83, s82, 31
	s_lshl_b64 s[0:1], s[82:83], 20
	v_readlane_b32 s34, v247, 33
	v_readlane_b32 s35, v247, 34
	s_add_u32 s84, s34, s0
	s_addc_u32 s85, s35, s1
	s_and_b64 s[0:1], s[2:3], exec
	s_cselect_b32 s0, s85, s89
	s_cselect_b32 s1, s84, s88
	s_ashr_i32 s81, s80, 31
	s_lshl_b64 s[34:35], s[80:81], 20
	s_add_u32 s86, s13, s34
	s_addc_u32 s87, s30, s35
	s_and_b64 s[34:35], s[2:3], exec
	s_cselect_b32 s52, s87, s91
	s_cselect_b32 s74, s86, s90
	s_add_u32 s88, s88, 0x80080
	s_addc_u32 s89, s89, 0
	s_add_u32 s75, s90, 0x100
	s_addc_u32 s77, s91, 0
	s_mov_b32 s81, -2
	ds_read_b128 v[146:149], v164
	ds_read_b128 v[150:153], v164 offset:1024
	ds_read_b128 v[154:157], v164 offset:2048
	ds_read_b128 v[158:161], v164 offset:3072
	ds_read_b128 v[168:171], v165
	ds_read_b128 v[172:175], v165 offset:1024
	ds_read_b128 v[176:179], v165 offset:2048
	ds_read_b128 v[180:183], v165 offset:3072
	s_add_u32 s34, s88, 0xfff80080
	s_addc_u32 s35, s89, -1
	s_cmp_eq_u32 s81, 28
	s_cselect_b32 s91, s0, s35
	s_cselect_b32 s90, s1, s34
	s_cselect_b32 s35, s52, s77
	s_cselect_b32 s34, s74, s75
	v_lshl_add_u64 v[218:219], s[88:89], 0, v[138:139]
	s_add_i32 m0, s33, 0xc000
	ds_read_b128 v[184:187], v166
	ds_read_b128 v[188:191], v166 offset:1024
	ds_read_b128 v[192:195], v166 offset:2048
	ds_read_b128 v[196:199], v166 offset:3072
	ds_read_b128 v[200:203], v166 offset:4096
	ds_read_b128 v[204:207], v166 offset:5120
	ds_read_b128 v[208:211], v166 offset:6144
	ds_read_b128 v[212:215], v166 offset:7168
	global_load_lds_dwordx4 v[218:219], off
	v_lshl_add_u64 v[218:219], s[88:89], 0, v[140:141]
	s_add_i32 m0, s33, 0xe000
	s_nop 0
	global_load_lds_dwordx4 v[218:219], off
	s_waitcnt vmcnt(8)
	s_waitcnt lgkmcnt(0)
	s_barrier
	s_setprio 1
	s_waitcnt lgkmcnt(0)
	v_mfma_f32_16x16x32_bf16 v[126:129], v[146:149], v[184:187], 0
	v_mfma_f32_16x16x32_bf16 v[122:125], v[154:157], v[184:187], 0
	v_mfma_f32_16x16x32_bf16 v[110:113], v[146:149], v[192:195], 0
	v_mfma_f32_16x16x32_bf16 v[106:109], v[154:157], v[192:195], 0
	v_mfma_f32_16x16x32_bf16 v[94:97], v[146:149], v[200:203], 0
	v_mfma_f32_16x16x32_bf16 v[90:93], v[154:157], v[200:203], 0
	v_mfma_f32_16x16x32_bf16 v[78:81], v[146:149], v[208:211], 0
	v_mfma_f32_16x16x32_bf16 v[74:77], v[154:157], v[208:211], 0
	v_mfma_f32_16x16x32_bf16 v[126:129], v[150:153], v[188:191], v[126:129]
	v_mfma_f32_16x16x32_bf16 v[122:125], v[158:161], v[188:191], v[122:125]
	v_mfma_f32_16x16x32_bf16 v[110:113], v[150:153], v[196:199], v[110:113]
	v_mfma_f32_16x16x32_bf16 v[106:109], v[158:161], v[196:199], v[106:109]
	v_mfma_f32_16x16x32_bf16 v[94:97], v[150:153], v[204:207], v[94:97]
	v_mfma_f32_16x16x32_bf16 v[90:93], v[158:161], v[204:207], v[90:93]
	v_mfma_f32_16x16x32_bf16 v[78:81], v[150:153], v[212:215], v[78:81]
	v_mfma_f32_16x16x32_bf16 v[74:77], v[158:161], v[212:215], v[74:77]
	s_setprio 0
	s_setprio 1
	v_mfma_f32_16x16x32_bf16 v[118:121], v[168:171], v[184:187], 0
	v_mfma_f32_16x16x32_bf16 v[114:117], v[176:179], v[184:187], 0
	v_mfma_f32_16x16x32_bf16 v[102:105], v[168:171], v[192:195], 0
	v_mfma_f32_16x16x32_bf16 v[98:101], v[176:179], v[192:195], 0
	v_mfma_f32_16x16x32_bf16 v[86:89], v[168:171], v[200:203], 0
	v_mfma_f32_16x16x32_bf16 v[82:85], v[176:179], v[200:203], 0
	v_mfma_f32_16x16x32_bf16 v[70:73], v[168:171], v[208:211], 0
	v_mfma_f32_16x16x32_bf16 v[66:69], v[176:179], v[208:211], 0
	v_mfma_f32_16x16x32_bf16 v[118:121], v[172:175], v[188:191], v[118:121]
	v_mfma_f32_16x16x32_bf16 v[114:117], v[180:183], v[188:191], v[114:117]
	v_mfma_f32_16x16x32_bf16 v[102:105], v[172:175], v[196:199], v[102:105]
	v_mfma_f32_16x16x32_bf16 v[98:101], v[180:183], v[196:199], v[98:101]
	v_mfma_f32_16x16x32_bf16 v[86:89], v[172:175], v[204:207], v[86:89]
	v_mfma_f32_16x16x32_bf16 v[82:85], v[180:183], v[204:207], v[82:85]
	v_mfma_f32_16x16x32_bf16 v[70:73], v[172:175], v[212:215], v[70:73]
	v_mfma_f32_16x16x32_bf16 v[66:69], v[180:183], v[212:215], v[66:69]
	s_setprio 0
	s_barrier
	s_add_i32 s53, s71, s31
	v_lshl_add_u64 v[218:219], s[34:35], 0, v[132:133]
	s_mov_b32 m0, s53
	ds_read_b128 v[184:187], v166 offset:16384
	ds_read_b128 v[188:191], v166 offset:17408
	ds_read_b128 v[192:195], v166 offset:18432
	ds_read_b128 v[196:199], v166 offset:19456
	ds_read_b128 v[200:203], v166 offset:20480
	ds_read_b128 v[204:207], v166 offset:21504
	ds_read_b128 v[208:211], v166 offset:22528
	ds_read_b128 v[212:215], v166 offset:23552
	global_load_lds_dwordx4 v[218:219], off
	s_add_i32 m0, s53, 0x2000
	s_add_u32 s54, s34, 0x80000
	v_lshl_add_u64 v[220:221], s[34:35], 0, v[136:137]
	s_addc_u32 s55, s35, 0
	s_add_i32 s53, s72, s31
	global_load_lds_dwordx4 v[220:221], off
	v_lshl_add_u64 v[222:223], s[54:55], 0, v[132:133]
	s_mov_b32 m0, s53
	v_lshl_add_u64 v[224:225], s[90:91], 0, v[134:135]
	global_load_lds_dwordx4 v[222:223], off
	v_lshl_add_u64 v[222:223], s[54:55], 0, v[136:137]
	s_add_i32 m0, s53, 0x2000
	s_nop 0
	global_load_lds_dwordx4 v[222:223], off
	v_lshl_add_u64 v[222:223], s[90:91], 0, v[130:131]
	s_mov_b32 m0, s33
	s_nop 0
	global_load_lds_dwordx4 v[222:223], off
	s_mov_b32 m0, s56
	s_nop 0
	global_load_lds_dwordx4 v[224:225], off
	s_waitcnt vmcnt(8)
	s_waitcnt lgkmcnt(0)
	s_barrier
	s_setprio 1
	s_waitcnt lgkmcnt(0)
	v_mfma_f32_16x16x32_bf16 v[62:65], v[146:149], v[184:187], 0
	v_mfma_f32_16x16x32_bf16 v[58:61], v[154:157], v[184:187], 0
	v_mfma_f32_16x16x32_bf16 v[46:49], v[146:149], v[192:195], 0
	v_mfma_f32_16x16x32_bf16 v[42:45], v[154:157], v[192:195], 0
	v_mfma_f32_16x16x32_bf16 v[30:33], v[146:149], v[200:203], 0
	v_mfma_f32_16x16x32_bf16 v[26:29], v[154:157], v[200:203], 0
	v_mfma_f32_16x16x32_bf16 v[14:17], v[146:149], v[208:211], 0
	v_mfma_f32_16x16x32_bf16 v[10:13], v[154:157], v[208:211], 0
	v_mfma_f32_16x16x32_bf16 v[62:65], v[150:153], v[188:191], v[62:65]
	v_mfma_f32_16x16x32_bf16 v[58:61], v[158:161], v[188:191], v[58:61]
	v_mfma_f32_16x16x32_bf16 v[46:49], v[150:153], v[196:199], v[46:49]
	v_mfma_f32_16x16x32_bf16 v[42:45], v[158:161], v[196:199], v[42:45]
	v_mfma_f32_16x16x32_bf16 v[30:33], v[150:153], v[204:207], v[30:33]
	v_mfma_f32_16x16x32_bf16 v[26:29], v[158:161], v[204:207], v[26:29]
	v_mfma_f32_16x16x32_bf16 v[14:17], v[150:153], v[212:215], v[14:17]
	v_mfma_f32_16x16x32_bf16 v[10:13], v[158:161], v[212:215], v[10:13]
	s_setprio 0
	s_setprio 1
	v_mfma_f32_16x16x32_bf16 v[54:57], v[168:171], v[184:187], 0
	v_mfma_f32_16x16x32_bf16 v[50:53], v[176:179], v[184:187], 0
	v_mfma_f32_16x16x32_bf16 v[38:41], v[168:171], v[192:195], 0
	v_mfma_f32_16x16x32_bf16 v[34:37], v[176:179], v[192:195], 0
	v_mfma_f32_16x16x32_bf16 v[22:25], v[168:171], v[200:203], 0
	v_mfma_f32_16x16x32_bf16 v[18:21], v[176:179], v[200:203], 0
	v_mfma_f32_16x16x32_bf16 v[6:9], v[168:171], v[208:211], 0
	v_mfma_f32_16x16x32_bf16 v[2:5], v[176:179], v[208:211], 0
	v_mfma_f32_16x16x32_bf16 v[54:57], v[172:175], v[188:191], v[54:57]
	v_mfma_f32_16x16x32_bf16 v[50:53], v[180:183], v[188:191], v[50:53]
	v_mfma_f32_16x16x32_bf16 v[38:41], v[172:175], v[196:199], v[38:41]
	v_mfma_f32_16x16x32_bf16 v[34:37], v[180:183], v[196:199], v[34:37]
	v_mfma_f32_16x16x32_bf16 v[22:25], v[172:175], v[204:207], v[22:25]
	v_mfma_f32_16x16x32_bf16 v[18:21], v[180:183], v[204:207], v[18:21]
	v_mfma_f32_16x16x32_bf16 v[6:9], v[172:175], v[212:215], v[6:9]
	v_mfma_f32_16x16x32_bf16 v[2:5], v[180:183], v[212:215], v[2:5]
	s_setprio 0
	s_barrier
	s_add_i32 s53, 0, 0x18000
	s_add_i32 s62, 0, 0x1c000
	v_add_u32_e32 v158, s53, v162
	v_add_u32_e32 v167, s62, v162
	ds_read_b128 v[146:149], v158
	ds_read_b128 v[150:153], v158 offset:1024
	ds_read_b128 v[154:157], v158 offset:2048
	ds_read_b128 v[158:161], v158 offset:3072
	ds_read_b128 v[168:171], v167
	ds_read_b128 v[172:175], v167 offset:1024
	ds_read_b128 v[176:179], v167 offset:2048
	ds_read_b128 v[180:183], v167 offset:3072
	s_add_u32 s54, s90, 0x80000
	s_addc_u32 s55, s91, 0
	s_mov_b32 m0, s57
	v_lshl_add_u64 v[226:227], s[54:55], 0, v[130:131]
	ds_read_b128 v[184:187], v166 offset:32768
	ds_read_b128 v[188:191], v166 offset:33792
	ds_read_b128 v[192:195], v166 offset:34816
	ds_read_b128 v[196:199], v166 offset:35840
	ds_read_b128 v[200:203], v166 offset:36864
	ds_read_b128 v[204:207], v166 offset:37888
	ds_read_b128 v[208:211], v166 offset:38912
	ds_read_b128 v[212:215], v166 offset:39936
	global_load_lds_dwordx4 v[226:227], off
	v_lshl_add_u64 v[226:227], s[54:55], 0, v[134:135]
	s_mov_b32 m0, s58
	s_nop 0
	global_load_lds_dwordx4 v[226:227], off
	s_waitcnt vmcnt(8)
	s_waitcnt lgkmcnt(0)
	s_barrier
	s_setprio 1
	s_waitcnt lgkmcnt(0)
	v_mfma_f32_16x16x32_bf16 v[126:129], v[146:149], v[184:187], v[126:129]
	v_mfma_f32_16x16x32_bf16 v[122:125], v[154:157], v[184:187], v[122:125]
	v_mfma_f32_16x16x32_bf16 v[110:113], v[146:149], v[192:195], v[110:113]
	v_mfma_f32_16x16x32_bf16 v[106:109], v[154:157], v[192:195], v[106:109]
	v_mfma_f32_16x16x32_bf16 v[94:97], v[146:149], v[200:203], v[94:97]
	v_mfma_f32_16x16x32_bf16 v[90:93], v[154:157], v[200:203], v[90:93]
	v_mfma_f32_16x16x32_bf16 v[78:81], v[146:149], v[208:211], v[78:81]
	v_mfma_f32_16x16x32_bf16 v[74:77], v[154:157], v[208:211], v[74:77]
	v_mfma_f32_16x16x32_bf16 v[126:129], v[150:153], v[188:191], v[126:129]
	v_mfma_f32_16x16x32_bf16 v[122:125], v[158:161], v[188:191], v[122:125]
	v_mfma_f32_16x16x32_bf16 v[110:113], v[150:153], v[196:199], v[110:113]
	v_mfma_f32_16x16x32_bf16 v[106:109], v[158:161], v[196:199], v[106:109]
	v_mfma_f32_16x16x32_bf16 v[94:97], v[150:153], v[204:207], v[94:97]
	v_mfma_f32_16x16x32_bf16 v[90:93], v[158:161], v[204:207], v[90:93]
	v_mfma_f32_16x16x32_bf16 v[78:81], v[150:153], v[212:215], v[78:81]
	v_mfma_f32_16x16x32_bf16 v[74:77], v[158:161], v[212:215], v[74:77]
	s_setprio 0
	s_setprio 1
	v_mfma_f32_16x16x32_bf16 v[118:121], v[168:171], v[184:187], v[118:121]
	v_mfma_f32_16x16x32_bf16 v[114:117], v[176:179], v[184:187], v[114:117]
	v_mfma_f32_16x16x32_bf16 v[102:105], v[168:171], v[192:195], v[102:105]
	v_mfma_f32_16x16x32_bf16 v[98:101], v[176:179], v[192:195], v[98:101]
	v_mfma_f32_16x16x32_bf16 v[86:89], v[168:171], v[200:203], v[86:89]
	v_mfma_f32_16x16x32_bf16 v[82:85], v[176:179], v[200:203], v[82:85]
	v_mfma_f32_16x16x32_bf16 v[70:73], v[168:171], v[208:211], v[70:73]
	v_mfma_f32_16x16x32_bf16 v[66:69], v[176:179], v[208:211], v[66:69]
	v_mfma_f32_16x16x32_bf16 v[118:121], v[172:175], v[188:191], v[118:121]
	v_mfma_f32_16x16x32_bf16 v[114:117], v[180:183], v[188:191], v[114:117]
	v_mfma_f32_16x16x32_bf16 v[102:105], v[172:175], v[196:199], v[102:105]
	v_mfma_f32_16x16x32_bf16 v[98:101], v[180:183], v[196:199], v[98:101]
	v_mfma_f32_16x16x32_bf16 v[86:89], v[172:175], v[204:207], v[86:89]
	v_mfma_f32_16x16x32_bf16 v[82:85], v[180:183], v[204:207], v[82:85]
	v_mfma_f32_16x16x32_bf16 v[70:73], v[172:175], v[212:215], v[70:73]
	v_mfma_f32_16x16x32_bf16 v[66:69], v[180:183], v[212:215], v[66:69]
	s_setprio 0
	s_barrier
	s_add_i32 s53, s53, s31
	v_lshl_add_u64 v[218:219], v[218:219], 0, s[8:9]
	s_mov_b32 m0, s53
	ds_read_b128 v[184:187], v166 offset:49152
	ds_read_b128 v[188:191], v166 offset:50176
	ds_read_b128 v[192:195], v166 offset:51200
	ds_read_b128 v[196:199], v166 offset:52224
	ds_read_b128 v[200:203], v166 offset:53248
	ds_read_b128 v[204:207], v166 offset:54272
	ds_read_b128 v[208:211], v166 offset:55296
	ds_read_b128 v[212:215], v166 offset:56320
	global_load_lds_dwordx4 v[218:219], off
	s_add_i32 m0, s53, 0x2000
	s_add_u32 s34, s34, 0x80080
	v_lshl_add_u64 v[218:219], v[220:221], 0, s[8:9]
	s_addc_u32 s35, s35, 0
	s_add_i32 s53, s62, s31
	global_load_lds_dwordx4 v[218:219], off
	v_lshl_add_u64 v[218:219], s[34:35], 0, v[132:133]
	s_mov_b32 m0, s53
	s_nop 0
	global_load_lds_dwordx4 v[218:219], off
	v_lshl_add_u64 v[218:219], s[34:35], 0, v[136:137]
	s_add_i32 m0, s53, 0x2000
	s_nop 0
	global_load_lds_dwordx4 v[218:219], off
	v_lshl_add_u64 v[218:219], v[222:223], 0, s[8:9]
	s_mov_b32 m0, s60
	s_nop 0
	global_load_lds_dwordx4 v[218:219], off
	v_lshl_add_u64 v[218:219], v[224:225], 0, s[8:9]
	s_mov_b32 m0, s61
	s_nop 0
	global_load_lds_dwordx4 v[218:219], off
	s_waitcnt vmcnt(8)
	s_waitcnt lgkmcnt(0)
	s_barrier
	s_setprio 1
	s_waitcnt lgkmcnt(0)
	v_mfma_f32_16x16x32_bf16 v[62:65], v[146:149], v[184:187], v[62:65]
	v_mfma_f32_16x16x32_bf16 v[58:61], v[154:157], v[184:187], v[58:61]
	v_mfma_f32_16x16x32_bf16 v[46:49], v[146:149], v[192:195], v[46:49]
	v_mfma_f32_16x16x32_bf16 v[42:45], v[154:157], v[192:195], v[42:45]
	v_mfma_f32_16x16x32_bf16 v[30:33], v[146:149], v[200:203], v[30:33]
	v_mfma_f32_16x16x32_bf16 v[26:29], v[154:157], v[200:203], v[26:29]
	v_mfma_f32_16x16x32_bf16 v[14:17], v[146:149], v[208:211], v[14:17]
	v_mfma_f32_16x16x32_bf16 v[10:13], v[154:157], v[208:211], v[10:13]
	v_mfma_f32_16x16x32_bf16 v[62:65], v[150:153], v[188:191], v[62:65]
	v_mfma_f32_16x16x32_bf16 v[58:61], v[158:161], v[188:191], v[58:61]
	v_mfma_f32_16x16x32_bf16 v[46:49], v[150:153], v[196:199], v[46:49]
	v_mfma_f32_16x16x32_bf16 v[42:45], v[158:161], v[196:199], v[42:45]
	v_mfma_f32_16x16x32_bf16 v[30:33], v[150:153], v[204:207], v[30:33]
	v_mfma_f32_16x16x32_bf16 v[26:29], v[158:161], v[204:207], v[26:29]
	v_mfma_f32_16x16x32_bf16 v[14:17], v[150:153], v[212:215], v[14:17]
	v_mfma_f32_16x16x32_bf16 v[10:13], v[158:161], v[212:215], v[10:13]
	s_setprio 0
	s_setprio 1
	v_mfma_f32_16x16x32_bf16 v[54:57], v[168:171], v[184:187], v[54:57]
	v_mfma_f32_16x16x32_bf16 v[50:53], v[176:179], v[184:187], v[50:53]
	v_mfma_f32_16x16x32_bf16 v[38:41], v[168:171], v[192:195], v[38:41]
	v_mfma_f32_16x16x32_bf16 v[34:37], v[176:179], v[192:195], v[34:37]
	v_mfma_f32_16x16x32_bf16 v[22:25], v[168:171], v[200:203], v[22:25]
	v_mfma_f32_16x16x32_bf16 v[18:21], v[176:179], v[200:203], v[18:21]
	v_mfma_f32_16x16x32_bf16 v[6:9], v[168:171], v[208:211], v[6:9]
	v_mfma_f32_16x16x32_bf16 v[2:5], v[176:179], v[208:211], v[2:5]
	v_mfma_f32_16x16x32_bf16 v[54:57], v[172:175], v[188:191], v[54:57]
	v_mfma_f32_16x16x32_bf16 v[50:53], v[180:183], v[188:191], v[50:53]
	v_mfma_f32_16x16x32_bf16 v[38:41], v[172:175], v[196:199], v[38:41]
	v_mfma_f32_16x16x32_bf16 v[34:37], v[180:183], v[196:199], v[34:37]
	v_mfma_f32_16x16x32_bf16 v[22:25], v[172:175], v[204:207], v[22:25]
	v_mfma_f32_16x16x32_bf16 v[18:21], v[180:183], v[204:207], v[18:21]
	v_mfma_f32_16x16x32_bf16 v[6:9], v[172:175], v[212:215], v[6:9]
	v_mfma_f32_16x16x32_bf16 v[2:5], v[180:183], v[212:215], v[2:5]
	s_setprio 0
	s_barrier
	s_add_i32 s81, s81, 2
	s_add_u32 s88, s88, 0x100
	s_addc_u32 s89, s89, 0
	s_add_u32 s75, s75, 0x100
	s_addc_u32 s77, s77, 0

.LBB0_1123:
	s_ashr_i32 s83, s82, 31
	s_lshl_b64 s[0:1], s[82:83], 20
	v_readlane_b32 s34, v247, 45
	s_add_u32 s84, s34, s0
	v_readlane_b32 s0, v247, 47
	s_addc_u32 s85, s0, s1
	s_and_b64 s[0:1], s[2:3], exec
	s_cselect_b32 s0, s85, s89
	s_cselect_b32 s1, s84, s88
	s_ashr_i32 s81, s80, 31
	s_lshl_b64 s[34:35], s[80:81], 20
	s_add_u32 s86, s12, s34
	s_addc_u32 s87, s13, s35
	s_and_b64 s[34:35], s[2:3], exec
	s_cselect_b32 s52, s87, s91
	s_cselect_b32 s77, s86, s90
	s_add_u32 s88, s88, 0x80080
	s_addc_u32 s89, s89, 0
	s_add_u32 s81, s90, 0x100
	s_addc_u32 s83, s91, 0
	s_mov_b32 s92, -2
	ds_read_b128 v[146:149], v153
	ds_read_b128 v[156:159], v153 offset:1024
	ds_read_b128 v[160:163], v153 offset:2048
	ds_read_b128 v[164:167], v153 offset:3072
	ds_read_b128 v[168:171], v154
	ds_read_b128 v[172:175], v154 offset:1024
	ds_read_b128 v[176:179], v154 offset:2048
	ds_read_b128 v[180:183], v154 offset:3072
	s_add_u32 s34, s88, 0xfff80080
	s_addc_u32 s35, s89, -1
	s_cmp_eq_u32 s92, 28
	s_cselect_b32 s91, s0, s35
	s_cselect_b32 s90, s1, s34
	s_cselect_b32 s35, s52, s83
	s_cselect_b32 s34, s77, s81
	v_lshl_add_u64 v[218:219], s[88:89], 0, v[138:139]
	s_add_i32 m0, s56, 0xc000
	ds_read_b128 v[184:187], v155
	ds_read_b128 v[188:191], v155 offset:1024
	ds_read_b128 v[192:195], v155 offset:2048
	ds_read_b128 v[196:199], v155 offset:3072
	ds_read_b128 v[200:203], v155 offset:4096
	ds_read_b128 v[204:207], v155 offset:5120
	ds_read_b128 v[208:211], v155 offset:6144
	ds_read_b128 v[212:215], v155 offset:7168
	global_load_lds_dwordx4 v[218:219], off
	v_lshl_add_u64 v[218:219], s[88:89], 0, v[140:141]
	s_add_i32 m0, s56, 0xe000
	s_nop 0
	global_load_lds_dwordx4 v[218:219], off
	s_waitcnt vmcnt(8)
	s_waitcnt lgkmcnt(0)
	s_barrier
	s_setprio 1
	s_waitcnt lgkmcnt(0)
	v_mfma_f32_16x16x32_bf16 v[126:129], v[146:149], v[184:187], 0
	v_mfma_f32_16x16x32_bf16 v[118:121], v[160:163], v[184:187], 0
	v_mfma_f32_16x16x32_bf16 v[110:113], v[146:149], v[192:195], 0
	v_mfma_f32_16x16x32_bf16 v[102:105], v[160:163], v[192:195], 0
	v_mfma_f32_16x16x32_bf16 v[94:97], v[146:149], v[200:203], 0
	v_mfma_f32_16x16x32_bf16 v[86:89], v[160:163], v[200:203], 0
	v_mfma_f32_16x16x32_bf16 v[78:81], v[146:149], v[208:211], 0
	v_mfma_f32_16x16x32_bf16 v[70:73], v[160:163], v[208:211], 0
	v_mfma_f32_16x16x32_bf16 v[126:129], v[156:159], v[188:191], v[126:129]
	v_mfma_f32_16x16x32_bf16 v[118:121], v[164:167], v[188:191], v[118:121]
	v_mfma_f32_16x16x32_bf16 v[110:113], v[156:159], v[196:199], v[110:113]
	v_mfma_f32_16x16x32_bf16 v[102:105], v[164:167], v[196:199], v[102:105]
	v_mfma_f32_16x16x32_bf16 v[94:97], v[156:159], v[204:207], v[94:97]
	v_mfma_f32_16x16x32_bf16 v[86:89], v[164:167], v[204:207], v[86:89]
	v_mfma_f32_16x16x32_bf16 v[78:81], v[156:159], v[212:215], v[78:81]
	v_mfma_f32_16x16x32_bf16 v[70:73], v[164:167], v[212:215], v[70:73]
	s_setprio 0
	s_setprio 1
	v_mfma_f32_16x16x32_bf16 v[122:125], v[168:171], v[184:187], 0
	v_mfma_f32_16x16x32_bf16 v[114:117], v[176:179], v[184:187], 0
	v_mfma_f32_16x16x32_bf16 v[106:109], v[168:171], v[192:195], 0
	v_mfma_f32_16x16x32_bf16 v[98:101], v[176:179], v[192:195], 0
	v_mfma_f32_16x16x32_bf16 v[90:93], v[168:171], v[200:203], 0
	v_mfma_f32_16x16x32_bf16 v[82:85], v[176:179], v[200:203], 0
	v_mfma_f32_16x16x32_bf16 v[74:77], v[168:171], v[208:211], 0
	v_mfma_f32_16x16x32_bf16 v[66:69], v[176:179], v[208:211], 0
	v_mfma_f32_16x16x32_bf16 v[122:125], v[172:175], v[188:191], v[122:125]
	v_mfma_f32_16x16x32_bf16 v[114:117], v[180:183], v[188:191], v[114:117]
	v_mfma_f32_16x16x32_bf16 v[106:109], v[172:175], v[196:199], v[106:109]
	v_mfma_f32_16x16x32_bf16 v[98:101], v[180:183], v[196:199], v[98:101]
	v_mfma_f32_16x16x32_bf16 v[90:93], v[172:175], v[204:207], v[90:93]
	v_mfma_f32_16x16x32_bf16 v[82:85], v[180:183], v[204:207], v[82:85]
	v_mfma_f32_16x16x32_bf16 v[74:77], v[172:175], v[212:215], v[74:77]
	v_mfma_f32_16x16x32_bf16 v[66:69], v[180:183], v[212:215], v[66:69]
	s_setprio 0
	s_barrier
	s_add_i32 s53, s72, s30
	v_lshl_add_u64 v[218:219], s[34:35], 0, v[134:135]
	s_mov_b32 m0, s53
	ds_read_b128 v[184:187], v155 offset:16384
	ds_read_b128 v[188:191], v155 offset:17408
	ds_read_b128 v[192:195], v155 offset:18432
	ds_read_b128 v[196:199], v155 offset:19456
	ds_read_b128 v[200:203], v155 offset:20480
	ds_read_b128 v[204:207], v155 offset:21504
	ds_read_b128 v[208:211], v155 offset:22528
	ds_read_b128 v[212:215], v155 offset:23552
	global_load_lds_dwordx4 v[218:219], off
	s_add_i32 m0, s53, 0x2000
	s_add_u32 s54, s34, 0x80000
	v_lshl_add_u64 v[220:221], s[34:35], 0, v[130:131]
	s_addc_u32 s55, s35, 0
	s_add_i32 s53, s73, s30
	global_load_lds_dwordx4 v[220:221], off
	v_lshl_add_u64 v[222:223], s[54:55], 0, v[134:135]
	s_mov_b32 m0, s53
	v_lshl_add_u64 v[224:225], s[90:91], 0, v[132:133]
	global_load_lds_dwordx4 v[222:223], off
	v_lshl_add_u64 v[222:223], s[54:55], 0, v[130:131]
	s_add_i32 m0, s53, 0x2000
	s_nop 0
	global_load_lds_dwordx4 v[222:223], off
	v_lshl_add_u64 v[222:223], s[90:91], 0, v[136:137]
	s_mov_b32 m0, s56
	s_nop 0
	global_load_lds_dwordx4 v[222:223], off
	s_mov_b32 m0, s57
	s_nop 0
	global_load_lds_dwordx4 v[224:225], off
	s_waitcnt vmcnt(8)
	s_waitcnt lgkmcnt(0)
	s_barrier
	s_setprio 1
	s_waitcnt lgkmcnt(0)
	v_mfma_f32_16x16x32_bf16 v[62:65], v[146:149], v[184:187], 0
	v_mfma_f32_16x16x32_bf16 v[54:57], v[160:163], v[184:187], 0
	v_mfma_f32_16x16x32_bf16 v[46:49], v[146:149], v[192:195], 0
	v_mfma_f32_16x16x32_bf16 v[38:41], v[160:163], v[192:195], 0
	v_mfma_f32_16x16x32_bf16 v[30:33], v[146:149], v[200:203], 0
	v_mfma_f32_16x16x32_bf16 v[22:25], v[160:163], v[200:203], 0
	v_mfma_f32_16x16x32_bf16 v[14:17], v[146:149], v[208:211], 0
	v_mfma_f32_16x16x32_bf16 v[6:9], v[160:163], v[208:211], 0
	v_mfma_f32_16x16x32_bf16 v[62:65], v[156:159], v[188:191], v[62:65]
	v_mfma_f32_16x16x32_bf16 v[54:57], v[164:167], v[188:191], v[54:57]
	v_mfma_f32_16x16x32_bf16 v[46:49], v[156:159], v[196:199], v[46:49]
	v_mfma_f32_16x16x32_bf16 v[38:41], v[164:167], v[196:199], v[38:41]
	v_mfma_f32_16x16x32_bf16 v[30:33], v[156:159], v[204:207], v[30:33]
	v_mfma_f32_16x16x32_bf16 v[22:25], v[164:167], v[204:207], v[22:25]
	v_mfma_f32_16x16x32_bf16 v[14:17], v[156:159], v[212:215], v[14:17]
	v_mfma_f32_16x16x32_bf16 v[6:9], v[164:167], v[212:215], v[6:9]
	s_setprio 0
	s_setprio 1
	v_mfma_f32_16x16x32_bf16 v[58:61], v[168:171], v[184:187], 0
	v_mfma_f32_16x16x32_bf16 v[50:53], v[176:179], v[184:187], 0
	v_mfma_f32_16x16x32_bf16 v[42:45], v[168:171], v[192:195], 0
	v_mfma_f32_16x16x32_bf16 v[34:37], v[176:179], v[192:195], 0
	v_mfma_f32_16x16x32_bf16 v[26:29], v[168:171], v[200:203], 0
	v_mfma_f32_16x16x32_bf16 v[18:21], v[176:179], v[200:203], 0
	v_mfma_f32_16x16x32_bf16 v[10:13], v[168:171], v[208:211], 0
	v_mfma_f32_16x16x32_bf16 v[2:5], v[176:179], v[208:211], 0
	v_mfma_f32_16x16x32_bf16 v[58:61], v[172:175], v[188:191], v[58:61]
	v_mfma_f32_16x16x32_bf16 v[50:53], v[180:183], v[188:191], v[50:53]
	v_mfma_f32_16x16x32_bf16 v[42:45], v[172:175], v[196:199], v[42:45]
	v_mfma_f32_16x16x32_bf16 v[34:37], v[180:183], v[196:199], v[34:37]
	v_mfma_f32_16x16x32_bf16 v[26:29], v[172:175], v[204:207], v[26:29]
	v_mfma_f32_16x16x32_bf16 v[18:21], v[180:183], v[204:207], v[18:21]
	v_mfma_f32_16x16x32_bf16 v[10:13], v[172:175], v[212:215], v[10:13]
	v_mfma_f32_16x16x32_bf16 v[2:5], v[180:183], v[212:215], v[2:5]
	s_setprio 0
	s_barrier
	s_add_i32 s53, 0, 0x18000
	s_add_i32 s62, 0, 0x1c000
	v_add_u32_e32 v164, s53, v151
	v_add_u32_e32 v180, s62, v151
	ds_read_b128 v[146:149], v164
	ds_read_b128 v[156:159], v164 offset:1024
	ds_read_b128 v[160:163], v164 offset:2048
	ds_read_b128 v[164:167], v164 offset:3072
	ds_read_b128 v[168:171], v180
	ds_read_b128 v[172:175], v180 offset:1024
	ds_read_b128 v[176:179], v180 offset:2048
	ds_read_b128 v[180:183], v180 offset:3072
	s_add_u32 s54, s90, 0x80000
	s_addc_u32 s55, s91, 0
	s_mov_b32 m0, s58
	v_lshl_add_u64 v[226:227], s[54:55], 0, v[136:137]
	ds_read_b128 v[184:187], v155 offset:32768
	ds_read_b128 v[188:191], v155 offset:33792
	ds_read_b128 v[192:195], v155 offset:34816
	ds_read_b128 v[196:199], v155 offset:35840
	ds_read_b128 v[200:203], v155 offset:36864
	ds_read_b128 v[204:207], v155 offset:37888
	ds_read_b128 v[208:211], v155 offset:38912
	ds_read_b128 v[212:215], v155 offset:39936
	global_load_lds_dwordx4 v[226:227], off
	v_lshl_add_u64 v[226:227], s[54:55], 0, v[132:133]
	s_mov_b32 m0, s59
	s_nop 0
	global_load_lds_dwordx4 v[226:227], off
	s_waitcnt vmcnt(8)
	s_waitcnt lgkmcnt(0)
	s_barrier
	s_setprio 1
	s_waitcnt lgkmcnt(0)
	v_mfma_f32_16x16x32_bf16 v[126:129], v[146:149], v[184:187], v[126:129]
	v_mfma_f32_16x16x32_bf16 v[118:121], v[160:163], v[184:187], v[118:121]
	v_mfma_f32_16x16x32_bf16 v[110:113], v[146:149], v[192:195], v[110:113]
	v_mfma_f32_16x16x32_bf16 v[102:105], v[160:163], v[192:195], v[102:105]
	v_mfma_f32_16x16x32_bf16 v[94:97], v[146:149], v[200:203], v[94:97]
	v_mfma_f32_16x16x32_bf16 v[86:89], v[160:163], v[200:203], v[86:89]
	v_mfma_f32_16x16x32_bf16 v[78:81], v[146:149], v[208:211], v[78:81]
	v_mfma_f32_16x16x32_bf16 v[70:73], v[160:163], v[208:211], v[70:73]
	v_mfma_f32_16x16x32_bf16 v[126:129], v[156:159], v[188:191], v[126:129]
	v_mfma_f32_16x16x32_bf16 v[118:121], v[164:167], v[188:191], v[118:121]
	v_mfma_f32_16x16x32_bf16 v[110:113], v[156:159], v[196:199], v[110:113]
	v_mfma_f32_16x16x32_bf16 v[102:105], v[164:167], v[196:199], v[102:105]
	v_mfma_f32_16x16x32_bf16 v[94:97], v[156:159], v[204:207], v[94:97]
	v_mfma_f32_16x16x32_bf16 v[86:89], v[164:167], v[204:207], v[86:89]
	v_mfma_f32_16x16x32_bf16 v[78:81], v[156:159], v[212:215], v[78:81]
	v_mfma_f32_16x16x32_bf16 v[70:73], v[164:167], v[212:215], v[70:73]
	s_setprio 0
	s_setprio 1
	v_mfma_f32_16x16x32_bf16 v[122:125], v[168:171], v[184:187], v[122:125]
	v_mfma_f32_16x16x32_bf16 v[114:117], v[176:179], v[184:187], v[114:117]
	v_mfma_f32_16x16x32_bf16 v[106:109], v[168:171], v[192:195], v[106:109]
	v_mfma_f32_16x16x32_bf16 v[98:101], v[176:179], v[192:195], v[98:101]
	v_mfma_f32_16x16x32_bf16 v[90:93], v[168:171], v[200:203], v[90:93]
	v_mfma_f32_16x16x32_bf16 v[82:85], v[176:179], v[200:203], v[82:85]
	v_mfma_f32_16x16x32_bf16 v[74:77], v[168:171], v[208:211], v[74:77]
	v_mfma_f32_16x16x32_bf16 v[66:69], v[176:179], v[208:211], v[66:69]
	v_mfma_f32_16x16x32_bf16 v[122:125], v[172:175], v[188:191], v[122:125]
	v_mfma_f32_16x16x32_bf16 v[114:117], v[180:183], v[188:191], v[114:117]
	v_mfma_f32_16x16x32_bf16 v[106:109], v[172:175], v[196:199], v[106:109]
	v_mfma_f32_16x16x32_bf16 v[98:101], v[180:183], v[196:199], v[98:101]
	v_mfma_f32_16x16x32_bf16 v[90:93], v[172:175], v[204:207], v[90:93]
	v_mfma_f32_16x16x32_bf16 v[82:85], v[180:183], v[204:207], v[82:85]
	v_mfma_f32_16x16x32_bf16 v[74:77], v[172:175], v[212:215], v[74:77]
	v_mfma_f32_16x16x32_bf16 v[66:69], v[180:183], v[212:215], v[66:69]
	s_setprio 0
	s_barrier
	s_add_i32 s53, s53, s30
	v_lshl_add_u64 v[218:219], v[218:219], 0, s[8:9]
	s_mov_b32 m0, s53
	ds_read_b128 v[184:187], v155 offset:49152
	ds_read_b128 v[188:191], v155 offset:50176
	ds_read_b128 v[192:195], v155 offset:51200
	ds_read_b128 v[196:199], v155 offset:52224
	ds_read_b128 v[200:203], v155 offset:53248
	ds_read_b128 v[204:207], v155 offset:54272
	ds_read_b128 v[208:211], v155 offset:55296
	ds_read_b128 v[212:215], v155 offset:56320
	global_load_lds_dwordx4 v[218:219], off
	s_add_i32 m0, s53, 0x2000
	s_add_u32 s34, s34, 0x80080
	v_lshl_add_u64 v[218:219], v[220:221], 0, s[8:9]
	s_addc_u32 s35, s35, 0
	s_add_i32 s53, s62, s30
	global_load_lds_dwordx4 v[218:219], off
	v_lshl_add_u64 v[218:219], s[34:35], 0, v[134:135]
	s_mov_b32 m0, s53
	s_nop 0
	global_load_lds_dwordx4 v[218:219], off
	v_lshl_add_u64 v[218:219], s[34:35], 0, v[130:131]
	s_add_i32 m0, s53, 0x2000
	s_nop 0
	global_load_lds_dwordx4 v[218:219], off
	v_lshl_add_u64 v[218:219], v[222:223], 0, s[8:9]
	s_mov_b32 m0, s61
	s_nop 0
	global_load_lds_dwordx4 v[218:219], off
	v_lshl_add_u64 v[218:219], v[224:225], 0, s[8:9]
	s_mov_b32 m0, s70
	s_nop 0
	global_load_lds_dwordx4 v[218:219], off
	s_waitcnt vmcnt(8)
	s_waitcnt lgkmcnt(0)
	s_barrier
	s_setprio 1
	s_waitcnt lgkmcnt(0)
	v_mfma_f32_16x16x32_bf16 v[62:65], v[146:149], v[184:187], v[62:65]
	v_mfma_f32_16x16x32_bf16 v[54:57], v[160:163], v[184:187], v[54:57]
	v_mfma_f32_16x16x32_bf16 v[46:49], v[146:149], v[192:195], v[46:49]
	v_mfma_f32_16x16x32_bf16 v[38:41], v[160:163], v[192:195], v[38:41]
	v_mfma_f32_16x16x32_bf16 v[30:33], v[146:149], v[200:203], v[30:33]
	v_mfma_f32_16x16x32_bf16 v[22:25], v[160:163], v[200:203], v[22:25]
	v_mfma_f32_16x16x32_bf16 v[14:17], v[146:149], v[208:211], v[14:17]
	v_mfma_f32_16x16x32_bf16 v[6:9], v[160:163], v[208:211], v[6:9]
	v_mfma_f32_16x16x32_bf16 v[62:65], v[156:159], v[188:191], v[62:65]
	v_mfma_f32_16x16x32_bf16 v[54:57], v[164:167], v[188:191], v[54:57]
	v_mfma_f32_16x16x32_bf16 v[46:49], v[156:159], v[196:199], v[46:49]
	v_mfma_f32_16x16x32_bf16 v[38:41], v[164:167], v[196:199], v[38:41]
	v_mfma_f32_16x16x32_bf16 v[30:33], v[156:159], v[204:207], v[30:33]
	v_mfma_f32_16x16x32_bf16 v[22:25], v[164:167], v[204:207], v[22:25]
	v_mfma_f32_16x16x32_bf16 v[14:17], v[156:159], v[212:215], v[14:17]
	v_mfma_f32_16x16x32_bf16 v[6:9], v[164:167], v[212:215], v[6:9]
	s_setprio 0
	s_setprio 1
	v_mfma_f32_16x16x32_bf16 v[58:61], v[168:171], v[184:187], v[58:61]
	v_mfma_f32_16x16x32_bf16 v[50:53], v[176:179], v[184:187], v[50:53]
	v_mfma_f32_16x16x32_bf16 v[42:45], v[168:171], v[192:195], v[42:45]
	v_mfma_f32_16x16x32_bf16 v[34:37], v[176:179], v[192:195], v[34:37]
	v_mfma_f32_16x16x32_bf16 v[26:29], v[168:171], v[200:203], v[26:29]
	v_mfma_f32_16x16x32_bf16 v[18:21], v[176:179], v[200:203], v[18:21]
	v_mfma_f32_16x16x32_bf16 v[10:13], v[168:171], v[208:211], v[10:13]
	v_mfma_f32_16x16x32_bf16 v[2:5], v[176:179], v[208:211], v[2:5]
	v_mfma_f32_16x16x32_bf16 v[58:61], v[172:175], v[188:191], v[58:61]
	v_mfma_f32_16x16x32_bf16 v[50:53], v[180:183], v[188:191], v[50:53]
	v_mfma_f32_16x16x32_bf16 v[42:45], v[172:175], v[196:199], v[42:45]
	v_mfma_f32_16x16x32_bf16 v[34:37], v[180:183], v[196:199], v[34:37]
	v_mfma_f32_16x16x32_bf16 v[26:29], v[172:175], v[204:207], v[26:29]
	v_mfma_f32_16x16x32_bf16 v[18:21], v[180:183], v[204:207], v[18:21]
	v_mfma_f32_16x16x32_bf16 v[10:13], v[172:175], v[212:215], v[10:13]
	v_mfma_f32_16x16x32_bf16 v[2:5], v[180:183], v[212:215], v[2:5]
	s_setprio 0
	s_barrier
	s_add_i32 s92, s92, 2
	s_add_u32 s88, s88, 0x100
	s_addc_u32 s89, s89, 0
	s_add_u32 s81, s81, 0x100
	s_addc_u32 s83, s83, 0

.LBB0_1236:
	s_add_u32 s76, s76, 0x160080
	s_addc_u32 s77, s77, 0
	s_add_u32 s0, s84, 0x100
	s_addc_u32 s1, s85, 0
	s_mov_b32 s52, -2
	ds_read_b128 v[146:149], v164
	ds_read_b128 v[150:153], v164 offset:1024
	ds_read_b128 v[154:157], v164 offset:2048
	ds_read_b128 v[158:161], v164 offset:3072
	ds_read_b128 v[168:171], v165
	ds_read_b128 v[172:175], v165 offset:1024
	ds_read_b128 v[176:179], v165 offset:2048
	ds_read_b128 v[180:183], v165 offset:3072
	s_add_u32 s34, s76, 0xffea0080
	s_addc_u32 s35, s77, -1
	s_cmpk_eq_i32 s52, 0x54
	s_cselect_b32 s85, s5, s35
	s_cselect_b32 s84, s4, s34
	s_cselect_b32 s35, s83, s1
	s_cselect_b32 s34, s82, s0
	v_lshl_add_u64 v[218:219], s[76:77], 0, v[138:139]
	s_add_i32 m0, s33, 0xc000
	ds_read_b128 v[184:187], v166
	ds_read_b128 v[188:191], v166 offset:1024
	ds_read_b128 v[192:195], v166 offset:2048
	ds_read_b128 v[196:199], v166 offset:3072
	ds_read_b128 v[200:203], v166 offset:4096
	ds_read_b128 v[204:207], v166 offset:5120
	ds_read_b128 v[208:211], v166 offset:6144
	ds_read_b128 v[212:215], v166 offset:7168
	global_load_lds_dwordx4 v[218:219], off
	v_lshl_add_u64 v[218:219], s[76:77], 0, v[140:141]
	s_add_i32 m0, s33, 0xe000
	s_nop 0
	global_load_lds_dwordx4 v[218:219], off
	s_waitcnt vmcnt(8)
	s_waitcnt lgkmcnt(0)
	s_barrier
	s_setprio 1
	s_waitcnt lgkmcnt(0)
	v_mfma_f32_16x16x32_bf16 v[126:129], v[146:149], v[184:187], 0
	v_mfma_f32_16x16x32_bf16 v[122:125], v[154:157], v[184:187], 0
	v_mfma_f32_16x16x32_bf16 v[110:113], v[146:149], v[192:195], 0
	v_mfma_f32_16x16x32_bf16 v[106:109], v[154:157], v[192:195], 0
	v_mfma_f32_16x16x32_bf16 v[94:97], v[146:149], v[200:203], 0
	v_mfma_f32_16x16x32_bf16 v[90:93], v[154:157], v[200:203], 0
	v_mfma_f32_16x16x32_bf16 v[78:81], v[146:149], v[208:211], 0
	v_mfma_f32_16x16x32_bf16 v[74:77], v[154:157], v[208:211], 0
	v_mfma_f32_16x16x32_bf16 v[126:129], v[150:153], v[188:191], v[126:129]
	v_mfma_f32_16x16x32_bf16 v[122:125], v[158:161], v[188:191], v[122:125]
	v_mfma_f32_16x16x32_bf16 v[110:113], v[150:153], v[196:199], v[110:113]
	v_mfma_f32_16x16x32_bf16 v[106:109], v[158:161], v[196:199], v[106:109]
	v_mfma_f32_16x16x32_bf16 v[94:97], v[150:153], v[204:207], v[94:97]
	v_mfma_f32_16x16x32_bf16 v[90:93], v[158:161], v[204:207], v[90:93]
	v_mfma_f32_16x16x32_bf16 v[78:81], v[150:153], v[212:215], v[78:81]
	v_mfma_f32_16x16x32_bf16 v[74:77], v[158:161], v[212:215], v[74:77]
	s_setprio 0
	s_setprio 1
	v_mfma_f32_16x16x32_bf16 v[118:121], v[168:171], v[184:187], 0
	v_mfma_f32_16x16x32_bf16 v[114:117], v[176:179], v[184:187], 0
	v_mfma_f32_16x16x32_bf16 v[102:105], v[168:171], v[192:195], 0
	v_mfma_f32_16x16x32_bf16 v[98:101], v[176:179], v[192:195], 0
	v_mfma_f32_16x16x32_bf16 v[86:89], v[168:171], v[200:203], 0
	v_mfma_f32_16x16x32_bf16 v[82:85], v[176:179], v[200:203], 0
	v_mfma_f32_16x16x32_bf16 v[70:73], v[168:171], v[208:211], 0
	v_mfma_f32_16x16x32_bf16 v[66:69], v[176:179], v[208:211], 0
	v_mfma_f32_16x16x32_bf16 v[118:121], v[172:175], v[188:191], v[118:121]
	v_mfma_f32_16x16x32_bf16 v[114:117], v[180:183], v[188:191], v[114:117]
	v_mfma_f32_16x16x32_bf16 v[102:105], v[172:175], v[196:199], v[102:105]
	v_mfma_f32_16x16x32_bf16 v[98:101], v[180:183], v[196:199], v[98:101]
	v_mfma_f32_16x16x32_bf16 v[86:89], v[172:175], v[204:207], v[86:89]
	v_mfma_f32_16x16x32_bf16 v[82:85], v[180:183], v[204:207], v[82:85]
	v_mfma_f32_16x16x32_bf16 v[70:73], v[172:175], v[212:215], v[70:73]
	v_mfma_f32_16x16x32_bf16 v[66:69], v[180:183], v[212:215], v[66:69]
	s_setprio 0
	s_barrier
	s_add_i32 s53, s71, s31
	v_lshl_add_u64 v[218:219], s[34:35], 0, v[132:133]
	s_mov_b32 m0, s53
	ds_read_b128 v[184:187], v166 offset:16384
	ds_read_b128 v[188:191], v166 offset:17408
	ds_read_b128 v[192:195], v166 offset:18432
	ds_read_b128 v[196:199], v166 offset:19456
	ds_read_b128 v[200:203], v166 offset:20480
	ds_read_b128 v[204:207], v166 offset:21504
	ds_read_b128 v[208:211], v166 offset:22528
	ds_read_b128 v[212:215], v166 offset:23552
	global_load_lds_dwordx4 v[218:219], off
	s_add_i32 m0, s53, 0x2000
	s_add_u32 s54, s34, 0x160000
	v_lshl_add_u64 v[220:221], s[34:35], 0, v[136:137]
	s_addc_u32 s55, s35, 0
	s_add_i32 s53, s72, s31
	global_load_lds_dwordx4 v[220:221], off
	v_lshl_add_u64 v[222:223], s[54:55], 0, v[132:133]
	s_mov_b32 m0, s53
	v_lshl_add_u64 v[224:225], s[84:85], 0, v[134:135]
	global_load_lds_dwordx4 v[222:223], off
	v_lshl_add_u64 v[222:223], s[54:55], 0, v[136:137]
	s_add_i32 m0, s53, 0x2000
	s_nop 0
	global_load_lds_dwordx4 v[222:223], off
	v_lshl_add_u64 v[222:223], s[84:85], 0, v[130:131]
	s_mov_b32 m0, s33
	s_nop 0
	global_load_lds_dwordx4 v[222:223], off
	s_mov_b32 m0, s56
	s_nop 0
	global_load_lds_dwordx4 v[224:225], off
	s_waitcnt vmcnt(8)
	s_waitcnt lgkmcnt(0)
	s_barrier
	s_setprio 1
	s_waitcnt lgkmcnt(0)
	v_mfma_f32_16x16x32_bf16 v[62:65], v[146:149], v[184:187], 0
	v_mfma_f32_16x16x32_bf16 v[58:61], v[154:157], v[184:187], 0
	v_mfma_f32_16x16x32_bf16 v[46:49], v[146:149], v[192:195], 0
	v_mfma_f32_16x16x32_bf16 v[42:45], v[154:157], v[192:195], 0
	v_mfma_f32_16x16x32_bf16 v[30:33], v[146:149], v[200:203], 0
	v_mfma_f32_16x16x32_bf16 v[26:29], v[154:157], v[200:203], 0
	v_mfma_f32_16x16x32_bf16 v[14:17], v[146:149], v[208:211], 0
	v_mfma_f32_16x16x32_bf16 v[10:13], v[154:157], v[208:211], 0
	v_mfma_f32_16x16x32_bf16 v[62:65], v[150:153], v[188:191], v[62:65]
	v_mfma_f32_16x16x32_bf16 v[58:61], v[158:161], v[188:191], v[58:61]
	v_mfma_f32_16x16x32_bf16 v[46:49], v[150:153], v[196:199], v[46:49]
	v_mfma_f32_16x16x32_bf16 v[42:45], v[158:161], v[196:199], v[42:45]
	v_mfma_f32_16x16x32_bf16 v[30:33], v[150:153], v[204:207], v[30:33]
	v_mfma_f32_16x16x32_bf16 v[26:29], v[158:161], v[204:207], v[26:29]
	v_mfma_f32_16x16x32_bf16 v[14:17], v[150:153], v[212:215], v[14:17]
	v_mfma_f32_16x16x32_bf16 v[10:13], v[158:161], v[212:215], v[10:13]
	s_setprio 0
	s_setprio 1
	v_mfma_f32_16x16x32_bf16 v[54:57], v[168:171], v[184:187], 0
	v_mfma_f32_16x16x32_bf16 v[50:53], v[176:179], v[184:187], 0
	v_mfma_f32_16x16x32_bf16 v[38:41], v[168:171], v[192:195], 0
	v_mfma_f32_16x16x32_bf16 v[34:37], v[176:179], v[192:195], 0
	v_mfma_f32_16x16x32_bf16 v[22:25], v[168:171], v[200:203], 0
	v_mfma_f32_16x16x32_bf16 v[18:21], v[176:179], v[200:203], 0
	v_mfma_f32_16x16x32_bf16 v[6:9], v[168:171], v[208:211], 0
	v_mfma_f32_16x16x32_bf16 v[2:5], v[176:179], v[208:211], 0
	v_mfma_f32_16x16x32_bf16 v[54:57], v[172:175], v[188:191], v[54:57]
	v_mfma_f32_16x16x32_bf16 v[50:53], v[180:183], v[188:191], v[50:53]
	v_mfma_f32_16x16x32_bf16 v[38:41], v[172:175], v[196:199], v[38:41]
	v_mfma_f32_16x16x32_bf16 v[34:37], v[180:183], v[196:199], v[34:37]
	v_mfma_f32_16x16x32_bf16 v[22:25], v[172:175], v[204:207], v[22:25]
	v_mfma_f32_16x16x32_bf16 v[18:21], v[180:183], v[204:207], v[18:21]
	v_mfma_f32_16x16x32_bf16 v[6:9], v[172:175], v[212:215], v[6:9]
	v_mfma_f32_16x16x32_bf16 v[2:5], v[180:183], v[212:215], v[2:5]
	s_setprio 0
	s_barrier
	s_add_i32 s53, 0, 0x18000
	s_add_i32 s62, 0, 0x1c000
	v_add_u32_e32 v158, s53, v162
	v_add_u32_e32 v167, s62, v162
	ds_read_b128 v[146:149], v158
	ds_read_b128 v[150:153], v158 offset:1024
	ds_read_b128 v[154:157], v158 offset:2048
	ds_read_b128 v[158:161], v158 offset:3072
	ds_read_b128 v[168:171], v167
	ds_read_b128 v[172:175], v167 offset:1024
	ds_read_b128 v[176:179], v167 offset:2048
	ds_read_b128 v[180:183], v167 offset:3072
	s_add_u32 s54, s84, 0x160000
	s_addc_u32 s55, s85, 0
	s_mov_b32 m0, s57
	v_lshl_add_u64 v[226:227], s[54:55], 0, v[130:131]
	ds_read_b128 v[184:187], v166 offset:32768
	ds_read_b128 v[188:191], v166 offset:33792
	ds_read_b128 v[192:195], v166 offset:34816
	ds_read_b128 v[196:199], v166 offset:35840
	ds_read_b128 v[200:203], v166 offset:36864
	ds_read_b128 v[204:207], v166 offset:37888
	ds_read_b128 v[208:211], v166 offset:38912
	ds_read_b128 v[212:215], v166 offset:39936
	global_load_lds_dwordx4 v[226:227], off
	v_lshl_add_u64 v[226:227], s[54:55], 0, v[134:135]
	s_mov_b32 m0, s58
	s_nop 0
	global_load_lds_dwordx4 v[226:227], off
	s_waitcnt vmcnt(8)
	s_waitcnt lgkmcnt(0)
	s_barrier
	s_setprio 1
	s_waitcnt lgkmcnt(0)
	v_mfma_f32_16x16x32_bf16 v[126:129], v[146:149], v[184:187], v[126:129]
	v_mfma_f32_16x16x32_bf16 v[122:125], v[154:157], v[184:187], v[122:125]
	v_mfma_f32_16x16x32_bf16 v[110:113], v[146:149], v[192:195], v[110:113]
	v_mfma_f32_16x16x32_bf16 v[106:109], v[154:157], v[192:195], v[106:109]
	v_mfma_f32_16x16x32_bf16 v[94:97], v[146:149], v[200:203], v[94:97]
	v_mfma_f32_16x16x32_bf16 v[90:93], v[154:157], v[200:203], v[90:93]
	v_mfma_f32_16x16x32_bf16 v[78:81], v[146:149], v[208:211], v[78:81]
	v_mfma_f32_16x16x32_bf16 v[74:77], v[154:157], v[208:211], v[74:77]
	v_mfma_f32_16x16x32_bf16 v[126:129], v[150:153], v[188:191], v[126:129]
	v_mfma_f32_16x16x32_bf16 v[122:125], v[158:161], v[188:191], v[122:125]
	v_mfma_f32_16x16x32_bf16 v[110:113], v[150:153], v[196:199], v[110:113]
	v_mfma_f32_16x16x32_bf16 v[106:109], v[158:161], v[196:199], v[106:109]
	v_mfma_f32_16x16x32_bf16 v[94:97], v[150:153], v[204:207], v[94:97]
	v_mfma_f32_16x16x32_bf16 v[90:93], v[158:161], v[204:207], v[90:93]
	v_mfma_f32_16x16x32_bf16 v[78:81], v[150:153], v[212:215], v[78:81]
	v_mfma_f32_16x16x32_bf16 v[74:77], v[158:161], v[212:215], v[74:77]
	s_setprio 0
	s_setprio 1
	v_mfma_f32_16x16x32_bf16 v[118:121], v[168:171], v[184:187], v[118:121]
	v_mfma_f32_16x16x32_bf16 v[114:117], v[176:179], v[184:187], v[114:117]
	v_mfma_f32_16x16x32_bf16 v[102:105], v[168:171], v[192:195], v[102:105]
	v_mfma_f32_16x16x32_bf16 v[98:101], v[176:179], v[192:195], v[98:101]
	v_mfma_f32_16x16x32_bf16 v[86:89], v[168:171], v[200:203], v[86:89]
	v_mfma_f32_16x16x32_bf16 v[82:85], v[176:179], v[200:203], v[82:85]
	v_mfma_f32_16x16x32_bf16 v[70:73], v[168:171], v[208:211], v[70:73]
	v_mfma_f32_16x16x32_bf16 v[66:69], v[176:179], v[208:211], v[66:69]
	v_mfma_f32_16x16x32_bf16 v[118:121], v[172:175], v[188:191], v[118:121]
	v_mfma_f32_16x16x32_bf16 v[114:117], v[180:183], v[188:191], v[114:117]
	v_mfma_f32_16x16x32_bf16 v[102:105], v[172:175], v[196:199], v[102:105]
	v_mfma_f32_16x16x32_bf16 v[98:101], v[180:183], v[196:199], v[98:101]
	v_mfma_f32_16x16x32_bf16 v[86:89], v[172:175], v[204:207], v[86:89]
	v_mfma_f32_16x16x32_bf16 v[82:85], v[180:183], v[204:207], v[82:85]
	v_mfma_f32_16x16x32_bf16 v[70:73], v[172:175], v[212:215], v[70:73]
	v_mfma_f32_16x16x32_bf16 v[66:69], v[180:183], v[212:215], v[66:69]
	s_setprio 0
	s_barrier
	s_add_i32 s53, s53, s31
	v_lshl_add_u64 v[218:219], v[218:219], 0, s[78:79]
	s_mov_b32 m0, s53
	ds_read_b128 v[184:187], v166 offset:49152
	ds_read_b128 v[188:191], v166 offset:50176
	ds_read_b128 v[192:195], v166 offset:51200
	ds_read_b128 v[196:199], v166 offset:52224
	ds_read_b128 v[200:203], v166 offset:53248
	ds_read_b128 v[204:207], v166 offset:54272
	ds_read_b128 v[208:211], v166 offset:55296
	ds_read_b128 v[212:215], v166 offset:56320
	global_load_lds_dwordx4 v[218:219], off
	s_add_i32 m0, s53, 0x2000
	s_add_u32 s34, s34, 0x160080
	v_lshl_add_u64 v[218:219], v[220:221], 0, s[78:79]
	s_addc_u32 s35, s35, 0
	s_add_i32 s53, s62, s31
	global_load_lds_dwordx4 v[218:219], off
	v_lshl_add_u64 v[218:219], s[34:35], 0, v[132:133]
	s_mov_b32 m0, s53
	s_nop 0
	global_load_lds_dwordx4 v[218:219], off
	v_lshl_add_u64 v[218:219], s[34:35], 0, v[136:137]
	s_add_i32 m0, s53, 0x2000
	s_nop 0
	global_load_lds_dwordx4 v[218:219], off
	v_lshl_add_u64 v[218:219], v[222:223], 0, s[78:79]
	s_mov_b32 m0, s60
	s_nop 0
	global_load_lds_dwordx4 v[218:219], off
	v_lshl_add_u64 v[218:219], v[224:225], 0, s[78:79]
	s_mov_b32 m0, s61
	s_nop 0
	global_load_lds_dwordx4 v[218:219], off
	s_waitcnt vmcnt(8)
	s_waitcnt lgkmcnt(0)
	s_barrier
	s_setprio 1
	s_waitcnt lgkmcnt(0)
	v_mfma_f32_16x16x32_bf16 v[62:65], v[146:149], v[184:187], v[62:65]
	v_mfma_f32_16x16x32_bf16 v[58:61], v[154:157], v[184:187], v[58:61]
	v_mfma_f32_16x16x32_bf16 v[46:49], v[146:149], v[192:195], v[46:49]
	v_mfma_f32_16x16x32_bf16 v[42:45], v[154:157], v[192:195], v[42:45]
	v_mfma_f32_16x16x32_bf16 v[30:33], v[146:149], v[200:203], v[30:33]
	v_mfma_f32_16x16x32_bf16 v[26:29], v[154:157], v[200:203], v[26:29]
	v_mfma_f32_16x16x32_bf16 v[14:17], v[146:149], v[208:211], v[14:17]
	v_mfma_f32_16x16x32_bf16 v[10:13], v[154:157], v[208:211], v[10:13]
	v_mfma_f32_16x16x32_bf16 v[62:65], v[150:153], v[188:191], v[62:65]
	v_mfma_f32_16x16x32_bf16 v[58:61], v[158:161], v[188:191], v[58:61]
	v_mfma_f32_16x16x32_bf16 v[46:49], v[150:153], v[196:199], v[46:49]
	v_mfma_f32_16x16x32_bf16 v[42:45], v[158:161], v[196:199], v[42:45]
	v_mfma_f32_16x16x32_bf16 v[30:33], v[150:153], v[204:207], v[30:33]
	v_mfma_f32_16x16x32_bf16 v[26:29], v[158:161], v[204:207], v[26:29]
	v_mfma_f32_16x16x32_bf16 v[14:17], v[150:153], v[212:215], v[14:17]
	v_mfma_f32_16x16x32_bf16 v[10:13], v[158:161], v[212:215], v[10:13]
	s_setprio 0
	s_setprio 1
	v_mfma_f32_16x16x32_bf16 v[54:57], v[168:171], v[184:187], v[54:57]
	v_mfma_f32_16x16x32_bf16 v[50:53], v[176:179], v[184:187], v[50:53]
	v_mfma_f32_16x16x32_bf16 v[38:41], v[168:171], v[192:195], v[38:41]
	v_mfma_f32_16x16x32_bf16 v[34:37], v[176:179], v[192:195], v[34:37]
	v_mfma_f32_16x16x32_bf16 v[22:25], v[168:171], v[200:203], v[22:25]
	v_mfma_f32_16x16x32_bf16 v[18:21], v[176:179], v[200:203], v[18:21]
	v_mfma_f32_16x16x32_bf16 v[6:9], v[168:171], v[208:211], v[6:9]
	v_mfma_f32_16x16x32_bf16 v[2:5], v[176:179], v[208:211], v[2:5]
	v_mfma_f32_16x16x32_bf16 v[54:57], v[172:175], v[188:191], v[54:57]
	v_mfma_f32_16x16x32_bf16 v[50:53], v[180:183], v[188:191], v[50:53]
	v_mfma_f32_16x16x32_bf16 v[38:41], v[172:175], v[196:199], v[38:41]
	v_mfma_f32_16x16x32_bf16 v[34:37], v[180:183], v[196:199], v[34:37]
	v_mfma_f32_16x16x32_bf16 v[22:25], v[172:175], v[204:207], v[22:25]
	v_mfma_f32_16x16x32_bf16 v[18:21], v[180:183], v[204:207], v[18:21]
	v_mfma_f32_16x16x32_bf16 v[6:9], v[172:175], v[212:215], v[6:9]
	v_mfma_f32_16x16x32_bf16 v[2:5], v[180:183], v[212:215], v[2:5]
	s_setprio 0
	s_barrier
	s_add_i32 s52, s52, 2
	s_add_u32 s76, s76, 0x100
	s_addc_u32 s77, s77, 0
	s_add_u32 s0, s0, 0x100
	s_addc_u32 s1, s1, 0

.LBB0_1623:
	s_ashr_i32 s83, s82, 31
	s_lshl_b64 s[0:1], s[82:83], 20
	v_readlane_b32 s34, v247, 45
	s_add_u32 s84, s34, s0
	v_readlane_b32 s0, v247, 47
	s_addc_u32 s85, s0, s1
	s_and_b64 s[0:1], s[2:3], exec
	s_cselect_b32 s0, s85, s89
	s_cselect_b32 s1, s84, s88
	s_ashr_i32 s81, s80, 31
	s_lshl_b64 s[34:35], s[80:81], 20
	s_add_u32 s86, s13, s34
	s_addc_u32 s87, s30, s35
	s_and_b64 s[34:35], s[2:3], exec
	s_cselect_b32 s52, s87, s91
	s_cselect_b32 s75, s86, s90
	s_add_u32 s88, s88, 0x80080
	s_addc_u32 s89, s89, 0
	s_add_u32 s77, s90, 0x100
	s_addc_u32 s81, s91, 0
	s_mov_b32 s83, -2
	ds_read_b128 v[154:157], v151
	ds_read_b128 v[158:161], v151 offset:1024
	ds_read_b128 v[162:165], v151 offset:2048
	ds_read_b128 v[166:169], v151 offset:3072
	ds_read_b128 v[170:173], v152
	ds_read_b128 v[174:177], v152 offset:1024
	ds_read_b128 v[178:181], v152 offset:2048
	ds_read_b128 v[182:185], v152 offset:3072
	s_add_u32 s34, s88, 0xfff80080
	s_addc_u32 s35, s89, -1
	s_cmp_eq_u32 s83, 28
	s_cselect_b32 s91, s0, s35
	s_cselect_b32 s90, s1, s34
	s_cselect_b32 s35, s52, s81
	s_cselect_b32 s34, s75, s77
	v_lshl_add_u64 v[146:147], s[88:89], 0, v[138:139]
	s_add_i32 m0, s33, 0xc000
	ds_read_b128 v[186:189], v153
	ds_read_b128 v[190:193], v153 offset:1024
	ds_read_b128 v[194:197], v153 offset:2048
	ds_read_b128 v[198:201], v153 offset:3072
	ds_read_b128 v[202:205], v153 offset:4096
	ds_read_b128 v[206:209], v153 offset:5120
	ds_read_b128 v[210:213], v153 offset:6144
	ds_read_b128 v[218:221], v153 offset:7168
	global_load_lds_dwordx4 v[146:147], off
	v_lshl_add_u64 v[146:147], s[88:89], 0, v[140:141]
	s_add_i32 m0, s33, 0xe000
	s_nop 0
	global_load_lds_dwordx4 v[146:147], off
	s_waitcnt vmcnt(8)
	s_waitcnt lgkmcnt(0)
	s_barrier
	s_setprio 1
	s_waitcnt lgkmcnt(0)
	v_mfma_f32_16x16x32_bf16 v[126:129], v[154:157], v[186:189], 0
	v_mfma_f32_16x16x32_bf16 v[122:125], v[162:165], v[186:189], 0
	v_mfma_f32_16x16x32_bf16 v[114:117], v[154:157], v[194:197], 0
	v_mfma_f32_16x16x32_bf16 v[106:109], v[162:165], v[194:197], 0
	v_mfma_f32_16x16x32_bf16 v[98:101], v[154:157], v[202:205], 0
	v_mfma_f32_16x16x32_bf16 v[90:93], v[162:165], v[202:205], 0
	v_mfma_f32_16x16x32_bf16 v[82:85], v[154:157], v[210:213], 0
	v_mfma_f32_16x16x32_bf16 v[74:77], v[162:165], v[210:213], 0
	v_mfma_f32_16x16x32_bf16 v[126:129], v[158:161], v[190:193], v[126:129]
	v_mfma_f32_16x16x32_bf16 v[122:125], v[166:169], v[190:193], v[122:125]
	v_mfma_f32_16x16x32_bf16 v[114:117], v[158:161], v[198:201], v[114:117]
	v_mfma_f32_16x16x32_bf16 v[106:109], v[166:169], v[198:201], v[106:109]
	v_mfma_f32_16x16x32_bf16 v[98:101], v[158:161], v[206:209], v[98:101]
	v_mfma_f32_16x16x32_bf16 v[90:93], v[166:169], v[206:209], v[90:93]
	v_mfma_f32_16x16x32_bf16 v[82:85], v[158:161], v[218:221], v[82:85]
	v_mfma_f32_16x16x32_bf16 v[74:77], v[166:169], v[218:221], v[74:77]
	s_setprio 0
	s_setprio 1
	v_mfma_f32_16x16x32_bf16 v[118:121], v[170:173], v[186:189], 0
	v_mfma_f32_16x16x32_bf16 v[110:113], v[178:181], v[186:189], 0
	v_mfma_f32_16x16x32_bf16 v[102:105], v[170:173], v[194:197], 0
	v_mfma_f32_16x16x32_bf16 v[94:97], v[178:181], v[194:197], 0
	v_mfma_f32_16x16x32_bf16 v[86:89], v[170:173], v[202:205], 0
	v_mfma_f32_16x16x32_bf16 v[78:81], v[178:181], v[202:205], 0
	v_mfma_f32_16x16x32_bf16 v[70:73], v[170:173], v[210:213], 0
	v_mfma_f32_16x16x32_bf16 v[66:69], v[178:181], v[210:213], 0
	v_mfma_f32_16x16x32_bf16 v[118:121], v[174:177], v[190:193], v[118:121]
	v_mfma_f32_16x16x32_bf16 v[110:113], v[182:185], v[190:193], v[110:113]
	v_mfma_f32_16x16x32_bf16 v[102:105], v[174:177], v[198:201], v[102:105]
	v_mfma_f32_16x16x32_bf16 v[94:97], v[182:185], v[198:201], v[94:97]
	v_mfma_f32_16x16x32_bf16 v[86:89], v[174:177], v[206:209], v[86:89]
	v_mfma_f32_16x16x32_bf16 v[78:81], v[182:185], v[206:209], v[78:81]
	v_mfma_f32_16x16x32_bf16 v[70:73], v[174:177], v[218:221], v[70:73]
	v_mfma_f32_16x16x32_bf16 v[66:69], v[182:185], v[218:221], v[66:69]
	s_setprio 0
	s_barrier
	s_add_i32 s53, s71, s12
	v_lshl_add_u64 v[146:147], s[34:35], 0, v[134:135]
	s_mov_b32 m0, s53
	ds_read_b128 v[186:189], v153 offset:16384
	ds_read_b128 v[190:193], v153 offset:17408
	ds_read_b128 v[194:197], v153 offset:18432
	ds_read_b128 v[198:201], v153 offset:19456
	ds_read_b128 v[202:205], v153 offset:20480
	ds_read_b128 v[206:209], v153 offset:21504
	ds_read_b128 v[210:213], v153 offset:22528
	ds_read_b128 v[218:221], v153 offset:23552
	global_load_lds_dwordx4 v[146:147], off
	s_add_i32 m0, s53, 0x2000
	s_add_u32 s54, s34, 0x80000
	v_lshl_add_u64 v[214:215], s[34:35], 0, v[130:131]
	s_addc_u32 s55, s35, 0
	s_add_i32 s53, s72, s12
	global_load_lds_dwordx4 v[214:215], off
	v_lshl_add_u64 v[222:223], s[54:55], 0, v[134:135]
	s_mov_b32 m0, s53
	v_lshl_add_u64 v[224:225], s[90:91], 0, v[132:133]
	global_load_lds_dwordx4 v[222:223], off
	v_lshl_add_u64 v[222:223], s[54:55], 0, v[130:131]
	s_add_i32 m0, s53, 0x2000
	s_nop 0
	global_load_lds_dwordx4 v[222:223], off
	v_lshl_add_u64 v[222:223], s[90:91], 0, v[136:137]
	s_mov_b32 m0, s33
	s_nop 0
	global_load_lds_dwordx4 v[222:223], off
	s_mov_b32 m0, s56
	s_nop 0
	global_load_lds_dwordx4 v[224:225], off
	s_waitcnt vmcnt(8)
	s_waitcnt lgkmcnt(0)
	s_barrier
	s_setprio 1
	s_waitcnt lgkmcnt(0)
	v_mfma_f32_16x16x32_bf16 v[62:65], v[154:157], v[186:189], 0
	v_mfma_f32_16x16x32_bf16 v[58:61], v[162:165], v[186:189], 0
	v_mfma_f32_16x16x32_bf16 v[50:53], v[154:157], v[194:197], 0
	v_mfma_f32_16x16x32_bf16 v[42:45], v[162:165], v[194:197], 0
	v_mfma_f32_16x16x32_bf16 v[34:37], v[154:157], v[202:205], 0
	v_mfma_f32_16x16x32_bf16 v[26:29], v[162:165], v[202:205], 0
	v_mfma_f32_16x16x32_bf16 v[18:21], v[154:157], v[210:213], 0
	v_mfma_f32_16x16x32_bf16 v[10:13], v[162:165], v[210:213], 0
	v_mfma_f32_16x16x32_bf16 v[62:65], v[158:161], v[190:193], v[62:65]
	v_mfma_f32_16x16x32_bf16 v[58:61], v[166:169], v[190:193], v[58:61]
	v_mfma_f32_16x16x32_bf16 v[50:53], v[158:161], v[198:201], v[50:53]
	v_mfma_f32_16x16x32_bf16 v[42:45], v[166:169], v[198:201], v[42:45]
	v_mfma_f32_16x16x32_bf16 v[34:37], v[158:161], v[206:209], v[34:37]
	v_mfma_f32_16x16x32_bf16 v[26:29], v[166:169], v[206:209], v[26:29]
	v_mfma_f32_16x16x32_bf16 v[18:21], v[158:161], v[218:221], v[18:21]
	v_mfma_f32_16x16x32_bf16 v[10:13], v[166:169], v[218:221], v[10:13]
	s_setprio 0
	s_setprio 1
	v_mfma_f32_16x16x32_bf16 v[54:57], v[170:173], v[186:189], 0
	v_mfma_f32_16x16x32_bf16 v[46:49], v[178:181], v[186:189], 0
	v_mfma_f32_16x16x32_bf16 v[38:41], v[170:173], v[194:197], 0
	v_mfma_f32_16x16x32_bf16 v[30:33], v[178:181], v[194:197], 0
	v_mfma_f32_16x16x32_bf16 v[22:25], v[170:173], v[202:205], 0
	v_mfma_f32_16x16x32_bf16 v[14:17], v[178:181], v[202:205], 0
	v_mfma_f32_16x16x32_bf16 v[6:9], v[170:173], v[210:213], 0
	v_mfma_f32_16x16x32_bf16 v[2:5], v[178:181], v[210:213], 0
	v_mfma_f32_16x16x32_bf16 v[54:57], v[174:177], v[190:193], v[54:57]
	v_mfma_f32_16x16x32_bf16 v[46:49], v[182:185], v[190:193], v[46:49]
	v_mfma_f32_16x16x32_bf16 v[38:41], v[174:177], v[198:201], v[38:41]
	v_mfma_f32_16x16x32_bf16 v[30:33], v[182:185], v[198:201], v[30:33]
	v_mfma_f32_16x16x32_bf16 v[22:25], v[174:177], v[206:209], v[22:25]
	v_mfma_f32_16x16x32_bf16 v[14:17], v[182:185], v[206:209], v[14:17]
	v_mfma_f32_16x16x32_bf16 v[6:9], v[174:177], v[218:221], v[6:9]
	v_mfma_f32_16x16x32_bf16 v[2:5], v[182:185], v[218:221], v[2:5]
	s_setprio 0
	s_barrier
	s_add_i32 s53, 0, 0x18000
	s_add_i32 s62, 0, 0x1c000
	v_add_u32_e32 v166, s53, v149
	v_add_u32_e32 v182, s62, v149
	ds_read_b128 v[154:157], v166
	ds_read_b128 v[158:161], v166 offset:1024
	ds_read_b128 v[162:165], v166 offset:2048
	ds_read_b128 v[166:169], v166 offset:3072
	ds_read_b128 v[170:173], v182
	ds_read_b128 v[174:177], v182 offset:1024
	ds_read_b128 v[178:181], v182 offset:2048
	ds_read_b128 v[182:185], v182 offset:3072
	s_add_u32 s54, s90, 0x80000
	s_addc_u32 s55, s91, 0
	s_mov_b32 m0, s57
	v_lshl_add_u64 v[226:227], s[54:55], 0, v[136:137]
	ds_read_b128 v[186:189], v153 offset:32768
	ds_read_b128 v[190:193], v153 offset:33792
	ds_read_b128 v[194:197], v153 offset:34816
	ds_read_b128 v[198:201], v153 offset:35840
	ds_read_b128 v[202:205], v153 offset:36864
	ds_read_b128 v[206:209], v153 offset:37888
	ds_read_b128 v[210:213], v153 offset:38912
	ds_read_b128 v[218:221], v153 offset:39936
	global_load_lds_dwordx4 v[226:227], off
	v_lshl_add_u64 v[226:227], s[54:55], 0, v[132:133]
	s_mov_b32 m0, s58
	s_nop 0
	global_load_lds_dwordx4 v[226:227], off
	s_waitcnt vmcnt(8)
	s_waitcnt lgkmcnt(0)
	s_barrier
	s_setprio 1
	s_waitcnt lgkmcnt(0)
	v_mfma_f32_16x16x32_bf16 v[126:129], v[154:157], v[186:189], v[126:129]
	v_mfma_f32_16x16x32_bf16 v[122:125], v[162:165], v[186:189], v[122:125]
	v_mfma_f32_16x16x32_bf16 v[114:117], v[154:157], v[194:197], v[114:117]
	v_mfma_f32_16x16x32_bf16 v[106:109], v[162:165], v[194:197], v[106:109]
	v_mfma_f32_16x16x32_bf16 v[98:101], v[154:157], v[202:205], v[98:101]
	v_mfma_f32_16x16x32_bf16 v[90:93], v[162:165], v[202:205], v[90:93]
	v_mfma_f32_16x16x32_bf16 v[82:85], v[154:157], v[210:213], v[82:85]
	v_mfma_f32_16x16x32_bf16 v[74:77], v[162:165], v[210:213], v[74:77]
	v_mfma_f32_16x16x32_bf16 v[126:129], v[158:161], v[190:193], v[126:129]
	v_mfma_f32_16x16x32_bf16 v[122:125], v[166:169], v[190:193], v[122:125]
	v_mfma_f32_16x16x32_bf16 v[114:117], v[158:161], v[198:201], v[114:117]
	v_mfma_f32_16x16x32_bf16 v[106:109], v[166:169], v[198:201], v[106:109]
	v_mfma_f32_16x16x32_bf16 v[98:101], v[158:161], v[206:209], v[98:101]
	v_mfma_f32_16x16x32_bf16 v[90:93], v[166:169], v[206:209], v[90:93]
	v_mfma_f32_16x16x32_bf16 v[82:85], v[158:161], v[218:221], v[82:85]
	v_mfma_f32_16x16x32_bf16 v[74:77], v[166:169], v[218:221], v[74:77]
	s_setprio 0
	s_setprio 1
	v_mfma_f32_16x16x32_bf16 v[118:121], v[170:173], v[186:189], v[118:121]
	v_mfma_f32_16x16x32_bf16 v[110:113], v[178:181], v[186:189], v[110:113]
	v_mfma_f32_16x16x32_bf16 v[102:105], v[170:173], v[194:197], v[102:105]
	v_mfma_f32_16x16x32_bf16 v[94:97], v[178:181], v[194:197], v[94:97]
	v_mfma_f32_16x16x32_bf16 v[86:89], v[170:173], v[202:205], v[86:89]
	v_mfma_f32_16x16x32_bf16 v[78:81], v[178:181], v[202:205], v[78:81]
	v_mfma_f32_16x16x32_bf16 v[70:73], v[170:173], v[210:213], v[70:73]
	v_mfma_f32_16x16x32_bf16 v[66:69], v[178:181], v[210:213], v[66:69]
	v_mfma_f32_16x16x32_bf16 v[118:121], v[174:177], v[190:193], v[118:121]
	v_mfma_f32_16x16x32_bf16 v[110:113], v[182:185], v[190:193], v[110:113]
	v_mfma_f32_16x16x32_bf16 v[102:105], v[174:177], v[198:201], v[102:105]
	v_mfma_f32_16x16x32_bf16 v[94:97], v[182:185], v[198:201], v[94:97]
	v_mfma_f32_16x16x32_bf16 v[86:89], v[174:177], v[206:209], v[86:89]
	v_mfma_f32_16x16x32_bf16 v[78:81], v[182:185], v[206:209], v[78:81]
	v_mfma_f32_16x16x32_bf16 v[70:73], v[174:177], v[218:221], v[70:73]
	v_mfma_f32_16x16x32_bf16 v[66:69], v[182:185], v[218:221], v[66:69]
	s_setprio 0
	s_barrier
	s_add_i32 s53, s53, s12
	v_lshl_add_u64 v[146:147], v[146:147], 0, s[8:9]
	s_mov_b32 m0, s53
	ds_read_b128 v[186:189], v153 offset:49152
	ds_read_b128 v[190:193], v153 offset:50176
	ds_read_b128 v[194:197], v153 offset:51200
	ds_read_b128 v[198:201], v153 offset:52224
	ds_read_b128 v[202:205], v153 offset:53248
	ds_read_b128 v[206:209], v153 offset:54272
	ds_read_b128 v[210:213], v153 offset:55296
	ds_read_b128 v[218:221], v153 offset:56320
	global_load_lds_dwordx4 v[146:147], off
	s_add_i32 m0, s53, 0x2000
	s_add_u32 s34, s34, 0x80080
	v_lshl_add_u64 v[146:147], v[214:215], 0, s[8:9]
	s_addc_u32 s35, s35, 0
	s_add_i32 s53, s62, s12
	global_load_lds_dwordx4 v[146:147], off
	v_lshl_add_u64 v[146:147], s[34:35], 0, v[134:135]
	s_mov_b32 m0, s53
	s_nop 0
	global_load_lds_dwordx4 v[146:147], off
	v_lshl_add_u64 v[146:147], s[34:35], 0, v[130:131]
	s_add_i32 m0, s53, 0x2000
	s_nop 0
	global_load_lds_dwordx4 v[146:147], off
	v_lshl_add_u64 v[146:147], v[222:223], 0, s[8:9]
	s_mov_b32 m0, s60
	s_nop 0
	global_load_lds_dwordx4 v[146:147], off
	v_lshl_add_u64 v[146:147], v[224:225], 0, s[8:9]
	s_mov_b32 m0, s61
	s_nop 0
	global_load_lds_dwordx4 v[146:147], off
	s_waitcnt vmcnt(8)
	s_waitcnt lgkmcnt(0)
	s_barrier
	s_setprio 1
	s_waitcnt lgkmcnt(0)
	v_mfma_f32_16x16x32_bf16 v[62:65], v[154:157], v[186:189], v[62:65]
	v_mfma_f32_16x16x32_bf16 v[58:61], v[162:165], v[186:189], v[58:61]
	v_mfma_f32_16x16x32_bf16 v[50:53], v[154:157], v[194:197], v[50:53]
	v_mfma_f32_16x16x32_bf16 v[42:45], v[162:165], v[194:197], v[42:45]
	v_mfma_f32_16x16x32_bf16 v[34:37], v[154:157], v[202:205], v[34:37]
	v_mfma_f32_16x16x32_bf16 v[26:29], v[162:165], v[202:205], v[26:29]
	v_mfma_f32_16x16x32_bf16 v[18:21], v[154:157], v[210:213], v[18:21]
	v_mfma_f32_16x16x32_bf16 v[10:13], v[162:165], v[210:213], v[10:13]
	v_mfma_f32_16x16x32_bf16 v[62:65], v[158:161], v[190:193], v[62:65]
	v_mfma_f32_16x16x32_bf16 v[58:61], v[166:169], v[190:193], v[58:61]
	v_mfma_f32_16x16x32_bf16 v[50:53], v[158:161], v[198:201], v[50:53]
	v_mfma_f32_16x16x32_bf16 v[42:45], v[166:169], v[198:201], v[42:45]
	v_mfma_f32_16x16x32_bf16 v[34:37], v[158:161], v[206:209], v[34:37]
	v_mfma_f32_16x16x32_bf16 v[26:29], v[166:169], v[206:209], v[26:29]
	v_mfma_f32_16x16x32_bf16 v[18:21], v[158:161], v[218:221], v[18:21]
	v_mfma_f32_16x16x32_bf16 v[10:13], v[166:169], v[218:221], v[10:13]
	s_setprio 0
	s_setprio 1
	v_mfma_f32_16x16x32_bf16 v[54:57], v[170:173], v[186:189], v[54:57]
	v_mfma_f32_16x16x32_bf16 v[46:49], v[178:181], v[186:189], v[46:49]
	v_mfma_f32_16x16x32_bf16 v[38:41], v[170:173], v[194:197], v[38:41]
	v_mfma_f32_16x16x32_bf16 v[30:33], v[178:181], v[194:197], v[30:33]
	v_mfma_f32_16x16x32_bf16 v[22:25], v[170:173], v[202:205], v[22:25]
	v_mfma_f32_16x16x32_bf16 v[14:17], v[178:181], v[202:205], v[14:17]
	v_mfma_f32_16x16x32_bf16 v[6:9], v[170:173], v[210:213], v[6:9]
	v_mfma_f32_16x16x32_bf16 v[2:5], v[178:181], v[210:213], v[2:5]
	v_mfma_f32_16x16x32_bf16 v[54:57], v[174:177], v[190:193], v[54:57]
	v_mfma_f32_16x16x32_bf16 v[46:49], v[182:185], v[190:193], v[46:49]
	v_mfma_f32_16x16x32_bf16 v[38:41], v[174:177], v[198:201], v[38:41]
	v_mfma_f32_16x16x32_bf16 v[30:33], v[182:185], v[198:201], v[30:33]
	v_mfma_f32_16x16x32_bf16 v[22:25], v[174:177], v[206:209], v[22:25]
	v_mfma_f32_16x16x32_bf16 v[14:17], v[182:185], v[206:209], v[14:17]
	v_mfma_f32_16x16x32_bf16 v[6:9], v[174:177], v[218:221], v[6:9]
	v_mfma_f32_16x16x32_bf16 v[2:5], v[182:185], v[218:221], v[2:5]
	s_setprio 0
	s_barrier
	s_add_i32 s83, s83, 2
	s_add_u32 s88, s88, 0x100
	s_addc_u32 s89, s89, 0
	s_add_u32 s77, s77, 0x100
	s_addc_u32 s81, s81, 0

.LBB0_2088:
	s_add_u32 s38, s38, 0x160080
	s_addc_u32 s39, s39, 0
	s_add_u32 s0, s40, 0x100
	s_addc_u32 s1, s41, 0
	s_mov_b32 s52, -2
	ds_read_b128 v[130:133], v178
	ds_read_b128 v[134:137], v178 offset:1024
	ds_read_b128 v[138:141], v178 offset:2048
	ds_read_b128 v[142:145], v178 offset:3072
	ds_read_b128 v[162:165], v179
	ds_read_b128 v[166:169], v179 offset:1024
	ds_read_b128 v[170:173], v179 offset:2048
	ds_read_b128 v[182:185], v179 offset:3072
	s_add_u32 s34, s38, 0xffea0080
	s_addc_u32 s35, s39, -1
	s_cmpk_eq_i32 s52, 0x54
	s_cselect_b32 s41, s5, s35
	s_cselect_b32 s40, s4, s34
	s_cselect_b32 s35, s37, s1
	s_cselect_b32 s34, s36, s0
	v_lshl_add_u64 v[174:175], s[38:39], 0, v[154:155]
	s_add_i32 m0, s33, 0xc000
	ds_read_b128 v[186:189], v180
	ds_read_b128 v[190:193], v180 offset:1024
	ds_read_b128 v[194:197], v180 offset:2048
	ds_read_b128 v[198:201], v180 offset:3072
	ds_read_b128 v[202:205], v180 offset:4096
	ds_read_b128 v[206:209], v180 offset:5120
	ds_read_b128 v[210:213], v180 offset:6144
	ds_read_b128 v[218:221], v180 offset:7168
	global_load_lds_dwordx4 v[174:175], off
	v_lshl_add_u64 v[174:175], s[38:39], 0, v[156:157]
	s_add_i32 m0, s33, 0xe000
	s_nop 0
	global_load_lds_dwordx4 v[174:175], off
	s_waitcnt vmcnt(8)
	s_waitcnt lgkmcnt(0)
	s_barrier
	s_setprio 1
	s_waitcnt lgkmcnt(0)
	v_mfma_f32_16x16x32_bf16 v[126:129], v[130:133], v[186:189], 0
	v_mfma_f32_16x16x32_bf16 v[122:125], v[138:141], v[186:189], 0
	v_mfma_f32_16x16x32_bf16 v[110:113], v[130:133], v[194:197], 0
	v_mfma_f32_16x16x32_bf16 v[106:109], v[138:141], v[194:197], 0
	v_mfma_f32_16x16x32_bf16 v[94:97], v[130:133], v[202:205], 0
	v_mfma_f32_16x16x32_bf16 v[90:93], v[138:141], v[202:205], 0
	v_mfma_f32_16x16x32_bf16 v[78:81], v[130:133], v[210:213], 0
	v_mfma_f32_16x16x32_bf16 v[74:77], v[138:141], v[210:213], 0
	v_mfma_f32_16x16x32_bf16 v[126:129], v[134:137], v[190:193], v[126:129]
	v_mfma_f32_16x16x32_bf16 v[122:125], v[142:145], v[190:193], v[122:125]
	v_mfma_f32_16x16x32_bf16 v[110:113], v[134:137], v[198:201], v[110:113]
	v_mfma_f32_16x16x32_bf16 v[106:109], v[142:145], v[198:201], v[106:109]
	v_mfma_f32_16x16x32_bf16 v[94:97], v[134:137], v[206:209], v[94:97]
	v_mfma_f32_16x16x32_bf16 v[90:93], v[142:145], v[206:209], v[90:93]
	v_mfma_f32_16x16x32_bf16 v[78:81], v[134:137], v[218:221], v[78:81]
	v_mfma_f32_16x16x32_bf16 v[74:77], v[142:145], v[218:221], v[74:77]
	s_setprio 0
	s_setprio 1
	v_mfma_f32_16x16x32_bf16 v[118:121], v[162:165], v[186:189], 0
	v_mfma_f32_16x16x32_bf16 v[114:117], v[170:173], v[186:189], 0
	v_mfma_f32_16x16x32_bf16 v[102:105], v[162:165], v[194:197], 0
	v_mfma_f32_16x16x32_bf16 v[98:101], v[170:173], v[194:197], 0
	v_mfma_f32_16x16x32_bf16 v[86:89], v[162:165], v[202:205], 0
	v_mfma_f32_16x16x32_bf16 v[82:85], v[170:173], v[202:205], 0
	v_mfma_f32_16x16x32_bf16 v[70:73], v[162:165], v[210:213], 0
	v_mfma_f32_16x16x32_bf16 v[66:69], v[170:173], v[210:213], 0
	v_mfma_f32_16x16x32_bf16 v[118:121], v[166:169], v[190:193], v[118:121]
	v_mfma_f32_16x16x32_bf16 v[114:117], v[182:185], v[190:193], v[114:117]
	v_mfma_f32_16x16x32_bf16 v[102:105], v[166:169], v[198:201], v[102:105]
	v_mfma_f32_16x16x32_bf16 v[98:101], v[182:185], v[198:201], v[98:101]
	v_mfma_f32_16x16x32_bf16 v[86:89], v[166:169], v[206:209], v[86:89]
	v_mfma_f32_16x16x32_bf16 v[82:85], v[182:185], v[206:209], v[82:85]
	v_mfma_f32_16x16x32_bf16 v[70:73], v[166:169], v[218:221], v[70:73]
	v_mfma_f32_16x16x32_bf16 v[66:69], v[182:185], v[218:221], v[66:69]
	s_setprio 0
	s_barrier
	s_add_i32 s53, s61, s31
	v_lshl_add_u64 v[174:175], s[34:35], 0, v[148:149]
	s_mov_b32 m0, s53
	ds_read_b128 v[186:189], v180 offset:16384
	ds_read_b128 v[190:193], v180 offset:17408
	ds_read_b128 v[194:197], v180 offset:18432
	ds_read_b128 v[198:201], v180 offset:19456
	ds_read_b128 v[202:205], v180 offset:20480
	ds_read_b128 v[206:209], v180 offset:21504
	ds_read_b128 v[210:213], v180 offset:22528
	ds_read_b128 v[218:221], v180 offset:23552
	global_load_lds_dwordx4 v[174:175], off
	s_add_i32 m0, s53, 0x2000
	s_add_u32 s54, s34, 0x160000
	v_lshl_add_u64 v[214:215], s[34:35], 0, v[152:153]
	s_addc_u32 s55, s35, 0
	s_add_i32 s53, s70, s31
	global_load_lds_dwordx4 v[214:215], off
	v_lshl_add_u64 v[222:223], s[54:55], 0, v[148:149]
	s_mov_b32 m0, s53
	v_lshl_add_u64 v[224:225], s[40:41], 0, v[150:151]
	global_load_lds_dwordx4 v[222:223], off
	v_lshl_add_u64 v[222:223], s[54:55], 0, v[152:153]
	s_add_i32 m0, s53, 0x2000
	s_nop 0
	global_load_lds_dwordx4 v[222:223], off
	v_lshl_add_u64 v[222:223], s[40:41], 0, v[146:147]
	s_mov_b32 m0, s33
	s_nop 0
	global_load_lds_dwordx4 v[222:223], off
	s_mov_b32 m0, s46
	s_nop 0
	global_load_lds_dwordx4 v[224:225], off
	s_waitcnt vmcnt(8)
	s_waitcnt lgkmcnt(0)
	s_barrier
	s_setprio 1
	s_waitcnt lgkmcnt(0)
	v_mfma_f32_16x16x32_bf16 v[62:65], v[130:133], v[186:189], 0
	v_mfma_f32_16x16x32_bf16 v[58:61], v[138:141], v[186:189], 0
	v_mfma_f32_16x16x32_bf16 v[50:53], v[130:133], v[194:197], 0
	v_mfma_f32_16x16x32_bf16 v[42:45], v[138:141], v[194:197], 0
	v_mfma_f32_16x16x32_bf16 v[38:41], v[130:133], v[202:205], 0
	v_mfma_f32_16x16x32_bf16 v[34:37], v[138:141], v[202:205], 0
	v_mfma_f32_16x16x32_bf16 v[14:17], v[130:133], v[210:213], 0
	v_mfma_f32_16x16x32_bf16 v[10:13], v[138:141], v[210:213], 0
	v_mfma_f32_16x16x32_bf16 v[62:65], v[134:137], v[190:193], v[62:65]
	v_mfma_f32_16x16x32_bf16 v[58:61], v[142:145], v[190:193], v[58:61]
	v_mfma_f32_16x16x32_bf16 v[50:53], v[134:137], v[198:201], v[50:53]
	v_mfma_f32_16x16x32_bf16 v[42:45], v[142:145], v[198:201], v[42:45]
	v_mfma_f32_16x16x32_bf16 v[38:41], v[134:137], v[206:209], v[38:41]
	v_mfma_f32_16x16x32_bf16 v[34:37], v[142:145], v[206:209], v[34:37]
	v_mfma_f32_16x16x32_bf16 v[14:17], v[134:137], v[218:221], v[14:17]
	v_mfma_f32_16x16x32_bf16 v[10:13], v[142:145], v[218:221], v[10:13]
	s_setprio 0
	s_setprio 1
	v_mfma_f32_16x16x32_bf16 v[54:57], v[162:165], v[186:189], 0
	v_mfma_f32_16x16x32_bf16 v[46:49], v[170:173], v[186:189], 0
	v_mfma_f32_16x16x32_bf16 v[30:33], v[162:165], v[194:197], 0
	v_mfma_f32_16x16x32_bf16 v[26:29], v[170:173], v[194:197], 0
	v_mfma_f32_16x16x32_bf16 v[22:25], v[162:165], v[202:205], 0
	v_mfma_f32_16x16x32_bf16 v[18:21], v[170:173], v[202:205], 0
	v_mfma_f32_16x16x32_bf16 v[6:9], v[162:165], v[210:213], 0
	v_mfma_f32_16x16x32_bf16 v[2:5], v[170:173], v[210:213], 0
	v_mfma_f32_16x16x32_bf16 v[54:57], v[166:169], v[190:193], v[54:57]
	v_mfma_f32_16x16x32_bf16 v[46:49], v[182:185], v[190:193], v[46:49]
	v_mfma_f32_16x16x32_bf16 v[30:33], v[166:169], v[198:201], v[30:33]
	v_mfma_f32_16x16x32_bf16 v[26:29], v[182:185], v[198:201], v[26:29]
	v_mfma_f32_16x16x32_bf16 v[22:25], v[166:169], v[206:209], v[22:25]
	v_mfma_f32_16x16x32_bf16 v[18:21], v[182:185], v[206:209], v[18:21]
	v_mfma_f32_16x16x32_bf16 v[6:9], v[166:169], v[218:221], v[6:9]
	v_mfma_f32_16x16x32_bf16 v[2:5], v[182:185], v[218:221], v[2:5]
	s_setprio 0
	s_barrier
	s_add_i32 s53, 0, 0x18000
	s_add_i32 s54, 0, 0x1c000
	v_add_u32_e32 v142, s53, v176
	v_add_u32_e32 v181, s54, v176
	ds_read_b128 v[130:133], v142
	ds_read_b128 v[134:137], v142 offset:1024
	ds_read_b128 v[138:141], v142 offset:2048
	ds_read_b128 v[142:145], v142 offset:3072
	ds_read_b128 v[162:165], v181
	ds_read_b128 v[166:169], v181 offset:1024
	ds_read_b128 v[170:173], v181 offset:2048
	ds_read_b128 v[182:185], v181 offset:3072
	s_add_u32 s40, s40, 0x160000
	s_addc_u32 s41, s41, 0
	s_mov_b32 m0, s47
	v_lshl_add_u64 v[226:227], s[40:41], 0, v[146:147]
	ds_read_b128 v[186:189], v180 offset:32768
	ds_read_b128 v[190:193], v180 offset:33792
	ds_read_b128 v[194:197], v180 offset:34816
	ds_read_b128 v[198:201], v180 offset:35840
	ds_read_b128 v[202:205], v180 offset:36864
	ds_read_b128 v[206:209], v180 offset:37888
	ds_read_b128 v[210:213], v180 offset:38912
	ds_read_b128 v[218:221], v180 offset:39936
	global_load_lds_dwordx4 v[226:227], off
	v_lshl_add_u64 v[226:227], s[40:41], 0, v[150:151]
	s_mov_b32 m0, s56
	s_nop 0
	global_load_lds_dwordx4 v[226:227], off
	s_waitcnt vmcnt(8)
	s_waitcnt lgkmcnt(0)
	s_barrier
	s_setprio 1
	s_waitcnt lgkmcnt(0)
	v_mfma_f32_16x16x32_bf16 v[126:129], v[130:133], v[186:189], v[126:129]
	v_mfma_f32_16x16x32_bf16 v[122:125], v[138:141], v[186:189], v[122:125]
	v_mfma_f32_16x16x32_bf16 v[110:113], v[130:133], v[194:197], v[110:113]
	v_mfma_f32_16x16x32_bf16 v[106:109], v[138:141], v[194:197], v[106:109]
	v_mfma_f32_16x16x32_bf16 v[94:97], v[130:133], v[202:205], v[94:97]
	v_mfma_f32_16x16x32_bf16 v[90:93], v[138:141], v[202:205], v[90:93]
	v_mfma_f32_16x16x32_bf16 v[78:81], v[130:133], v[210:213], v[78:81]
	v_mfma_f32_16x16x32_bf16 v[74:77], v[138:141], v[210:213], v[74:77]
	v_mfma_f32_16x16x32_bf16 v[126:129], v[134:137], v[190:193], v[126:129]
	v_mfma_f32_16x16x32_bf16 v[122:125], v[142:145], v[190:193], v[122:125]
	v_mfma_f32_16x16x32_bf16 v[110:113], v[134:137], v[198:201], v[110:113]
	v_mfma_f32_16x16x32_bf16 v[106:109], v[142:145], v[198:201], v[106:109]
	v_mfma_f32_16x16x32_bf16 v[94:97], v[134:137], v[206:209], v[94:97]
	v_mfma_f32_16x16x32_bf16 v[90:93], v[142:145], v[206:209], v[90:93]
	v_mfma_f32_16x16x32_bf16 v[78:81], v[134:137], v[218:221], v[78:81]
	v_mfma_f32_16x16x32_bf16 v[74:77], v[142:145], v[218:221], v[74:77]
	s_setprio 0
	s_setprio 1
	v_mfma_f32_16x16x32_bf16 v[118:121], v[162:165], v[186:189], v[118:121]
	v_mfma_f32_16x16x32_bf16 v[114:117], v[170:173], v[186:189], v[114:117]
	v_mfma_f32_16x16x32_bf16 v[102:105], v[162:165], v[194:197], v[102:105]
	v_mfma_f32_16x16x32_bf16 v[98:101], v[170:173], v[194:197], v[98:101]
	v_mfma_f32_16x16x32_bf16 v[86:89], v[162:165], v[202:205], v[86:89]
	v_mfma_f32_16x16x32_bf16 v[82:85], v[170:173], v[202:205], v[82:85]
	v_mfma_f32_16x16x32_bf16 v[70:73], v[162:165], v[210:213], v[70:73]
	v_mfma_f32_16x16x32_bf16 v[66:69], v[170:173], v[210:213], v[66:69]
	v_mfma_f32_16x16x32_bf16 v[118:121], v[166:169], v[190:193], v[118:121]
	v_mfma_f32_16x16x32_bf16 v[114:117], v[182:185], v[190:193], v[114:117]
	v_mfma_f32_16x16x32_bf16 v[102:105], v[166:169], v[198:201], v[102:105]
	v_mfma_f32_16x16x32_bf16 v[98:101], v[182:185], v[198:201], v[98:101]
	v_mfma_f32_16x16x32_bf16 v[86:89], v[166:169], v[206:209], v[86:89]
	v_mfma_f32_16x16x32_bf16 v[82:85], v[182:185], v[206:209], v[82:85]
	v_mfma_f32_16x16x32_bf16 v[70:73], v[166:169], v[218:221], v[70:73]
	v_mfma_f32_16x16x32_bf16 v[66:69], v[182:185], v[218:221], v[66:69]
	s_setprio 0
	s_barrier
	s_add_i32 s40, s53, s31
	v_lshl_add_u64 v[174:175], v[174:175], 0, s[24:25]
	s_mov_b32 m0, s40
	ds_read_b128 v[186:189], v180 offset:49152
	ds_read_b128 v[190:193], v180 offset:50176
	ds_read_b128 v[194:197], v180 offset:51200
	ds_read_b128 v[198:201], v180 offset:52224
	ds_read_b128 v[202:205], v180 offset:53248
	ds_read_b128 v[206:209], v180 offset:54272
	ds_read_b128 v[210:213], v180 offset:55296
	ds_read_b128 v[218:221], v180 offset:56320
	global_load_lds_dwordx4 v[174:175], off
	s_add_i32 m0, s40, 0x2000
	s_add_u32 s34, s34, 0x160080
	v_lshl_add_u64 v[174:175], v[214:215], 0, s[24:25]
	s_addc_u32 s35, s35, 0
	s_add_i32 s40, s54, s31
	global_load_lds_dwordx4 v[174:175], off
	v_lshl_add_u64 v[174:175], s[34:35], 0, v[148:149]
	s_mov_b32 m0, s40
	s_nop 0
	global_load_lds_dwordx4 v[174:175], off
	v_lshl_add_u64 v[174:175], s[34:35], 0, v[152:153]
	s_add_i32 m0, s40, 0x2000
	s_nop 0
	global_load_lds_dwordx4 v[174:175], off
	v_lshl_add_u64 v[174:175], v[222:223], 0, s[24:25]
	s_mov_b32 m0, s58
	s_nop 0
	global_load_lds_dwordx4 v[174:175], off
	v_lshl_add_u64 v[174:175], v[224:225], 0, s[24:25]
	s_mov_b32 m0, s59
	s_nop 0
	global_load_lds_dwordx4 v[174:175], off
	s_waitcnt vmcnt(8)
	s_waitcnt lgkmcnt(0)
	s_barrier
	s_setprio 1
	s_waitcnt lgkmcnt(0)
	v_mfma_f32_16x16x32_bf16 v[62:65], v[130:133], v[186:189], v[62:65]
	v_mfma_f32_16x16x32_bf16 v[58:61], v[138:141], v[186:189], v[58:61]
	v_mfma_f32_16x16x32_bf16 v[50:53], v[130:133], v[194:197], v[50:53]
	v_mfma_f32_16x16x32_bf16 v[42:45], v[138:141], v[194:197], v[42:45]
	v_mfma_f32_16x16x32_bf16 v[38:41], v[130:133], v[202:205], v[38:41]
	v_mfma_f32_16x16x32_bf16 v[34:37], v[138:141], v[202:205], v[34:37]
	v_mfma_f32_16x16x32_bf16 v[14:17], v[130:133], v[210:213], v[14:17]
	v_mfma_f32_16x16x32_bf16 v[10:13], v[138:141], v[210:213], v[10:13]
	v_mfma_f32_16x16x32_bf16 v[62:65], v[134:137], v[190:193], v[62:65]
	v_mfma_f32_16x16x32_bf16 v[58:61], v[142:145], v[190:193], v[58:61]
	v_mfma_f32_16x16x32_bf16 v[50:53], v[134:137], v[198:201], v[50:53]
	v_mfma_f32_16x16x32_bf16 v[42:45], v[142:145], v[198:201], v[42:45]
	v_mfma_f32_16x16x32_bf16 v[38:41], v[134:137], v[206:209], v[38:41]
	v_mfma_f32_16x16x32_bf16 v[34:37], v[142:145], v[206:209], v[34:37]
	v_mfma_f32_16x16x32_bf16 v[14:17], v[134:137], v[218:221], v[14:17]
	v_mfma_f32_16x16x32_bf16 v[10:13], v[142:145], v[218:221], v[10:13]
	s_setprio 0
	s_setprio 1
	v_mfma_f32_16x16x32_bf16 v[54:57], v[162:165], v[186:189], v[54:57]
	v_mfma_f32_16x16x32_bf16 v[46:49], v[170:173], v[186:189], v[46:49]
	v_mfma_f32_16x16x32_bf16 v[30:33], v[162:165], v[194:197], v[30:33]
	v_mfma_f32_16x16x32_bf16 v[26:29], v[170:173], v[194:197], v[26:29]
	v_mfma_f32_16x16x32_bf16 v[22:25], v[162:165], v[202:205], v[22:25]
	v_mfma_f32_16x16x32_bf16 v[18:21], v[170:173], v[202:205], v[18:21]
	v_mfma_f32_16x16x32_bf16 v[6:9], v[162:165], v[210:213], v[6:9]
	v_mfma_f32_16x16x32_bf16 v[2:5], v[170:173], v[210:213], v[2:5]
	v_mfma_f32_16x16x32_bf16 v[54:57], v[166:169], v[190:193], v[54:57]
	v_mfma_f32_16x16x32_bf16 v[46:49], v[182:185], v[190:193], v[46:49]
	v_mfma_f32_16x16x32_bf16 v[30:33], v[166:169], v[198:201], v[30:33]
	v_mfma_f32_16x16x32_bf16 v[26:29], v[182:185], v[198:201], v[26:29]
	v_mfma_f32_16x16x32_bf16 v[22:25], v[166:169], v[206:209], v[22:25]
	v_mfma_f32_16x16x32_bf16 v[18:21], v[182:185], v[206:209], v[18:21]
	v_mfma_f32_16x16x32_bf16 v[6:9], v[166:169], v[218:221], v[6:9]
	v_mfma_f32_16x16x32_bf16 v[2:5], v[182:185], v[218:221], v[2:5]
	s_setprio 0
	s_barrier
	s_add_i32 s52, s52, 2
	s_add_u32 s38, s38, 0x100
	s_addc_u32 s39, s39, 0
	s_add_u32 s0, s0, 0x100
	s_addc_u32 s1, s1, 0

.LBB0_2217:
	s_ashr_i32 s37, s36, 31
	s_lshl_b64 s[0:1], s[36:37], 20
	v_readlane_b32 s27, v247, 45
	s_add_u32 s38, s27, s0
	v_readlane_b32 s0, v247, 47
	s_addc_u32 s39, s0, s1
	s_and_b64 s[0:1], s[2:3], exec
	s_cselect_b32 s0, s39, s35
	s_cselect_b32 s1, s38, s34
	s_ashr_i32 s27, s26, 31
	s_lshl_b64 s[40:41], s[26:27], 20
	s_add_u32 s40, s12, s40
	s_addc_u32 s41, s13, s41
	s_and_b64 s[52:53], s[2:3], exec
	s_cselect_b32 s27, s41, s79
	s_cselect_b32 s37, s40, s78
	s_add_u32 s76, s34, 0x80080
	s_addc_u32 s77, s35, 0
	s_add_u32 s52, s78, 0x100
	s_addc_u32 s75, s79, 0
	s_mov_b32 s80, -2
	ds_read_b128 v[146:149], v153
	ds_read_b128 v[156:159], v153 offset:1024
	ds_read_b128 v[160:163], v153 offset:2048
	ds_read_b128 v[164:167], v153 offset:3072
	ds_read_b128 v[168:171], v154
	ds_read_b128 v[172:175], v154 offset:1024
	ds_read_b128 v[176:179], v154 offset:2048
	ds_read_b128 v[180:183], v154 offset:3072
	s_add_u32 s34, s76, 0xfff80080
	s_addc_u32 s35, s77, -1
	s_cmp_eq_u32 s80, 28
	s_cselect_b32 s79, s0, s35
	s_cselect_b32 s78, s1, s34
	s_cselect_b32 s35, s27, s75
	s_cselect_b32 s34, s37, s52
	v_lshl_add_u64 v[218:219], s[76:77], 0, v[138:139]
	s_add_i32 m0, s47, 0xc000
	ds_read_b128 v[184:187], v155
	ds_read_b128 v[188:191], v155 offset:1024
	ds_read_b128 v[192:195], v155 offset:2048
	ds_read_b128 v[196:199], v155 offset:3072
	ds_read_b128 v[200:203], v155 offset:4096
	ds_read_b128 v[204:207], v155 offset:5120
	ds_read_b128 v[208:211], v155 offset:6144
	ds_read_b128 v[212:215], v155 offset:7168
	global_load_lds_dwordx4 v[218:219], off
	v_lshl_add_u64 v[218:219], s[76:77], 0, v[140:141]
	s_add_i32 m0, s47, 0xe000
	s_nop 0
	global_load_lds_dwordx4 v[218:219], off
	s_waitcnt vmcnt(8)
	s_waitcnt lgkmcnt(0)
	s_barrier
	s_setprio 1
	s_waitcnt lgkmcnt(0)
	v_mfma_f32_16x16x32_bf16 v[126:129], v[146:149], v[184:187], 0
	v_mfma_f32_16x16x32_bf16 v[118:121], v[160:163], v[184:187], 0
	v_mfma_f32_16x16x32_bf16 v[110:113], v[146:149], v[192:195], 0
	v_mfma_f32_16x16x32_bf16 v[102:105], v[160:163], v[192:195], 0
	v_mfma_f32_16x16x32_bf16 v[94:97], v[146:149], v[200:203], 0
	v_mfma_f32_16x16x32_bf16 v[86:89], v[160:163], v[200:203], 0
	v_mfma_f32_16x16x32_bf16 v[78:81], v[146:149], v[208:211], 0
	v_mfma_f32_16x16x32_bf16 v[70:73], v[160:163], v[208:211], 0
	v_mfma_f32_16x16x32_bf16 v[126:129], v[156:159], v[188:191], v[126:129]
	v_mfma_f32_16x16x32_bf16 v[118:121], v[164:167], v[188:191], v[118:121]
	v_mfma_f32_16x16x32_bf16 v[110:113], v[156:159], v[196:199], v[110:113]
	v_mfma_f32_16x16x32_bf16 v[102:105], v[164:167], v[196:199], v[102:105]
	v_mfma_f32_16x16x32_bf16 v[94:97], v[156:159], v[204:207], v[94:97]
	v_mfma_f32_16x16x32_bf16 v[86:89], v[164:167], v[204:207], v[86:89]
	v_mfma_f32_16x16x32_bf16 v[78:81], v[156:159], v[212:215], v[78:81]
	v_mfma_f32_16x16x32_bf16 v[70:73], v[164:167], v[212:215], v[70:73]
	s_setprio 0
	s_setprio 1
	v_mfma_f32_16x16x32_bf16 v[122:125], v[168:171], v[184:187], 0
	v_mfma_f32_16x16x32_bf16 v[114:117], v[176:179], v[184:187], 0
	v_mfma_f32_16x16x32_bf16 v[106:109], v[168:171], v[192:195], 0
	v_mfma_f32_16x16x32_bf16 v[98:101], v[176:179], v[192:195], 0
	v_mfma_f32_16x16x32_bf16 v[90:93], v[168:171], v[200:203], 0
	v_mfma_f32_16x16x32_bf16 v[82:85], v[176:179], v[200:203], 0
	v_mfma_f32_16x16x32_bf16 v[74:77], v[168:171], v[208:211], 0
	v_mfma_f32_16x16x32_bf16 v[66:69], v[176:179], v[208:211], 0
	v_mfma_f32_16x16x32_bf16 v[122:125], v[172:175], v[188:191], v[122:125]
	v_mfma_f32_16x16x32_bf16 v[114:117], v[180:183], v[188:191], v[114:117]
	v_mfma_f32_16x16x32_bf16 v[106:109], v[172:175], v[196:199], v[106:109]
	v_mfma_f32_16x16x32_bf16 v[98:101], v[180:183], v[196:199], v[98:101]
	v_mfma_f32_16x16x32_bf16 v[90:93], v[172:175], v[204:207], v[90:93]
	v_mfma_f32_16x16x32_bf16 v[82:85], v[180:183], v[204:207], v[82:85]
	v_mfma_f32_16x16x32_bf16 v[74:77], v[172:175], v[212:215], v[74:77]
	v_mfma_f32_16x16x32_bf16 v[66:69], v[180:183], v[212:215], v[66:69]
	s_setprio 0
	s_barrier
	s_add_i32 s53, s71, s30
	v_lshl_add_u64 v[218:219], s[34:35], 0, v[134:135]
	s_mov_b32 m0, s53
	ds_read_b128 v[184:187], v155 offset:16384
	ds_read_b128 v[188:191], v155 offset:17408
	ds_read_b128 v[192:195], v155 offset:18432
	ds_read_b128 v[196:199], v155 offset:19456
	ds_read_b128 v[200:203], v155 offset:20480
	ds_read_b128 v[204:207], v155 offset:21504
	ds_read_b128 v[208:211], v155 offset:22528
	ds_read_b128 v[212:215], v155 offset:23552
	global_load_lds_dwordx4 v[218:219], off
	s_add_i32 m0, s53, 0x2000
	s_add_u32 s54, s34, 0x80000
	v_lshl_add_u64 v[220:221], s[34:35], 0, v[130:131]
	s_addc_u32 s55, s35, 0
	s_add_i32 s53, s72, s30
	global_load_lds_dwordx4 v[220:221], off
	v_lshl_add_u64 v[222:223], s[54:55], 0, v[134:135]
	s_mov_b32 m0, s53
	v_lshl_add_u64 v[224:225], s[78:79], 0, v[132:133]
	global_load_lds_dwordx4 v[222:223], off
	v_lshl_add_u64 v[222:223], s[54:55], 0, v[130:131]
	s_add_i32 m0, s53, 0x2000
	s_nop 0
	global_load_lds_dwordx4 v[222:223], off
	v_lshl_add_u64 v[222:223], s[78:79], 0, v[136:137]
	s_mov_b32 m0, s47
	s_nop 0
	global_load_lds_dwordx4 v[222:223], off
	s_mov_b32 m0, s56
	s_nop 0
	global_load_lds_dwordx4 v[224:225], off
	s_waitcnt vmcnt(8)
	s_waitcnt lgkmcnt(0)
	s_barrier
	s_setprio 1
	s_waitcnt lgkmcnt(0)
	v_mfma_f32_16x16x32_bf16 v[62:65], v[146:149], v[184:187], 0
	v_mfma_f32_16x16x32_bf16 v[54:57], v[160:163], v[184:187], 0
	v_mfma_f32_16x16x32_bf16 v[46:49], v[146:149], v[192:195], 0
	v_mfma_f32_16x16x32_bf16 v[38:41], v[160:163], v[192:195], 0
	v_mfma_f32_16x16x32_bf16 v[30:33], v[146:149], v[200:203], 0
	v_mfma_f32_16x16x32_bf16 v[22:25], v[160:163], v[200:203], 0
	v_mfma_f32_16x16x32_bf16 v[14:17], v[146:149], v[208:211], 0
	v_mfma_f32_16x16x32_bf16 v[6:9], v[160:163], v[208:211], 0
	v_mfma_f32_16x16x32_bf16 v[62:65], v[156:159], v[188:191], v[62:65]
	v_mfma_f32_16x16x32_bf16 v[54:57], v[164:167], v[188:191], v[54:57]
	v_mfma_f32_16x16x32_bf16 v[46:49], v[156:159], v[196:199], v[46:49]
	v_mfma_f32_16x16x32_bf16 v[38:41], v[164:167], v[196:199], v[38:41]
	v_mfma_f32_16x16x32_bf16 v[30:33], v[156:159], v[204:207], v[30:33]
	v_mfma_f32_16x16x32_bf16 v[22:25], v[164:167], v[204:207], v[22:25]
	v_mfma_f32_16x16x32_bf16 v[14:17], v[156:159], v[212:215], v[14:17]
	v_mfma_f32_16x16x32_bf16 v[6:9], v[164:167], v[212:215], v[6:9]
	s_setprio 0
	s_setprio 1
	v_mfma_f32_16x16x32_bf16 v[58:61], v[168:171], v[184:187], 0
	v_mfma_f32_16x16x32_bf16 v[50:53], v[176:179], v[184:187], 0
	v_mfma_f32_16x16x32_bf16 v[42:45], v[168:171], v[192:195], 0
	v_mfma_f32_16x16x32_bf16 v[34:37], v[176:179], v[192:195], 0
	v_mfma_f32_16x16x32_bf16 v[26:29], v[168:171], v[200:203], 0
	v_mfma_f32_16x16x32_bf16 v[18:21], v[176:179], v[200:203], 0
	v_mfma_f32_16x16x32_bf16 v[10:13], v[168:171], v[208:211], 0
	v_mfma_f32_16x16x32_bf16 v[2:5], v[176:179], v[208:211], 0
	v_mfma_f32_16x16x32_bf16 v[58:61], v[172:175], v[188:191], v[58:61]
	v_mfma_f32_16x16x32_bf16 v[50:53], v[180:183], v[188:191], v[50:53]
	v_mfma_f32_16x16x32_bf16 v[42:45], v[172:175], v[196:199], v[42:45]
	v_mfma_f32_16x16x32_bf16 v[34:37], v[180:183], v[196:199], v[34:37]
	v_mfma_f32_16x16x32_bf16 v[26:29], v[172:175], v[204:207], v[26:29]
	v_mfma_f32_16x16x32_bf16 v[18:21], v[180:183], v[204:207], v[18:21]
	v_mfma_f32_16x16x32_bf16 v[10:13], v[172:175], v[212:215], v[10:13]
	v_mfma_f32_16x16x32_bf16 v[2:5], v[180:183], v[212:215], v[2:5]
	s_setprio 0
	s_barrier
	s_add_i32 s53, 0, 0x18000
	s_add_i32 s62, 0, 0x1c000
	v_add_u32_e32 v164, s53, v151
	v_add_u32_e32 v180, s62, v151
	ds_read_b128 v[146:149], v164
	ds_read_b128 v[156:159], v164 offset:1024
	ds_read_b128 v[160:163], v164 offset:2048
	ds_read_b128 v[164:167], v164 offset:3072
	ds_read_b128 v[168:171], v180
	ds_read_b128 v[172:175], v180 offset:1024
	ds_read_b128 v[176:179], v180 offset:2048
	ds_read_b128 v[180:183], v180 offset:3072
	s_add_u32 s54, s78, 0x80000
	s_addc_u32 s55, s79, 0
	s_mov_b32 m0, s57
	v_lshl_add_u64 v[226:227], s[54:55], 0, v[136:137]
	ds_read_b128 v[184:187], v155 offset:32768
	ds_read_b128 v[188:191], v155 offset:33792
	ds_read_b128 v[192:195], v155 offset:34816
	ds_read_b128 v[196:199], v155 offset:35840
	ds_read_b128 v[200:203], v155 offset:36864
	ds_read_b128 v[204:207], v155 offset:37888
	ds_read_b128 v[208:211], v155 offset:38912
	ds_read_b128 v[212:215], v155 offset:39936
	global_load_lds_dwordx4 v[226:227], off
	v_lshl_add_u64 v[226:227], s[54:55], 0, v[132:133]
	s_mov_b32 m0, s58
	s_nop 0
	global_load_lds_dwordx4 v[226:227], off
	s_waitcnt vmcnt(8)
	s_waitcnt lgkmcnt(0)
	s_barrier
	s_setprio 1
	s_waitcnt lgkmcnt(0)
	v_mfma_f32_16x16x32_bf16 v[126:129], v[146:149], v[184:187], v[126:129]
	v_mfma_f32_16x16x32_bf16 v[118:121], v[160:163], v[184:187], v[118:121]
	v_mfma_f32_16x16x32_bf16 v[110:113], v[146:149], v[192:195], v[110:113]
	v_mfma_f32_16x16x32_bf16 v[102:105], v[160:163], v[192:195], v[102:105]
	v_mfma_f32_16x16x32_bf16 v[94:97], v[146:149], v[200:203], v[94:97]
	v_mfma_f32_16x16x32_bf16 v[86:89], v[160:163], v[200:203], v[86:89]
	v_mfma_f32_16x16x32_bf16 v[78:81], v[146:149], v[208:211], v[78:81]
	v_mfma_f32_16x16x32_bf16 v[70:73], v[160:163], v[208:211], v[70:73]
	v_mfma_f32_16x16x32_bf16 v[126:129], v[156:159], v[188:191], v[126:129]
	v_mfma_f32_16x16x32_bf16 v[118:121], v[164:167], v[188:191], v[118:121]
	v_mfma_f32_16x16x32_bf16 v[110:113], v[156:159], v[196:199], v[110:113]
	v_mfma_f32_16x16x32_bf16 v[102:105], v[164:167], v[196:199], v[102:105]
	v_mfma_f32_16x16x32_bf16 v[94:97], v[156:159], v[204:207], v[94:97]
	v_mfma_f32_16x16x32_bf16 v[86:89], v[164:167], v[204:207], v[86:89]
	v_mfma_f32_16x16x32_bf16 v[78:81], v[156:159], v[212:215], v[78:81]
	v_mfma_f32_16x16x32_bf16 v[70:73], v[164:167], v[212:215], v[70:73]
	s_setprio 0
	s_setprio 1
	v_mfma_f32_16x16x32_bf16 v[122:125], v[168:171], v[184:187], v[122:125]
	v_mfma_f32_16x16x32_bf16 v[114:117], v[176:179], v[184:187], v[114:117]
	v_mfma_f32_16x16x32_bf16 v[106:109], v[168:171], v[192:195], v[106:109]
	v_mfma_f32_16x16x32_bf16 v[98:101], v[176:179], v[192:195], v[98:101]
	v_mfma_f32_16x16x32_bf16 v[90:93], v[168:171], v[200:203], v[90:93]
	v_mfma_f32_16x16x32_bf16 v[82:85], v[176:179], v[200:203], v[82:85]
	v_mfma_f32_16x16x32_bf16 v[74:77], v[168:171], v[208:211], v[74:77]
	v_mfma_f32_16x16x32_bf16 v[66:69], v[176:179], v[208:211], v[66:69]
	v_mfma_f32_16x16x32_bf16 v[122:125], v[172:175], v[188:191], v[122:125]
	v_mfma_f32_16x16x32_bf16 v[114:117], v[180:183], v[188:191], v[114:117]
	v_mfma_f32_16x16x32_bf16 v[106:109], v[172:175], v[196:199], v[106:109]
	v_mfma_f32_16x16x32_bf16 v[98:101], v[180:183], v[196:199], v[98:101]
	v_mfma_f32_16x16x32_bf16 v[90:93], v[172:175], v[204:207], v[90:93]
	v_mfma_f32_16x16x32_bf16 v[82:85], v[180:183], v[204:207], v[82:85]
	v_mfma_f32_16x16x32_bf16 v[74:77], v[172:175], v[212:215], v[74:77]
	v_mfma_f32_16x16x32_bf16 v[66:69], v[180:183], v[212:215], v[66:69]
	s_setprio 0
	s_barrier
	s_add_i32 s53, s53, s30
	v_lshl_add_u64 v[218:219], v[218:219], 0, s[8:9]
	s_mov_b32 m0, s53
	ds_read_b128 v[184:187], v155 offset:49152
	ds_read_b128 v[188:191], v155 offset:50176
	ds_read_b128 v[192:195], v155 offset:51200
	ds_read_b128 v[196:199], v155 offset:52224
	ds_read_b128 v[200:203], v155 offset:53248
	ds_read_b128 v[204:207], v155 offset:54272
	ds_read_b128 v[208:211], v155 offset:55296
	ds_read_b128 v[212:215], v155 offset:56320
	global_load_lds_dwordx4 v[218:219], off
	s_add_i32 m0, s53, 0x2000
	s_add_u32 s34, s34, 0x80080
	v_lshl_add_u64 v[218:219], v[220:221], 0, s[8:9]
	s_addc_u32 s35, s35, 0
	s_add_i32 s53, s62, s30
	global_load_lds_dwordx4 v[218:219], off
	v_lshl_add_u64 v[218:219], s[34:35], 0, v[134:135]
	s_mov_b32 m0, s53
	s_nop 0
	global_load_lds_dwordx4 v[218:219], off
	v_lshl_add_u64 v[218:219], s[34:35], 0, v[130:131]
	s_add_i32 m0, s53, 0x2000
	s_nop 0
	global_load_lds_dwordx4 v[218:219], off
	v_lshl_add_u64 v[218:219], v[222:223], 0, s[8:9]
	s_mov_b32 m0, s60
	s_nop 0
	global_load_lds_dwordx4 v[218:219], off
	v_lshl_add_u64 v[218:219], v[224:225], 0, s[8:9]
	s_mov_b32 m0, s61
	s_nop 0
	global_load_lds_dwordx4 v[218:219], off
	s_waitcnt vmcnt(8)
	s_waitcnt lgkmcnt(0)
	s_barrier
	s_setprio 1
	s_waitcnt lgkmcnt(0)
	v_mfma_f32_16x16x32_bf16 v[62:65], v[146:149], v[184:187], v[62:65]
	v_mfma_f32_16x16x32_bf16 v[54:57], v[160:163], v[184:187], v[54:57]
	v_mfma_f32_16x16x32_bf16 v[46:49], v[146:149], v[192:195], v[46:49]
	v_mfma_f32_16x16x32_bf16 v[38:41], v[160:163], v[192:195], v[38:41]
	v_mfma_f32_16x16x32_bf16 v[30:33], v[146:149], v[200:203], v[30:33]
	v_mfma_f32_16x16x32_bf16 v[22:25], v[160:163], v[200:203], v[22:25]
	v_mfma_f32_16x16x32_bf16 v[14:17], v[146:149], v[208:211], v[14:17]
	v_mfma_f32_16x16x32_bf16 v[6:9], v[160:163], v[208:211], v[6:9]
	v_mfma_f32_16x16x32_bf16 v[62:65], v[156:159], v[188:191], v[62:65]
	v_mfma_f32_16x16x32_bf16 v[54:57], v[164:167], v[188:191], v[54:57]
	v_mfma_f32_16x16x32_bf16 v[46:49], v[156:159], v[196:199], v[46:49]
	v_mfma_f32_16x16x32_bf16 v[38:41], v[164:167], v[196:199], v[38:41]
	v_mfma_f32_16x16x32_bf16 v[30:33], v[156:159], v[204:207], v[30:33]
	v_mfma_f32_16x16x32_bf16 v[22:25], v[164:167], v[204:207], v[22:25]
	v_mfma_f32_16x16x32_bf16 v[14:17], v[156:159], v[212:215], v[14:17]
	v_mfma_f32_16x16x32_bf16 v[6:9], v[164:167], v[212:215], v[6:9]
	s_setprio 0
	s_setprio 1
	v_mfma_f32_16x16x32_bf16 v[58:61], v[168:171], v[184:187], v[58:61]
	v_mfma_f32_16x16x32_bf16 v[50:53], v[176:179], v[184:187], v[50:53]
	v_mfma_f32_16x16x32_bf16 v[42:45], v[168:171], v[192:195], v[42:45]
	v_mfma_f32_16x16x32_bf16 v[34:37], v[176:179], v[192:195], v[34:37]
	v_mfma_f32_16x16x32_bf16 v[26:29], v[168:171], v[200:203], v[26:29]
	v_mfma_f32_16x16x32_bf16 v[18:21], v[176:179], v[200:203], v[18:21]
	v_mfma_f32_16x16x32_bf16 v[10:13], v[168:171], v[208:211], v[10:13]
	v_mfma_f32_16x16x32_bf16 v[2:5], v[176:179], v[208:211], v[2:5]
	v_mfma_f32_16x16x32_bf16 v[58:61], v[172:175], v[188:191], v[58:61]
	v_mfma_f32_16x16x32_bf16 v[50:53], v[180:183], v[188:191], v[50:53]
	v_mfma_f32_16x16x32_bf16 v[42:45], v[172:175], v[196:199], v[42:45]
	v_mfma_f32_16x16x32_bf16 v[34:37], v[180:183], v[196:199], v[34:37]
	v_mfma_f32_16x16x32_bf16 v[26:29], v[172:175], v[204:207], v[26:29]
	v_mfma_f32_16x16x32_bf16 v[18:21], v[180:183], v[204:207], v[18:21]
	v_mfma_f32_16x16x32_bf16 v[10:13], v[172:175], v[212:215], v[10:13]
	v_mfma_f32_16x16x32_bf16 v[2:5], v[180:183], v[212:215], v[2:5]
	s_setprio 0
	s_barrier
	s_add_i32 s80, s80, 2
	s_add_u32 s76, s76, 0x100
	s_addc_u32 s77, s77, 0
	s_add_u32 s52, s52, 0x100
	s_addc_u32 s75, s75, 0

.LBB0_2461:
	s_ashr_i32 s83, s82, 31
	s_lshl_b64 s[0:1], s[82:83], 20
	v_readlane_b32 s7, v247, 45
	s_add_u32 s84, s7, s0
	v_readlane_b32 s0, v247, 47
	s_addc_u32 s85, s0, s1
	s_and_b64 s[0:1], s[4:5], exec
	s_cselect_b32 s0, s85, s77
	s_cselect_b32 s1, s84, s76
	s_ashr_i32 s81, s80, 31
	s_lshl_b64 s[34:35], s[80:81], 20
	s_add_u32 s86, s13, s34
	s_addc_u32 s87, s30, s35
	s_and_b64 s[34:35], s[4:5], exec
	s_cselect_b32 s7, s87, s89
	s_cselect_b32 s9, s86, s88
	s_add_u32 s76, s76, 0x80080
	s_addc_u32 s77, s77, 0
	s_add_u32 s36, s88, 0x100
	s_addc_u32 s52, s89, 0
	s_mov_b32 s74, -2
	s_waitcnt lgkmcnt(0)
	ds_read_b128 v[160:163], v155
	ds_read_b128 v[164:167], v155 offset:1024
	ds_read_b128 v[168:171], v155 offset:2048
	ds_read_b128 v[172:175], v155 offset:3072
	ds_read_b128 v[176:179], v156
	ds_read_b128 v[180:183], v156 offset:1024
	ds_read_b128 v[184:187], v156 offset:2048
	ds_read_b128 v[188:191], v156 offset:3072
	s_add_u32 s34, s76, 0xfff80080
	s_addc_u32 s35, s77, -1
	s_cmp_eq_u32 s74, 28
	s_cselect_b32 s89, s0, s35
	s_cselect_b32 s88, s1, s34
	s_cselect_b32 s35, s7, s52
	s_cselect_b32 s34, s9, s36
	v_lshl_add_u64 v[152:153], s[76:77], 0, v[144:145]
	s_add_i32 m0, s31, 0xc000
	ds_read_b128 v[192:195], v157
	ds_read_b128 v[196:199], v157 offset:1024
	ds_read_b128 v[200:203], v157 offset:2048
	ds_read_b128 v[204:207], v157 offset:3072
	ds_read_b128 v[208:211], v157 offset:4096
	ds_read_b128 v[212:215], v157 offset:5120
	ds_read_b128 v[218:221], v157 offset:6144
	ds_read_b128 v[222:225], v157 offset:7168
	global_load_lds_dwordx4 v[152:153], off
	v_lshl_add_u64 v[152:153], s[76:77], 0, v[146:147]
	s_add_i32 m0, s31, 0xe000
	s_nop 0
	global_load_lds_dwordx4 v[152:153], off
	s_waitcnt vmcnt(8)
	s_waitcnt lgkmcnt(0)
	s_barrier
	s_setprio 1
	s_waitcnt lgkmcnt(0)
	v_mfma_f32_16x16x32_bf16 v[126:129], v[160:163], v[192:195], 0
	v_mfma_f32_16x16x32_bf16 v[122:125], v[168:171], v[192:195], 0
	v_mfma_f32_16x16x32_bf16 v[110:113], v[160:163], v[200:203], 0
	v_mfma_f32_16x16x32_bf16 v[106:109], v[168:171], v[200:203], 0
	v_mfma_f32_16x16x32_bf16 v[94:97], v[160:163], v[208:211], 0
	v_mfma_f32_16x16x32_bf16 v[90:93], v[168:171], v[208:211], 0
	v_mfma_f32_16x16x32_bf16 v[78:81], v[160:163], v[218:221], 0
	v_mfma_f32_16x16x32_bf16 v[74:77], v[168:171], v[218:221], 0
	v_mfma_f32_16x16x32_bf16 v[126:129], v[164:167], v[196:199], v[126:129]
	v_mfma_f32_16x16x32_bf16 v[122:125], v[172:175], v[196:199], v[122:125]
	v_mfma_f32_16x16x32_bf16 v[110:113], v[164:167], v[204:207], v[110:113]
	v_mfma_f32_16x16x32_bf16 v[106:109], v[172:175], v[204:207], v[106:109]
	v_mfma_f32_16x16x32_bf16 v[94:97], v[164:167], v[212:215], v[94:97]
	v_mfma_f32_16x16x32_bf16 v[90:93], v[172:175], v[212:215], v[90:93]
	v_mfma_f32_16x16x32_bf16 v[78:81], v[164:167], v[222:225], v[78:81]
	v_mfma_f32_16x16x32_bf16 v[74:77], v[172:175], v[222:225], v[74:77]
	s_setprio 0
	s_setprio 1
	v_mfma_f32_16x16x32_bf16 v[118:121], v[176:179], v[192:195], 0
	v_mfma_f32_16x16x32_bf16 v[114:117], v[184:187], v[192:195], 0
	v_mfma_f32_16x16x32_bf16 v[102:105], v[176:179], v[200:203], 0
	v_mfma_f32_16x16x32_bf16 v[98:101], v[184:187], v[200:203], 0
	v_mfma_f32_16x16x32_bf16 v[86:89], v[176:179], v[208:211], 0
	v_mfma_f32_16x16x32_bf16 v[82:85], v[184:187], v[208:211], 0
	v_mfma_f32_16x16x32_bf16 v[70:73], v[176:179], v[218:221], 0
	v_mfma_f32_16x16x32_bf16 v[66:69], v[184:187], v[218:221], 0
	v_mfma_f32_16x16x32_bf16 v[118:121], v[180:183], v[196:199], v[118:121]
	v_mfma_f32_16x16x32_bf16 v[114:117], v[188:191], v[196:199], v[114:117]
	v_mfma_f32_16x16x32_bf16 v[102:105], v[180:183], v[204:207], v[102:105]
	v_mfma_f32_16x16x32_bf16 v[98:101], v[188:191], v[204:207], v[98:101]
	v_mfma_f32_16x16x32_bf16 v[86:89], v[180:183], v[212:215], v[86:89]
	v_mfma_f32_16x16x32_bf16 v[82:85], v[188:191], v[212:215], v[82:85]
	v_mfma_f32_16x16x32_bf16 v[70:73], v[180:183], v[222:225], v[70:73]
	v_mfma_f32_16x16x32_bf16 v[66:69], v[188:191], v[222:225], v[66:69]
	s_setprio 0
	s_barrier
	s_add_i32 s53, s71, s12
	v_lshl_add_u64 v[152:153], s[34:35], 0, v[132:133]
	s_mov_b32 m0, s53
	ds_read_b128 v[192:195], v157 offset:16384
	ds_read_b128 v[196:199], v157 offset:17408
	ds_read_b128 v[200:203], v157 offset:18432
	ds_read_b128 v[204:207], v157 offset:19456
	ds_read_b128 v[208:211], v157 offset:20480
	ds_read_b128 v[212:215], v157 offset:21504
	ds_read_b128 v[218:221], v157 offset:22528
	ds_read_b128 v[222:225], v157 offset:23552
	global_load_lds_dwordx4 v[152:153], off
	s_add_i32 m0, s53, 0x2000
	s_add_u32 s54, s34, 0x80000
	v_lshl_add_u64 v[226:227], s[34:35], 0, v[136:137]
	s_addc_u32 s55, s35, 0
	s_add_i32 s53, s72, s12
	global_load_lds_dwordx4 v[226:227], off
	v_lshl_add_u64 v[228:229], s[54:55], 0, v[132:133]
	s_mov_b32 m0, s53
	v_lshl_add_u64 v[230:231], s[88:89], 0, v[134:135]
	global_load_lds_dwordx4 v[228:229], off
	v_lshl_add_u64 v[228:229], s[54:55], 0, v[136:137]
	s_add_i32 m0, s53, 0x2000
	s_nop 0
	global_load_lds_dwordx4 v[228:229], off
	v_lshl_add_u64 v[228:229], s[88:89], 0, v[130:131]
	s_mov_b32 m0, s31
	s_nop 0
	global_load_lds_dwordx4 v[228:229], off
	s_mov_b32 m0, s33
	s_nop 0
	global_load_lds_dwordx4 v[230:231], off
	s_waitcnt vmcnt(8)
	s_waitcnt lgkmcnt(0)
	s_barrier
	s_setprio 1
	s_waitcnt lgkmcnt(0)
	v_mfma_f32_16x16x32_bf16 v[62:65], v[160:163], v[192:195], 0
	v_mfma_f32_16x16x32_bf16 v[58:61], v[168:171], v[192:195], 0
	v_mfma_f32_16x16x32_bf16 v[46:49], v[160:163], v[200:203], 0
	v_mfma_f32_16x16x32_bf16 v[42:45], v[168:171], v[200:203], 0
	v_mfma_f32_16x16x32_bf16 v[30:33], v[160:163], v[208:211], 0
	v_mfma_f32_16x16x32_bf16 v[26:29], v[168:171], v[208:211], 0
	v_mfma_f32_16x16x32_bf16 v[14:17], v[160:163], v[218:221], 0
	v_mfma_f32_16x16x32_bf16 v[10:13], v[168:171], v[218:221], 0
	v_mfma_f32_16x16x32_bf16 v[62:65], v[164:167], v[196:199], v[62:65]
	v_mfma_f32_16x16x32_bf16 v[58:61], v[172:175], v[196:199], v[58:61]
	v_mfma_f32_16x16x32_bf16 v[46:49], v[164:167], v[204:207], v[46:49]
	v_mfma_f32_16x16x32_bf16 v[42:45], v[172:175], v[204:207], v[42:45]
	v_mfma_f32_16x16x32_bf16 v[30:33], v[164:167], v[212:215], v[30:33]
	v_mfma_f32_16x16x32_bf16 v[26:29], v[172:175], v[212:215], v[26:29]
	v_mfma_f32_16x16x32_bf16 v[14:17], v[164:167], v[222:225], v[14:17]
	v_mfma_f32_16x16x32_bf16 v[10:13], v[172:175], v[222:225], v[10:13]
	s_setprio 0
	s_setprio 1
	v_mfma_f32_16x16x32_bf16 v[54:57], v[176:179], v[192:195], 0
	v_mfma_f32_16x16x32_bf16 v[50:53], v[184:187], v[192:195], 0
	v_mfma_f32_16x16x32_bf16 v[38:41], v[176:179], v[200:203], 0
	v_mfma_f32_16x16x32_bf16 v[34:37], v[184:187], v[200:203], 0
	v_mfma_f32_16x16x32_bf16 v[22:25], v[176:179], v[208:211], 0
	v_mfma_f32_16x16x32_bf16 v[18:21], v[184:187], v[208:211], 0
	v_mfma_f32_16x16x32_bf16 v[6:9], v[176:179], v[218:221], 0
	v_mfma_f32_16x16x32_bf16 v[2:5], v[184:187], v[218:221], 0
	v_mfma_f32_16x16x32_bf16 v[54:57], v[180:183], v[196:199], v[54:57]
	v_mfma_f32_16x16x32_bf16 v[50:53], v[188:191], v[196:199], v[50:53]
	v_mfma_f32_16x16x32_bf16 v[38:41], v[180:183], v[204:207], v[38:41]
	v_mfma_f32_16x16x32_bf16 v[34:37], v[188:191], v[204:207], v[34:37]
	v_mfma_f32_16x16x32_bf16 v[22:25], v[180:183], v[212:215], v[22:25]
	v_mfma_f32_16x16x32_bf16 v[18:21], v[188:191], v[212:215], v[18:21]
	v_mfma_f32_16x16x32_bf16 v[6:9], v[180:183], v[222:225], v[6:9]
	v_mfma_f32_16x16x32_bf16 v[2:5], v[188:191], v[222:225], v[2:5]
	s_setprio 0
	s_barrier
	s_add_i32 s53, 0, 0x18000
	v_add_u32_e32 v138, s53, v154
	s_add_i32 s62, 0, 0x1c000
	ds_read_b128 v[160:163], v138
	ds_read_b128 v[164:167], v138 offset:1024
	ds_read_b128 v[168:171], v138 offset:2048
	ds_read_b128 v[172:175], v138 offset:3072
	v_add_u32_e32 v138, s62, v154
	ds_read_b128 v[176:179], v138
	ds_read_b128 v[180:183], v138 offset:1024
	ds_read_b128 v[184:187], v138 offset:2048
	ds_read_b128 v[188:191], v138 offset:3072
	s_add_u32 s54, s88, 0x80000
	s_addc_u32 s55, s89, 0
	s_mov_b32 m0, s56
	v_lshl_add_u64 v[232:233], s[54:55], 0, v[130:131]
	ds_read_b128 v[192:195], v157 offset:32768
	ds_read_b128 v[196:199], v157 offset:33792
	ds_read_b128 v[200:203], v157 offset:34816
	ds_read_b128 v[204:207], v157 offset:35840
	ds_read_b128 v[208:211], v157 offset:36864
	ds_read_b128 v[212:215], v157 offset:37888
	ds_read_b128 v[218:221], v157 offset:38912
	ds_read_b128 v[222:225], v157 offset:39936
	global_load_lds_dwordx4 v[232:233], off
	v_lshl_add_u64 v[232:233], s[54:55], 0, v[134:135]
	s_mov_b32 m0, s57
	s_nop 0
	global_load_lds_dwordx4 v[232:233], off
	s_waitcnt vmcnt(8)
	s_waitcnt lgkmcnt(0)
	s_barrier
	s_setprio 1
	s_waitcnt lgkmcnt(0)
	v_mfma_f32_16x16x32_bf16 v[126:129], v[160:163], v[192:195], v[126:129]
	v_mfma_f32_16x16x32_bf16 v[122:125], v[168:171], v[192:195], v[122:125]
	v_mfma_f32_16x16x32_bf16 v[110:113], v[160:163], v[200:203], v[110:113]
	v_mfma_f32_16x16x32_bf16 v[106:109], v[168:171], v[200:203], v[106:109]
	v_mfma_f32_16x16x32_bf16 v[94:97], v[160:163], v[208:211], v[94:97]
	v_mfma_f32_16x16x32_bf16 v[90:93], v[168:171], v[208:211], v[90:93]
	v_mfma_f32_16x16x32_bf16 v[78:81], v[160:163], v[218:221], v[78:81]
	v_mfma_f32_16x16x32_bf16 v[74:77], v[168:171], v[218:221], v[74:77]
	v_mfma_f32_16x16x32_bf16 v[126:129], v[164:167], v[196:199], v[126:129]
	v_mfma_f32_16x16x32_bf16 v[122:125], v[172:175], v[196:199], v[122:125]
	v_mfma_f32_16x16x32_bf16 v[110:113], v[164:167], v[204:207], v[110:113]
	v_mfma_f32_16x16x32_bf16 v[106:109], v[172:175], v[204:207], v[106:109]
	v_mfma_f32_16x16x32_bf16 v[94:97], v[164:167], v[212:215], v[94:97]
	v_mfma_f32_16x16x32_bf16 v[90:93], v[172:175], v[212:215], v[90:93]
	v_mfma_f32_16x16x32_bf16 v[78:81], v[164:167], v[222:225], v[78:81]
	v_mfma_f32_16x16x32_bf16 v[74:77], v[172:175], v[222:225], v[74:77]
	s_setprio 0
	s_setprio 1
	v_mfma_f32_16x16x32_bf16 v[118:121], v[176:179], v[192:195], v[118:121]
	v_mfma_f32_16x16x32_bf16 v[114:117], v[184:187], v[192:195], v[114:117]
	v_mfma_f32_16x16x32_bf16 v[102:105], v[176:179], v[200:203], v[102:105]
	v_mfma_f32_16x16x32_bf16 v[98:101], v[184:187], v[200:203], v[98:101]
	v_mfma_f32_16x16x32_bf16 v[86:89], v[176:179], v[208:211], v[86:89]
	v_mfma_f32_16x16x32_bf16 v[82:85], v[184:187], v[208:211], v[82:85]
	v_mfma_f32_16x16x32_bf16 v[70:73], v[176:179], v[218:221], v[70:73]
	v_mfma_f32_16x16x32_bf16 v[66:69], v[184:187], v[218:221], v[66:69]
	v_mfma_f32_16x16x32_bf16 v[118:121], v[180:183], v[196:199], v[118:121]
	v_mfma_f32_16x16x32_bf16 v[114:117], v[188:191], v[196:199], v[114:117]
	v_mfma_f32_16x16x32_bf16 v[102:105], v[180:183], v[204:207], v[102:105]
	v_mfma_f32_16x16x32_bf16 v[98:101], v[188:191], v[204:207], v[98:101]
	v_mfma_f32_16x16x32_bf16 v[86:89], v[180:183], v[212:215], v[86:89]
	v_mfma_f32_16x16x32_bf16 v[82:85], v[188:191], v[212:215], v[82:85]
	v_mfma_f32_16x16x32_bf16 v[70:73], v[180:183], v[222:225], v[70:73]
	v_mfma_f32_16x16x32_bf16 v[66:69], v[188:191], v[222:225], v[66:69]
	s_setprio 0
	s_barrier
	s_add_i32 s53, s53, s12
	v_lshl_add_u64 v[152:153], v[152:153], 0, s[40:41]
	s_mov_b32 m0, s53
	ds_read_b128 v[192:195], v157 offset:49152
	ds_read_b128 v[196:199], v157 offset:50176
	ds_read_b128 v[200:203], v157 offset:51200
	ds_read_b128 v[204:207], v157 offset:52224
	ds_read_b128 v[208:211], v157 offset:53248
	ds_read_b128 v[212:215], v157 offset:54272
	ds_read_b128 v[218:221], v157 offset:55296
	ds_read_b128 v[222:225], v157 offset:56320
	global_load_lds_dwordx4 v[152:153], off
	s_add_i32 m0, s53, 0x2000
	s_add_u32 s34, s34, 0x80080
	v_lshl_add_u64 v[152:153], v[226:227], 0, s[40:41]
	s_addc_u32 s35, s35, 0
	s_add_i32 s53, s62, s12
	global_load_lds_dwordx4 v[152:153], off
	v_lshl_add_u64 v[152:153], s[34:35], 0, v[132:133]
	s_mov_b32 m0, s53
	s_nop 0
	global_load_lds_dwordx4 v[152:153], off
	v_lshl_add_u64 v[152:153], s[34:35], 0, v[136:137]
	s_add_i32 m0, s53, 0x2000
	s_nop 0
	global_load_lds_dwordx4 v[152:153], off
	v_lshl_add_u64 v[152:153], v[228:229], 0, s[40:41]
	s_mov_b32 m0, s59
	s_nop 0
	global_load_lds_dwordx4 v[152:153], off
	v_lshl_add_u64 v[152:153], v[230:231], 0, s[40:41]
	s_mov_b32 m0, s60
	s_nop 0
	global_load_lds_dwordx4 v[152:153], off
	s_waitcnt vmcnt(8)
	s_waitcnt lgkmcnt(0)
	s_barrier
	s_setprio 1
	s_waitcnt lgkmcnt(0)
	v_mfma_f32_16x16x32_bf16 v[62:65], v[160:163], v[192:195], v[62:65]
	v_mfma_f32_16x16x32_bf16 v[58:61], v[168:171], v[192:195], v[58:61]
	v_mfma_f32_16x16x32_bf16 v[46:49], v[160:163], v[200:203], v[46:49]
	v_mfma_f32_16x16x32_bf16 v[42:45], v[168:171], v[200:203], v[42:45]
	v_mfma_f32_16x16x32_bf16 v[30:33], v[160:163], v[208:211], v[30:33]
	v_mfma_f32_16x16x32_bf16 v[26:29], v[168:171], v[208:211], v[26:29]
	v_mfma_f32_16x16x32_bf16 v[14:17], v[160:163], v[218:221], v[14:17]
	v_mfma_f32_16x16x32_bf16 v[10:13], v[168:171], v[218:221], v[10:13]
	v_mfma_f32_16x16x32_bf16 v[62:65], v[164:167], v[196:199], v[62:65]
	v_mfma_f32_16x16x32_bf16 v[58:61], v[172:175], v[196:199], v[58:61]
	v_mfma_f32_16x16x32_bf16 v[46:49], v[164:167], v[204:207], v[46:49]
	v_mfma_f32_16x16x32_bf16 v[42:45], v[172:175], v[204:207], v[42:45]
	v_mfma_f32_16x16x32_bf16 v[30:33], v[164:167], v[212:215], v[30:33]
	v_mfma_f32_16x16x32_bf16 v[26:29], v[172:175], v[212:215], v[26:29]
	v_mfma_f32_16x16x32_bf16 v[14:17], v[164:167], v[222:225], v[14:17]
	v_mfma_f32_16x16x32_bf16 v[10:13], v[172:175], v[222:225], v[10:13]
	s_setprio 0
	s_setprio 1
	v_mfma_f32_16x16x32_bf16 v[54:57], v[176:179], v[192:195], v[54:57]
	v_mfma_f32_16x16x32_bf16 v[50:53], v[184:187], v[192:195], v[50:53]
	v_mfma_f32_16x16x32_bf16 v[38:41], v[176:179], v[200:203], v[38:41]
	v_mfma_f32_16x16x32_bf16 v[34:37], v[184:187], v[200:203], v[34:37]
	v_mfma_f32_16x16x32_bf16 v[22:25], v[176:179], v[208:211], v[22:25]
	v_mfma_f32_16x16x32_bf16 v[18:21], v[184:187], v[208:211], v[18:21]
	v_mfma_f32_16x16x32_bf16 v[6:9], v[176:179], v[218:221], v[6:9]
	v_mfma_f32_16x16x32_bf16 v[2:5], v[184:187], v[218:221], v[2:5]
	v_mfma_f32_16x16x32_bf16 v[54:57], v[180:183], v[196:199], v[54:57]
	v_mfma_f32_16x16x32_bf16 v[50:53], v[188:191], v[196:199], v[50:53]
	v_mfma_f32_16x16x32_bf16 v[38:41], v[180:183], v[204:207], v[38:41]
	v_mfma_f32_16x16x32_bf16 v[34:37], v[188:191], v[204:207], v[34:37]
	v_mfma_f32_16x16x32_bf16 v[22:25], v[180:183], v[212:215], v[22:25]
	v_mfma_f32_16x16x32_bf16 v[18:21], v[188:191], v[212:215], v[18:21]
	v_mfma_f32_16x16x32_bf16 v[6:9], v[180:183], v[222:225], v[6:9]
	v_mfma_f32_16x16x32_bf16 v[2:5], v[188:191], v[222:225], v[2:5]
	s_setprio 0
	s_barrier
	s_add_i32 s74, s74, 2
	s_add_u32 s76, s76, 0x100
	s_addc_u32 s77, s77, 0
	s_add_u32 s36, s36, 0x100
	s_addc_u32 s52, s52, 0

.LBB0_2628:
	s_ashr_i32 s37, s36, 31
	s_lshl_b64 s[0:1], s[36:37], 18
	v_readlane_b32 s27, v247, 27
	s_add_u32 s38, s27, s0
	v_readlane_b32 s0, v247, 29
	s_addc_u32 s39, s0, s1
	s_and_b64 s[0:1], s[2:3], exec
	s_cselect_b32 s0, s39, s35
	s_cselect_b32 s1, s38, s34
	s_ashr_i32 s27, s26, 31
	s_lshl_b64 s[40:41], s[26:27], 18
	s_add_u32 s40, s13, s40
	s_addc_u32 s41, s30, s41
	s_and_b64 s[52:53], s[2:3], exec
	s_cselect_b32 s27, s41, s77
	s_cselect_b32 s37, s40, s76
	s_add_u32 s74, s34, 0x20080
	s_addc_u32 s75, s35, 0
	s_add_u32 s52, s76, 0x100
	s_addc_u32 s78, s77, 0
	s_mov_b32 s79, -2
	ds_read_b128 v[146:149], v165
	ds_read_b128 v[150:153], v165 offset:1024
	ds_read_b128 v[168:171], v165 offset:2048
	ds_read_b128 v[172:175], v165 offset:3072
	ds_read_b128 v[176:179], v166
	ds_read_b128 v[180:183], v166 offset:1024
	ds_read_b128 v[184:187], v166 offset:2048
	ds_read_b128 v[188:191], v166 offset:3072
	s_add_u32 s34, s74, 0xfffe0080
	s_addc_u32 s35, s75, -1
	s_cmp_eq_u32 s79, 4
	s_cselect_b32 s77, s0, s35
	s_cselect_b32 s76, s1, s34
	s_cselect_b32 s35, s27, s78
	s_cselect_b32 s34, s37, s52
	v_lshl_add_u64 v[226:227], s[74:75], 0, v[138:139]
	s_add_i32 m0, s33, 0xc000
	ds_read_b128 v[192:195], v167
	ds_read_b128 v[196:199], v167 offset:1024
	ds_read_b128 v[200:203], v167 offset:2048
	ds_read_b128 v[204:207], v167 offset:3072
	ds_read_b128 v[208:211], v167 offset:4096
	ds_read_b128 v[212:215], v167 offset:5120
	ds_read_b128 v[218:221], v167 offset:6144
	ds_read_b128 v[222:225], v167 offset:7168
	global_load_lds_dwordx4 v[226:227], off
	v_lshl_add_u64 v[226:227], s[74:75], 0, v[140:141]
	s_add_i32 m0, s33, 0xe000
	s_nop 0
	global_load_lds_dwordx4 v[226:227], off
	s_waitcnt vmcnt(8)
	s_waitcnt lgkmcnt(0)
	s_barrier
	s_setprio 1
	s_waitcnt lgkmcnt(0)
	v_mfma_f32_16x16x32_bf16 v[126:129], v[146:149], v[192:195], 0
	v_mfma_f32_16x16x32_bf16 v[122:125], v[168:171], v[192:195], 0
	v_mfma_f32_16x16x32_bf16 v[114:117], v[146:149], v[200:203], 0
	v_mfma_f32_16x16x32_bf16 v[106:109], v[168:171], v[200:203], 0
	v_mfma_f32_16x16x32_bf16 v[98:101], v[146:149], v[208:211], 0
	v_mfma_f32_16x16x32_bf16 v[90:93], v[168:171], v[208:211], 0
	v_mfma_f32_16x16x32_bf16 v[82:85], v[146:149], v[218:221], 0
	v_mfma_f32_16x16x32_bf16 v[74:77], v[168:171], v[218:221], 0
	v_mfma_f32_16x16x32_bf16 v[126:129], v[150:153], v[196:199], v[126:129]
	v_mfma_f32_16x16x32_bf16 v[122:125], v[172:175], v[196:199], v[122:125]
	v_mfma_f32_16x16x32_bf16 v[114:117], v[150:153], v[204:207], v[114:117]
	v_mfma_f32_16x16x32_bf16 v[106:109], v[172:175], v[204:207], v[106:109]
	v_mfma_f32_16x16x32_bf16 v[98:101], v[150:153], v[212:215], v[98:101]
	v_mfma_f32_16x16x32_bf16 v[90:93], v[172:175], v[212:215], v[90:93]
	v_mfma_f32_16x16x32_bf16 v[82:85], v[150:153], v[222:225], v[82:85]
	v_mfma_f32_16x16x32_bf16 v[74:77], v[172:175], v[222:225], v[74:77]
	s_setprio 0
	s_setprio 1
	v_mfma_f32_16x16x32_bf16 v[118:121], v[176:179], v[192:195], 0
	v_mfma_f32_16x16x32_bf16 v[110:113], v[184:187], v[192:195], 0
	v_mfma_f32_16x16x32_bf16 v[102:105], v[176:179], v[200:203], 0
	v_mfma_f32_16x16x32_bf16 v[94:97], v[184:187], v[200:203], 0
	v_mfma_f32_16x16x32_bf16 v[86:89], v[176:179], v[208:211], 0
	v_mfma_f32_16x16x32_bf16 v[78:81], v[184:187], v[208:211], 0
	v_mfma_f32_16x16x32_bf16 v[70:73], v[176:179], v[218:221], 0
	v_mfma_f32_16x16x32_bf16 v[66:69], v[184:187], v[218:221], 0
	v_mfma_f32_16x16x32_bf16 v[118:121], v[180:183], v[196:199], v[118:121]
	v_mfma_f32_16x16x32_bf16 v[110:113], v[188:191], v[196:199], v[110:113]
	v_mfma_f32_16x16x32_bf16 v[102:105], v[180:183], v[204:207], v[102:105]
	v_mfma_f32_16x16x32_bf16 v[94:97], v[188:191], v[204:207], v[94:97]
	v_mfma_f32_16x16x32_bf16 v[86:89], v[180:183], v[212:215], v[86:89]
	v_mfma_f32_16x16x32_bf16 v[78:81], v[188:191], v[212:215], v[78:81]
	v_mfma_f32_16x16x32_bf16 v[70:73], v[180:183], v[222:225], v[70:73]
	v_mfma_f32_16x16x32_bf16 v[66:69], v[188:191], v[222:225], v[66:69]
	s_setprio 0
	s_barrier
	s_add_i32 s53, s70, s12
	v_lshl_add_u64 v[226:227], s[34:35], 0, v[132:133]
	s_mov_b32 m0, s53
	ds_read_b128 v[192:195], v167 offset:16384
	ds_read_b128 v[196:199], v167 offset:17408
	ds_read_b128 v[200:203], v167 offset:18432
	ds_read_b128 v[204:207], v167 offset:19456
	ds_read_b128 v[208:211], v167 offset:20480
	ds_read_b128 v[212:215], v167 offset:21504
	ds_read_b128 v[218:221], v167 offset:22528
	ds_read_b128 v[222:225], v167 offset:23552
	global_load_lds_dwordx4 v[226:227], off
	s_add_i32 m0, s53, 0x2000
	s_add_u32 s54, s34, 0x20000
	v_lshl_add_u64 v[228:229], s[34:35], 0, v[136:137]
	s_addc_u32 s55, s35, 0
	s_add_i32 s53, s71, s12
	global_load_lds_dwordx4 v[228:229], off
	v_lshl_add_u64 v[230:231], s[54:55], 0, v[132:133]
	s_mov_b32 m0, s53
	v_lshl_add_u64 v[232:233], s[76:77], 0, v[134:135]
	global_load_lds_dwordx4 v[230:231], off
	v_lshl_add_u64 v[230:231], s[54:55], 0, v[136:137]
	s_add_i32 m0, s53, 0x2000
	s_nop 0
	global_load_lds_dwordx4 v[230:231], off
	v_lshl_add_u64 v[230:231], s[76:77], 0, v[130:131]
	s_mov_b32 m0, s33
	s_nop 0
	global_load_lds_dwordx4 v[230:231], off
	s_mov_b32 m0, s47
	s_nop 0
	global_load_lds_dwordx4 v[232:233], off
	s_waitcnt vmcnt(8)
	s_waitcnt lgkmcnt(0)
	s_barrier
	s_setprio 1
	s_waitcnt lgkmcnt(0)
	v_mfma_f32_16x16x32_bf16 v[62:65], v[146:149], v[192:195], 0
	v_mfma_f32_16x16x32_bf16 v[58:61], v[168:171], v[192:195], 0
	v_mfma_f32_16x16x32_bf16 v[50:53], v[146:149], v[200:203], 0
	v_mfma_f32_16x16x32_bf16 v[42:45], v[168:171], v[200:203], 0
	v_mfma_f32_16x16x32_bf16 v[34:37], v[146:149], v[208:211], 0
	v_mfma_f32_16x16x32_bf16 v[26:29], v[168:171], v[208:211], 0
	v_mfma_f32_16x16x32_bf16 v[18:21], v[146:149], v[218:221], 0
	v_mfma_f32_16x16x32_bf16 v[10:13], v[168:171], v[218:221], 0
	v_mfma_f32_16x16x32_bf16 v[62:65], v[150:153], v[196:199], v[62:65]
	v_mfma_f32_16x16x32_bf16 v[58:61], v[172:175], v[196:199], v[58:61]
	v_mfma_f32_16x16x32_bf16 v[50:53], v[150:153], v[204:207], v[50:53]
	v_mfma_f32_16x16x32_bf16 v[42:45], v[172:175], v[204:207], v[42:45]
	v_mfma_f32_16x16x32_bf16 v[34:37], v[150:153], v[212:215], v[34:37]
	v_mfma_f32_16x16x32_bf16 v[26:29], v[172:175], v[212:215], v[26:29]
	v_mfma_f32_16x16x32_bf16 v[18:21], v[150:153], v[222:225], v[18:21]
	v_mfma_f32_16x16x32_bf16 v[10:13], v[172:175], v[222:225], v[10:13]
	s_setprio 0
	s_setprio 1
	v_mfma_f32_16x16x32_bf16 v[54:57], v[176:179], v[192:195], 0
	v_mfma_f32_16x16x32_bf16 v[46:49], v[184:187], v[192:195], 0
	v_mfma_f32_16x16x32_bf16 v[38:41], v[176:179], v[200:203], 0
	v_mfma_f32_16x16x32_bf16 v[30:33], v[184:187], v[200:203], 0
	v_mfma_f32_16x16x32_bf16 v[22:25], v[176:179], v[208:211], 0
	v_mfma_f32_16x16x32_bf16 v[14:17], v[184:187], v[208:211], 0
	v_mfma_f32_16x16x32_bf16 v[6:9], v[176:179], v[218:221], 0
	v_mfma_f32_16x16x32_bf16 v[2:5], v[184:187], v[218:221], 0
	v_mfma_f32_16x16x32_bf16 v[54:57], v[180:183], v[196:199], v[54:57]
	v_mfma_f32_16x16x32_bf16 v[46:49], v[188:191], v[196:199], v[46:49]
	v_mfma_f32_16x16x32_bf16 v[38:41], v[180:183], v[204:207], v[38:41]
	v_mfma_f32_16x16x32_bf16 v[30:33], v[188:191], v[204:207], v[30:33]
	v_mfma_f32_16x16x32_bf16 v[22:25], v[180:183], v[212:215], v[22:25]
	v_mfma_f32_16x16x32_bf16 v[14:17], v[188:191], v[212:215], v[14:17]
	v_mfma_f32_16x16x32_bf16 v[6:9], v[180:183], v[222:225], v[6:9]
	v_mfma_f32_16x16x32_bf16 v[2:5], v[188:191], v[222:225], v[2:5]
	s_setprio 0
	s_barrier
	s_add_i32 s53, 0, 0x18000
	s_add_i32 s62, 0, 0x1c000
	v_add_u32_e32 v172, s53, v162
	v_add_u32_e32 v188, s62, v162
	ds_read_b128 v[146:149], v172
	ds_read_b128 v[150:153], v172 offset:1024
	ds_read_b128 v[168:171], v172 offset:2048
	ds_read_b128 v[172:175], v172 offset:3072
	ds_read_b128 v[176:179], v188
	ds_read_b128 v[180:183], v188 offset:1024
	ds_read_b128 v[184:187], v188 offset:2048
	ds_read_b128 v[188:191], v188 offset:3072
	s_add_u32 s54, s76, 0x20000
	s_addc_u32 s55, s77, 0
	s_mov_b32 m0, s56
	v_lshl_add_u64 v[234:235], s[54:55], 0, v[130:131]
	ds_read_b128 v[192:195], v167 offset:32768
	ds_read_b128 v[196:199], v167 offset:33792
	ds_read_b128 v[200:203], v167 offset:34816
	ds_read_b128 v[204:207], v167 offset:35840
	ds_read_b128 v[208:211], v167 offset:36864
	ds_read_b128 v[212:215], v167 offset:37888
	ds_read_b128 v[218:221], v167 offset:38912
	ds_read_b128 v[222:225], v167 offset:39936
	global_load_lds_dwordx4 v[234:235], off
	v_lshl_add_u64 v[234:235], s[54:55], 0, v[134:135]
	s_mov_b32 m0, s57
	s_nop 0
	global_load_lds_dwordx4 v[234:235], off
	s_waitcnt vmcnt(8)
	s_waitcnt lgkmcnt(0)
	s_barrier
	s_setprio 1
	s_waitcnt lgkmcnt(0)
	v_mfma_f32_16x16x32_bf16 v[126:129], v[146:149], v[192:195], v[126:129]
	v_mfma_f32_16x16x32_bf16 v[122:125], v[168:171], v[192:195], v[122:125]
	v_mfma_f32_16x16x32_bf16 v[114:117], v[146:149], v[200:203], v[114:117]
	v_mfma_f32_16x16x32_bf16 v[106:109], v[168:171], v[200:203], v[106:109]
	v_mfma_f32_16x16x32_bf16 v[98:101], v[146:149], v[208:211], v[98:101]
	v_mfma_f32_16x16x32_bf16 v[90:93], v[168:171], v[208:211], v[90:93]
	v_mfma_f32_16x16x32_bf16 v[82:85], v[146:149], v[218:221], v[82:85]
	v_mfma_f32_16x16x32_bf16 v[74:77], v[168:171], v[218:221], v[74:77]
	v_mfma_f32_16x16x32_bf16 v[126:129], v[150:153], v[196:199], v[126:129]
	v_mfma_f32_16x16x32_bf16 v[122:125], v[172:175], v[196:199], v[122:125]
	v_mfma_f32_16x16x32_bf16 v[114:117], v[150:153], v[204:207], v[114:117]
	v_mfma_f32_16x16x32_bf16 v[106:109], v[172:175], v[204:207], v[106:109]
	v_mfma_f32_16x16x32_bf16 v[98:101], v[150:153], v[212:215], v[98:101]
	v_mfma_f32_16x16x32_bf16 v[90:93], v[172:175], v[212:215], v[90:93]
	v_mfma_f32_16x16x32_bf16 v[82:85], v[150:153], v[222:225], v[82:85]
	v_mfma_f32_16x16x32_bf16 v[74:77], v[172:175], v[222:225], v[74:77]
	s_setprio 0
	s_setprio 1
	v_mfma_f32_16x16x32_bf16 v[118:121], v[176:179], v[192:195], v[118:121]
	v_mfma_f32_16x16x32_bf16 v[110:113], v[184:187], v[192:195], v[110:113]
	v_mfma_f32_16x16x32_bf16 v[102:105], v[176:179], v[200:203], v[102:105]
	v_mfma_f32_16x16x32_bf16 v[94:97], v[184:187], v[200:203], v[94:97]
	v_mfma_f32_16x16x32_bf16 v[86:89], v[176:179], v[208:211], v[86:89]
	v_mfma_f32_16x16x32_bf16 v[78:81], v[184:187], v[208:211], v[78:81]
	v_mfma_f32_16x16x32_bf16 v[70:73], v[176:179], v[218:221], v[70:73]
	v_mfma_f32_16x16x32_bf16 v[66:69], v[184:187], v[218:221], v[66:69]
	v_mfma_f32_16x16x32_bf16 v[118:121], v[180:183], v[196:199], v[118:121]
	v_mfma_f32_16x16x32_bf16 v[110:113], v[188:191], v[196:199], v[110:113]
	v_mfma_f32_16x16x32_bf16 v[102:105], v[180:183], v[204:207], v[102:105]
	v_mfma_f32_16x16x32_bf16 v[94:97], v[188:191], v[204:207], v[94:97]
	v_mfma_f32_16x16x32_bf16 v[86:89], v[180:183], v[212:215], v[86:89]
	v_mfma_f32_16x16x32_bf16 v[78:81], v[188:191], v[212:215], v[78:81]
	v_mfma_f32_16x16x32_bf16 v[70:73], v[180:183], v[222:225], v[70:73]
	v_mfma_f32_16x16x32_bf16 v[66:69], v[188:191], v[222:225], v[66:69]
	s_setprio 0
	s_barrier
	s_add_i32 s53, s53, s12
	v_lshl_add_u64 v[226:227], v[226:227], 0, s[8:9]
	s_mov_b32 m0, s53
	ds_read_b128 v[192:195], v167 offset:49152
	ds_read_b128 v[196:199], v167 offset:50176
	ds_read_b128 v[200:203], v167 offset:51200
	ds_read_b128 v[204:207], v167 offset:52224
	ds_read_b128 v[208:211], v167 offset:53248
	ds_read_b128 v[212:215], v167 offset:54272
	ds_read_b128 v[218:221], v167 offset:55296
	ds_read_b128 v[222:225], v167 offset:56320
	global_load_lds_dwordx4 v[226:227], off
	s_add_i32 m0, s53, 0x2000
	s_add_u32 s34, s34, 0x20080
	v_lshl_add_u64 v[226:227], v[228:229], 0, s[8:9]
	s_addc_u32 s35, s35, 0
	s_add_i32 s53, s62, s12
	global_load_lds_dwordx4 v[226:227], off
	v_lshl_add_u64 v[226:227], s[34:35], 0, v[132:133]
	s_mov_b32 m0, s53
	s_nop 0
	global_load_lds_dwordx4 v[226:227], off
	v_lshl_add_u64 v[226:227], s[34:35], 0, v[136:137]
	s_add_i32 m0, s53, 0x2000
	s_nop 0
	global_load_lds_dwordx4 v[226:227], off
	v_lshl_add_u64 v[226:227], v[230:231], 0, s[8:9]
	s_mov_b32 m0, s59
	s_nop 0
	global_load_lds_dwordx4 v[226:227], off
	v_lshl_add_u64 v[226:227], v[232:233], 0, s[8:9]
	s_mov_b32 m0, s60
	s_nop 0
	global_load_lds_dwordx4 v[226:227], off
	s_waitcnt vmcnt(8)
	s_waitcnt lgkmcnt(0)
	s_barrier
	s_setprio 1
	s_waitcnt lgkmcnt(0)
	v_mfma_f32_16x16x32_bf16 v[62:65], v[146:149], v[192:195], v[62:65]
	v_mfma_f32_16x16x32_bf16 v[58:61], v[168:171], v[192:195], v[58:61]
	v_mfma_f32_16x16x32_bf16 v[50:53], v[146:149], v[200:203], v[50:53]
	v_mfma_f32_16x16x32_bf16 v[42:45], v[168:171], v[200:203], v[42:45]
	v_mfma_f32_16x16x32_bf16 v[34:37], v[146:149], v[208:211], v[34:37]
	v_mfma_f32_16x16x32_bf16 v[26:29], v[168:171], v[208:211], v[26:29]
	v_mfma_f32_16x16x32_bf16 v[18:21], v[146:149], v[218:221], v[18:21]
	v_mfma_f32_16x16x32_bf16 v[10:13], v[168:171], v[218:221], v[10:13]
	v_mfma_f32_16x16x32_bf16 v[62:65], v[150:153], v[196:199], v[62:65]
	v_mfma_f32_16x16x32_bf16 v[58:61], v[172:175], v[196:199], v[58:61]
	v_mfma_f32_16x16x32_bf16 v[50:53], v[150:153], v[204:207], v[50:53]
	v_mfma_f32_16x16x32_bf16 v[42:45], v[172:175], v[204:207], v[42:45]
	v_mfma_f32_16x16x32_bf16 v[34:37], v[150:153], v[212:215], v[34:37]
	v_mfma_f32_16x16x32_bf16 v[26:29], v[172:175], v[212:215], v[26:29]
	v_mfma_f32_16x16x32_bf16 v[18:21], v[150:153], v[222:225], v[18:21]
	v_mfma_f32_16x16x32_bf16 v[10:13], v[172:175], v[222:225], v[10:13]
	s_setprio 0
	s_setprio 1
	v_mfma_f32_16x16x32_bf16 v[54:57], v[176:179], v[192:195], v[54:57]
	v_mfma_f32_16x16x32_bf16 v[46:49], v[184:187], v[192:195], v[46:49]
	v_mfma_f32_16x16x32_bf16 v[38:41], v[176:179], v[200:203], v[38:41]
	v_mfma_f32_16x16x32_bf16 v[30:33], v[184:187], v[200:203], v[30:33]
	v_mfma_f32_16x16x32_bf16 v[22:25], v[176:179], v[208:211], v[22:25]
	v_mfma_f32_16x16x32_bf16 v[14:17], v[184:187], v[208:211], v[14:17]
	v_mfma_f32_16x16x32_bf16 v[6:9], v[176:179], v[218:221], v[6:9]
	v_mfma_f32_16x16x32_bf16 v[2:5], v[184:187], v[218:221], v[2:5]
	v_mfma_f32_16x16x32_bf16 v[54:57], v[180:183], v[196:199], v[54:57]
	v_mfma_f32_16x16x32_bf16 v[46:49], v[188:191], v[196:199], v[46:49]
	v_mfma_f32_16x16x32_bf16 v[38:41], v[180:183], v[204:207], v[38:41]
	v_mfma_f32_16x16x32_bf16 v[30:33], v[188:191], v[204:207], v[30:33]
	v_mfma_f32_16x16x32_bf16 v[22:25], v[180:183], v[212:215], v[22:25]
	v_mfma_f32_16x16x32_bf16 v[14:17], v[188:191], v[212:215], v[14:17]
	v_mfma_f32_16x16x32_bf16 v[6:9], v[180:183], v[222:225], v[6:9]
	v_mfma_f32_16x16x32_bf16 v[2:5], v[188:191], v[222:225], v[2:5]
	s_setprio 0
	s_barrier
	s_add_i32 s79, s79, 2
	s_add_u32 s74, s74, 0x100
	s_addc_u32 s75, s75, 0
	s_add_u32 s52, s52, 0x100
	s_addc_u32 s78, s78, 0

.LBB0_2658:
	s_ashr_i32 s37, s36, 31
	s_lshl_b64 s[0:1], s[36:37], 18
	v_readlane_b32 s27, v247, 43
	s_add_u32 s38, s27, s0
	v_readlane_b32 s0, v247, 25
	s_addc_u32 s39, s0, s1
	s_and_b64 s[0:1], s[2:3], exec
	s_cselect_b32 s0, s39, s75
	s_cselect_b32 s1, s38, s74
	s_ashr_i32 s27, s26, 31
	s_lshl_b64 s[34:35], s[26:27], 18
	s_add_u32 s40, s30, s34
	s_addc_u32 s41, s31, s35
	s_and_b64 s[34:35], s[2:3], exec
	s_cselect_b32 s27, s41, s77
	s_cselect_b32 s37, s40, s76
	s_add_u32 s74, s74, 0x20080
	s_addc_u32 s75, s75, 0
	s_add_u32 s52, s76, 0x100
	s_addc_u32 s71, s77, 0
	s_mov_b32 s72, -2
	ds_read_b128 v[146:149], v1
	ds_read_b128 v[160:163], v1 offset:1024
	ds_read_b128 v[164:167], v1 offset:2048
	ds_read_b128 v[168:171], v1 offset:3072
	ds_read_b128 v[172:175], v154
	ds_read_b128 v[176:179], v154 offset:1024
	ds_read_b128 v[180:183], v154 offset:2048
	ds_read_b128 v[184:187], v154 offset:3072
	s_add_u32 s34, s74, 0xfffe0080
	s_addc_u32 s35, s75, -1
	s_cmp_eq_u32 s72, 4
	s_cselect_b32 s77, s0, s35
	s_cselect_b32 s76, s1, s34
	s_cselect_b32 s35, s27, s71
	s_cselect_b32 s34, s37, s52
	v_lshl_add_u64 v[150:151], s[74:75], 0, v[138:139]
	s_add_i32 m0, s33, 0xc000
	ds_read_b128 v[188:191], v155
	ds_read_b128 v[192:195], v155 offset:1024
	ds_read_b128 v[196:199], v155 offset:2048
	ds_read_b128 v[200:203], v155 offset:3072
	ds_read_b128 v[204:207], v155 offset:4096
	ds_read_b128 v[208:211], v155 offset:5120
	ds_read_b128 v[212:215], v155 offset:6144
	ds_read_b128 v[218:221], v155 offset:7168
	global_load_lds_dwordx4 v[150:151], off
	v_lshl_add_u64 v[150:151], s[74:75], 0, v[140:141]
	s_add_i32 m0, s33, 0xe000
	s_nop 0
	global_load_lds_dwordx4 v[150:151], off
	s_waitcnt vmcnt(8)
	s_waitcnt lgkmcnt(0)
	s_barrier
	s_setprio 1
	s_waitcnt lgkmcnt(0)
	v_mfma_f32_16x16x32_bf16 v[126:129], v[146:149], v[188:191], 0
	v_mfma_f32_16x16x32_bf16 v[122:125], v[164:167], v[188:191], 0
	v_mfma_f32_16x16x32_bf16 v[110:113], v[146:149], v[196:199], 0
	v_mfma_f32_16x16x32_bf16 v[106:109], v[164:167], v[196:199], 0
	v_mfma_f32_16x16x32_bf16 v[94:97], v[146:149], v[204:207], 0
	v_mfma_f32_16x16x32_bf16 v[90:93], v[164:167], v[204:207], 0
	v_mfma_f32_16x16x32_bf16 v[78:81], v[146:149], v[212:215], 0
	v_mfma_f32_16x16x32_bf16 v[74:77], v[164:167], v[212:215], 0
	v_mfma_f32_16x16x32_bf16 v[126:129], v[160:163], v[192:195], v[126:129]
	v_mfma_f32_16x16x32_bf16 v[122:125], v[168:171], v[192:195], v[122:125]
	v_mfma_f32_16x16x32_bf16 v[110:113], v[160:163], v[200:203], v[110:113]
	v_mfma_f32_16x16x32_bf16 v[106:109], v[168:171], v[200:203], v[106:109]
	v_mfma_f32_16x16x32_bf16 v[94:97], v[160:163], v[208:211], v[94:97]
	v_mfma_f32_16x16x32_bf16 v[90:93], v[168:171], v[208:211], v[90:93]
	v_mfma_f32_16x16x32_bf16 v[78:81], v[160:163], v[218:221], v[78:81]
	v_mfma_f32_16x16x32_bf16 v[74:77], v[168:171], v[218:221], v[74:77]
	s_setprio 0
	s_setprio 1
	v_mfma_f32_16x16x32_bf16 v[118:121], v[172:175], v[188:191], 0
	v_mfma_f32_16x16x32_bf16 v[114:117], v[180:183], v[188:191], 0
	v_mfma_f32_16x16x32_bf16 v[102:105], v[172:175], v[196:199], 0
	v_mfma_f32_16x16x32_bf16 v[98:101], v[180:183], v[196:199], 0
	v_mfma_f32_16x16x32_bf16 v[86:89], v[172:175], v[204:207], 0
	v_mfma_f32_16x16x32_bf16 v[82:85], v[180:183], v[204:207], 0
	v_mfma_f32_16x16x32_bf16 v[70:73], v[172:175], v[212:215], 0
	v_mfma_f32_16x16x32_bf16 v[66:69], v[180:183], v[212:215], 0
	v_mfma_f32_16x16x32_bf16 v[118:121], v[176:179], v[192:195], v[118:121]
	v_mfma_f32_16x16x32_bf16 v[114:117], v[184:187], v[192:195], v[114:117]
	v_mfma_f32_16x16x32_bf16 v[102:105], v[176:179], v[200:203], v[102:105]
	v_mfma_f32_16x16x32_bf16 v[98:101], v[184:187], v[200:203], v[98:101]
	v_mfma_f32_16x16x32_bf16 v[86:89], v[176:179], v[208:211], v[86:89]
	v_mfma_f32_16x16x32_bf16 v[82:85], v[184:187], v[208:211], v[82:85]
	v_mfma_f32_16x16x32_bf16 v[70:73], v[176:179], v[218:221], v[70:73]
	v_mfma_f32_16x16x32_bf16 v[66:69], v[184:187], v[218:221], v[66:69]
	s_setprio 0
	s_barrier
	s_add_i32 s53, s60, s13
	v_lshl_add_u64 v[150:151], s[34:35], 0, v[132:133]
	s_mov_b32 m0, s53
	ds_read_b128 v[188:191], v155 offset:16384
	ds_read_b128 v[192:195], v155 offset:17408
	ds_read_b128 v[196:199], v155 offset:18432
	ds_read_b128 v[200:203], v155 offset:19456
	ds_read_b128 v[204:207], v155 offset:20480
	ds_read_b128 v[208:211], v155 offset:21504
	ds_read_b128 v[212:215], v155 offset:22528
	ds_read_b128 v[218:221], v155 offset:23552
	global_load_lds_dwordx4 v[150:151], off
	s_add_i32 m0, s53, 0x2000
	s_add_u32 s62, s34, 0x20000
	v_lshl_add_u64 v[222:223], s[34:35], 0, v[136:137]
	s_addc_u32 s63, s35, 0
	s_add_i32 s53, s61, s13
	global_load_lds_dwordx4 v[222:223], off
	v_lshl_add_u64 v[224:225], s[62:63], 0, v[132:133]
	s_mov_b32 m0, s53
	v_lshl_add_u64 v[226:227], s[76:77], 0, v[134:135]
	global_load_lds_dwordx4 v[224:225], off
	v_lshl_add_u64 v[224:225], s[62:63], 0, v[136:137]
	s_add_i32 m0, s53, 0x2000
	s_nop 0
	global_load_lds_dwordx4 v[224:225], off
	v_lshl_add_u64 v[224:225], s[76:77], 0, v[130:131]
	s_mov_b32 m0, s33
	s_nop 0
	global_load_lds_dwordx4 v[224:225], off
	s_mov_b32 m0, s47
	s_nop 0
	global_load_lds_dwordx4 v[226:227], off
	s_waitcnt vmcnt(8)
	s_waitcnt lgkmcnt(0)
	s_barrier
	s_setprio 1
	s_waitcnt lgkmcnt(0)
	v_mfma_f32_16x16x32_bf16 v[62:65], v[146:149], v[188:191], 0
	v_mfma_f32_16x16x32_bf16 v[58:61], v[164:167], v[188:191], 0
	v_mfma_f32_16x16x32_bf16 v[50:53], v[146:149], v[196:199], 0
	v_mfma_f32_16x16x32_bf16 v[42:45], v[164:167], v[196:199], 0
	v_mfma_f32_16x16x32_bf16 v[34:37], v[146:149], v[204:207], 0
	v_mfma_f32_16x16x32_bf16 v[26:29], v[164:167], v[204:207], 0
	v_mfma_f32_16x16x32_bf16 v[18:21], v[146:149], v[212:215], 0
	v_mfma_f32_16x16x32_bf16 v[10:13], v[164:167], v[212:215], 0
	v_mfma_f32_16x16x32_bf16 v[62:65], v[160:163], v[192:195], v[62:65]
	v_mfma_f32_16x16x32_bf16 v[58:61], v[168:171], v[192:195], v[58:61]
	v_mfma_f32_16x16x32_bf16 v[50:53], v[160:163], v[200:203], v[50:53]
	v_mfma_f32_16x16x32_bf16 v[42:45], v[168:171], v[200:203], v[42:45]
	v_mfma_f32_16x16x32_bf16 v[34:37], v[160:163], v[208:211], v[34:37]
	v_mfma_f32_16x16x32_bf16 v[26:29], v[168:171], v[208:211], v[26:29]
	v_mfma_f32_16x16x32_bf16 v[18:21], v[160:163], v[218:221], v[18:21]
	v_mfma_f32_16x16x32_bf16 v[10:13], v[168:171], v[218:221], v[10:13]
	s_setprio 0
	s_setprio 1
	v_mfma_f32_16x16x32_bf16 v[54:57], v[172:175], v[188:191], 0
	v_mfma_f32_16x16x32_bf16 v[46:49], v[180:183], v[188:191], 0
	v_mfma_f32_16x16x32_bf16 v[38:41], v[172:175], v[196:199], 0
	v_mfma_f32_16x16x32_bf16 v[30:33], v[180:183], v[196:199], 0
	v_mfma_f32_16x16x32_bf16 v[22:25], v[172:175], v[204:207], 0
	v_mfma_f32_16x16x32_bf16 v[14:17], v[180:183], v[204:207], 0
	v_mfma_f32_16x16x32_bf16 v[6:9], v[172:175], v[212:215], 0
	v_mfma_f32_16x16x32_bf16 v[2:5], v[180:183], v[212:215], 0
	v_mfma_f32_16x16x32_bf16 v[54:57], v[176:179], v[192:195], v[54:57]
	v_mfma_f32_16x16x32_bf16 v[46:49], v[184:187], v[192:195], v[46:49]
	v_mfma_f32_16x16x32_bf16 v[38:41], v[176:179], v[200:203], v[38:41]
	v_mfma_f32_16x16x32_bf16 v[30:33], v[184:187], v[200:203], v[30:33]
	v_mfma_f32_16x16x32_bf16 v[22:25], v[176:179], v[208:211], v[22:25]
	v_mfma_f32_16x16x32_bf16 v[14:17], v[184:187], v[208:211], v[14:17]
	v_mfma_f32_16x16x32_bf16 v[6:9], v[176:179], v[218:221], v[6:9]
	v_mfma_f32_16x16x32_bf16 v[2:5], v[184:187], v[218:221], v[2:5]
	s_setprio 0
	s_barrier
	s_add_i32 s53, 0, 0x18000
	v_add_u32_e32 v156, s53, v153
	s_add_i32 s66, 0, 0x1c000
	ds_read_b128 v[146:149], v156
	ds_read_b128 v[160:163], v156 offset:1024
	ds_read_b128 v[164:167], v156 offset:2048
	ds_read_b128 v[168:171], v156 offset:3072
	v_add_u32_e32 v156, s66, v153
	ds_read_b128 v[172:175], v156
	ds_read_b128 v[176:179], v156 offset:1024
	ds_read_b128 v[180:183], v156 offset:2048
	ds_read_b128 v[184:187], v156 offset:3072
	s_add_u32 s62, s76, 0x20000
	s_addc_u32 s63, s77, 0
	s_mov_b32 m0, s54
	v_lshl_add_u64 v[228:229], s[62:63], 0, v[130:131]
	ds_read_b128 v[188:191], v155 offset:32768
	ds_read_b128 v[192:195], v155 offset:33792
	ds_read_b128 v[196:199], v155 offset:34816
	ds_read_b128 v[200:203], v155 offset:35840
	ds_read_b128 v[204:207], v155 offset:36864
	ds_read_b128 v[208:211], v155 offset:37888
	ds_read_b128 v[212:215], v155 offset:38912
	ds_read_b128 v[218:221], v155 offset:39936
	global_load_lds_dwordx4 v[228:229], off
	v_lshl_add_u64 v[228:229], s[62:63], 0, v[134:135]
	s_mov_b32 m0, s55
	s_nop 0
	global_load_lds_dwordx4 v[228:229], off
	s_waitcnt vmcnt(8)
	s_waitcnt lgkmcnt(0)
	s_barrier
	s_setprio 1
	s_waitcnt lgkmcnt(0)
	v_mfma_f32_16x16x32_bf16 v[126:129], v[146:149], v[188:191], v[126:129]
	v_mfma_f32_16x16x32_bf16 v[122:125], v[164:167], v[188:191], v[122:125]
	v_mfma_f32_16x16x32_bf16 v[110:113], v[146:149], v[196:199], v[110:113]
	v_mfma_f32_16x16x32_bf16 v[106:109], v[164:167], v[196:199], v[106:109]
	v_mfma_f32_16x16x32_bf16 v[94:97], v[146:149], v[204:207], v[94:97]
	v_mfma_f32_16x16x32_bf16 v[90:93], v[164:167], v[204:207], v[90:93]
	v_mfma_f32_16x16x32_bf16 v[78:81], v[146:149], v[212:215], v[78:81]
	v_mfma_f32_16x16x32_bf16 v[74:77], v[164:167], v[212:215], v[74:77]
	v_mfma_f32_16x16x32_bf16 v[126:129], v[160:163], v[192:195], v[126:129]
	v_mfma_f32_16x16x32_bf16 v[122:125], v[168:171], v[192:195], v[122:125]
	v_mfma_f32_16x16x32_bf16 v[110:113], v[160:163], v[200:203], v[110:113]
	v_mfma_f32_16x16x32_bf16 v[106:109], v[168:171], v[200:203], v[106:109]
	v_mfma_f32_16x16x32_bf16 v[94:97], v[160:163], v[208:211], v[94:97]
	v_mfma_f32_16x16x32_bf16 v[90:93], v[168:171], v[208:211], v[90:93]
	v_mfma_f32_16x16x32_bf16 v[78:81], v[160:163], v[218:221], v[78:81]
	v_mfma_f32_16x16x32_bf16 v[74:77], v[168:171], v[218:221], v[74:77]
	s_setprio 0
	s_setprio 1
	v_mfma_f32_16x16x32_bf16 v[118:121], v[172:175], v[188:191], v[118:121]
	v_mfma_f32_16x16x32_bf16 v[114:117], v[180:183], v[188:191], v[114:117]
	v_mfma_f32_16x16x32_bf16 v[102:105], v[172:175], v[196:199], v[102:105]
	v_mfma_f32_16x16x32_bf16 v[98:101], v[180:183], v[196:199], v[98:101]
	v_mfma_f32_16x16x32_bf16 v[86:89], v[172:175], v[204:207], v[86:89]
	v_mfma_f32_16x16x32_bf16 v[82:85], v[180:183], v[204:207], v[82:85]
	v_mfma_f32_16x16x32_bf16 v[70:73], v[172:175], v[212:215], v[70:73]
	v_mfma_f32_16x16x32_bf16 v[66:69], v[180:183], v[212:215], v[66:69]
	v_mfma_f32_16x16x32_bf16 v[118:121], v[176:179], v[192:195], v[118:121]
	v_mfma_f32_16x16x32_bf16 v[114:117], v[184:187], v[192:195], v[114:117]
	v_mfma_f32_16x16x32_bf16 v[102:105], v[176:179], v[200:203], v[102:105]
	v_mfma_f32_16x16x32_bf16 v[98:101], v[184:187], v[200:203], v[98:101]
	v_mfma_f32_16x16x32_bf16 v[86:89], v[176:179], v[208:211], v[86:89]
	v_mfma_f32_16x16x32_bf16 v[82:85], v[184:187], v[208:211], v[82:85]
	v_mfma_f32_16x16x32_bf16 v[70:73], v[176:179], v[218:221], v[70:73]
	v_mfma_f32_16x16x32_bf16 v[66:69], v[184:187], v[218:221], v[66:69]
	s_setprio 0
	s_barrier
	s_add_i32 s53, s53, s13
	v_lshl_add_u64 v[150:151], v[150:151], 0, s[8:9]
	s_mov_b32 m0, s53
	ds_read_b128 v[188:191], v155 offset:49152
	ds_read_b128 v[192:195], v155 offset:50176
	ds_read_b128 v[196:199], v155 offset:51200
	ds_read_b128 v[200:203], v155 offset:52224
	ds_read_b128 v[204:207], v155 offset:53248
	ds_read_b128 v[208:211], v155 offset:54272
	ds_read_b128 v[212:215], v155 offset:55296
	ds_read_b128 v[218:221], v155 offset:56320
	global_load_lds_dwordx4 v[150:151], off
	s_add_i32 m0, s53, 0x2000
	s_add_u32 s34, s34, 0x20080
	v_lshl_add_u64 v[150:151], v[222:223], 0, s[8:9]
	s_addc_u32 s35, s35, 0
	s_add_i32 s53, s66, s13
	global_load_lds_dwordx4 v[150:151], off
	v_lshl_add_u64 v[150:151], s[34:35], 0, v[132:133]
	s_mov_b32 m0, s53
	s_nop 0
	global_load_lds_dwordx4 v[150:151], off
	v_lshl_add_u64 v[150:151], s[34:35], 0, v[136:137]
	s_add_i32 m0, s53, 0x2000
	s_nop 0
	global_load_lds_dwordx4 v[150:151], off
	v_lshl_add_u64 v[150:151], v[224:225], 0, s[8:9]
	s_mov_b32 m0, s57
	s_nop 0
	global_load_lds_dwordx4 v[150:151], off
	v_lshl_add_u64 v[150:151], v[226:227], 0, s[8:9]
	s_mov_b32 m0, s58
	s_nop 0
	global_load_lds_dwordx4 v[150:151], off
	s_waitcnt vmcnt(8)
	s_waitcnt lgkmcnt(0)
	s_barrier
	s_setprio 1
	s_waitcnt lgkmcnt(0)
	v_mfma_f32_16x16x32_bf16 v[62:65], v[146:149], v[188:191], v[62:65]
	v_mfma_f32_16x16x32_bf16 v[58:61], v[164:167], v[188:191], v[58:61]
	v_mfma_f32_16x16x32_bf16 v[50:53], v[146:149], v[196:199], v[50:53]
	v_mfma_f32_16x16x32_bf16 v[42:45], v[164:167], v[196:199], v[42:45]
	v_mfma_f32_16x16x32_bf16 v[34:37], v[146:149], v[204:207], v[34:37]
	v_mfma_f32_16x16x32_bf16 v[26:29], v[164:167], v[204:207], v[26:29]
	v_mfma_f32_16x16x32_bf16 v[18:21], v[146:149], v[212:215], v[18:21]
	v_mfma_f32_16x16x32_bf16 v[10:13], v[164:167], v[212:215], v[10:13]
	v_mfma_f32_16x16x32_bf16 v[62:65], v[160:163], v[192:195], v[62:65]
	v_mfma_f32_16x16x32_bf16 v[58:61], v[168:171], v[192:195], v[58:61]
	v_mfma_f32_16x16x32_bf16 v[50:53], v[160:163], v[200:203], v[50:53]
	v_mfma_f32_16x16x32_bf16 v[42:45], v[168:171], v[200:203], v[42:45]
	v_mfma_f32_16x16x32_bf16 v[34:37], v[160:163], v[208:211], v[34:37]
	v_mfma_f32_16x16x32_bf16 v[26:29], v[168:171], v[208:211], v[26:29]
	v_mfma_f32_16x16x32_bf16 v[18:21], v[160:163], v[218:221], v[18:21]
	v_mfma_f32_16x16x32_bf16 v[10:13], v[168:171], v[218:221], v[10:13]
	s_setprio 0
	s_setprio 1
	v_mfma_f32_16x16x32_bf16 v[54:57], v[172:175], v[188:191], v[54:57]
	v_mfma_f32_16x16x32_bf16 v[46:49], v[180:183], v[188:191], v[46:49]
	v_mfma_f32_16x16x32_bf16 v[38:41], v[172:175], v[196:199], v[38:41]
	v_mfma_f32_16x16x32_bf16 v[30:33], v[180:183], v[196:199], v[30:33]
	v_mfma_f32_16x16x32_bf16 v[22:25], v[172:175], v[204:207], v[22:25]
	v_mfma_f32_16x16x32_bf16 v[14:17], v[180:183], v[204:207], v[14:17]
	v_mfma_f32_16x16x32_bf16 v[6:9], v[172:175], v[212:215], v[6:9]
	v_mfma_f32_16x16x32_bf16 v[2:5], v[180:183], v[212:215], v[2:5]
	v_mfma_f32_16x16x32_bf16 v[54:57], v[176:179], v[192:195], v[54:57]
	v_mfma_f32_16x16x32_bf16 v[46:49], v[184:187], v[192:195], v[46:49]
	v_mfma_f32_16x16x32_bf16 v[38:41], v[176:179], v[200:203], v[38:41]
	v_mfma_f32_16x16x32_bf16 v[30:33], v[184:187], v[200:203], v[30:33]
	v_mfma_f32_16x16x32_bf16 v[22:25], v[176:179], v[208:211], v[22:25]
	v_mfma_f32_16x16x32_bf16 v[14:17], v[184:187], v[208:211], v[14:17]
	v_mfma_f32_16x16x32_bf16 v[6:9], v[176:179], v[218:221], v[6:9]
	v_mfma_f32_16x16x32_bf16 v[2:5], v[184:187], v[218:221], v[2:5]
	s_setprio 0
	s_barrier
	s_add_i32 s72, s72, 2
	s_add_u32 s74, s74, 0x100
	s_addc_u32 s75, s75, 0
	s_add_u32 s52, s52, 0x100
	s_addc_u32 s71, s71, 0

.LBB0_2937:
	s_ashr_i32 s39, s38, 31
	s_lshl_b64 s[0:1], s[38:39], 20
	v_readlane_b32 s34, v247, 33
	v_readlane_b32 s35, v247, 34
	s_add_u32 s40, s34, s0
	s_addc_u32 s41, s35, s1
	s_and_b64 s[0:1], s[2:3], exec
	s_cselect_b32 s0, s41, s47
	s_cselect_b32 s1, s40, s46
	s_ashr_i32 s37, s36, 31
	s_lshl_b64 s[34:35], s[36:37], 20
	s_add_u32 s42, s13, s34
	s_addc_u32 s43, s30, s35
	s_and_b64 s[34:35], s[2:3], exec
	s_cselect_b32 s37, s43, s69
	s_cselect_b32 s39, s42, s68
	s_add_u32 s46, s46, 0x80080
	s_addc_u32 s47, s47, 0
	s_add_u32 s70, s68, 0x100
	s_addc_u32 s71, s69, 0
	s_mov_b32 s72, -2
	ds_read_b128 v[130:133], v174
	ds_read_b128 v[134:137], v174 offset:1024
	ds_read_b128 v[138:141], v174 offset:2048
	ds_read_b128 v[158:161], v174 offset:3072
	ds_read_b128 v[162:165], v175
	ds_read_b128 v[166:169], v175 offset:1024
	ds_read_b128 v[178:181], v175 offset:2048
	ds_read_b128 v[182:185], v175 offset:3072
	s_add_u32 s34, s46, 0xfff80080
	s_addc_u32 s35, s47, -1
	s_cmp_eq_u32 s72, 28
	s_cselect_b32 s69, s0, s35
	s_cselect_b32 s68, s1, s34
	s_cselect_b32 s35, s37, s71
	s_cselect_b32 s34, s39, s70
	v_lshl_add_u64 v[170:171], s[46:47], 0, v[150:151]
	s_add_i32 m0, s33, 0xc000
	ds_read_b128 v[186:189], v176
	ds_read_b128 v[190:193], v176 offset:1024
	ds_read_b128 v[194:197], v176 offset:2048
	ds_read_b128 v[198:201], v176 offset:3072
	ds_read_b128 v[202:205], v176 offset:4096
	ds_read_b128 v[206:209], v176 offset:5120
	ds_read_b128 v[210:213], v176 offset:6144
	ds_read_b128 v[218:221], v176 offset:7168
	global_load_lds_dwordx4 v[170:171], off
	v_lshl_add_u64 v[170:171], s[46:47], 0, v[152:153]
	s_add_i32 m0, s33, 0xe000
	s_nop 0
	global_load_lds_dwordx4 v[170:171], off
	s_waitcnt vmcnt(8)
	s_waitcnt lgkmcnt(0)
	s_barrier
	s_setprio 1
	s_waitcnt lgkmcnt(0)
	v_mfma_f32_16x16x32_bf16 v[126:129], v[130:133], v[186:189], 0
	v_mfma_f32_16x16x32_bf16 v[122:125], v[138:141], v[186:189], 0
	v_mfma_f32_16x16x32_bf16 v[110:113], v[130:133], v[194:197], 0
	v_mfma_f32_16x16x32_bf16 v[106:109], v[138:141], v[194:197], 0
	v_mfma_f32_16x16x32_bf16 v[94:97], v[130:133], v[202:205], 0
	v_mfma_f32_16x16x32_bf16 v[90:93], v[138:141], v[202:205], 0
	v_mfma_f32_16x16x32_bf16 v[78:81], v[130:133], v[210:213], 0
	v_mfma_f32_16x16x32_bf16 v[74:77], v[138:141], v[210:213], 0
	v_mfma_f32_16x16x32_bf16 v[126:129], v[134:137], v[190:193], v[126:129]
	v_mfma_f32_16x16x32_bf16 v[122:125], v[158:161], v[190:193], v[122:125]
	v_mfma_f32_16x16x32_bf16 v[110:113], v[134:137], v[198:201], v[110:113]
	v_mfma_f32_16x16x32_bf16 v[106:109], v[158:161], v[198:201], v[106:109]
	v_mfma_f32_16x16x32_bf16 v[94:97], v[134:137], v[206:209], v[94:97]
	v_mfma_f32_16x16x32_bf16 v[90:93], v[158:161], v[206:209], v[90:93]
	v_mfma_f32_16x16x32_bf16 v[78:81], v[134:137], v[218:221], v[78:81]
	v_mfma_f32_16x16x32_bf16 v[74:77], v[158:161], v[218:221], v[74:77]
	s_setprio 0
	s_setprio 1
	v_mfma_f32_16x16x32_bf16 v[118:121], v[162:165], v[186:189], 0
	v_mfma_f32_16x16x32_bf16 v[114:117], v[178:181], v[186:189], 0
	v_mfma_f32_16x16x32_bf16 v[102:105], v[162:165], v[194:197], 0
	v_mfma_f32_16x16x32_bf16 v[98:101], v[178:181], v[194:197], 0
	v_mfma_f32_16x16x32_bf16 v[86:89], v[162:165], v[202:205], 0
	v_mfma_f32_16x16x32_bf16 v[82:85], v[178:181], v[202:205], 0
	v_mfma_f32_16x16x32_bf16 v[70:73], v[162:165], v[210:213], 0
	v_mfma_f32_16x16x32_bf16 v[66:69], v[178:181], v[210:213], 0
	v_mfma_f32_16x16x32_bf16 v[118:121], v[166:169], v[190:193], v[118:121]
	v_mfma_f32_16x16x32_bf16 v[114:117], v[182:185], v[190:193], v[114:117]
	v_mfma_f32_16x16x32_bf16 v[102:105], v[166:169], v[198:201], v[102:105]
	v_mfma_f32_16x16x32_bf16 v[98:101], v[182:185], v[198:201], v[98:101]
	v_mfma_f32_16x16x32_bf16 v[86:89], v[166:169], v[206:209], v[86:89]
	v_mfma_f32_16x16x32_bf16 v[82:85], v[182:185], v[206:209], v[82:85]
	v_mfma_f32_16x16x32_bf16 v[70:73], v[166:169], v[218:221], v[70:73]
	v_mfma_f32_16x16x32_bf16 v[66:69], v[182:185], v[218:221], v[66:69]
	s_setprio 0
	s_barrier
	s_add_i32 s62, s58, s31
	v_lshl_add_u64 v[170:171], s[34:35], 0, v[144:145]
	s_mov_b32 m0, s62
	ds_read_b128 v[186:189], v176 offset:16384
	ds_read_b128 v[190:193], v176 offset:17408
	ds_read_b128 v[194:197], v176 offset:18432
	ds_read_b128 v[198:201], v176 offset:19456
	ds_read_b128 v[202:205], v176 offset:20480
	ds_read_b128 v[206:209], v176 offset:21504
	ds_read_b128 v[210:213], v176 offset:22528
	ds_read_b128 v[218:221], v176 offset:23552
	global_load_lds_dwordx4 v[170:171], off
	s_add_i32 m0, s62, 0x2000
	s_add_u32 s62, s34, 0x80000
	v_lshl_add_u64 v[214:215], s[34:35], 0, v[148:149]
	s_addc_u32 s63, s35, 0
	s_add_i32 s66, s59, s31
	global_load_lds_dwordx4 v[214:215], off
	v_lshl_add_u64 v[222:223], s[62:63], 0, v[144:145]
	s_mov_b32 m0, s66
	v_lshl_add_u64 v[224:225], s[68:69], 0, v[146:147]
	global_load_lds_dwordx4 v[222:223], off
	v_lshl_add_u64 v[222:223], s[62:63], 0, v[148:149]
	s_add_i32 m0, s66, 0x2000
	s_nop 0
	global_load_lds_dwordx4 v[222:223], off
	v_lshl_add_u64 v[222:223], s[68:69], 0, v[142:143]
	s_mov_b32 m0, s33
	s_nop 0
	global_load_lds_dwordx4 v[222:223], off
	s_mov_b32 m0, s45
	s_nop 0
	global_load_lds_dwordx4 v[224:225], off
	s_waitcnt vmcnt(8)
	s_waitcnt lgkmcnt(0)
	s_barrier
	s_setprio 1
	s_waitcnt lgkmcnt(0)
	v_mfma_f32_16x16x32_bf16 v[62:65], v[130:133], v[186:189], 0
	v_mfma_f32_16x16x32_bf16 v[58:61], v[138:141], v[186:189], 0
	v_mfma_f32_16x16x32_bf16 v[50:53], v[130:133], v[194:197], 0
	v_mfma_f32_16x16x32_bf16 v[42:45], v[138:141], v[194:197], 0
	v_mfma_f32_16x16x32_bf16 v[38:41], v[130:133], v[202:205], 0
	v_mfma_f32_16x16x32_bf16 v[34:37], v[138:141], v[202:205], 0
	v_mfma_f32_16x16x32_bf16 v[14:17], v[130:133], v[210:213], 0
	v_mfma_f32_16x16x32_bf16 v[10:13], v[138:141], v[210:213], 0
	v_mfma_f32_16x16x32_bf16 v[62:65], v[134:137], v[190:193], v[62:65]
	v_mfma_f32_16x16x32_bf16 v[58:61], v[158:161], v[190:193], v[58:61]
	v_mfma_f32_16x16x32_bf16 v[50:53], v[134:137], v[198:201], v[50:53]
	v_mfma_f32_16x16x32_bf16 v[42:45], v[158:161], v[198:201], v[42:45]
	v_mfma_f32_16x16x32_bf16 v[38:41], v[134:137], v[206:209], v[38:41]
	v_mfma_f32_16x16x32_bf16 v[34:37], v[158:161], v[206:209], v[34:37]
	v_mfma_f32_16x16x32_bf16 v[14:17], v[134:137], v[218:221], v[14:17]
	v_mfma_f32_16x16x32_bf16 v[10:13], v[158:161], v[218:221], v[10:13]
	s_setprio 0
	s_setprio 1
	v_mfma_f32_16x16x32_bf16 v[54:57], v[162:165], v[186:189], 0
	v_mfma_f32_16x16x32_bf16 v[46:49], v[178:181], v[186:189], 0
	v_mfma_f32_16x16x32_bf16 v[30:33], v[162:165], v[194:197], 0
	v_mfma_f32_16x16x32_bf16 v[26:29], v[178:181], v[194:197], 0
	v_mfma_f32_16x16x32_bf16 v[22:25], v[162:165], v[202:205], 0
	v_mfma_f32_16x16x32_bf16 v[18:21], v[178:181], v[202:205], 0
	v_mfma_f32_16x16x32_bf16 v[6:9], v[162:165], v[210:213], 0
	v_mfma_f32_16x16x32_bf16 v[2:5], v[178:181], v[210:213], 0
	v_mfma_f32_16x16x32_bf16 v[54:57], v[166:169], v[190:193], v[54:57]
	v_mfma_f32_16x16x32_bf16 v[46:49], v[182:185], v[190:193], v[46:49]
	v_mfma_f32_16x16x32_bf16 v[30:33], v[166:169], v[198:201], v[30:33]
	v_mfma_f32_16x16x32_bf16 v[26:29], v[182:185], v[198:201], v[26:29]
	v_mfma_f32_16x16x32_bf16 v[22:25], v[166:169], v[206:209], v[22:25]
	v_mfma_f32_16x16x32_bf16 v[18:21], v[182:185], v[206:209], v[18:21]
	v_mfma_f32_16x16x32_bf16 v[6:9], v[166:169], v[218:221], v[6:9]
	v_mfma_f32_16x16x32_bf16 v[2:5], v[182:185], v[218:221], v[2:5]
	s_setprio 0
	s_barrier
	s_add_i32 s66, 0, 0x18000
	s_add_i32 s67, 0, 0x1c000
	v_add_u32_e32 v158, s66, v172
	v_add_u32_e32 v177, s67, v172
	ds_read_b128 v[130:133], v158
	ds_read_b128 v[134:137], v158 offset:1024
	ds_read_b128 v[138:141], v158 offset:2048
	ds_read_b128 v[158:161], v158 offset:3072
	ds_read_b128 v[162:165], v177
	ds_read_b128 v[166:169], v177 offset:1024
	ds_read_b128 v[178:181], v177 offset:2048
	ds_read_b128 v[182:185], v177 offset:3072
	s_add_u32 s62, s68, 0x80000
	s_addc_u32 s63, s69, 0
	s_mov_b32 m0, s52
	v_lshl_add_u64 v[226:227], s[62:63], 0, v[142:143]
	ds_read_b128 v[186:189], v176 offset:32768
	ds_read_b128 v[190:193], v176 offset:33792
	ds_read_b128 v[194:197], v176 offset:34816
	ds_read_b128 v[198:201], v176 offset:35840
	ds_read_b128 v[202:205], v176 offset:36864
	ds_read_b128 v[206:209], v176 offset:37888
	ds_read_b128 v[210:213], v176 offset:38912
	ds_read_b128 v[218:221], v176 offset:39936
	global_load_lds_dwordx4 v[226:227], off
	v_lshl_add_u64 v[226:227], s[62:63], 0, v[146:147]
	s_mov_b32 m0, s53
	s_nop 0
	global_load_lds_dwordx4 v[226:227], off
	s_waitcnt vmcnt(8)
	s_waitcnt lgkmcnt(0)
	s_barrier
	s_setprio 1
	s_waitcnt lgkmcnt(0)
	v_mfma_f32_16x16x32_bf16 v[126:129], v[130:133], v[186:189], v[126:129]
	v_mfma_f32_16x16x32_bf16 v[122:125], v[138:141], v[186:189], v[122:125]
	v_mfma_f32_16x16x32_bf16 v[110:113], v[130:133], v[194:197], v[110:113]
	v_mfma_f32_16x16x32_bf16 v[106:109], v[138:141], v[194:197], v[106:109]
	v_mfma_f32_16x16x32_bf16 v[94:97], v[130:133], v[202:205], v[94:97]
	v_mfma_f32_16x16x32_bf16 v[90:93], v[138:141], v[202:205], v[90:93]
	v_mfma_f32_16x16x32_bf16 v[78:81], v[130:133], v[210:213], v[78:81]
	v_mfma_f32_16x16x32_bf16 v[74:77], v[138:141], v[210:213], v[74:77]
	v_mfma_f32_16x16x32_bf16 v[126:129], v[134:137], v[190:193], v[126:129]
	v_mfma_f32_16x16x32_bf16 v[122:125], v[158:161], v[190:193], v[122:125]
	v_mfma_f32_16x16x32_bf16 v[110:113], v[134:137], v[198:201], v[110:113]
	v_mfma_f32_16x16x32_bf16 v[106:109], v[158:161], v[198:201], v[106:109]
	v_mfma_f32_16x16x32_bf16 v[94:97], v[134:137], v[206:209], v[94:97]
	v_mfma_f32_16x16x32_bf16 v[90:93], v[158:161], v[206:209], v[90:93]
	v_mfma_f32_16x16x32_bf16 v[78:81], v[134:137], v[218:221], v[78:81]
	v_mfma_f32_16x16x32_bf16 v[74:77], v[158:161], v[218:221], v[74:77]
	s_setprio 0
	s_setprio 1
	v_mfma_f32_16x16x32_bf16 v[118:121], v[162:165], v[186:189], v[118:121]
	v_mfma_f32_16x16x32_bf16 v[114:117], v[178:181], v[186:189], v[114:117]
	v_mfma_f32_16x16x32_bf16 v[102:105], v[162:165], v[194:197], v[102:105]
	v_mfma_f32_16x16x32_bf16 v[98:101], v[178:181], v[194:197], v[98:101]
	v_mfma_f32_16x16x32_bf16 v[86:89], v[162:165], v[202:205], v[86:89]
	v_mfma_f32_16x16x32_bf16 v[82:85], v[178:181], v[202:205], v[82:85]
	v_mfma_f32_16x16x32_bf16 v[70:73], v[162:165], v[210:213], v[70:73]
	v_mfma_f32_16x16x32_bf16 v[66:69], v[178:181], v[210:213], v[66:69]
	v_mfma_f32_16x16x32_bf16 v[118:121], v[166:169], v[190:193], v[118:121]
	v_mfma_f32_16x16x32_bf16 v[114:117], v[182:185], v[190:193], v[114:117]
	v_mfma_f32_16x16x32_bf16 v[102:105], v[166:169], v[198:201], v[102:105]
	v_mfma_f32_16x16x32_bf16 v[98:101], v[182:185], v[198:201], v[98:101]
	v_mfma_f32_16x16x32_bf16 v[86:89], v[166:169], v[206:209], v[86:89]
	v_mfma_f32_16x16x32_bf16 v[82:85], v[182:185], v[206:209], v[82:85]
	v_mfma_f32_16x16x32_bf16 v[70:73], v[166:169], v[218:221], v[70:73]
	v_mfma_f32_16x16x32_bf16 v[66:69], v[182:185], v[218:221], v[66:69]
	s_setprio 0
	s_barrier
	s_add_i32 s62, s66, s31
	v_lshl_add_u64 v[170:171], v[170:171], 0, s[24:25]
	s_mov_b32 m0, s62
	ds_read_b128 v[186:189], v176 offset:49152
	ds_read_b128 v[190:193], v176 offset:50176
	ds_read_b128 v[194:197], v176 offset:51200
	ds_read_b128 v[198:201], v176 offset:52224
	ds_read_b128 v[202:205], v176 offset:53248
	ds_read_b128 v[206:209], v176 offset:54272
	ds_read_b128 v[210:213], v176 offset:55296
	ds_read_b128 v[218:221], v176 offset:56320
	global_load_lds_dwordx4 v[170:171], off
	s_add_i32 m0, s62, 0x2000
	s_add_u32 s34, s34, 0x80080
	v_lshl_add_u64 v[170:171], v[214:215], 0, s[24:25]
	s_addc_u32 s35, s35, 0
	s_add_i32 s62, s67, s31
	global_load_lds_dwordx4 v[170:171], off
	v_lshl_add_u64 v[170:171], s[34:35], 0, v[144:145]
	s_mov_b32 m0, s62
	s_nop 0
	global_load_lds_dwordx4 v[170:171], off
	v_lshl_add_u64 v[170:171], s[34:35], 0, v[148:149]
	s_add_i32 m0, s62, 0x2000
	s_nop 0
	global_load_lds_dwordx4 v[170:171], off
	v_lshl_add_u64 v[170:171], v[222:223], 0, s[24:25]
	s_mov_b32 m0, s55
	s_nop 0
	global_load_lds_dwordx4 v[170:171], off
	v_lshl_add_u64 v[170:171], v[224:225], 0, s[24:25]
	s_mov_b32 m0, s56
	s_nop 0
	global_load_lds_dwordx4 v[170:171], off
	s_waitcnt vmcnt(8)
	s_waitcnt lgkmcnt(0)
	s_barrier
	s_setprio 1
	s_waitcnt lgkmcnt(0)
	v_mfma_f32_16x16x32_bf16 v[62:65], v[130:133], v[186:189], v[62:65]
	v_mfma_f32_16x16x32_bf16 v[58:61], v[138:141], v[186:189], v[58:61]
	v_mfma_f32_16x16x32_bf16 v[50:53], v[130:133], v[194:197], v[50:53]
	v_mfma_f32_16x16x32_bf16 v[42:45], v[138:141], v[194:197], v[42:45]
	v_mfma_f32_16x16x32_bf16 v[38:41], v[130:133], v[202:205], v[38:41]
	v_mfma_f32_16x16x32_bf16 v[34:37], v[138:141], v[202:205], v[34:37]
	v_mfma_f32_16x16x32_bf16 v[14:17], v[130:133], v[210:213], v[14:17]
	v_mfma_f32_16x16x32_bf16 v[10:13], v[138:141], v[210:213], v[10:13]
	v_mfma_f32_16x16x32_bf16 v[62:65], v[134:137], v[190:193], v[62:65]
	v_mfma_f32_16x16x32_bf16 v[58:61], v[158:161], v[190:193], v[58:61]
	v_mfma_f32_16x16x32_bf16 v[50:53], v[134:137], v[198:201], v[50:53]
	v_mfma_f32_16x16x32_bf16 v[42:45], v[158:161], v[198:201], v[42:45]
	v_mfma_f32_16x16x32_bf16 v[38:41], v[134:137], v[206:209], v[38:41]
	v_mfma_f32_16x16x32_bf16 v[34:37], v[158:161], v[206:209], v[34:37]
	v_mfma_f32_16x16x32_bf16 v[14:17], v[134:137], v[218:221], v[14:17]
	v_mfma_f32_16x16x32_bf16 v[10:13], v[158:161], v[218:221], v[10:13]
	s_setprio 0
	s_setprio 1
	v_mfma_f32_16x16x32_bf16 v[54:57], v[162:165], v[186:189], v[54:57]
	v_mfma_f32_16x16x32_bf16 v[46:49], v[178:181], v[186:189], v[46:49]
	v_mfma_f32_16x16x32_bf16 v[30:33], v[162:165], v[194:197], v[30:33]
	v_mfma_f32_16x16x32_bf16 v[26:29], v[178:181], v[194:197], v[26:29]
	v_mfma_f32_16x16x32_bf16 v[22:25], v[162:165], v[202:205], v[22:25]
	v_mfma_f32_16x16x32_bf16 v[18:21], v[178:181], v[202:205], v[18:21]
	v_mfma_f32_16x16x32_bf16 v[6:9], v[162:165], v[210:213], v[6:9]
	v_mfma_f32_16x16x32_bf16 v[2:5], v[178:181], v[210:213], v[2:5]
	v_mfma_f32_16x16x32_bf16 v[54:57], v[166:169], v[190:193], v[54:57]
	v_mfma_f32_16x16x32_bf16 v[46:49], v[182:185], v[190:193], v[46:49]
	v_mfma_f32_16x16x32_bf16 v[30:33], v[166:169], v[198:201], v[30:33]
	v_mfma_f32_16x16x32_bf16 v[26:29], v[182:185], v[198:201], v[26:29]
	v_mfma_f32_16x16x32_bf16 v[22:25], v[166:169], v[206:209], v[22:25]
	v_mfma_f32_16x16x32_bf16 v[18:21], v[182:185], v[206:209], v[18:21]
	v_mfma_f32_16x16x32_bf16 v[6:9], v[166:169], v[218:221], v[6:9]
	v_mfma_f32_16x16x32_bf16 v[2:5], v[182:185], v[218:221], v[2:5]
	s_setprio 0
	s_barrier
	s_add_i32 s72, s72, 2
	s_add_u32 s46, s46, 0x100
	s_addc_u32 s47, s47, 0
	s_add_u32 s70, s70, 0x100
	s_addc_u32 s71, s71, 0

.LBB0_3066:
	s_ashr_i32 s37, s36, 31
	s_lshl_b64 s[0:1], s[36:37], 20
	v_readlane_b32 s27, v247, 45
	s_add_u32 s38, s27, s0
	v_readlane_b32 s0, v247, 47
	s_addc_u32 s39, s0, s1
	s_and_b64 s[0:1], s[2:3], exec
	s_cselect_b32 s0, s39, s35
	s_cselect_b32 s1, s38, s34
	s_ashr_i32 s27, s26, 31
	s_lshl_b64 s[40:41], s[26:27], 20
	s_add_u32 s40, s12, s40
	s_addc_u32 s41, s13, s41
	s_and_b64 s[44:45], s[2:3], exec
	s_cselect_b32 s27, s41, s47
	s_cselect_b32 s37, s40, s46
	s_add_u32 s44, s34, 0x80080
	s_addc_u32 s45, s35, 0
	s_add_u32 s69, s46, 0x100
	s_addc_u32 s70, s47, 0
	s_mov_b32 s71, -2
	ds_read_b128 v[146:149], v153
	ds_read_b128 v[156:159], v153 offset:1024
	ds_read_b128 v[160:163], v153 offset:2048
	ds_read_b128 v[164:167], v153 offset:3072
	ds_read_b128 v[168:171], v154
	ds_read_b128 v[172:175], v154 offset:1024
	ds_read_b128 v[176:179], v154 offset:2048
	ds_read_b128 v[180:183], v154 offset:3072
	s_add_u32 s34, s44, 0xfff80080
	s_addc_u32 s35, s45, -1
	s_cmp_eq_u32 s71, 28
	s_cselect_b32 s47, s0, s35
	s_cselect_b32 s46, s1, s34
	s_cselect_b32 s35, s27, s70
	s_cselect_b32 s34, s37, s69
	v_lshl_add_u64 v[218:219], s[44:45], 0, v[138:139]
	s_add_i32 m0, s43, 0xc000
	ds_read_b128 v[184:187], v155
	ds_read_b128 v[188:191], v155 offset:1024
	ds_read_b128 v[192:195], v155 offset:2048
	ds_read_b128 v[196:199], v155 offset:3072
	ds_read_b128 v[200:203], v155 offset:4096
	ds_read_b128 v[204:207], v155 offset:5120
	ds_read_b128 v[208:211], v155 offset:6144
	ds_read_b128 v[212:215], v155 offset:7168
	global_load_lds_dwordx4 v[218:219], off
	v_lshl_add_u64 v[218:219], s[44:45], 0, v[140:141]
	s_add_i32 m0, s43, 0xe000
	s_nop 0
	global_load_lds_dwordx4 v[218:219], off
	s_waitcnt vmcnt(8)
	s_waitcnt lgkmcnt(0)
	s_barrier
	s_setprio 1
	s_waitcnt lgkmcnt(0)
	v_mfma_f32_16x16x32_bf16 v[126:129], v[146:149], v[184:187], 0
	v_mfma_f32_16x16x32_bf16 v[118:121], v[160:163], v[184:187], 0
	v_mfma_f32_16x16x32_bf16 v[110:113], v[146:149], v[192:195], 0
	v_mfma_f32_16x16x32_bf16 v[102:105], v[160:163], v[192:195], 0
	v_mfma_f32_16x16x32_bf16 v[94:97], v[146:149], v[200:203], 0
	v_mfma_f32_16x16x32_bf16 v[86:89], v[160:163], v[200:203], 0
	v_mfma_f32_16x16x32_bf16 v[78:81], v[146:149], v[208:211], 0
	v_mfma_f32_16x16x32_bf16 v[70:73], v[160:163], v[208:211], 0
	v_mfma_f32_16x16x32_bf16 v[126:129], v[156:159], v[188:191], v[126:129]
	v_mfma_f32_16x16x32_bf16 v[118:121], v[164:167], v[188:191], v[118:121]
	v_mfma_f32_16x16x32_bf16 v[110:113], v[156:159], v[196:199], v[110:113]
	v_mfma_f32_16x16x32_bf16 v[102:105], v[164:167], v[196:199], v[102:105]
	v_mfma_f32_16x16x32_bf16 v[94:97], v[156:159], v[204:207], v[94:97]
	v_mfma_f32_16x16x32_bf16 v[86:89], v[164:167], v[204:207], v[86:89]
	v_mfma_f32_16x16x32_bf16 v[78:81], v[156:159], v[212:215], v[78:81]
	v_mfma_f32_16x16x32_bf16 v[70:73], v[164:167], v[212:215], v[70:73]
	s_setprio 0
	s_setprio 1
	v_mfma_f32_16x16x32_bf16 v[122:125], v[168:171], v[184:187], 0
	v_mfma_f32_16x16x32_bf16 v[114:117], v[176:179], v[184:187], 0
	v_mfma_f32_16x16x32_bf16 v[106:109], v[168:171], v[192:195], 0
	v_mfma_f32_16x16x32_bf16 v[98:101], v[176:179], v[192:195], 0
	v_mfma_f32_16x16x32_bf16 v[90:93], v[168:171], v[200:203], 0
	v_mfma_f32_16x16x32_bf16 v[82:85], v[176:179], v[200:203], 0
	v_mfma_f32_16x16x32_bf16 v[74:77], v[168:171], v[208:211], 0
	v_mfma_f32_16x16x32_bf16 v[66:69], v[176:179], v[208:211], 0
	v_mfma_f32_16x16x32_bf16 v[122:125], v[172:175], v[188:191], v[122:125]
	v_mfma_f32_16x16x32_bf16 v[114:117], v[180:183], v[188:191], v[114:117]
	v_mfma_f32_16x16x32_bf16 v[106:109], v[172:175], v[196:199], v[106:109]
	v_mfma_f32_16x16x32_bf16 v[98:101], v[180:183], v[196:199], v[98:101]
	v_mfma_f32_16x16x32_bf16 v[90:93], v[172:175], v[204:207], v[90:93]
	v_mfma_f32_16x16x32_bf16 v[82:85], v[180:183], v[204:207], v[82:85]
	v_mfma_f32_16x16x32_bf16 v[74:77], v[172:175], v[212:215], v[74:77]
	v_mfma_f32_16x16x32_bf16 v[66:69], v[180:183], v[212:215], v[66:69]
	s_setprio 0
	s_barrier
	s_add_i32 s62, s59, s30
	v_lshl_add_u64 v[218:219], s[34:35], 0, v[134:135]
	s_mov_b32 m0, s62
	ds_read_b128 v[184:187], v155 offset:16384
	ds_read_b128 v[188:191], v155 offset:17408
	ds_read_b128 v[192:195], v155 offset:18432
	ds_read_b128 v[196:199], v155 offset:19456
	ds_read_b128 v[200:203], v155 offset:20480
	ds_read_b128 v[204:207], v155 offset:21504
	ds_read_b128 v[208:211], v155 offset:22528
	ds_read_b128 v[212:215], v155 offset:23552
	global_load_lds_dwordx4 v[218:219], off
	s_add_i32 m0, s62, 0x2000
	s_add_u32 s62, s34, 0x80000
	v_lshl_add_u64 v[220:221], s[34:35], 0, v[130:131]
	s_addc_u32 s63, s35, 0
	s_add_i32 s66, s60, s30
	global_load_lds_dwordx4 v[220:221], off
	v_lshl_add_u64 v[222:223], s[62:63], 0, v[134:135]
	s_mov_b32 m0, s66
	v_lshl_add_u64 v[224:225], s[46:47], 0, v[132:133]
	global_load_lds_dwordx4 v[222:223], off
	v_lshl_add_u64 v[222:223], s[62:63], 0, v[130:131]
	s_add_i32 m0, s66, 0x2000
	s_nop 0
	global_load_lds_dwordx4 v[222:223], off
	v_lshl_add_u64 v[222:223], s[46:47], 0, v[136:137]
	s_mov_b32 m0, s43
	s_nop 0
	global_load_lds_dwordx4 v[222:223], off
	s_mov_b32 m0, s52
	s_nop 0
	global_load_lds_dwordx4 v[224:225], off
	s_waitcnt vmcnt(8)
	s_waitcnt lgkmcnt(0)
	s_barrier
	s_setprio 1
	s_waitcnt lgkmcnt(0)
	v_mfma_f32_16x16x32_bf16 v[62:65], v[146:149], v[184:187], 0
	v_mfma_f32_16x16x32_bf16 v[54:57], v[160:163], v[184:187], 0
	v_mfma_f32_16x16x32_bf16 v[46:49], v[146:149], v[192:195], 0
	v_mfma_f32_16x16x32_bf16 v[38:41], v[160:163], v[192:195], 0
	v_mfma_f32_16x16x32_bf16 v[30:33], v[146:149], v[200:203], 0
	v_mfma_f32_16x16x32_bf16 v[22:25], v[160:163], v[200:203], 0
	v_mfma_f32_16x16x32_bf16 v[14:17], v[146:149], v[208:211], 0
	v_mfma_f32_16x16x32_bf16 v[6:9], v[160:163], v[208:211], 0
	v_mfma_f32_16x16x32_bf16 v[62:65], v[156:159], v[188:191], v[62:65]
	v_mfma_f32_16x16x32_bf16 v[54:57], v[164:167], v[188:191], v[54:57]
	v_mfma_f32_16x16x32_bf16 v[46:49], v[156:159], v[196:199], v[46:49]
	v_mfma_f32_16x16x32_bf16 v[38:41], v[164:167], v[196:199], v[38:41]
	v_mfma_f32_16x16x32_bf16 v[30:33], v[156:159], v[204:207], v[30:33]
	v_mfma_f32_16x16x32_bf16 v[22:25], v[164:167], v[204:207], v[22:25]
	v_mfma_f32_16x16x32_bf16 v[14:17], v[156:159], v[212:215], v[14:17]
	v_mfma_f32_16x16x32_bf16 v[6:9], v[164:167], v[212:215], v[6:9]
	s_setprio 0
	s_setprio 1
	v_mfma_f32_16x16x32_bf16 v[58:61], v[168:171], v[184:187], 0
	v_mfma_f32_16x16x32_bf16 v[50:53], v[176:179], v[184:187], 0
	v_mfma_f32_16x16x32_bf16 v[42:45], v[168:171], v[192:195], 0
	v_mfma_f32_16x16x32_bf16 v[34:37], v[176:179], v[192:195], 0
	v_mfma_f32_16x16x32_bf16 v[26:29], v[168:171], v[200:203], 0
	v_mfma_f32_16x16x32_bf16 v[18:21], v[176:179], v[200:203], 0
	v_mfma_f32_16x16x32_bf16 v[10:13], v[168:171], v[208:211], 0
	v_mfma_f32_16x16x32_bf16 v[2:5], v[176:179], v[208:211], 0
	v_mfma_f32_16x16x32_bf16 v[58:61], v[172:175], v[188:191], v[58:61]
	v_mfma_f32_16x16x32_bf16 v[50:53], v[180:183], v[188:191], v[50:53]
	v_mfma_f32_16x16x32_bf16 v[42:45], v[172:175], v[196:199], v[42:45]
	v_mfma_f32_16x16x32_bf16 v[34:37], v[180:183], v[196:199], v[34:37]
	v_mfma_f32_16x16x32_bf16 v[26:29], v[172:175], v[204:207], v[26:29]
	v_mfma_f32_16x16x32_bf16 v[18:21], v[180:183], v[204:207], v[18:21]
	v_mfma_f32_16x16x32_bf16 v[10:13], v[172:175], v[212:215], v[10:13]
	v_mfma_f32_16x16x32_bf16 v[2:5], v[180:183], v[212:215], v[2:5]
	s_setprio 0
	s_barrier
	s_add_i32 s62, 0, 0x18000
	s_add_i32 s63, 0, 0x1c000
	v_add_u32_e32 v164, s62, v151
	v_add_u32_e32 v180, s63, v151
	ds_read_b128 v[146:149], v164
	ds_read_b128 v[156:159], v164 offset:1024
	ds_read_b128 v[160:163], v164 offset:2048
	ds_read_b128 v[164:167], v164 offset:3072
	ds_read_b128 v[168:171], v180
	ds_read_b128 v[172:175], v180 offset:1024
	ds_read_b128 v[176:179], v180 offset:2048
	ds_read_b128 v[180:183], v180 offset:3072
	s_add_u32 s46, s46, 0x80000
	s_addc_u32 s47, s47, 0
	s_mov_b32 m0, s53
	v_lshl_add_u64 v[226:227], s[46:47], 0, v[136:137]
	ds_read_b128 v[184:187], v155 offset:32768
	ds_read_b128 v[188:191], v155 offset:33792
	ds_read_b128 v[192:195], v155 offset:34816
	ds_read_b128 v[196:199], v155 offset:35840
	ds_read_b128 v[200:203], v155 offset:36864
	ds_read_b128 v[204:207], v155 offset:37888
	ds_read_b128 v[208:211], v155 offset:38912
	ds_read_b128 v[212:215], v155 offset:39936
	global_load_lds_dwordx4 v[226:227], off
	v_lshl_add_u64 v[226:227], s[46:47], 0, v[132:133]
	s_mov_b32 m0, s54
	s_nop 0
	global_load_lds_dwordx4 v[226:227], off
	s_waitcnt vmcnt(8)
	s_waitcnt lgkmcnt(0)
	s_barrier
	s_setprio 1
	s_waitcnt lgkmcnt(0)
	v_mfma_f32_16x16x32_bf16 v[126:129], v[146:149], v[184:187], v[126:129]
	v_mfma_f32_16x16x32_bf16 v[118:121], v[160:163], v[184:187], v[118:121]
	v_mfma_f32_16x16x32_bf16 v[110:113], v[146:149], v[192:195], v[110:113]
	v_mfma_f32_16x16x32_bf16 v[102:105], v[160:163], v[192:195], v[102:105]
	v_mfma_f32_16x16x32_bf16 v[94:97], v[146:149], v[200:203], v[94:97]
	v_mfma_f32_16x16x32_bf16 v[86:89], v[160:163], v[200:203], v[86:89]
	v_mfma_f32_16x16x32_bf16 v[78:81], v[146:149], v[208:211], v[78:81]
	v_mfma_f32_16x16x32_bf16 v[70:73], v[160:163], v[208:211], v[70:73]
	v_mfma_f32_16x16x32_bf16 v[126:129], v[156:159], v[188:191], v[126:129]
	v_mfma_f32_16x16x32_bf16 v[118:121], v[164:167], v[188:191], v[118:121]
	v_mfma_f32_16x16x32_bf16 v[110:113], v[156:159], v[196:199], v[110:113]
	v_mfma_f32_16x16x32_bf16 v[102:105], v[164:167], v[196:199], v[102:105]
	v_mfma_f32_16x16x32_bf16 v[94:97], v[156:159], v[204:207], v[94:97]
	v_mfma_f32_16x16x32_bf16 v[86:89], v[164:167], v[204:207], v[86:89]
	v_mfma_f32_16x16x32_bf16 v[78:81], v[156:159], v[212:215], v[78:81]
	v_mfma_f32_16x16x32_bf16 v[70:73], v[164:167], v[212:215], v[70:73]
	s_setprio 0
	s_setprio 1
	v_mfma_f32_16x16x32_bf16 v[122:125], v[168:171], v[184:187], v[122:125]
	v_mfma_f32_16x16x32_bf16 v[114:117], v[176:179], v[184:187], v[114:117]
	v_mfma_f32_16x16x32_bf16 v[106:109], v[168:171], v[192:195], v[106:109]
	v_mfma_f32_16x16x32_bf16 v[98:101], v[176:179], v[192:195], v[98:101]
	v_mfma_f32_16x16x32_bf16 v[90:93], v[168:171], v[200:203], v[90:93]
	v_mfma_f32_16x16x32_bf16 v[82:85], v[176:179], v[200:203], v[82:85]
	v_mfma_f32_16x16x32_bf16 v[74:77], v[168:171], v[208:211], v[74:77]
	v_mfma_f32_16x16x32_bf16 v[66:69], v[176:179], v[208:211], v[66:69]
	v_mfma_f32_16x16x32_bf16 v[122:125], v[172:175], v[188:191], v[122:125]
	v_mfma_f32_16x16x32_bf16 v[114:117], v[180:183], v[188:191], v[114:117]
	v_mfma_f32_16x16x32_bf16 v[106:109], v[172:175], v[196:199], v[106:109]
	v_mfma_f32_16x16x32_bf16 v[98:101], v[180:183], v[196:199], v[98:101]
	v_mfma_f32_16x16x32_bf16 v[90:93], v[172:175], v[204:207], v[90:93]
	v_mfma_f32_16x16x32_bf16 v[82:85], v[180:183], v[204:207], v[82:85]
	v_mfma_f32_16x16x32_bf16 v[74:77], v[172:175], v[212:215], v[74:77]
	v_mfma_f32_16x16x32_bf16 v[66:69], v[180:183], v[212:215], v[66:69]
	s_setprio 0
	s_barrier
	s_add_i32 s46, s62, s30
	v_lshl_add_u64 v[218:219], v[218:219], 0, s[8:9]
	s_mov_b32 m0, s46
	ds_read_b128 v[184:187], v155 offset:49152
	ds_read_b128 v[188:191], v155 offset:50176
	ds_read_b128 v[192:195], v155 offset:51200
	ds_read_b128 v[196:199], v155 offset:52224
	ds_read_b128 v[200:203], v155 offset:53248
	ds_read_b128 v[204:207], v155 offset:54272
	ds_read_b128 v[208:211], v155 offset:55296
	ds_read_b128 v[212:215], v155 offset:56320
	global_load_lds_dwordx4 v[218:219], off
	s_add_i32 m0, s46, 0x2000
	s_add_u32 s34, s34, 0x80080
	v_lshl_add_u64 v[218:219], v[220:221], 0, s[8:9]
	s_addc_u32 s35, s35, 0
	s_add_i32 s46, s63, s30
	global_load_lds_dwordx4 v[218:219], off
	v_lshl_add_u64 v[218:219], s[34:35], 0, v[134:135]
	s_mov_b32 m0, s46
	s_nop 0
	global_load_lds_dwordx4 v[218:219], off
	v_lshl_add_u64 v[218:219], s[34:35], 0, v[130:131]
	s_add_i32 m0, s46, 0x2000
	s_nop 0
	global_load_lds_dwordx4 v[218:219], off
	v_lshl_add_u64 v[218:219], v[222:223], 0, s[8:9]
	s_mov_b32 m0, s56
	s_nop 0
	global_load_lds_dwordx4 v[218:219], off
	v_lshl_add_u64 v[218:219], v[224:225], 0, s[8:9]
	s_mov_b32 m0, s57
	s_nop 0
	global_load_lds_dwordx4 v[218:219], off
	s_waitcnt vmcnt(8)
	s_waitcnt lgkmcnt(0)
	s_barrier
	s_setprio 1
	s_waitcnt lgkmcnt(0)
	v_mfma_f32_16x16x32_bf16 v[62:65], v[146:149], v[184:187], v[62:65]
	v_mfma_f32_16x16x32_bf16 v[54:57], v[160:163], v[184:187], v[54:57]
	v_mfma_f32_16x16x32_bf16 v[46:49], v[146:149], v[192:195], v[46:49]
	v_mfma_f32_16x16x32_bf16 v[38:41], v[160:163], v[192:195], v[38:41]
	v_mfma_f32_16x16x32_bf16 v[30:33], v[146:149], v[200:203], v[30:33]
	v_mfma_f32_16x16x32_bf16 v[22:25], v[160:163], v[200:203], v[22:25]
	v_mfma_f32_16x16x32_bf16 v[14:17], v[146:149], v[208:211], v[14:17]
	v_mfma_f32_16x16x32_bf16 v[6:9], v[160:163], v[208:211], v[6:9]
	v_mfma_f32_16x16x32_bf16 v[62:65], v[156:159], v[188:191], v[62:65]
	v_mfma_f32_16x16x32_bf16 v[54:57], v[164:167], v[188:191], v[54:57]
	v_mfma_f32_16x16x32_bf16 v[46:49], v[156:159], v[196:199], v[46:49]
	v_mfma_f32_16x16x32_bf16 v[38:41], v[164:167], v[196:199], v[38:41]
	v_mfma_f32_16x16x32_bf16 v[30:33], v[156:159], v[204:207], v[30:33]
	v_mfma_f32_16x16x32_bf16 v[22:25], v[164:167], v[204:207], v[22:25]
	v_mfma_f32_16x16x32_bf16 v[14:17], v[156:159], v[212:215], v[14:17]
	v_mfma_f32_16x16x32_bf16 v[6:9], v[164:167], v[212:215], v[6:9]
	s_setprio 0
	s_setprio 1
	v_mfma_f32_16x16x32_bf16 v[58:61], v[168:171], v[184:187], v[58:61]
	v_mfma_f32_16x16x32_bf16 v[50:53], v[176:179], v[184:187], v[50:53]
	v_mfma_f32_16x16x32_bf16 v[42:45], v[168:171], v[192:195], v[42:45]
	v_mfma_f32_16x16x32_bf16 v[34:37], v[176:179], v[192:195], v[34:37]
	v_mfma_f32_16x16x32_bf16 v[26:29], v[168:171], v[200:203], v[26:29]
	v_mfma_f32_16x16x32_bf16 v[18:21], v[176:179], v[200:203], v[18:21]
	v_mfma_f32_16x16x32_bf16 v[10:13], v[168:171], v[208:211], v[10:13]
	v_mfma_f32_16x16x32_bf16 v[2:5], v[176:179], v[208:211], v[2:5]
	v_mfma_f32_16x16x32_bf16 v[58:61], v[172:175], v[188:191], v[58:61]
	v_mfma_f32_16x16x32_bf16 v[50:53], v[180:183], v[188:191], v[50:53]
	v_mfma_f32_16x16x32_bf16 v[42:45], v[172:175], v[196:199], v[42:45]
	v_mfma_f32_16x16x32_bf16 v[34:37], v[180:183], v[196:199], v[34:37]
	v_mfma_f32_16x16x32_bf16 v[26:29], v[172:175], v[204:207], v[26:29]
	v_mfma_f32_16x16x32_bf16 v[18:21], v[180:183], v[204:207], v[18:21]
	v_mfma_f32_16x16x32_bf16 v[10:13], v[172:175], v[212:215], v[10:13]
	v_mfma_f32_16x16x32_bf16 v[2:5], v[180:183], v[212:215], v[2:5]
	s_setprio 0
	s_barrier
	s_add_i32 s71, s71, 2
	s_add_u32 s44, s44, 0x100
	s_addc_u32 s45, s45, 0
	s_add_u32 s69, s69, 0x100
	s_addc_u32 s70, s70, 0

.LBB0_3179:
	s_add_u32 s40, s40, 0x160080
	s_addc_u32 s41, s41, 0
	s_add_u32 s0, s42, 0x100
	s_addc_u32 s1, s43, 0
	s_mov_b32 s60, -2
	ds_read_b128 v[130:133], v174
	ds_read_b128 v[134:137], v174 offset:1024
	ds_read_b128 v[138:141], v174 offset:2048
	ds_read_b128 v[158:161], v174 offset:3072
	ds_read_b128 v[162:165], v175
	ds_read_b128 v[166:169], v175 offset:1024
	ds_read_b128 v[178:181], v175 offset:2048
	ds_read_b128 v[182:185], v175 offset:3072
	s_add_u32 s34, s40, 0xffea0080
	s_addc_u32 s35, s41, -1
	s_cmpk_eq_i32 s60, 0x54
	s_cselect_b32 s43, s5, s35
	s_cselect_b32 s42, s4, s34
	s_cselect_b32 s35, s39, s1
	s_cselect_b32 s34, s38, s0
	v_lshl_add_u64 v[170:171], s[40:41], 0, v[150:151]
	s_add_i32 m0, s33, 0xc000
	ds_read_b128 v[186:189], v176
	ds_read_b128 v[190:193], v176 offset:1024
	ds_read_b128 v[194:197], v176 offset:2048
	ds_read_b128 v[198:201], v176 offset:3072
	ds_read_b128 v[202:205], v176 offset:4096
	ds_read_b128 v[206:209], v176 offset:5120
	ds_read_b128 v[210:213], v176 offset:6144
	ds_read_b128 v[218:221], v176 offset:7168
	global_load_lds_dwordx4 v[170:171], off
	v_lshl_add_u64 v[170:171], s[40:41], 0, v[152:153]
	s_add_i32 m0, s33, 0xe000
	s_nop 0
	global_load_lds_dwordx4 v[170:171], off
	s_waitcnt vmcnt(8)
	s_waitcnt lgkmcnt(0)
	s_barrier
	s_setprio 1
	s_waitcnt lgkmcnt(0)
	v_mfma_f32_16x16x32_bf16 v[126:129], v[130:133], v[186:189], 0
	v_mfma_f32_16x16x32_bf16 v[122:125], v[138:141], v[186:189], 0
	v_mfma_f32_16x16x32_bf16 v[110:113], v[130:133], v[194:197], 0
	v_mfma_f32_16x16x32_bf16 v[106:109], v[138:141], v[194:197], 0
	v_mfma_f32_16x16x32_bf16 v[94:97], v[130:133], v[202:205], 0
	v_mfma_f32_16x16x32_bf16 v[90:93], v[138:141], v[202:205], 0
	v_mfma_f32_16x16x32_bf16 v[78:81], v[130:133], v[210:213], 0
	v_mfma_f32_16x16x32_bf16 v[74:77], v[138:141], v[210:213], 0
	v_mfma_f32_16x16x32_bf16 v[126:129], v[134:137], v[190:193], v[126:129]
	v_mfma_f32_16x16x32_bf16 v[122:125], v[158:161], v[190:193], v[122:125]
	v_mfma_f32_16x16x32_bf16 v[110:113], v[134:137], v[198:201], v[110:113]
	v_mfma_f32_16x16x32_bf16 v[106:109], v[158:161], v[198:201], v[106:109]
	v_mfma_f32_16x16x32_bf16 v[94:97], v[134:137], v[206:209], v[94:97]
	v_mfma_f32_16x16x32_bf16 v[90:93], v[158:161], v[206:209], v[90:93]
	v_mfma_f32_16x16x32_bf16 v[78:81], v[134:137], v[218:221], v[78:81]
	v_mfma_f32_16x16x32_bf16 v[74:77], v[158:161], v[218:221], v[74:77]
	s_setprio 0
	s_setprio 1
	v_mfma_f32_16x16x32_bf16 v[118:121], v[162:165], v[186:189], 0
	v_mfma_f32_16x16x32_bf16 v[114:117], v[178:181], v[186:189], 0
	v_mfma_f32_16x16x32_bf16 v[102:105], v[162:165], v[194:197], 0
	v_mfma_f32_16x16x32_bf16 v[98:101], v[178:181], v[194:197], 0
	v_mfma_f32_16x16x32_bf16 v[86:89], v[162:165], v[202:205], 0
	v_mfma_f32_16x16x32_bf16 v[82:85], v[178:181], v[202:205], 0
	v_mfma_f32_16x16x32_bf16 v[70:73], v[162:165], v[210:213], 0
	v_mfma_f32_16x16x32_bf16 v[66:69], v[178:181], v[210:213], 0
	v_mfma_f32_16x16x32_bf16 v[118:121], v[166:169], v[190:193], v[118:121]
	v_mfma_f32_16x16x32_bf16 v[114:117], v[182:185], v[190:193], v[114:117]
	v_mfma_f32_16x16x32_bf16 v[102:105], v[166:169], v[198:201], v[102:105]
	v_mfma_f32_16x16x32_bf16 v[98:101], v[182:185], v[198:201], v[98:101]
	v_mfma_f32_16x16x32_bf16 v[86:89], v[166:169], v[206:209], v[86:89]
	v_mfma_f32_16x16x32_bf16 v[82:85], v[182:185], v[206:209], v[82:85]
	v_mfma_f32_16x16x32_bf16 v[70:73], v[166:169], v[218:221], v[70:73]
	v_mfma_f32_16x16x32_bf16 v[66:69], v[182:185], v[218:221], v[66:69]
	s_setprio 0
	s_barrier
	s_add_i32 s61, s53, s31
	v_lshl_add_u64 v[170:171], s[34:35], 0, v[144:145]
	s_mov_b32 m0, s61
	ds_read_b128 v[186:189], v176 offset:16384
	ds_read_b128 v[190:193], v176 offset:17408
	ds_read_b128 v[194:197], v176 offset:18432
	ds_read_b128 v[198:201], v176 offset:19456
	ds_read_b128 v[202:205], v176 offset:20480
	ds_read_b128 v[206:209], v176 offset:21504
	ds_read_b128 v[210:213], v176 offset:22528
	ds_read_b128 v[218:221], v176 offset:23552
	global_load_lds_dwordx4 v[170:171], off
	s_add_i32 m0, s61, 0x2000
	s_add_u32 s62, s34, 0x160000
	v_lshl_add_u64 v[214:215], s[34:35], 0, v[148:149]
	s_addc_u32 s63, s35, 0
	s_add_i32 s61, s54, s31
	global_load_lds_dwordx4 v[214:215], off
	v_lshl_add_u64 v[222:223], s[62:63], 0, v[144:145]
	s_mov_b32 m0, s61
	v_lshl_add_u64 v[224:225], s[42:43], 0, v[146:147]
	global_load_lds_dwordx4 v[222:223], off
	v_lshl_add_u64 v[222:223], s[62:63], 0, v[148:149]
	s_add_i32 m0, s61, 0x2000
	s_nop 0
	global_load_lds_dwordx4 v[222:223], off
	v_lshl_add_u64 v[222:223], s[42:43], 0, v[142:143]
	s_mov_b32 m0, s33
	s_nop 0
	global_load_lds_dwordx4 v[222:223], off
	s_mov_b32 m0, s44
	s_nop 0
	global_load_lds_dwordx4 v[224:225], off
	s_waitcnt vmcnt(8)
	s_waitcnt lgkmcnt(0)
	s_barrier
	s_setprio 1
	s_waitcnt lgkmcnt(0)
	v_mfma_f32_16x16x32_bf16 v[62:65], v[130:133], v[186:189], 0
	v_mfma_f32_16x16x32_bf16 v[58:61], v[138:141], v[186:189], 0
	v_mfma_f32_16x16x32_bf16 v[50:53], v[130:133], v[194:197], 0
	v_mfma_f32_16x16x32_bf16 v[42:45], v[138:141], v[194:197], 0
	v_mfma_f32_16x16x32_bf16 v[38:41], v[130:133], v[202:205], 0
	v_mfma_f32_16x16x32_bf16 v[34:37], v[138:141], v[202:205], 0
	v_mfma_f32_16x16x32_bf16 v[14:17], v[130:133], v[210:213], 0
	v_mfma_f32_16x16x32_bf16 v[10:13], v[138:141], v[210:213], 0
	v_mfma_f32_16x16x32_bf16 v[62:65], v[134:137], v[190:193], v[62:65]
	v_mfma_f32_16x16x32_bf16 v[58:61], v[158:161], v[190:193], v[58:61]
	v_mfma_f32_16x16x32_bf16 v[50:53], v[134:137], v[198:201], v[50:53]
	v_mfma_f32_16x16x32_bf16 v[42:45], v[158:161], v[198:201], v[42:45]
	v_mfma_f32_16x16x32_bf16 v[38:41], v[134:137], v[206:209], v[38:41]
	v_mfma_f32_16x16x32_bf16 v[34:37], v[158:161], v[206:209], v[34:37]
	v_mfma_f32_16x16x32_bf16 v[14:17], v[134:137], v[218:221], v[14:17]
	v_mfma_f32_16x16x32_bf16 v[10:13], v[158:161], v[218:221], v[10:13]
	s_setprio 0
	s_setprio 1
	v_mfma_f32_16x16x32_bf16 v[54:57], v[162:165], v[186:189], 0
	v_mfma_f32_16x16x32_bf16 v[46:49], v[178:181], v[186:189], 0
	v_mfma_f32_16x16x32_bf16 v[30:33], v[162:165], v[194:197], 0
	v_mfma_f32_16x16x32_bf16 v[26:29], v[178:181], v[194:197], 0
	v_mfma_f32_16x16x32_bf16 v[22:25], v[162:165], v[202:205], 0
	v_mfma_f32_16x16x32_bf16 v[18:21], v[178:181], v[202:205], 0
	v_mfma_f32_16x16x32_bf16 v[6:9], v[162:165], v[210:213], 0
	v_mfma_f32_16x16x32_bf16 v[2:5], v[178:181], v[210:213], 0
	v_mfma_f32_16x16x32_bf16 v[54:57], v[166:169], v[190:193], v[54:57]
	v_mfma_f32_16x16x32_bf16 v[46:49], v[182:185], v[190:193], v[46:49]
	v_mfma_f32_16x16x32_bf16 v[30:33], v[166:169], v[198:201], v[30:33]
	v_mfma_f32_16x16x32_bf16 v[26:29], v[182:185], v[198:201], v[26:29]
	v_mfma_f32_16x16x32_bf16 v[22:25], v[166:169], v[206:209], v[22:25]
	v_mfma_f32_16x16x32_bf16 v[18:21], v[182:185], v[206:209], v[18:21]
	v_mfma_f32_16x16x32_bf16 v[6:9], v[166:169], v[218:221], v[6:9]
	v_mfma_f32_16x16x32_bf16 v[2:5], v[182:185], v[218:221], v[2:5]
	s_setprio 0
	s_barrier
	s_add_i32 s61, 0, 0x18000
	s_add_i32 s62, 0, 0x1c000
	v_add_u32_e32 v158, s61, v172
	v_add_u32_e32 v177, s62, v172
	ds_read_b128 v[130:133], v158
	ds_read_b128 v[134:137], v158 offset:1024
	ds_read_b128 v[138:141], v158 offset:2048
	ds_read_b128 v[158:161], v158 offset:3072
	ds_read_b128 v[162:165], v177
	ds_read_b128 v[166:169], v177 offset:1024
	ds_read_b128 v[178:181], v177 offset:2048
	ds_read_b128 v[182:185], v177 offset:3072
	s_add_u32 s42, s42, 0x160000
	s_addc_u32 s43, s43, 0
	s_mov_b32 m0, s45
	v_lshl_add_u64 v[226:227], s[42:43], 0, v[142:143]
	ds_read_b128 v[186:189], v176 offset:32768
	ds_read_b128 v[190:193], v176 offset:33792
	ds_read_b128 v[194:197], v176 offset:34816
	ds_read_b128 v[198:201], v176 offset:35840
	ds_read_b128 v[202:205], v176 offset:36864
	ds_read_b128 v[206:209], v176 offset:37888
	ds_read_b128 v[210:213], v176 offset:38912
	ds_read_b128 v[218:221], v176 offset:39936
	global_load_lds_dwordx4 v[226:227], off
	v_lshl_add_u64 v[226:227], s[42:43], 0, v[146:147]
	s_mov_b32 m0, s46
	s_nop 0
	global_load_lds_dwordx4 v[226:227], off
	s_waitcnt vmcnt(8)
	s_waitcnt lgkmcnt(0)
	s_barrier
	s_setprio 1
	s_waitcnt lgkmcnt(0)
	v_mfma_f32_16x16x32_bf16 v[126:129], v[130:133], v[186:189], v[126:129]
	v_mfma_f32_16x16x32_bf16 v[122:125], v[138:141], v[186:189], v[122:125]
	v_mfma_f32_16x16x32_bf16 v[110:113], v[130:133], v[194:197], v[110:113]
	v_mfma_f32_16x16x32_bf16 v[106:109], v[138:141], v[194:197], v[106:109]
	v_mfma_f32_16x16x32_bf16 v[94:97], v[130:133], v[202:205], v[94:97]
	v_mfma_f32_16x16x32_bf16 v[90:93], v[138:141], v[202:205], v[90:93]
	v_mfma_f32_16x16x32_bf16 v[78:81], v[130:133], v[210:213], v[78:81]
	v_mfma_f32_16x16x32_bf16 v[74:77], v[138:141], v[210:213], v[74:77]
	v_mfma_f32_16x16x32_bf16 v[126:129], v[134:137], v[190:193], v[126:129]
	v_mfma_f32_16x16x32_bf16 v[122:125], v[158:161], v[190:193], v[122:125]
	v_mfma_f32_16x16x32_bf16 v[110:113], v[134:137], v[198:201], v[110:113]
	v_mfma_f32_16x16x32_bf16 v[106:109], v[158:161], v[198:201], v[106:109]
	v_mfma_f32_16x16x32_bf16 v[94:97], v[134:137], v[206:209], v[94:97]
	v_mfma_f32_16x16x32_bf16 v[90:93], v[158:161], v[206:209], v[90:93]
	v_mfma_f32_16x16x32_bf16 v[78:81], v[134:137], v[218:221], v[78:81]
	v_mfma_f32_16x16x32_bf16 v[74:77], v[158:161], v[218:221], v[74:77]
	s_setprio 0
	s_setprio 1
	v_mfma_f32_16x16x32_bf16 v[118:121], v[162:165], v[186:189], v[118:121]
	v_mfma_f32_16x16x32_bf16 v[114:117], v[178:181], v[186:189], v[114:117]
	v_mfma_f32_16x16x32_bf16 v[102:105], v[162:165], v[194:197], v[102:105]
	v_mfma_f32_16x16x32_bf16 v[98:101], v[178:181], v[194:197], v[98:101]
	v_mfma_f32_16x16x32_bf16 v[86:89], v[162:165], v[202:205], v[86:89]
	v_mfma_f32_16x16x32_bf16 v[82:85], v[178:181], v[202:205], v[82:85]
	v_mfma_f32_16x16x32_bf16 v[70:73], v[162:165], v[210:213], v[70:73]
	v_mfma_f32_16x16x32_bf16 v[66:69], v[178:181], v[210:213], v[66:69]
	v_mfma_f32_16x16x32_bf16 v[118:121], v[166:169], v[190:193], v[118:121]
	v_mfma_f32_16x16x32_bf16 v[114:117], v[182:185], v[190:193], v[114:117]
	v_mfma_f32_16x16x32_bf16 v[102:105], v[166:169], v[198:201], v[102:105]
	v_mfma_f32_16x16x32_bf16 v[98:101], v[182:185], v[198:201], v[98:101]
	v_mfma_f32_16x16x32_bf16 v[86:89], v[166:169], v[206:209], v[86:89]
	v_mfma_f32_16x16x32_bf16 v[82:85], v[182:185], v[206:209], v[82:85]
	v_mfma_f32_16x16x32_bf16 v[70:73], v[166:169], v[218:221], v[70:73]
	v_mfma_f32_16x16x32_bf16 v[66:69], v[182:185], v[218:221], v[66:69]
	s_setprio 0
	s_barrier
	s_add_i32 s42, s61, s31
	v_lshl_add_u64 v[170:171], v[170:171], 0, s[24:25]
	s_mov_b32 m0, s42
	ds_read_b128 v[186:189], v176 offset:49152
	ds_read_b128 v[190:193], v176 offset:50176
	ds_read_b128 v[194:197], v176 offset:51200
	ds_read_b128 v[198:201], v176 offset:52224
	ds_read_b128 v[202:205], v176 offset:53248
	ds_read_b128 v[206:209], v176 offset:54272
	ds_read_b128 v[210:213], v176 offset:55296
	ds_read_b128 v[218:221], v176 offset:56320
	global_load_lds_dwordx4 v[170:171], off
	s_add_i32 m0, s42, 0x2000
	s_add_u32 s34, s34, 0x160080
	v_lshl_add_u64 v[170:171], v[214:215], 0, s[24:25]
	s_addc_u32 s35, s35, 0
	s_add_i32 s42, s62, s31
	global_load_lds_dwordx4 v[170:171], off
	v_lshl_add_u64 v[170:171], s[34:35], 0, v[144:145]
	s_mov_b32 m0, s42
	s_nop 0
	global_load_lds_dwordx4 v[170:171], off
	v_lshl_add_u64 v[170:171], s[34:35], 0, v[148:149]
	s_add_i32 m0, s42, 0x2000
	s_nop 0
	global_load_lds_dwordx4 v[170:171], off
	v_lshl_add_u64 v[170:171], v[222:223], 0, s[24:25]
	s_mov_b32 m0, s48
	s_nop 0
	global_load_lds_dwordx4 v[170:171], off
	v_lshl_add_u64 v[170:171], v[224:225], 0, s[24:25]
	s_mov_b32 m0, s49
	s_nop 0
	global_load_lds_dwordx4 v[170:171], off
	s_waitcnt vmcnt(8)
	s_waitcnt lgkmcnt(0)
	s_barrier
	s_setprio 1
	s_waitcnt lgkmcnt(0)
	v_mfma_f32_16x16x32_bf16 v[62:65], v[130:133], v[186:189], v[62:65]
	v_mfma_f32_16x16x32_bf16 v[58:61], v[138:141], v[186:189], v[58:61]
	v_mfma_f32_16x16x32_bf16 v[50:53], v[130:133], v[194:197], v[50:53]
	v_mfma_f32_16x16x32_bf16 v[42:45], v[138:141], v[194:197], v[42:45]
	v_mfma_f32_16x16x32_bf16 v[38:41], v[130:133], v[202:205], v[38:41]
	v_mfma_f32_16x16x32_bf16 v[34:37], v[138:141], v[202:205], v[34:37]
	v_mfma_f32_16x16x32_bf16 v[14:17], v[130:133], v[210:213], v[14:17]
	v_mfma_f32_16x16x32_bf16 v[10:13], v[138:141], v[210:213], v[10:13]
	v_mfma_f32_16x16x32_bf16 v[62:65], v[134:137], v[190:193], v[62:65]
	v_mfma_f32_16x16x32_bf16 v[58:61], v[158:161], v[190:193], v[58:61]
	v_mfma_f32_16x16x32_bf16 v[50:53], v[134:137], v[198:201], v[50:53]
	v_mfma_f32_16x16x32_bf16 v[42:45], v[158:161], v[198:201], v[42:45]
	v_mfma_f32_16x16x32_bf16 v[38:41], v[134:137], v[206:209], v[38:41]
	v_mfma_f32_16x16x32_bf16 v[34:37], v[158:161], v[206:209], v[34:37]
	v_mfma_f32_16x16x32_bf16 v[14:17], v[134:137], v[218:221], v[14:17]
	v_mfma_f32_16x16x32_bf16 v[10:13], v[158:161], v[218:221], v[10:13]
	s_setprio 0
	s_setprio 1
	v_mfma_f32_16x16x32_bf16 v[54:57], v[162:165], v[186:189], v[54:57]
	v_mfma_f32_16x16x32_bf16 v[46:49], v[178:181], v[186:189], v[46:49]
	v_mfma_f32_16x16x32_bf16 v[30:33], v[162:165], v[194:197], v[30:33]
	v_mfma_f32_16x16x32_bf16 v[26:29], v[178:181], v[194:197], v[26:29]
	v_mfma_f32_16x16x32_bf16 v[22:25], v[162:165], v[202:205], v[22:25]
	v_mfma_f32_16x16x32_bf16 v[18:21], v[178:181], v[202:205], v[18:21]
	v_mfma_f32_16x16x32_bf16 v[6:9], v[162:165], v[210:213], v[6:9]
	v_mfma_f32_16x16x32_bf16 v[2:5], v[178:181], v[210:213], v[2:5]
	v_mfma_f32_16x16x32_bf16 v[54:57], v[166:169], v[190:193], v[54:57]
	v_mfma_f32_16x16x32_bf16 v[46:49], v[182:185], v[190:193], v[46:49]
	v_mfma_f32_16x16x32_bf16 v[30:33], v[166:169], v[198:201], v[30:33]
	v_mfma_f32_16x16x32_bf16 v[26:29], v[182:185], v[198:201], v[26:29]
	v_mfma_f32_16x16x32_bf16 v[22:25], v[166:169], v[206:209], v[22:25]
	v_mfma_f32_16x16x32_bf16 v[18:21], v[182:185], v[206:209], v[18:21]
	v_mfma_f32_16x16x32_bf16 v[6:9], v[166:169], v[218:221], v[6:9]
	v_mfma_f32_16x16x32_bf16 v[2:5], v[182:185], v[218:221], v[2:5]
	s_setprio 0
	s_barrier
	s_add_i32 s60, s60, 2
	s_add_u32 s40, s40, 0x100
	s_addc_u32 s41, s41, 0
	s_add_u32 s0, s0, 0x100
	s_addc_u32 s1, s1, 0

.LBB0_3308:
	s_ashr_i32 s37, s36, 31
	s_lshl_b64 s[0:1], s[36:37], 20
	v_readlane_b32 s27, v247, 45
	s_add_u32 s38, s27, s0
	v_readlane_b32 s0, v247, 47
	s_addc_u32 s39, s0, s1
	s_and_b64 s[0:1], s[2:3], exec
	s_cselect_b32 s0, s39, s35
	s_cselect_b32 s1, s38, s34
	s_ashr_i32 s27, s26, 31
	s_lshl_b64 s[40:41], s[26:27], 20
	s_add_u32 s40, s12, s40
	s_addc_u32 s41, s13, s41
	s_and_b64 s[44:45], s[2:3], exec
	s_cselect_b32 s27, s41, s47
	s_cselect_b32 s37, s40, s46
	s_add_u32 s44, s34, 0x80080
	s_addc_u32 s45, s35, 0
	s_add_u32 s61, s46, 0x100
	s_addc_u32 s68, s47, 0
	s_mov_b32 s69, -2
	ds_read_b128 v[146:149], v153
	ds_read_b128 v[156:159], v153 offset:1024
	ds_read_b128 v[160:163], v153 offset:2048
	ds_read_b128 v[164:167], v153 offset:3072
	ds_read_b128 v[168:171], v154
	ds_read_b128 v[172:175], v154 offset:1024
	ds_read_b128 v[176:179], v154 offset:2048
	ds_read_b128 v[180:183], v154 offset:3072
	s_add_u32 s34, s44, 0xfff80080
	s_addc_u32 s35, s45, -1
	s_cmp_eq_u32 s69, 28
	s_cselect_b32 s47, s0, s35
	s_cselect_b32 s46, s1, s34
	s_cselect_b32 s35, s27, s68
	s_cselect_b32 s34, s37, s61
	v_lshl_add_u64 v[218:219], s[44:45], 0, v[138:139]
	s_add_i32 m0, s43, 0xc000
	ds_read_b128 v[184:187], v155
	ds_read_b128 v[188:191], v155 offset:1024
	ds_read_b128 v[192:195], v155 offset:2048
	ds_read_b128 v[196:199], v155 offset:3072
	ds_read_b128 v[200:203], v155 offset:4096
	ds_read_b128 v[204:207], v155 offset:5120
	ds_read_b128 v[208:211], v155 offset:6144
	ds_read_b128 v[212:215], v155 offset:7168
	global_load_lds_dwordx4 v[218:219], off
	v_lshl_add_u64 v[218:219], s[44:45], 0, v[140:141]
	s_add_i32 m0, s43, 0xe000
	s_nop 0
	global_load_lds_dwordx4 v[218:219], off
	s_waitcnt vmcnt(8)
	s_waitcnt lgkmcnt(0)
	s_barrier
	s_setprio 1
	s_waitcnt lgkmcnt(0)
	v_mfma_f32_16x16x32_bf16 v[126:129], v[146:149], v[184:187], 0
	v_mfma_f32_16x16x32_bf16 v[118:121], v[160:163], v[184:187], 0
	v_mfma_f32_16x16x32_bf16 v[110:113], v[146:149], v[192:195], 0
	v_mfma_f32_16x16x32_bf16 v[102:105], v[160:163], v[192:195], 0
	v_mfma_f32_16x16x32_bf16 v[94:97], v[146:149], v[200:203], 0
	v_mfma_f32_16x16x32_bf16 v[86:89], v[160:163], v[200:203], 0
	v_mfma_f32_16x16x32_bf16 v[78:81], v[146:149], v[208:211], 0
	v_mfma_f32_16x16x32_bf16 v[70:73], v[160:163], v[208:211], 0
	v_mfma_f32_16x16x32_bf16 v[126:129], v[156:159], v[188:191], v[126:129]
	v_mfma_f32_16x16x32_bf16 v[118:121], v[164:167], v[188:191], v[118:121]
	v_mfma_f32_16x16x32_bf16 v[110:113], v[156:159], v[196:199], v[110:113]
	v_mfma_f32_16x16x32_bf16 v[102:105], v[164:167], v[196:199], v[102:105]
	v_mfma_f32_16x16x32_bf16 v[94:97], v[156:159], v[204:207], v[94:97]
	v_mfma_f32_16x16x32_bf16 v[86:89], v[164:167], v[204:207], v[86:89]
	v_mfma_f32_16x16x32_bf16 v[78:81], v[156:159], v[212:215], v[78:81]
	v_mfma_f32_16x16x32_bf16 v[70:73], v[164:167], v[212:215], v[70:73]
	s_setprio 0
	s_setprio 1
	v_mfma_f32_16x16x32_bf16 v[122:125], v[168:171], v[184:187], 0
	v_mfma_f32_16x16x32_bf16 v[114:117], v[176:179], v[184:187], 0
	v_mfma_f32_16x16x32_bf16 v[106:109], v[168:171], v[192:195], 0
	v_mfma_f32_16x16x32_bf16 v[98:101], v[176:179], v[192:195], 0
	v_mfma_f32_16x16x32_bf16 v[90:93], v[168:171], v[200:203], 0
	v_mfma_f32_16x16x32_bf16 v[82:85], v[176:179], v[200:203], 0
	v_mfma_f32_16x16x32_bf16 v[74:77], v[168:171], v[208:211], 0
	v_mfma_f32_16x16x32_bf16 v[66:69], v[176:179], v[208:211], 0
	v_mfma_f32_16x16x32_bf16 v[122:125], v[172:175], v[188:191], v[122:125]
	v_mfma_f32_16x16x32_bf16 v[114:117], v[180:183], v[188:191], v[114:117]
	v_mfma_f32_16x16x32_bf16 v[106:109], v[172:175], v[196:199], v[106:109]
	v_mfma_f32_16x16x32_bf16 v[98:101], v[180:183], v[196:199], v[98:101]
	v_mfma_f32_16x16x32_bf16 v[90:93], v[172:175], v[204:207], v[90:93]
	v_mfma_f32_16x16x32_bf16 v[82:85], v[180:183], v[204:207], v[82:85]
	v_mfma_f32_16x16x32_bf16 v[74:77], v[172:175], v[212:215], v[74:77]
	v_mfma_f32_16x16x32_bf16 v[66:69], v[180:183], v[212:215], v[66:69]
	s_setprio 0
	s_barrier
	s_add_i32 s62, s57, s30
	v_lshl_add_u64 v[218:219], s[34:35], 0, v[134:135]
	s_mov_b32 m0, s62
	ds_read_b128 v[184:187], v155 offset:16384
	ds_read_b128 v[188:191], v155 offset:17408
	ds_read_b128 v[192:195], v155 offset:18432
	ds_read_b128 v[196:199], v155 offset:19456
	ds_read_b128 v[200:203], v155 offset:20480
	ds_read_b128 v[204:207], v155 offset:21504
	ds_read_b128 v[208:211], v155 offset:22528
	ds_read_b128 v[212:215], v155 offset:23552
	global_load_lds_dwordx4 v[218:219], off
	s_add_i32 m0, s62, 0x2000
	s_add_u32 s62, s34, 0x80000
	v_lshl_add_u64 v[220:221], s[34:35], 0, v[130:131]
	s_addc_u32 s63, s35, 0
	s_add_i32 s66, s58, s30
	global_load_lds_dwordx4 v[220:221], off
	v_lshl_add_u64 v[222:223], s[62:63], 0, v[134:135]
	s_mov_b32 m0, s66
	v_lshl_add_u64 v[224:225], s[46:47], 0, v[132:133]
	global_load_lds_dwordx4 v[222:223], off
	v_lshl_add_u64 v[222:223], s[62:63], 0, v[130:131]
	s_add_i32 m0, s66, 0x2000
	s_nop 0
	global_load_lds_dwordx4 v[222:223], off
	v_lshl_add_u64 v[222:223], s[46:47], 0, v[136:137]
	s_mov_b32 m0, s43
	s_nop 0
	global_load_lds_dwordx4 v[222:223], off
	s_mov_b32 m0, s48
	s_nop 0
	global_load_lds_dwordx4 v[224:225], off
	s_waitcnt vmcnt(8)
	s_waitcnt lgkmcnt(0)
	s_barrier
	s_setprio 1
	s_waitcnt lgkmcnt(0)
	v_mfma_f32_16x16x32_bf16 v[62:65], v[146:149], v[184:187], 0
	v_mfma_f32_16x16x32_bf16 v[54:57], v[160:163], v[184:187], 0
	v_mfma_f32_16x16x32_bf16 v[46:49], v[146:149], v[192:195], 0
	v_mfma_f32_16x16x32_bf16 v[38:41], v[160:163], v[192:195], 0
	v_mfma_f32_16x16x32_bf16 v[30:33], v[146:149], v[200:203], 0
	v_mfma_f32_16x16x32_bf16 v[22:25], v[160:163], v[200:203], 0
	v_mfma_f32_16x16x32_bf16 v[14:17], v[146:149], v[208:211], 0
	v_mfma_f32_16x16x32_bf16 v[6:9], v[160:163], v[208:211], 0
	v_mfma_f32_16x16x32_bf16 v[62:65], v[156:159], v[188:191], v[62:65]
	v_mfma_f32_16x16x32_bf16 v[54:57], v[164:167], v[188:191], v[54:57]
	v_mfma_f32_16x16x32_bf16 v[46:49], v[156:159], v[196:199], v[46:49]
	v_mfma_f32_16x16x32_bf16 v[38:41], v[164:167], v[196:199], v[38:41]
	v_mfma_f32_16x16x32_bf16 v[30:33], v[156:159], v[204:207], v[30:33]
	v_mfma_f32_16x16x32_bf16 v[22:25], v[164:167], v[204:207], v[22:25]
	v_mfma_f32_16x16x32_bf16 v[14:17], v[156:159], v[212:215], v[14:17]
	v_mfma_f32_16x16x32_bf16 v[6:9], v[164:167], v[212:215], v[6:9]
	s_setprio 0
	s_setprio 1
	v_mfma_f32_16x16x32_bf16 v[58:61], v[168:171], v[184:187], 0
	v_mfma_f32_16x16x32_bf16 v[50:53], v[176:179], v[184:187], 0
	v_mfma_f32_16x16x32_bf16 v[42:45], v[168:171], v[192:195], 0
	v_mfma_f32_16x16x32_bf16 v[34:37], v[176:179], v[192:195], 0
	v_mfma_f32_16x16x32_bf16 v[26:29], v[168:171], v[200:203], 0
	v_mfma_f32_16x16x32_bf16 v[18:21], v[176:179], v[200:203], 0
	v_mfma_f32_16x16x32_bf16 v[10:13], v[168:171], v[208:211], 0
	v_mfma_f32_16x16x32_bf16 v[2:5], v[176:179], v[208:211], 0
	v_mfma_f32_16x16x32_bf16 v[58:61], v[172:175], v[188:191], v[58:61]
	v_mfma_f32_16x16x32_bf16 v[50:53], v[180:183], v[188:191], v[50:53]
	v_mfma_f32_16x16x32_bf16 v[42:45], v[172:175], v[196:199], v[42:45]
	v_mfma_f32_16x16x32_bf16 v[34:37], v[180:183], v[196:199], v[34:37]
	v_mfma_f32_16x16x32_bf16 v[26:29], v[172:175], v[204:207], v[26:29]
	v_mfma_f32_16x16x32_bf16 v[18:21], v[180:183], v[204:207], v[18:21]
	v_mfma_f32_16x16x32_bf16 v[10:13], v[172:175], v[212:215], v[10:13]
	v_mfma_f32_16x16x32_bf16 v[2:5], v[180:183], v[212:215], v[2:5]
	s_setprio 0
	s_barrier
	s_add_i32 s62, 0, 0x18000
	s_add_i32 s63, 0, 0x1c000
	v_add_u32_e32 v164, s62, v151
	v_add_u32_e32 v180, s63, v151
	ds_read_b128 v[146:149], v164
	ds_read_b128 v[156:159], v164 offset:1024
	ds_read_b128 v[160:163], v164 offset:2048
	ds_read_b128 v[164:167], v164 offset:3072
	ds_read_b128 v[168:171], v180
	ds_read_b128 v[172:175], v180 offset:1024
	ds_read_b128 v[176:179], v180 offset:2048
	ds_read_b128 v[180:183], v180 offset:3072
	s_add_u32 s46, s46, 0x80000
	s_addc_u32 s47, s47, 0
	s_mov_b32 m0, s49
	v_lshl_add_u64 v[226:227], s[46:47], 0, v[136:137]
	ds_read_b128 v[184:187], v155 offset:32768
	ds_read_b128 v[188:191], v155 offset:33792
	ds_read_b128 v[192:195], v155 offset:34816
	ds_read_b128 v[196:199], v155 offset:35840
	ds_read_b128 v[200:203], v155 offset:36864
	ds_read_b128 v[204:207], v155 offset:37888
	ds_read_b128 v[208:211], v155 offset:38912
	ds_read_b128 v[212:215], v155 offset:39936
	global_load_lds_dwordx4 v[226:227], off
	v_lshl_add_u64 v[226:227], s[46:47], 0, v[132:133]
	s_mov_b32 m0, s52
	s_nop 0
	global_load_lds_dwordx4 v[226:227], off
	s_waitcnt vmcnt(8)
	s_waitcnt lgkmcnt(0)
	s_barrier
	s_setprio 1
	s_waitcnt lgkmcnt(0)
	v_mfma_f32_16x16x32_bf16 v[126:129], v[146:149], v[184:187], v[126:129]
	v_mfma_f32_16x16x32_bf16 v[118:121], v[160:163], v[184:187], v[118:121]
	v_mfma_f32_16x16x32_bf16 v[110:113], v[146:149], v[192:195], v[110:113]
	v_mfma_f32_16x16x32_bf16 v[102:105], v[160:163], v[192:195], v[102:105]
	v_mfma_f32_16x16x32_bf16 v[94:97], v[146:149], v[200:203], v[94:97]
	v_mfma_f32_16x16x32_bf16 v[86:89], v[160:163], v[200:203], v[86:89]
	v_mfma_f32_16x16x32_bf16 v[78:81], v[146:149], v[208:211], v[78:81]
	v_mfma_f32_16x16x32_bf16 v[70:73], v[160:163], v[208:211], v[70:73]
	v_mfma_f32_16x16x32_bf16 v[126:129], v[156:159], v[188:191], v[126:129]
	v_mfma_f32_16x16x32_bf16 v[118:121], v[164:167], v[188:191], v[118:121]
	v_mfma_f32_16x16x32_bf16 v[110:113], v[156:159], v[196:199], v[110:113]
	v_mfma_f32_16x16x32_bf16 v[102:105], v[164:167], v[196:199], v[102:105]
	v_mfma_f32_16x16x32_bf16 v[94:97], v[156:159], v[204:207], v[94:97]
	v_mfma_f32_16x16x32_bf16 v[86:89], v[164:167], v[204:207], v[86:89]
	v_mfma_f32_16x16x32_bf16 v[78:81], v[156:159], v[212:215], v[78:81]
	v_mfma_f32_16x16x32_bf16 v[70:73], v[164:167], v[212:215], v[70:73]
	s_setprio 0
	s_setprio 1
	v_mfma_f32_16x16x32_bf16 v[122:125], v[168:171], v[184:187], v[122:125]
	v_mfma_f32_16x16x32_bf16 v[114:117], v[176:179], v[184:187], v[114:117]
	v_mfma_f32_16x16x32_bf16 v[106:109], v[168:171], v[192:195], v[106:109]
	v_mfma_f32_16x16x32_bf16 v[98:101], v[176:179], v[192:195], v[98:101]
	v_mfma_f32_16x16x32_bf16 v[90:93], v[168:171], v[200:203], v[90:93]
	v_mfma_f32_16x16x32_bf16 v[82:85], v[176:179], v[200:203], v[82:85]
	v_mfma_f32_16x16x32_bf16 v[74:77], v[168:171], v[208:211], v[74:77]
	v_mfma_f32_16x16x32_bf16 v[66:69], v[176:179], v[208:211], v[66:69]
	v_mfma_f32_16x16x32_bf16 v[122:125], v[172:175], v[188:191], v[122:125]
	v_mfma_f32_16x16x32_bf16 v[114:117], v[180:183], v[188:191], v[114:117]
	v_mfma_f32_16x16x32_bf16 v[106:109], v[172:175], v[196:199], v[106:109]
	v_mfma_f32_16x16x32_bf16 v[98:101], v[180:183], v[196:199], v[98:101]
	v_mfma_f32_16x16x32_bf16 v[90:93], v[172:175], v[204:207], v[90:93]
	v_mfma_f32_16x16x32_bf16 v[82:85], v[180:183], v[204:207], v[82:85]
	v_mfma_f32_16x16x32_bf16 v[74:77], v[172:175], v[212:215], v[74:77]
	v_mfma_f32_16x16x32_bf16 v[66:69], v[180:183], v[212:215], v[66:69]
	s_setprio 0
	s_barrier
	s_add_i32 s46, s62, s30
	v_lshl_add_u64 v[218:219], v[218:219], 0, s[8:9]
	s_mov_b32 m0, s46
	ds_read_b128 v[184:187], v155 offset:49152
	ds_read_b128 v[188:191], v155 offset:50176
	ds_read_b128 v[192:195], v155 offset:51200
	ds_read_b128 v[196:199], v155 offset:52224
	ds_read_b128 v[200:203], v155 offset:53248
	ds_read_b128 v[204:207], v155 offset:54272
	ds_read_b128 v[208:211], v155 offset:55296
	ds_read_b128 v[212:215], v155 offset:56320
	global_load_lds_dwordx4 v[218:219], off
	s_add_i32 m0, s46, 0x2000
	s_add_u32 s34, s34, 0x80080
	v_lshl_add_u64 v[218:219], v[220:221], 0, s[8:9]
	s_addc_u32 s35, s35, 0
	s_add_i32 s46, s63, s30
	global_load_lds_dwordx4 v[218:219], off
	v_lshl_add_u64 v[218:219], s[34:35], 0, v[134:135]
	s_mov_b32 m0, s46
	s_nop 0
	global_load_lds_dwordx4 v[218:219], off
	v_lshl_add_u64 v[218:219], s[34:35], 0, v[130:131]
	s_add_i32 m0, s46, 0x2000
	s_nop 0
	global_load_lds_dwordx4 v[218:219], off
	v_lshl_add_u64 v[218:219], v[222:223], 0, s[8:9]
	s_mov_b32 m0, s54
	s_nop 0
	global_load_lds_dwordx4 v[218:219], off
	v_lshl_add_u64 v[218:219], v[224:225], 0, s[8:9]
	s_mov_b32 m0, s55
	s_nop 0
	global_load_lds_dwordx4 v[218:219], off
	s_waitcnt vmcnt(8)
	s_waitcnt lgkmcnt(0)
	s_barrier
	s_setprio 1
	s_waitcnt lgkmcnt(0)
	v_mfma_f32_16x16x32_bf16 v[62:65], v[146:149], v[184:187], v[62:65]
	v_mfma_f32_16x16x32_bf16 v[54:57], v[160:163], v[184:187], v[54:57]
	v_mfma_f32_16x16x32_bf16 v[46:49], v[146:149], v[192:195], v[46:49]
	v_mfma_f32_16x16x32_bf16 v[38:41], v[160:163], v[192:195], v[38:41]
	v_mfma_f32_16x16x32_bf16 v[30:33], v[146:149], v[200:203], v[30:33]
	v_mfma_f32_16x16x32_bf16 v[22:25], v[160:163], v[200:203], v[22:25]
	v_mfma_f32_16x16x32_bf16 v[14:17], v[146:149], v[208:211], v[14:17]
	v_mfma_f32_16x16x32_bf16 v[6:9], v[160:163], v[208:211], v[6:9]
	v_mfma_f32_16x16x32_bf16 v[62:65], v[156:159], v[188:191], v[62:65]
	v_mfma_f32_16x16x32_bf16 v[54:57], v[164:167], v[188:191], v[54:57]
	v_mfma_f32_16x16x32_bf16 v[46:49], v[156:159], v[196:199], v[46:49]
	v_mfma_f32_16x16x32_bf16 v[38:41], v[164:167], v[196:199], v[38:41]
	v_mfma_f32_16x16x32_bf16 v[30:33], v[156:159], v[204:207], v[30:33]
	v_mfma_f32_16x16x32_bf16 v[22:25], v[164:167], v[204:207], v[22:25]
	v_mfma_f32_16x16x32_bf16 v[14:17], v[156:159], v[212:215], v[14:17]
	v_mfma_f32_16x16x32_bf16 v[6:9], v[164:167], v[212:215], v[6:9]
	s_setprio 0
	s_setprio 1
	v_mfma_f32_16x16x32_bf16 v[58:61], v[168:171], v[184:187], v[58:61]
	v_mfma_f32_16x16x32_bf16 v[50:53], v[176:179], v[184:187], v[50:53]
	v_mfma_f32_16x16x32_bf16 v[42:45], v[168:171], v[192:195], v[42:45]
	v_mfma_f32_16x16x32_bf16 v[34:37], v[176:179], v[192:195], v[34:37]
	v_mfma_f32_16x16x32_bf16 v[26:29], v[168:171], v[200:203], v[26:29]
	v_mfma_f32_16x16x32_bf16 v[18:21], v[176:179], v[200:203], v[18:21]
	v_mfma_f32_16x16x32_bf16 v[10:13], v[168:171], v[208:211], v[10:13]
	v_mfma_f32_16x16x32_bf16 v[2:5], v[176:179], v[208:211], v[2:5]
	v_mfma_f32_16x16x32_bf16 v[58:61], v[172:175], v[188:191], v[58:61]
	v_mfma_f32_16x16x32_bf16 v[50:53], v[180:183], v[188:191], v[50:53]
	v_mfma_f32_16x16x32_bf16 v[42:45], v[172:175], v[196:199], v[42:45]
	v_mfma_f32_16x16x32_bf16 v[34:37], v[180:183], v[196:199], v[34:37]
	v_mfma_f32_16x16x32_bf16 v[26:29], v[172:175], v[204:207], v[26:29]
	v_mfma_f32_16x16x32_bf16 v[18:21], v[180:183], v[204:207], v[18:21]
	v_mfma_f32_16x16x32_bf16 v[10:13], v[172:175], v[212:215], v[10:13]
	v_mfma_f32_16x16x32_bf16 v[2:5], v[180:183], v[212:215], v[2:5]
	s_setprio 0
	s_barrier
	s_add_i32 s69, s69, 2
	s_add_u32 s44, s44, 0x100
	s_addc_u32 s45, s45, 0
	s_add_u32 s61, s61, 0x100
	s_addc_u32 s68, s68, 0

.LBB0_3532:
	s_ashr_i32 s37, s36, 31
	s_lshl_b64 s[0:1], s[36:37], 20
	v_readlane_b32 s27, v247, 45
	s_add_u32 s38, s27, s0
	v_readlane_b32 s0, v247, 47
	s_addc_u32 s39, s0, s1
	s_and_b64 s[0:1], s[2:3], exec
	s_cselect_b32 s0, s39, s35
	s_cselect_b32 s1, s38, s34
	s_ashr_i32 s27, s26, 31
	s_lshl_b64 s[40:41], s[26:27], 20
	s_add_u32 s40, s13, s40
	s_addc_u32 s41, s30, s41
	s_and_b64 s[44:45], s[2:3], exec
	s_cselect_b32 s27, s41, s47
	s_cselect_b32 s37, s40, s46
	s_add_u32 s44, s34, 0x80080
	s_addc_u32 s45, s35, 0
	s_add_u32 s60, s46, 0x100
	s_addc_u32 s61, s47, 0
	s_mov_b32 s68, -2
	ds_read_b128 v[154:157], v151
	ds_read_b128 v[158:161], v151 offset:1024
	ds_read_b128 v[162:165], v151 offset:2048
	ds_read_b128 v[166:169], v151 offset:3072
	ds_read_b128 v[170:173], v152
	ds_read_b128 v[174:177], v152 offset:1024
	ds_read_b128 v[178:181], v152 offset:2048
	ds_read_b128 v[182:185], v152 offset:3072
	s_add_u32 s34, s44, 0xfff80080
	s_addc_u32 s35, s45, -1
	s_cmp_eq_u32 s68, 28
	s_cselect_b32 s47, s0, s35
	s_cselect_b32 s46, s1, s34
	s_cselect_b32 s35, s27, s61
	s_cselect_b32 s34, s37, s60
	v_lshl_add_u64 v[146:147], s[44:45], 0, v[138:139]
	s_add_i32 m0, s33, 0xc000
	ds_read_b128 v[186:189], v153
	ds_read_b128 v[190:193], v153 offset:1024
	ds_read_b128 v[194:197], v153 offset:2048
	ds_read_b128 v[198:201], v153 offset:3072
	ds_read_b128 v[202:205], v153 offset:4096
	ds_read_b128 v[206:209], v153 offset:5120
	ds_read_b128 v[210:213], v153 offset:6144
	ds_read_b128 v[218:221], v153 offset:7168
	global_load_lds_dwordx4 v[146:147], off
	v_lshl_add_u64 v[146:147], s[44:45], 0, v[140:141]
	s_add_i32 m0, s33, 0xe000
	s_nop 0
	global_load_lds_dwordx4 v[146:147], off
	s_waitcnt vmcnt(8)
	s_waitcnt lgkmcnt(0)
	s_barrier
	s_setprio 1
	s_waitcnt lgkmcnt(0)
	v_mfma_f32_16x16x32_bf16 v[126:129], v[154:157], v[186:189], 0
	v_mfma_f32_16x16x32_bf16 v[122:125], v[162:165], v[186:189], 0
	v_mfma_f32_16x16x32_bf16 v[114:117], v[154:157], v[194:197], 0
	v_mfma_f32_16x16x32_bf16 v[106:109], v[162:165], v[194:197], 0
	v_mfma_f32_16x16x32_bf16 v[98:101], v[154:157], v[202:205], 0
	v_mfma_f32_16x16x32_bf16 v[90:93], v[162:165], v[202:205], 0
	v_mfma_f32_16x16x32_bf16 v[82:85], v[154:157], v[210:213], 0
	v_mfma_f32_16x16x32_bf16 v[74:77], v[162:165], v[210:213], 0
	v_mfma_f32_16x16x32_bf16 v[126:129], v[158:161], v[190:193], v[126:129]
	v_mfma_f32_16x16x32_bf16 v[122:125], v[166:169], v[190:193], v[122:125]
	v_mfma_f32_16x16x32_bf16 v[114:117], v[158:161], v[198:201], v[114:117]
	v_mfma_f32_16x16x32_bf16 v[106:109], v[166:169], v[198:201], v[106:109]
	v_mfma_f32_16x16x32_bf16 v[98:101], v[158:161], v[206:209], v[98:101]
	v_mfma_f32_16x16x32_bf16 v[90:93], v[166:169], v[206:209], v[90:93]
	v_mfma_f32_16x16x32_bf16 v[82:85], v[158:161], v[218:221], v[82:85]
	v_mfma_f32_16x16x32_bf16 v[74:77], v[166:169], v[218:221], v[74:77]
	s_setprio 0
	s_setprio 1
	v_mfma_f32_16x16x32_bf16 v[118:121], v[170:173], v[186:189], 0
	v_mfma_f32_16x16x32_bf16 v[110:113], v[178:181], v[186:189], 0
	v_mfma_f32_16x16x32_bf16 v[102:105], v[170:173], v[194:197], 0
	v_mfma_f32_16x16x32_bf16 v[94:97], v[178:181], v[194:197], 0
	v_mfma_f32_16x16x32_bf16 v[86:89], v[170:173], v[202:205], 0
	v_mfma_f32_16x16x32_bf16 v[78:81], v[178:181], v[202:205], 0
	v_mfma_f32_16x16x32_bf16 v[70:73], v[170:173], v[210:213], 0
	v_mfma_f32_16x16x32_bf16 v[66:69], v[178:181], v[210:213], 0
	v_mfma_f32_16x16x32_bf16 v[118:121], v[174:177], v[190:193], v[118:121]
	v_mfma_f32_16x16x32_bf16 v[110:113], v[182:185], v[190:193], v[110:113]
	v_mfma_f32_16x16x32_bf16 v[102:105], v[174:177], v[198:201], v[102:105]
	v_mfma_f32_16x16x32_bf16 v[94:97], v[182:185], v[198:201], v[94:97]
	v_mfma_f32_16x16x32_bf16 v[86:89], v[174:177], v[206:209], v[86:89]
	v_mfma_f32_16x16x32_bf16 v[78:81], v[182:185], v[206:209], v[78:81]
	v_mfma_f32_16x16x32_bf16 v[70:73], v[174:177], v[218:221], v[70:73]
	v_mfma_f32_16x16x32_bf16 v[66:69], v[182:185], v[218:221], v[66:69]
	s_setprio 0
	s_barrier
	s_add_i32 s62, s56, s12
	v_lshl_add_u64 v[146:147], s[34:35], 0, v[134:135]
	s_mov_b32 m0, s62
	ds_read_b128 v[186:189], v153 offset:16384
	ds_read_b128 v[190:193], v153 offset:17408
	ds_read_b128 v[194:197], v153 offset:18432
	ds_read_b128 v[198:201], v153 offset:19456
	ds_read_b128 v[202:205], v153 offset:20480
	ds_read_b128 v[206:209], v153 offset:21504
	ds_read_b128 v[210:213], v153 offset:22528
	ds_read_b128 v[218:221], v153 offset:23552
	global_load_lds_dwordx4 v[146:147], off
	s_add_i32 m0, s62, 0x2000
	s_add_u32 s62, s34, 0x80000
	v_lshl_add_u64 v[214:215], s[34:35], 0, v[130:131]
	s_addc_u32 s63, s35, 0
	s_add_i32 s66, s57, s12
	global_load_lds_dwordx4 v[214:215], off
	v_lshl_add_u64 v[222:223], s[62:63], 0, v[134:135]
	s_mov_b32 m0, s66
	v_lshl_add_u64 v[224:225], s[46:47], 0, v[132:133]
	global_load_lds_dwordx4 v[222:223], off
	v_lshl_add_u64 v[222:223], s[62:63], 0, v[130:131]
	s_add_i32 m0, s66, 0x2000
	s_nop 0
	global_load_lds_dwordx4 v[222:223], off
	v_lshl_add_u64 v[222:223], s[46:47], 0, v[136:137]
	s_mov_b32 m0, s33
	s_nop 0
	global_load_lds_dwordx4 v[222:223], off
	s_mov_b32 m0, s43
	s_nop 0
	global_load_lds_dwordx4 v[224:225], off
	s_waitcnt vmcnt(8)
	s_waitcnt lgkmcnt(0)
	s_barrier
	s_setprio 1
	s_waitcnt lgkmcnt(0)
	v_mfma_f32_16x16x32_bf16 v[62:65], v[154:157], v[186:189], 0
	v_mfma_f32_16x16x32_bf16 v[58:61], v[162:165], v[186:189], 0
	v_mfma_f32_16x16x32_bf16 v[50:53], v[154:157], v[194:197], 0
	v_mfma_f32_16x16x32_bf16 v[42:45], v[162:165], v[194:197], 0
	v_mfma_f32_16x16x32_bf16 v[34:37], v[154:157], v[202:205], 0
	v_mfma_f32_16x16x32_bf16 v[26:29], v[162:165], v[202:205], 0
	v_mfma_f32_16x16x32_bf16 v[18:21], v[154:157], v[210:213], 0
	v_mfma_f32_16x16x32_bf16 v[10:13], v[162:165], v[210:213], 0
	v_mfma_f32_16x16x32_bf16 v[62:65], v[158:161], v[190:193], v[62:65]
	v_mfma_f32_16x16x32_bf16 v[58:61], v[166:169], v[190:193], v[58:61]
	v_mfma_f32_16x16x32_bf16 v[50:53], v[158:161], v[198:201], v[50:53]
	v_mfma_f32_16x16x32_bf16 v[42:45], v[166:169], v[198:201], v[42:45]
	v_mfma_f32_16x16x32_bf16 v[34:37], v[158:161], v[206:209], v[34:37]
	v_mfma_f32_16x16x32_bf16 v[26:29], v[166:169], v[206:209], v[26:29]
	v_mfma_f32_16x16x32_bf16 v[18:21], v[158:161], v[218:221], v[18:21]
	v_mfma_f32_16x16x32_bf16 v[10:13], v[166:169], v[218:221], v[10:13]
	s_setprio 0
	s_setprio 1
	v_mfma_f32_16x16x32_bf16 v[54:57], v[170:173], v[186:189], 0
	v_mfma_f32_16x16x32_bf16 v[46:49], v[178:181], v[186:189], 0
	v_mfma_f32_16x16x32_bf16 v[38:41], v[170:173], v[194:197], 0
	v_mfma_f32_16x16x32_bf16 v[30:33], v[178:181], v[194:197], 0
	v_mfma_f32_16x16x32_bf16 v[22:25], v[170:173], v[202:205], 0
	v_mfma_f32_16x16x32_bf16 v[14:17], v[178:181], v[202:205], 0
	v_mfma_f32_16x16x32_bf16 v[6:9], v[170:173], v[210:213], 0
	v_mfma_f32_16x16x32_bf16 v[2:5], v[178:181], v[210:213], 0
	v_mfma_f32_16x16x32_bf16 v[54:57], v[174:177], v[190:193], v[54:57]
	v_mfma_f32_16x16x32_bf16 v[46:49], v[182:185], v[190:193], v[46:49]
	v_mfma_f32_16x16x32_bf16 v[38:41], v[174:177], v[198:201], v[38:41]
	v_mfma_f32_16x16x32_bf16 v[30:33], v[182:185], v[198:201], v[30:33]
	v_mfma_f32_16x16x32_bf16 v[22:25], v[174:177], v[206:209], v[22:25]
	v_mfma_f32_16x16x32_bf16 v[14:17], v[182:185], v[206:209], v[14:17]
	v_mfma_f32_16x16x32_bf16 v[6:9], v[174:177], v[218:221], v[6:9]
	v_mfma_f32_16x16x32_bf16 v[2:5], v[182:185], v[218:221], v[2:5]
	s_setprio 0
	s_barrier
	s_add_i32 s62, 0, 0x18000
	s_add_i32 s63, 0, 0x1c000
	v_add_u32_e32 v166, s62, v149
	v_add_u32_e32 v182, s63, v149
	ds_read_b128 v[154:157], v166
	ds_read_b128 v[158:161], v166 offset:1024
	ds_read_b128 v[162:165], v166 offset:2048
	ds_read_b128 v[166:169], v166 offset:3072
	ds_read_b128 v[170:173], v182
	ds_read_b128 v[174:177], v182 offset:1024
	ds_read_b128 v[178:181], v182 offset:2048
	ds_read_b128 v[182:185], v182 offset:3072
	s_add_u32 s46, s46, 0x80000
	s_addc_u32 s47, s47, 0
	s_mov_b32 m0, s48
	v_lshl_add_u64 v[226:227], s[46:47], 0, v[136:137]
	ds_read_b128 v[186:189], v153 offset:32768
	ds_read_b128 v[190:193], v153 offset:33792
	ds_read_b128 v[194:197], v153 offset:34816
	ds_read_b128 v[198:201], v153 offset:35840
	ds_read_b128 v[202:205], v153 offset:36864
	ds_read_b128 v[206:209], v153 offset:37888
	ds_read_b128 v[210:213], v153 offset:38912
	ds_read_b128 v[218:221], v153 offset:39936
	global_load_lds_dwordx4 v[226:227], off
	v_lshl_add_u64 v[226:227], s[46:47], 0, v[132:133]
	s_mov_b32 m0, s49
	s_nop 0
	global_load_lds_dwordx4 v[226:227], off
	s_waitcnt vmcnt(8)
	s_waitcnt lgkmcnt(0)
	s_barrier
	s_setprio 1
	s_waitcnt lgkmcnt(0)
	v_mfma_f32_16x16x32_bf16 v[126:129], v[154:157], v[186:189], v[126:129]
	v_mfma_f32_16x16x32_bf16 v[122:125], v[162:165], v[186:189], v[122:125]
	v_mfma_f32_16x16x32_bf16 v[114:117], v[154:157], v[194:197], v[114:117]
	v_mfma_f32_16x16x32_bf16 v[106:109], v[162:165], v[194:197], v[106:109]
	v_mfma_f32_16x16x32_bf16 v[98:101], v[154:157], v[202:205], v[98:101]
	v_mfma_f32_16x16x32_bf16 v[90:93], v[162:165], v[202:205], v[90:93]
	v_mfma_f32_16x16x32_bf16 v[82:85], v[154:157], v[210:213], v[82:85]
	v_mfma_f32_16x16x32_bf16 v[74:77], v[162:165], v[210:213], v[74:77]
	v_mfma_f32_16x16x32_bf16 v[126:129], v[158:161], v[190:193], v[126:129]
	v_mfma_f32_16x16x32_bf16 v[122:125], v[166:169], v[190:193], v[122:125]
	v_mfma_f32_16x16x32_bf16 v[114:117], v[158:161], v[198:201], v[114:117]
	v_mfma_f32_16x16x32_bf16 v[106:109], v[166:169], v[198:201], v[106:109]
	v_mfma_f32_16x16x32_bf16 v[98:101], v[158:161], v[206:209], v[98:101]
	v_mfma_f32_16x16x32_bf16 v[90:93], v[166:169], v[206:209], v[90:93]
	v_mfma_f32_16x16x32_bf16 v[82:85], v[158:161], v[218:221], v[82:85]
	v_mfma_f32_16x16x32_bf16 v[74:77], v[166:169], v[218:221], v[74:77]
	s_setprio 0
	s_setprio 1
	v_mfma_f32_16x16x32_bf16 v[118:121], v[170:173], v[186:189], v[118:121]
	v_mfma_f32_16x16x32_bf16 v[110:113], v[178:181], v[186:189], v[110:113]
	v_mfma_f32_16x16x32_bf16 v[102:105], v[170:173], v[194:197], v[102:105]
	v_mfma_f32_16x16x32_bf16 v[94:97], v[178:181], v[194:197], v[94:97]
	v_mfma_f32_16x16x32_bf16 v[86:89], v[170:173], v[202:205], v[86:89]
	v_mfma_f32_16x16x32_bf16 v[78:81], v[178:181], v[202:205], v[78:81]
	v_mfma_f32_16x16x32_bf16 v[70:73], v[170:173], v[210:213], v[70:73]
	v_mfma_f32_16x16x32_bf16 v[66:69], v[178:181], v[210:213], v[66:69]
	v_mfma_f32_16x16x32_bf16 v[118:121], v[174:177], v[190:193], v[118:121]
	v_mfma_f32_16x16x32_bf16 v[110:113], v[182:185], v[190:193], v[110:113]
	v_mfma_f32_16x16x32_bf16 v[102:105], v[174:177], v[198:201], v[102:105]
	v_mfma_f32_16x16x32_bf16 v[94:97], v[182:185], v[198:201], v[94:97]
	v_mfma_f32_16x16x32_bf16 v[86:89], v[174:177], v[206:209], v[86:89]
	v_mfma_f32_16x16x32_bf16 v[78:81], v[182:185], v[206:209], v[78:81]
	v_mfma_f32_16x16x32_bf16 v[70:73], v[174:177], v[218:221], v[70:73]
	v_mfma_f32_16x16x32_bf16 v[66:69], v[182:185], v[218:221], v[66:69]
	s_setprio 0
	s_barrier
	s_add_i32 s46, s62, s12
	v_lshl_add_u64 v[146:147], v[146:147], 0, s[8:9]
	s_mov_b32 m0, s46
	ds_read_b128 v[186:189], v153 offset:49152
	ds_read_b128 v[190:193], v153 offset:50176
	ds_read_b128 v[194:197], v153 offset:51200
	ds_read_b128 v[198:201], v153 offset:52224
	ds_read_b128 v[202:205], v153 offset:53248
	ds_read_b128 v[206:209], v153 offset:54272
	ds_read_b128 v[210:213], v153 offset:55296
	ds_read_b128 v[218:221], v153 offset:56320
	global_load_lds_dwordx4 v[146:147], off
	s_add_i32 m0, s46, 0x2000
	s_add_u32 s34, s34, 0x80080
	v_lshl_add_u64 v[146:147], v[214:215], 0, s[8:9]
	s_addc_u32 s35, s35, 0
	s_add_i32 s46, s63, s12
	global_load_lds_dwordx4 v[146:147], off
	v_lshl_add_u64 v[146:147], s[34:35], 0, v[134:135]
	s_mov_b32 m0, s46
	s_nop 0
	global_load_lds_dwordx4 v[146:147], off
	v_lshl_add_u64 v[146:147], s[34:35], 0, v[130:131]
	s_add_i32 m0, s46, 0x2000
	s_nop 0
	global_load_lds_dwordx4 v[146:147], off
	v_lshl_add_u64 v[146:147], v[222:223], 0, s[8:9]
	s_mov_b32 m0, s53
	s_nop 0
	global_load_lds_dwordx4 v[146:147], off
	v_lshl_add_u64 v[146:147], v[224:225], 0, s[8:9]
	s_mov_b32 m0, s54
	s_nop 0
	global_load_lds_dwordx4 v[146:147], off
	s_waitcnt vmcnt(8)
	s_waitcnt lgkmcnt(0)
	s_barrier
	s_setprio 1
	s_waitcnt lgkmcnt(0)
	v_mfma_f32_16x16x32_bf16 v[62:65], v[154:157], v[186:189], v[62:65]
	v_mfma_f32_16x16x32_bf16 v[58:61], v[162:165], v[186:189], v[58:61]
	v_mfma_f32_16x16x32_bf16 v[50:53], v[154:157], v[194:197], v[50:53]
	v_mfma_f32_16x16x32_bf16 v[42:45], v[162:165], v[194:197], v[42:45]
	v_mfma_f32_16x16x32_bf16 v[34:37], v[154:157], v[202:205], v[34:37]
	v_mfma_f32_16x16x32_bf16 v[26:29], v[162:165], v[202:205], v[26:29]
	v_mfma_f32_16x16x32_bf16 v[18:21], v[154:157], v[210:213], v[18:21]
	v_mfma_f32_16x16x32_bf16 v[10:13], v[162:165], v[210:213], v[10:13]
	v_mfma_f32_16x16x32_bf16 v[62:65], v[158:161], v[190:193], v[62:65]
	v_mfma_f32_16x16x32_bf16 v[58:61], v[166:169], v[190:193], v[58:61]
	v_mfma_f32_16x16x32_bf16 v[50:53], v[158:161], v[198:201], v[50:53]
	v_mfma_f32_16x16x32_bf16 v[42:45], v[166:169], v[198:201], v[42:45]
	v_mfma_f32_16x16x32_bf16 v[34:37], v[158:161], v[206:209], v[34:37]
	v_mfma_f32_16x16x32_bf16 v[26:29], v[166:169], v[206:209], v[26:29]
	v_mfma_f32_16x16x32_bf16 v[18:21], v[158:161], v[218:221], v[18:21]
	v_mfma_f32_16x16x32_bf16 v[10:13], v[166:169], v[218:221], v[10:13]
	s_setprio 0
	s_setprio 1
	v_mfma_f32_16x16x32_bf16 v[54:57], v[170:173], v[186:189], v[54:57]
	v_mfma_f32_16x16x32_bf16 v[46:49], v[178:181], v[186:189], v[46:49]
	v_mfma_f32_16x16x32_bf16 v[38:41], v[170:173], v[194:197], v[38:41]
	v_mfma_f32_16x16x32_bf16 v[30:33], v[178:181], v[194:197], v[30:33]
	v_mfma_f32_16x16x32_bf16 v[22:25], v[170:173], v[202:205], v[22:25]
	v_mfma_f32_16x16x32_bf16 v[14:17], v[178:181], v[202:205], v[14:17]
	v_mfma_f32_16x16x32_bf16 v[6:9], v[170:173], v[210:213], v[6:9]
	v_mfma_f32_16x16x32_bf16 v[2:5], v[178:181], v[210:213], v[2:5]
	v_mfma_f32_16x16x32_bf16 v[54:57], v[174:177], v[190:193], v[54:57]
	v_mfma_f32_16x16x32_bf16 v[46:49], v[182:185], v[190:193], v[46:49]
	v_mfma_f32_16x16x32_bf16 v[38:41], v[174:177], v[198:201], v[38:41]
	v_mfma_f32_16x16x32_bf16 v[30:33], v[182:185], v[198:201], v[30:33]
	v_mfma_f32_16x16x32_bf16 v[22:25], v[174:177], v[206:209], v[22:25]
	v_mfma_f32_16x16x32_bf16 v[14:17], v[182:185], v[206:209], v[14:17]
	v_mfma_f32_16x16x32_bf16 v[6:9], v[174:177], v[218:221], v[6:9]
	v_mfma_f32_16x16x32_bf16 v[2:5], v[182:185], v[218:221], v[2:5]
	s_setprio 0
	s_barrier
	s_add_i32 s68, s68, 2
	s_add_u32 s44, s44, 0x100
	s_addc_u32 s45, s45, 0
	s_add_u32 s60, s60, 0x100
	s_addc_u32 s61, s61, 0

.LBB0_3705:
	s_ashr_i32 s27, s26, 31
	s_lshl_b64 s[0:1], s[26:27], 20
	v_readlane_b32 s34, v247, 33
	v_readlane_b32 s35, v247, 34
	s_add_u32 s36, s34, s0
	s_addc_u32 s37, s35, s1
	s_and_b64 s[0:1], s[2:3], exec
	s_cselect_b32 s0, s37, s43
	s_cselect_b32 s1, s36, s42
	s_ashr_i32 s25, s24, 31
	s_lshl_b64 s[34:35], s[24:25], 20
	s_add_u32 s38, s31, s34
	s_addc_u32 s39, s33, s35
	s_and_b64 s[34:35], s[2:3], exec
	s_cselect_b32 s25, s39, s45
	s_cselect_b32 s27, s38, s44
	s_add_u32 s42, s42, 0x80080
	s_addc_u32 s43, s43, 0
	s_add_u32 s58, s44, 0x100
	s_addc_u32 s59, s45, 0
	s_mov_b32 s60, -2
	ds_read_b128 v[130:133], v174
	ds_read_b128 v[134:137], v174 offset:1024
	ds_read_b128 v[138:141], v174 offset:2048
	ds_read_b128 v[158:161], v174 offset:3072
	ds_read_b128 v[162:165], v175
	ds_read_b128 v[166:169], v175 offset:1024
	ds_read_b128 v[178:181], v175 offset:2048
	ds_read_b128 v[182:185], v175 offset:3072
	s_add_u32 s34, s42, 0xfff80080
	s_addc_u32 s35, s43, -1
	s_cmp_eq_u32 s60, 28
	s_cselect_b32 s45, s0, s35
	s_cselect_b32 s44, s1, s34
	s_cselect_b32 s35, s25, s59
	s_cselect_b32 s34, s27, s58
	v_lshl_add_u64 v[170:171], s[42:43], 0, v[150:151]
	s_add_i32 m0, s41, 0xc000
	ds_read_b128 v[186:189], v176
	ds_read_b128 v[190:193], v176 offset:1024
	ds_read_b128 v[194:197], v176 offset:2048
	ds_read_b128 v[198:201], v176 offset:3072
	ds_read_b128 v[202:205], v176 offset:4096
	ds_read_b128 v[206:209], v176 offset:5120
	ds_read_b128 v[210:213], v176 offset:6144
	ds_read_b128 v[218:221], v176 offset:7168
	global_load_lds_dwordx4 v[170:171], off
	v_lshl_add_u64 v[170:171], s[42:43], 0, v[152:153]
	s_add_i32 m0, s41, 0xe000
	s_nop 0
	global_load_lds_dwordx4 v[170:171], off
	s_waitcnt vmcnt(8)
	s_waitcnt lgkmcnt(0)
	s_barrier
	s_setprio 1
	s_waitcnt lgkmcnt(0)
	v_mfma_f32_16x16x32_bf16 v[126:129], v[130:133], v[186:189], 0
	v_mfma_f32_16x16x32_bf16 v[122:125], v[138:141], v[186:189], 0
	v_mfma_f32_16x16x32_bf16 v[110:113], v[130:133], v[194:197], 0
	v_mfma_f32_16x16x32_bf16 v[106:109], v[138:141], v[194:197], 0
	v_mfma_f32_16x16x32_bf16 v[94:97], v[130:133], v[202:205], 0
	v_mfma_f32_16x16x32_bf16 v[90:93], v[138:141], v[202:205], 0
	v_mfma_f32_16x16x32_bf16 v[78:81], v[130:133], v[210:213], 0
	v_mfma_f32_16x16x32_bf16 v[74:77], v[138:141], v[210:213], 0
	v_mfma_f32_16x16x32_bf16 v[126:129], v[134:137], v[190:193], v[126:129]
	v_mfma_f32_16x16x32_bf16 v[122:125], v[158:161], v[190:193], v[122:125]
	v_mfma_f32_16x16x32_bf16 v[110:113], v[134:137], v[198:201], v[110:113]
	v_mfma_f32_16x16x32_bf16 v[106:109], v[158:161], v[198:201], v[106:109]
	v_mfma_f32_16x16x32_bf16 v[94:97], v[134:137], v[206:209], v[94:97]
	v_mfma_f32_16x16x32_bf16 v[90:93], v[158:161], v[206:209], v[90:93]
	v_mfma_f32_16x16x32_bf16 v[78:81], v[134:137], v[218:221], v[78:81]
	v_mfma_f32_16x16x32_bf16 v[74:77], v[158:161], v[218:221], v[74:77]
	s_setprio 0
	s_setprio 1
	v_mfma_f32_16x16x32_bf16 v[118:121], v[162:165], v[186:189], 0
	v_mfma_f32_16x16x32_bf16 v[114:117], v[178:181], v[186:189], 0
	v_mfma_f32_16x16x32_bf16 v[102:105], v[162:165], v[194:197], 0
	v_mfma_f32_16x16x32_bf16 v[98:101], v[178:181], v[194:197], 0
	v_mfma_f32_16x16x32_bf16 v[86:89], v[162:165], v[202:205], 0
	v_mfma_f32_16x16x32_bf16 v[82:85], v[178:181], v[202:205], 0
	v_mfma_f32_16x16x32_bf16 v[70:73], v[162:165], v[210:213], 0
	v_mfma_f32_16x16x32_bf16 v[66:69], v[178:181], v[210:213], 0
	v_mfma_f32_16x16x32_bf16 v[118:121], v[166:169], v[190:193], v[118:121]
	v_mfma_f32_16x16x32_bf16 v[114:117], v[182:185], v[190:193], v[114:117]
	v_mfma_f32_16x16x32_bf16 v[102:105], v[166:169], v[198:201], v[102:105]
	v_mfma_f32_16x16x32_bf16 v[98:101], v[182:185], v[198:201], v[98:101]
	v_mfma_f32_16x16x32_bf16 v[86:89], v[166:169], v[206:209], v[86:89]
	v_mfma_f32_16x16x32_bf16 v[82:85], v[182:185], v[206:209], v[82:85]
	v_mfma_f32_16x16x32_bf16 v[70:73], v[166:169], v[218:221], v[70:73]
	v_mfma_f32_16x16x32_bf16 v[66:69], v[182:185], v[218:221], v[66:69]
	s_setprio 0
	s_barrier
	s_add_i32 s61, s54, s46
	v_lshl_add_u64 v[170:171], s[34:35], 0, v[144:145]
	s_mov_b32 m0, s61
	ds_read_b128 v[186:189], v176 offset:16384
	ds_read_b128 v[190:193], v176 offset:17408
	ds_read_b128 v[194:197], v176 offset:18432
	ds_read_b128 v[198:201], v176 offset:19456
	ds_read_b128 v[202:205], v176 offset:20480
	ds_read_b128 v[206:209], v176 offset:21504
	ds_read_b128 v[210:213], v176 offset:22528
	ds_read_b128 v[218:221], v176 offset:23552
	global_load_lds_dwordx4 v[170:171], off
	s_add_i32 m0, s61, 0x2000
	s_add_u32 s62, s34, 0x80000
	v_lshl_add_u64 v[214:215], s[34:35], 0, v[148:149]
	s_addc_u32 s63, s35, 0
	s_add_i32 s61, s55, s46
	global_load_lds_dwordx4 v[214:215], off
	v_lshl_add_u64 v[222:223], s[62:63], 0, v[144:145]
	s_mov_b32 m0, s61
	v_lshl_add_u64 v[224:225], s[44:45], 0, v[146:147]
	global_load_lds_dwordx4 v[222:223], off
	v_lshl_add_u64 v[222:223], s[62:63], 0, v[148:149]
	s_add_i32 m0, s61, 0x2000
	s_nop 0
	global_load_lds_dwordx4 v[222:223], off
	v_lshl_add_u64 v[222:223], s[44:45], 0, v[142:143]
	s_mov_b32 m0, s41
	s_nop 0
	global_load_lds_dwordx4 v[222:223], off
	s_mov_b32 m0, s47
	s_nop 0
	global_load_lds_dwordx4 v[224:225], off
	s_waitcnt vmcnt(8)
	s_waitcnt lgkmcnt(0)
	s_barrier
	s_setprio 1
	s_waitcnt lgkmcnt(0)
	v_mfma_f32_16x16x32_bf16 v[62:65], v[130:133], v[186:189], 0
	v_mfma_f32_16x16x32_bf16 v[58:61], v[138:141], v[186:189], 0
	v_mfma_f32_16x16x32_bf16 v[50:53], v[130:133], v[194:197], 0
	v_mfma_f32_16x16x32_bf16 v[42:45], v[138:141], v[194:197], 0
	v_mfma_f32_16x16x32_bf16 v[38:41], v[130:133], v[202:205], 0
	v_mfma_f32_16x16x32_bf16 v[34:37], v[138:141], v[202:205], 0
	v_mfma_f32_16x16x32_bf16 v[14:17], v[130:133], v[210:213], 0
	v_mfma_f32_16x16x32_bf16 v[10:13], v[138:141], v[210:213], 0
	v_mfma_f32_16x16x32_bf16 v[62:65], v[134:137], v[190:193], v[62:65]
	v_mfma_f32_16x16x32_bf16 v[58:61], v[158:161], v[190:193], v[58:61]
	v_mfma_f32_16x16x32_bf16 v[50:53], v[134:137], v[198:201], v[50:53]
	v_mfma_f32_16x16x32_bf16 v[42:45], v[158:161], v[198:201], v[42:45]
	v_mfma_f32_16x16x32_bf16 v[38:41], v[134:137], v[206:209], v[38:41]
	v_mfma_f32_16x16x32_bf16 v[34:37], v[158:161], v[206:209], v[34:37]
	v_mfma_f32_16x16x32_bf16 v[14:17], v[134:137], v[218:221], v[14:17]
	v_mfma_f32_16x16x32_bf16 v[10:13], v[158:161], v[218:221], v[10:13]
	s_setprio 0
	s_setprio 1
	v_mfma_f32_16x16x32_bf16 v[54:57], v[162:165], v[186:189], 0
	v_mfma_f32_16x16x32_bf16 v[46:49], v[178:181], v[186:189], 0
	v_mfma_f32_16x16x32_bf16 v[30:33], v[162:165], v[194:197], 0
	v_mfma_f32_16x16x32_bf16 v[26:29], v[178:181], v[194:197], 0
	v_mfma_f32_16x16x32_bf16 v[22:25], v[162:165], v[202:205], 0
	v_mfma_f32_16x16x32_bf16 v[18:21], v[178:181], v[202:205], 0
	v_mfma_f32_16x16x32_bf16 v[6:9], v[162:165], v[210:213], 0
	v_mfma_f32_16x16x32_bf16 v[2:5], v[178:181], v[210:213], 0
	v_mfma_f32_16x16x32_bf16 v[54:57], v[166:169], v[190:193], v[54:57]
	v_mfma_f32_16x16x32_bf16 v[46:49], v[182:185], v[190:193], v[46:49]
	v_mfma_f32_16x16x32_bf16 v[30:33], v[166:169], v[198:201], v[30:33]
	v_mfma_f32_16x16x32_bf16 v[26:29], v[182:185], v[198:201], v[26:29]
	v_mfma_f32_16x16x32_bf16 v[22:25], v[166:169], v[206:209], v[22:25]
	v_mfma_f32_16x16x32_bf16 v[18:21], v[182:185], v[206:209], v[18:21]
	v_mfma_f32_16x16x32_bf16 v[6:9], v[166:169], v[218:221], v[6:9]
	v_mfma_f32_16x16x32_bf16 v[2:5], v[182:185], v[218:221], v[2:5]
	s_setprio 0
	s_barrier
	s_add_i32 s61, 0, 0x18000
	s_add_i32 s62, 0, 0x1c000
	v_add_u32_e32 v158, s61, v172
	v_add_u32_e32 v177, s62, v172
	ds_read_b128 v[130:133], v158
	ds_read_b128 v[134:137], v158 offset:1024
	ds_read_b128 v[138:141], v158 offset:2048
	ds_read_b128 v[158:161], v158 offset:3072
	ds_read_b128 v[162:165], v177
	ds_read_b128 v[166:169], v177 offset:1024
	ds_read_b128 v[178:181], v177 offset:2048
	ds_read_b128 v[182:185], v177 offset:3072
	s_add_u32 s44, s44, 0x80000
	s_addc_u32 s45, s45, 0
	s_mov_b32 m0, s48
	v_lshl_add_u64 v[226:227], s[44:45], 0, v[142:143]
	ds_read_b128 v[186:189], v176 offset:32768
	ds_read_b128 v[190:193], v176 offset:33792
	ds_read_b128 v[194:197], v176 offset:34816
	ds_read_b128 v[198:201], v176 offset:35840
	ds_read_b128 v[202:205], v176 offset:36864
	ds_read_b128 v[206:209], v176 offset:37888
	ds_read_b128 v[210:213], v176 offset:38912
	ds_read_b128 v[218:221], v176 offset:39936
	global_load_lds_dwordx4 v[226:227], off
	v_lshl_add_u64 v[226:227], s[44:45], 0, v[146:147]
	s_mov_b32 m0, s49
	s_nop 0
	global_load_lds_dwordx4 v[226:227], off
	s_waitcnt vmcnt(8)
	s_waitcnt lgkmcnt(0)
	s_barrier
	s_setprio 1
	s_waitcnt lgkmcnt(0)
	v_mfma_f32_16x16x32_bf16 v[126:129], v[130:133], v[186:189], v[126:129]
	v_mfma_f32_16x16x32_bf16 v[122:125], v[138:141], v[186:189], v[122:125]
	v_mfma_f32_16x16x32_bf16 v[110:113], v[130:133], v[194:197], v[110:113]
	v_mfma_f32_16x16x32_bf16 v[106:109], v[138:141], v[194:197], v[106:109]
	v_mfma_f32_16x16x32_bf16 v[94:97], v[130:133], v[202:205], v[94:97]
	v_mfma_f32_16x16x32_bf16 v[90:93], v[138:141], v[202:205], v[90:93]
	v_mfma_f32_16x16x32_bf16 v[78:81], v[130:133], v[210:213], v[78:81]
	v_mfma_f32_16x16x32_bf16 v[74:77], v[138:141], v[210:213], v[74:77]
	v_mfma_f32_16x16x32_bf16 v[126:129], v[134:137], v[190:193], v[126:129]
	v_mfma_f32_16x16x32_bf16 v[122:125], v[158:161], v[190:193], v[122:125]
	v_mfma_f32_16x16x32_bf16 v[110:113], v[134:137], v[198:201], v[110:113]
	v_mfma_f32_16x16x32_bf16 v[106:109], v[158:161], v[198:201], v[106:109]
	v_mfma_f32_16x16x32_bf16 v[94:97], v[134:137], v[206:209], v[94:97]
	v_mfma_f32_16x16x32_bf16 v[90:93], v[158:161], v[206:209], v[90:93]
	v_mfma_f32_16x16x32_bf16 v[78:81], v[134:137], v[218:221], v[78:81]
	v_mfma_f32_16x16x32_bf16 v[74:77], v[158:161], v[218:221], v[74:77]
	s_setprio 0
	s_setprio 1
	v_mfma_f32_16x16x32_bf16 v[118:121], v[162:165], v[186:189], v[118:121]
	v_mfma_f32_16x16x32_bf16 v[114:117], v[178:181], v[186:189], v[114:117]
	v_mfma_f32_16x16x32_bf16 v[102:105], v[162:165], v[194:197], v[102:105]
	v_mfma_f32_16x16x32_bf16 v[98:101], v[178:181], v[194:197], v[98:101]
	v_mfma_f32_16x16x32_bf16 v[86:89], v[162:165], v[202:205], v[86:89]
	v_mfma_f32_16x16x32_bf16 v[82:85], v[178:181], v[202:205], v[82:85]
	v_mfma_f32_16x16x32_bf16 v[70:73], v[162:165], v[210:213], v[70:73]
	v_mfma_f32_16x16x32_bf16 v[66:69], v[178:181], v[210:213], v[66:69]
	v_mfma_f32_16x16x32_bf16 v[118:121], v[166:169], v[190:193], v[118:121]
	v_mfma_f32_16x16x32_bf16 v[114:117], v[182:185], v[190:193], v[114:117]
	v_mfma_f32_16x16x32_bf16 v[102:105], v[166:169], v[198:201], v[102:105]
	v_mfma_f32_16x16x32_bf16 v[98:101], v[182:185], v[198:201], v[98:101]
	v_mfma_f32_16x16x32_bf16 v[86:89], v[166:169], v[206:209], v[86:89]
	v_mfma_f32_16x16x32_bf16 v[82:85], v[182:185], v[206:209], v[82:85]
	v_mfma_f32_16x16x32_bf16 v[70:73], v[166:169], v[218:221], v[70:73]
	v_mfma_f32_16x16x32_bf16 v[66:69], v[182:185], v[218:221], v[66:69]
	s_setprio 0
	s_barrier
	s_add_i32 s44, s61, s46
	v_lshl_add_u64 v[170:171], v[170:171], 0, s[12:13]
	s_mov_b32 m0, s44
	ds_read_b128 v[186:189], v176 offset:49152
	ds_read_b128 v[190:193], v176 offset:50176
	ds_read_b128 v[194:197], v176 offset:51200
	ds_read_b128 v[198:201], v176 offset:52224
	ds_read_b128 v[202:205], v176 offset:53248
	ds_read_b128 v[206:209], v176 offset:54272
	ds_read_b128 v[210:213], v176 offset:55296
	ds_read_b128 v[218:221], v176 offset:56320
	global_load_lds_dwordx4 v[170:171], off
	s_add_i32 m0, s44, 0x2000
	s_add_u32 s34, s34, 0x80080
	v_lshl_add_u64 v[170:171], v[214:215], 0, s[12:13]
	s_addc_u32 s35, s35, 0
	s_add_i32 s44, s62, s46
	global_load_lds_dwordx4 v[170:171], off
	v_lshl_add_u64 v[170:171], s[34:35], 0, v[144:145]
	s_mov_b32 m0, s44
	s_nop 0
	global_load_lds_dwordx4 v[170:171], off
	v_lshl_add_u64 v[170:171], s[34:35], 0, v[148:149]
	s_add_i32 m0, s44, 0x2000
	s_nop 0
	global_load_lds_dwordx4 v[170:171], off
	v_lshl_add_u64 v[170:171], v[222:223], 0, s[12:13]
	s_mov_b32 m0, s51
	s_nop 0
	global_load_lds_dwordx4 v[170:171], off
	v_lshl_add_u64 v[170:171], v[224:225], 0, s[12:13]
	s_mov_b32 m0, s52
	s_nop 0
	global_load_lds_dwordx4 v[170:171], off
	s_waitcnt vmcnt(8)
	s_waitcnt lgkmcnt(0)
	s_barrier
	s_setprio 1
	s_waitcnt lgkmcnt(0)
	v_mfma_f32_16x16x32_bf16 v[62:65], v[130:133], v[186:189], v[62:65]
	v_mfma_f32_16x16x32_bf16 v[58:61], v[138:141], v[186:189], v[58:61]
	v_mfma_f32_16x16x32_bf16 v[50:53], v[130:133], v[194:197], v[50:53]
	v_mfma_f32_16x16x32_bf16 v[42:45], v[138:141], v[194:197], v[42:45]
	v_mfma_f32_16x16x32_bf16 v[38:41], v[130:133], v[202:205], v[38:41]
	v_mfma_f32_16x16x32_bf16 v[34:37], v[138:141], v[202:205], v[34:37]
	v_mfma_f32_16x16x32_bf16 v[14:17], v[130:133], v[210:213], v[14:17]
	v_mfma_f32_16x16x32_bf16 v[10:13], v[138:141], v[210:213], v[10:13]
	v_mfma_f32_16x16x32_bf16 v[62:65], v[134:137], v[190:193], v[62:65]
	v_mfma_f32_16x16x32_bf16 v[58:61], v[158:161], v[190:193], v[58:61]
	v_mfma_f32_16x16x32_bf16 v[50:53], v[134:137], v[198:201], v[50:53]
	v_mfma_f32_16x16x32_bf16 v[42:45], v[158:161], v[198:201], v[42:45]
	v_mfma_f32_16x16x32_bf16 v[38:41], v[134:137], v[206:209], v[38:41]
	v_mfma_f32_16x16x32_bf16 v[34:37], v[158:161], v[206:209], v[34:37]
	v_mfma_f32_16x16x32_bf16 v[14:17], v[134:137], v[218:221], v[14:17]
	v_mfma_f32_16x16x32_bf16 v[10:13], v[158:161], v[218:221], v[10:13]
	s_setprio 0
	s_setprio 1
	v_mfma_f32_16x16x32_bf16 v[54:57], v[162:165], v[186:189], v[54:57]
	v_mfma_f32_16x16x32_bf16 v[46:49], v[178:181], v[186:189], v[46:49]
	v_mfma_f32_16x16x32_bf16 v[30:33], v[162:165], v[194:197], v[30:33]
	v_mfma_f32_16x16x32_bf16 v[26:29], v[178:181], v[194:197], v[26:29]
	v_mfma_f32_16x16x32_bf16 v[22:25], v[162:165], v[202:205], v[22:25]
	v_mfma_f32_16x16x32_bf16 v[18:21], v[178:181], v[202:205], v[18:21]
	v_mfma_f32_16x16x32_bf16 v[6:9], v[162:165], v[210:213], v[6:9]
	v_mfma_f32_16x16x32_bf16 v[2:5], v[178:181], v[210:213], v[2:5]
	v_mfma_f32_16x16x32_bf16 v[54:57], v[166:169], v[190:193], v[54:57]
	v_mfma_f32_16x16x32_bf16 v[46:49], v[182:185], v[190:193], v[46:49]
	v_mfma_f32_16x16x32_bf16 v[30:33], v[166:169], v[198:201], v[30:33]
	v_mfma_f32_16x16x32_bf16 v[26:29], v[182:185], v[198:201], v[26:29]
	v_mfma_f32_16x16x32_bf16 v[22:25], v[166:169], v[206:209], v[22:25]
	v_mfma_f32_16x16x32_bf16 v[18:21], v[182:185], v[206:209], v[18:21]
	v_mfma_f32_16x16x32_bf16 v[6:9], v[166:169], v[218:221], v[6:9]
	v_mfma_f32_16x16x32_bf16 v[2:5], v[182:185], v[218:221], v[2:5]
	s_setprio 0
	s_barrier
	s_add_i32 s60, s60, 2
	s_add_u32 s42, s42, 0x100
	s_addc_u32 s43, s43, 0
	s_add_u32 s58, s58, 0x100
	s_addc_u32 s59, s59, 0

.LBB0_3834:
	s_ashr_i32 s17, s16, 31
	s_lshl_b64 s[0:1], s[16:17], 20
	v_readlane_b32 s15, v247, 45
	s_add_u32 s24, s15, s0
	v_readlane_b32 s0, v247, 47
	s_addc_u32 s25, s0, s1
	s_and_b64 s[0:1], s[2:3], exec
	s_cselect_b32 s0, s25, s35
	s_cselect_b32 s1, s24, s34
	s_ashr_i32 s15, s14, 31
	s_lshl_b64 s[26:27], s[14:15], 20
	s_add_u32 s26, s30, s26
	s_addc_u32 s27, s31, s27
	s_and_b64 s[38:39], s[2:3], exec
	s_cselect_b32 s15, s27, s41
	s_cselect_b32 s17, s26, s40
	s_add_u32 s38, s34, 0x80080
	s_addc_u32 s39, s35, 0
	s_add_u32 s55, s40, 0x100
	s_addc_u32 s56, s41, 0
	s_mov_b32 s57, -2
	ds_read_b128 v[146:149], v153
	ds_read_b128 v[156:159], v153 offset:1024
	ds_read_b128 v[160:163], v153 offset:2048
	ds_read_b128 v[164:167], v153 offset:3072
	ds_read_b128 v[168:171], v154
	ds_read_b128 v[172:175], v154 offset:1024
	ds_read_b128 v[176:179], v154 offset:2048
	ds_read_b128 v[180:183], v154 offset:3072
	s_add_u32 s34, s38, 0xfff80080
	s_addc_u32 s35, s39, -1
	s_cmp_eq_u32 s57, 28
	s_cselect_b32 s41, s0, s35
	s_cselect_b32 s40, s1, s34
	s_cselect_b32 s35, s15, s56
	s_cselect_b32 s34, s17, s55
	v_lshl_add_u64 v[218:219], s[38:39], 0, v[138:139]
	s_add_i32 m0, s37, 0xc000
	ds_read_b128 v[184:187], v155
	ds_read_b128 v[188:191], v155 offset:1024
	ds_read_b128 v[192:195], v155 offset:2048
	ds_read_b128 v[196:199], v155 offset:3072
	ds_read_b128 v[200:203], v155 offset:4096
	ds_read_b128 v[204:207], v155 offset:5120
	ds_read_b128 v[208:211], v155 offset:6144
	ds_read_b128 v[212:215], v155 offset:7168
	global_load_lds_dwordx4 v[218:219], off
	v_lshl_add_u64 v[218:219], s[38:39], 0, v[140:141]
	s_add_i32 m0, s37, 0xe000
	s_nop 0
	global_load_lds_dwordx4 v[218:219], off
	s_waitcnt vmcnt(8)
	s_waitcnt lgkmcnt(0)
	s_barrier
	s_setprio 1
	s_waitcnt lgkmcnt(0)
	v_mfma_f32_16x16x32_bf16 v[126:129], v[146:149], v[184:187], 0
	v_mfma_f32_16x16x32_bf16 v[118:121], v[160:163], v[184:187], 0
	v_mfma_f32_16x16x32_bf16 v[110:113], v[146:149], v[192:195], 0
	v_mfma_f32_16x16x32_bf16 v[102:105], v[160:163], v[192:195], 0
	v_mfma_f32_16x16x32_bf16 v[94:97], v[146:149], v[200:203], 0
	v_mfma_f32_16x16x32_bf16 v[86:89], v[160:163], v[200:203], 0
	v_mfma_f32_16x16x32_bf16 v[78:81], v[146:149], v[208:211], 0
	v_mfma_f32_16x16x32_bf16 v[70:73], v[160:163], v[208:211], 0
	v_mfma_f32_16x16x32_bf16 v[126:129], v[156:159], v[188:191], v[126:129]
	v_mfma_f32_16x16x32_bf16 v[118:121], v[164:167], v[188:191], v[118:121]
	v_mfma_f32_16x16x32_bf16 v[110:113], v[156:159], v[196:199], v[110:113]
	v_mfma_f32_16x16x32_bf16 v[102:105], v[164:167], v[196:199], v[102:105]
	v_mfma_f32_16x16x32_bf16 v[94:97], v[156:159], v[204:207], v[94:97]
	v_mfma_f32_16x16x32_bf16 v[86:89], v[164:167], v[204:207], v[86:89]
	v_mfma_f32_16x16x32_bf16 v[78:81], v[156:159], v[212:215], v[78:81]
	v_mfma_f32_16x16x32_bf16 v[70:73], v[164:167], v[212:215], v[70:73]
	s_setprio 0
	s_setprio 1
	v_mfma_f32_16x16x32_bf16 v[122:125], v[168:171], v[184:187], 0
	v_mfma_f32_16x16x32_bf16 v[114:117], v[176:179], v[184:187], 0
	v_mfma_f32_16x16x32_bf16 v[106:109], v[168:171], v[192:195], 0
	v_mfma_f32_16x16x32_bf16 v[98:101], v[176:179], v[192:195], 0
	v_mfma_f32_16x16x32_bf16 v[90:93], v[168:171], v[200:203], 0
	v_mfma_f32_16x16x32_bf16 v[82:85], v[176:179], v[200:203], 0
	v_mfma_f32_16x16x32_bf16 v[74:77], v[168:171], v[208:211], 0
	v_mfma_f32_16x16x32_bf16 v[66:69], v[176:179], v[208:211], 0
	v_mfma_f32_16x16x32_bf16 v[122:125], v[172:175], v[188:191], v[122:125]
	v_mfma_f32_16x16x32_bf16 v[114:117], v[180:183], v[188:191], v[114:117]
	v_mfma_f32_16x16x32_bf16 v[106:109], v[172:175], v[196:199], v[106:109]
	v_mfma_f32_16x16x32_bf16 v[98:101], v[180:183], v[196:199], v[98:101]
	v_mfma_f32_16x16x32_bf16 v[90:93], v[172:175], v[204:207], v[90:93]
	v_mfma_f32_16x16x32_bf16 v[82:85], v[180:183], v[204:207], v[82:85]
	v_mfma_f32_16x16x32_bf16 v[74:77], v[172:175], v[212:215], v[74:77]
	v_mfma_f32_16x16x32_bf16 v[66:69], v[180:183], v[212:215], v[66:69]
	s_setprio 0
	s_barrier
	s_add_i32 s58, s51, s33
	v_lshl_add_u64 v[218:219], s[34:35], 0, v[134:135]
	s_mov_b32 m0, s58
	ds_read_b128 v[184:187], v155 offset:16384
	ds_read_b128 v[188:191], v155 offset:17408
	ds_read_b128 v[192:195], v155 offset:18432
	ds_read_b128 v[196:199], v155 offset:19456
	ds_read_b128 v[200:203], v155 offset:20480
	ds_read_b128 v[204:207], v155 offset:21504
	ds_read_b128 v[208:211], v155 offset:22528
	ds_read_b128 v[212:215], v155 offset:23552
	global_load_lds_dwordx4 v[218:219], off
	s_add_i32 m0, s58, 0x2000
	s_add_u32 s58, s34, 0x80000
	v_lshl_add_u64 v[220:221], s[34:35], 0, v[130:131]
	s_addc_u32 s59, s35, 0
	s_add_i32 s60, s52, s33
	global_load_lds_dwordx4 v[220:221], off
	v_lshl_add_u64 v[222:223], s[58:59], 0, v[134:135]
	s_mov_b32 m0, s60
	v_lshl_add_u64 v[224:225], s[40:41], 0, v[132:133]
	global_load_lds_dwordx4 v[222:223], off
	v_lshl_add_u64 v[222:223], s[58:59], 0, v[130:131]
	s_add_i32 m0, s60, 0x2000
	s_nop 0
	global_load_lds_dwordx4 v[222:223], off
	v_lshl_add_u64 v[222:223], s[40:41], 0, v[136:137]
	s_mov_b32 m0, s37
	s_nop 0
	global_load_lds_dwordx4 v[222:223], off
	s_mov_b32 m0, s44
	s_nop 0
	global_load_lds_dwordx4 v[224:225], off
	s_waitcnt vmcnt(8)
	s_waitcnt lgkmcnt(0)
	s_barrier
	s_setprio 1
	s_waitcnt lgkmcnt(0)
	v_mfma_f32_16x16x32_bf16 v[62:65], v[146:149], v[184:187], 0
	v_mfma_f32_16x16x32_bf16 v[54:57], v[160:163], v[184:187], 0
	v_mfma_f32_16x16x32_bf16 v[46:49], v[146:149], v[192:195], 0
	v_mfma_f32_16x16x32_bf16 v[38:41], v[160:163], v[192:195], 0
	v_mfma_f32_16x16x32_bf16 v[30:33], v[146:149], v[200:203], 0
	v_mfma_f32_16x16x32_bf16 v[22:25], v[160:163], v[200:203], 0
	v_mfma_f32_16x16x32_bf16 v[14:17], v[146:149], v[208:211], 0
	v_mfma_f32_16x16x32_bf16 v[6:9], v[160:163], v[208:211], 0
	v_mfma_f32_16x16x32_bf16 v[62:65], v[156:159], v[188:191], v[62:65]
	v_mfma_f32_16x16x32_bf16 v[54:57], v[164:167], v[188:191], v[54:57]
	v_mfma_f32_16x16x32_bf16 v[46:49], v[156:159], v[196:199], v[46:49]
	v_mfma_f32_16x16x32_bf16 v[38:41], v[164:167], v[196:199], v[38:41]
	v_mfma_f32_16x16x32_bf16 v[30:33], v[156:159], v[204:207], v[30:33]
	v_mfma_f32_16x16x32_bf16 v[22:25], v[164:167], v[204:207], v[22:25]
	v_mfma_f32_16x16x32_bf16 v[14:17], v[156:159], v[212:215], v[14:17]
	v_mfma_f32_16x16x32_bf16 v[6:9], v[164:167], v[212:215], v[6:9]
	s_setprio 0
	s_setprio 1
	v_mfma_f32_16x16x32_bf16 v[58:61], v[168:171], v[184:187], 0
	v_mfma_f32_16x16x32_bf16 v[50:53], v[176:179], v[184:187], 0
	v_mfma_f32_16x16x32_bf16 v[42:45], v[168:171], v[192:195], 0
	v_mfma_f32_16x16x32_bf16 v[34:37], v[176:179], v[192:195], 0
	v_mfma_f32_16x16x32_bf16 v[26:29], v[168:171], v[200:203], 0
	v_mfma_f32_16x16x32_bf16 v[18:21], v[176:179], v[200:203], 0
	v_mfma_f32_16x16x32_bf16 v[10:13], v[168:171], v[208:211], 0
	v_mfma_f32_16x16x32_bf16 v[2:5], v[176:179], v[208:211], 0
	v_mfma_f32_16x16x32_bf16 v[58:61], v[172:175], v[188:191], v[58:61]
	v_mfma_f32_16x16x32_bf16 v[50:53], v[180:183], v[188:191], v[50:53]
	v_mfma_f32_16x16x32_bf16 v[42:45], v[172:175], v[196:199], v[42:45]
	v_mfma_f32_16x16x32_bf16 v[34:37], v[180:183], v[196:199], v[34:37]
	v_mfma_f32_16x16x32_bf16 v[26:29], v[172:175], v[204:207], v[26:29]
	v_mfma_f32_16x16x32_bf16 v[18:21], v[180:183], v[204:207], v[18:21]
	v_mfma_f32_16x16x32_bf16 v[10:13], v[172:175], v[212:215], v[10:13]
	v_mfma_f32_16x16x32_bf16 v[2:5], v[180:183], v[212:215], v[2:5]
	s_setprio 0
	s_barrier
	s_add_i32 s58, 0, 0x18000
	s_add_i32 s59, 0, 0x1c000
	v_add_u32_e32 v164, s58, v151
	v_add_u32_e32 v180, s59, v151
	ds_read_b128 v[146:149], v164
	ds_read_b128 v[156:159], v164 offset:1024
	ds_read_b128 v[160:163], v164 offset:2048
	ds_read_b128 v[164:167], v164 offset:3072
	ds_read_b128 v[168:171], v180
	ds_read_b128 v[172:175], v180 offset:1024
	ds_read_b128 v[176:179], v180 offset:2048
	ds_read_b128 v[180:183], v180 offset:3072
	s_add_u32 s40, s40, 0x80000
	s_addc_u32 s41, s41, 0
	s_mov_b32 m0, s45
	v_lshl_add_u64 v[226:227], s[40:41], 0, v[136:137]
	ds_read_b128 v[184:187], v155 offset:32768
	ds_read_b128 v[188:191], v155 offset:33792
	ds_read_b128 v[192:195], v155 offset:34816
	ds_read_b128 v[196:199], v155 offset:35840
	ds_read_b128 v[200:203], v155 offset:36864
	ds_read_b128 v[204:207], v155 offset:37888
	ds_read_b128 v[208:211], v155 offset:38912
	ds_read_b128 v[212:215], v155 offset:39936
	global_load_lds_dwordx4 v[226:227], off
	v_lshl_add_u64 v[226:227], s[40:41], 0, v[132:133]
	s_mov_b32 m0, s46
	s_nop 0
	global_load_lds_dwordx4 v[226:227], off
	s_waitcnt vmcnt(8)
	s_waitcnt lgkmcnt(0)
	s_barrier
	s_setprio 1
	s_waitcnt lgkmcnt(0)
	v_mfma_f32_16x16x32_bf16 v[126:129], v[146:149], v[184:187], v[126:129]
	v_mfma_f32_16x16x32_bf16 v[118:121], v[160:163], v[184:187], v[118:121]
	v_mfma_f32_16x16x32_bf16 v[110:113], v[146:149], v[192:195], v[110:113]
	v_mfma_f32_16x16x32_bf16 v[102:105], v[160:163], v[192:195], v[102:105]
	v_mfma_f32_16x16x32_bf16 v[94:97], v[146:149], v[200:203], v[94:97]
	v_mfma_f32_16x16x32_bf16 v[86:89], v[160:163], v[200:203], v[86:89]
	v_mfma_f32_16x16x32_bf16 v[78:81], v[146:149], v[208:211], v[78:81]
	v_mfma_f32_16x16x32_bf16 v[70:73], v[160:163], v[208:211], v[70:73]
	v_mfma_f32_16x16x32_bf16 v[126:129], v[156:159], v[188:191], v[126:129]
	v_mfma_f32_16x16x32_bf16 v[118:121], v[164:167], v[188:191], v[118:121]
	v_mfma_f32_16x16x32_bf16 v[110:113], v[156:159], v[196:199], v[110:113]
	v_mfma_f32_16x16x32_bf16 v[102:105], v[164:167], v[196:199], v[102:105]
	v_mfma_f32_16x16x32_bf16 v[94:97], v[156:159], v[204:207], v[94:97]
	v_mfma_f32_16x16x32_bf16 v[86:89], v[164:167], v[204:207], v[86:89]
	v_mfma_f32_16x16x32_bf16 v[78:81], v[156:159], v[212:215], v[78:81]
	v_mfma_f32_16x16x32_bf16 v[70:73], v[164:167], v[212:215], v[70:73]
	s_setprio 0
	s_setprio 1
	v_mfma_f32_16x16x32_bf16 v[122:125], v[168:171], v[184:187], v[122:125]
	v_mfma_f32_16x16x32_bf16 v[114:117], v[176:179], v[184:187], v[114:117]
	v_mfma_f32_16x16x32_bf16 v[106:109], v[168:171], v[192:195], v[106:109]
	v_mfma_f32_16x16x32_bf16 v[98:101], v[176:179], v[192:195], v[98:101]
	v_mfma_f32_16x16x32_bf16 v[90:93], v[168:171], v[200:203], v[90:93]
	v_mfma_f32_16x16x32_bf16 v[82:85], v[176:179], v[200:203], v[82:85]
	v_mfma_f32_16x16x32_bf16 v[74:77], v[168:171], v[208:211], v[74:77]
	v_mfma_f32_16x16x32_bf16 v[66:69], v[176:179], v[208:211], v[66:69]
	v_mfma_f32_16x16x32_bf16 v[122:125], v[172:175], v[188:191], v[122:125]
	v_mfma_f32_16x16x32_bf16 v[114:117], v[180:183], v[188:191], v[114:117]
	v_mfma_f32_16x16x32_bf16 v[106:109], v[172:175], v[196:199], v[106:109]
	v_mfma_f32_16x16x32_bf16 v[98:101], v[180:183], v[196:199], v[98:101]
	v_mfma_f32_16x16x32_bf16 v[90:93], v[172:175], v[204:207], v[90:93]
	v_mfma_f32_16x16x32_bf16 v[82:85], v[180:183], v[204:207], v[82:85]
	v_mfma_f32_16x16x32_bf16 v[74:77], v[172:175], v[212:215], v[74:77]
	v_mfma_f32_16x16x32_bf16 v[66:69], v[180:183], v[212:215], v[66:69]
	s_setprio 0
	s_barrier
	s_add_i32 s40, s58, s33
	v_lshl_add_u64 v[218:219], v[218:219], 0, s[8:9]
	s_mov_b32 m0, s40
	ds_read_b128 v[184:187], v155 offset:49152
	ds_read_b128 v[188:191], v155 offset:50176
	ds_read_b128 v[192:195], v155 offset:51200
	ds_read_b128 v[196:199], v155 offset:52224
	ds_read_b128 v[200:203], v155 offset:53248
	ds_read_b128 v[204:207], v155 offset:54272
	ds_read_b128 v[208:211], v155 offset:55296
	ds_read_b128 v[212:215], v155 offset:56320
	global_load_lds_dwordx4 v[218:219], off
	s_add_i32 m0, s40, 0x2000
	s_add_u32 s34, s34, 0x80080
	v_lshl_add_u64 v[218:219], v[220:221], 0, s[8:9]
	s_addc_u32 s35, s35, 0
	s_add_i32 s40, s59, s33
	global_load_lds_dwordx4 v[218:219], off
	v_lshl_add_u64 v[218:219], s[34:35], 0, v[134:135]
	s_mov_b32 m0, s40
	s_nop 0
	global_load_lds_dwordx4 v[218:219], off
	v_lshl_add_u64 v[218:219], s[34:35], 0, v[130:131]
	s_add_i32 m0, s40, 0x2000
	s_nop 0
	global_load_lds_dwordx4 v[218:219], off
	v_lshl_add_u64 v[218:219], v[222:223], 0, s[8:9]
	s_mov_b32 m0, s48
	s_nop 0
	global_load_lds_dwordx4 v[218:219], off
	v_lshl_add_u64 v[218:219], v[224:225], 0, s[8:9]
	s_mov_b32 m0, s49
	s_nop 0
	global_load_lds_dwordx4 v[218:219], off
	s_waitcnt vmcnt(8)
	s_waitcnt lgkmcnt(0)
	s_barrier
	s_setprio 1
	s_waitcnt lgkmcnt(0)
	v_mfma_f32_16x16x32_bf16 v[62:65], v[146:149], v[184:187], v[62:65]
	v_mfma_f32_16x16x32_bf16 v[54:57], v[160:163], v[184:187], v[54:57]
	v_mfma_f32_16x16x32_bf16 v[46:49], v[146:149], v[192:195], v[46:49]
	v_mfma_f32_16x16x32_bf16 v[38:41], v[160:163], v[192:195], v[38:41]
	v_mfma_f32_16x16x32_bf16 v[30:33], v[146:149], v[200:203], v[30:33]
	v_mfma_f32_16x16x32_bf16 v[22:25], v[160:163], v[200:203], v[22:25]
	v_mfma_f32_16x16x32_bf16 v[14:17], v[146:149], v[208:211], v[14:17]
	v_mfma_f32_16x16x32_bf16 v[6:9], v[160:163], v[208:211], v[6:9]
	v_mfma_f32_16x16x32_bf16 v[62:65], v[156:159], v[188:191], v[62:65]
	v_mfma_f32_16x16x32_bf16 v[54:57], v[164:167], v[188:191], v[54:57]
	v_mfma_f32_16x16x32_bf16 v[46:49], v[156:159], v[196:199], v[46:49]
	v_mfma_f32_16x16x32_bf16 v[38:41], v[164:167], v[196:199], v[38:41]
	v_mfma_f32_16x16x32_bf16 v[30:33], v[156:159], v[204:207], v[30:33]
	v_mfma_f32_16x16x32_bf16 v[22:25], v[164:167], v[204:207], v[22:25]
	v_mfma_f32_16x16x32_bf16 v[14:17], v[156:159], v[212:215], v[14:17]
	v_mfma_f32_16x16x32_bf16 v[6:9], v[164:167], v[212:215], v[6:9]
	s_setprio 0
	s_setprio 1
	v_mfma_f32_16x16x32_bf16 v[58:61], v[168:171], v[184:187], v[58:61]
	v_mfma_f32_16x16x32_bf16 v[50:53], v[176:179], v[184:187], v[50:53]
	v_mfma_f32_16x16x32_bf16 v[42:45], v[168:171], v[192:195], v[42:45]
	v_mfma_f32_16x16x32_bf16 v[34:37], v[176:179], v[192:195], v[34:37]
	v_mfma_f32_16x16x32_bf16 v[26:29], v[168:171], v[200:203], v[26:29]
	v_mfma_f32_16x16x32_bf16 v[18:21], v[176:179], v[200:203], v[18:21]
	v_mfma_f32_16x16x32_bf16 v[10:13], v[168:171], v[208:211], v[10:13]
	v_mfma_f32_16x16x32_bf16 v[2:5], v[176:179], v[208:211], v[2:5]
	v_mfma_f32_16x16x32_bf16 v[58:61], v[172:175], v[188:191], v[58:61]
	v_mfma_f32_16x16x32_bf16 v[50:53], v[180:183], v[188:191], v[50:53]
	v_mfma_f32_16x16x32_bf16 v[42:45], v[172:175], v[196:199], v[42:45]
	v_mfma_f32_16x16x32_bf16 v[34:37], v[180:183], v[196:199], v[34:37]
	v_mfma_f32_16x16x32_bf16 v[26:29], v[172:175], v[204:207], v[26:29]
	v_mfma_f32_16x16x32_bf16 v[18:21], v[180:183], v[204:207], v[18:21]
	v_mfma_f32_16x16x32_bf16 v[10:13], v[172:175], v[212:215], v[10:13]
	v_mfma_f32_16x16x32_bf16 v[2:5], v[180:183], v[212:215], v[2:5]
	s_setprio 0
	s_barrier
	s_add_i32 s57, s57, 2
	s_add_u32 s38, s38, 0x100
	s_addc_u32 s39, s39, 0
	s_add_u32 s55, s55, 0x100
	s_addc_u32 s56, s56, 0

.LBB0_3929:
	s_add_u32 s18, s18, 0x160080
	s_addc_u32 s19, s19, 0
	s_add_u32 s0, s20, 0x100
	s_addc_u32 s1, s21, 0
	s_mov_b32 s45, -2
	ds_read_b128 v[144:147], v155
	ds_read_b128 v[148:151], v155 offset:1024
	ds_read_b128 v[158:161], v155 offset:2048
	ds_read_b128 v[162:165], v155 offset:3072
	ds_read_b128 v[166:169], v156
	ds_read_b128 v[170:173], v156 offset:1024
	ds_read_b128 v[174:177], v156 offset:2048
	ds_read_b128 v[178:181], v156 offset:3072
	s_add_u32 s20, s18, 0xffea0080
	s_addc_u32 s21, s19, -1
	s_cmpk_eq_i32 s45, 0x54
	s_cselect_b32 s23, s5, s21
	s_cselect_b32 s22, s4, s20
	s_cselect_b32 s21, s17, s1
	s_cselect_b32 s20, s16, s0
	v_lshl_add_u64 v[214:215], s[18:19], 0, v[136:137]
	s_add_i32 m0, s30, 0xc000
	ds_read_b128 v[182:185], v157
	ds_read_b128 v[186:189], v157 offset:1024
	ds_read_b128 v[190:193], v157 offset:2048
	ds_read_b128 v[194:197], v157 offset:3072
	ds_read_b128 v[198:201], v157 offset:4096
	ds_read_b128 v[202:205], v157 offset:5120
	ds_read_b128 v[206:209], v157 offset:6144
	ds_read_b128 v[210:213], v157 offset:7168
	global_load_lds_dwordx4 v[214:215], off
	v_lshl_add_u64 v[214:215], s[18:19], 0, v[138:139]
	s_add_i32 m0, s30, 0xe000
	s_nop 0
	global_load_lds_dwordx4 v[214:215], off
	s_waitcnt vmcnt(8)
	s_waitcnt lgkmcnt(0)
	s_barrier
	s_setprio 1
	s_waitcnt lgkmcnt(0)
	v_mfma_f32_16x16x32_bf16 v[124:127], v[144:147], v[182:185], 0
	v_mfma_f32_16x16x32_bf16 v[120:123], v[158:161], v[182:185], 0
	v_mfma_f32_16x16x32_bf16 v[116:119], v[144:147], v[190:193], 0
	v_mfma_f32_16x16x32_bf16 v[112:115], v[158:161], v[190:193], 0
	v_mfma_f32_16x16x32_bf16 v[92:95], v[144:147], v[198:201], 0
	v_mfma_f32_16x16x32_bf16 v[88:91], v[158:161], v[198:201], 0
	v_mfma_f32_16x16x32_bf16 v[84:87], v[144:147], v[206:209], 0
	v_mfma_f32_16x16x32_bf16 v[80:83], v[158:161], v[206:209], 0
	v_mfma_f32_16x16x32_bf16 v[124:127], v[148:151], v[186:189], v[124:127]
	v_mfma_f32_16x16x32_bf16 v[120:123], v[162:165], v[186:189], v[120:123]
	v_mfma_f32_16x16x32_bf16 v[116:119], v[148:151], v[194:197], v[116:119]
	v_mfma_f32_16x16x32_bf16 v[112:115], v[162:165], v[194:197], v[112:115]
	v_mfma_f32_16x16x32_bf16 v[92:95], v[148:151], v[202:205], v[92:95]
	v_mfma_f32_16x16x32_bf16 v[88:91], v[162:165], v[202:205], v[88:91]
	v_mfma_f32_16x16x32_bf16 v[84:87], v[148:151], v[210:213], v[84:87]
	v_mfma_f32_16x16x32_bf16 v[80:83], v[162:165], v[210:213], v[80:83]
	s_setprio 0
	s_setprio 1
	v_mfma_f32_16x16x32_bf16 v[108:111], v[166:169], v[182:185], 0
	v_mfma_f32_16x16x32_bf16 v[104:107], v[174:177], v[182:185], 0
	v_mfma_f32_16x16x32_bf16 v[100:103], v[166:169], v[190:193], 0
	v_mfma_f32_16x16x32_bf16 v[96:99], v[174:177], v[190:193], 0
	v_mfma_f32_16x16x32_bf16 v[76:79], v[166:169], v[198:201], 0
	v_mfma_f32_16x16x32_bf16 v[72:75], v[174:177], v[198:201], 0
	v_mfma_f32_16x16x32_bf16 v[68:71], v[166:169], v[206:209], 0
	v_mfma_f32_16x16x32_bf16 v[64:67], v[174:177], v[206:209], 0
	v_mfma_f32_16x16x32_bf16 v[108:111], v[170:173], v[186:189], v[108:111]
	v_mfma_f32_16x16x32_bf16 v[104:107], v[178:181], v[186:189], v[104:107]
	v_mfma_f32_16x16x32_bf16 v[100:103], v[170:173], v[194:197], v[100:103]
	v_mfma_f32_16x16x32_bf16 v[96:99], v[178:181], v[194:197], v[96:99]
	v_mfma_f32_16x16x32_bf16 v[76:79], v[170:173], v[202:205], v[76:79]
	v_mfma_f32_16x16x32_bf16 v[72:75], v[178:181], v[202:205], v[72:75]
	v_mfma_f32_16x16x32_bf16 v[68:71], v[170:173], v[210:213], v[68:71]
	v_mfma_f32_16x16x32_bf16 v[64:67], v[178:181], v[210:213], v[64:67]
	s_setprio 0
	s_barrier
	s_add_i32 s46, s39, s27
	v_lshl_add_u64 v[214:215], s[20:21], 0, v[130:131]
	s_mov_b32 m0, s46
	ds_read_b128 v[182:185], v157 offset:16384
	ds_read_b128 v[186:189], v157 offset:17408
	ds_read_b128 v[190:193], v157 offset:18432
	ds_read_b128 v[194:197], v157 offset:19456
	ds_read_b128 v[198:201], v157 offset:20480
	ds_read_b128 v[202:205], v157 offset:21504
	ds_read_b128 v[206:209], v157 offset:22528
	ds_read_b128 v[210:213], v157 offset:23552
	global_load_lds_dwordx4 v[214:215], off
	s_add_i32 m0, s46, 0x2000
	s_add_u32 s46, s20, 0x160000
	v_lshl_add_u64 v[216:217], s[20:21], 0, v[134:135]
	s_addc_u32 s47, s21, 0
	s_add_i32 s48, s40, s27
	global_load_lds_dwordx4 v[216:217], off
	v_lshl_add_u64 v[218:219], s[46:47], 0, v[130:131]
	s_mov_b32 m0, s48
	v_lshl_add_u64 v[220:221], s[22:23], 0, v[132:133]
	global_load_lds_dwordx4 v[218:219], off
	v_lshl_add_u64 v[218:219], s[46:47], 0, v[134:135]
	s_add_i32 m0, s48, 0x2000
	s_nop 0
	global_load_lds_dwordx4 v[218:219], off
	v_lshl_add_u64 v[218:219], s[22:23], 0, v[128:129]
	s_mov_b32 m0, s30
	s_nop 0
	global_load_lds_dwordx4 v[218:219], off
	s_mov_b32 m0, s31
	s_nop 0
	global_load_lds_dwordx4 v[220:221], off
	s_waitcnt vmcnt(8)
	s_waitcnt lgkmcnt(0)
	s_barrier
	s_setprio 1
	s_waitcnt lgkmcnt(0)
	v_mfma_f32_16x16x32_bf16 v[60:63], v[144:147], v[182:185], 0
	v_mfma_f32_16x16x32_bf16 v[56:59], v[158:161], v[182:185], 0
	v_mfma_f32_16x16x32_bf16 v[52:55], v[144:147], v[190:193], 0
	v_mfma_f32_16x16x32_bf16 v[48:51], v[158:161], v[190:193], 0
	v_mfma_f32_16x16x32_bf16 v[28:31], v[144:147], v[198:201], 0
	v_mfma_f32_16x16x32_bf16 v[24:27], v[158:161], v[198:201], 0
	v_mfma_f32_16x16x32_bf16 v[20:23], v[144:147], v[206:209], 0
	v_mfma_f32_16x16x32_bf16 v[16:19], v[158:161], v[206:209], 0
	v_mfma_f32_16x16x32_bf16 v[60:63], v[148:151], v[186:189], v[60:63]
	v_mfma_f32_16x16x32_bf16 v[56:59], v[162:165], v[186:189], v[56:59]
	v_mfma_f32_16x16x32_bf16 v[52:55], v[148:151], v[194:197], v[52:55]
	v_mfma_f32_16x16x32_bf16 v[48:51], v[162:165], v[194:197], v[48:51]
	v_mfma_f32_16x16x32_bf16 v[28:31], v[148:151], v[202:205], v[28:31]
	v_mfma_f32_16x16x32_bf16 v[24:27], v[162:165], v[202:205], v[24:27]
	v_mfma_f32_16x16x32_bf16 v[20:23], v[148:151], v[210:213], v[20:23]
	v_mfma_f32_16x16x32_bf16 v[16:19], v[162:165], v[210:213], v[16:19]
	s_setprio 0
	s_setprio 1
	v_mfma_f32_16x16x32_bf16 v[44:47], v[166:169], v[182:185], 0
	v_mfma_f32_16x16x32_bf16 v[40:43], v[174:177], v[182:185], 0
	v_mfma_f32_16x16x32_bf16 v[36:39], v[166:169], v[190:193], 0
	v_mfma_f32_16x16x32_bf16 v[32:35], v[174:177], v[190:193], 0
	v_mfma_f32_16x16x32_bf16 v[12:15], v[166:169], v[198:201], 0
	v_mfma_f32_16x16x32_bf16 v[8:11], v[174:177], v[198:201], 0
	v_mfma_f32_16x16x32_bf16 v[4:7], v[166:169], v[206:209], 0
	v_mfma_f32_16x16x32_bf16 v[0:3], v[174:177], v[206:209], 0
	v_mfma_f32_16x16x32_bf16 v[44:47], v[170:173], v[186:189], v[44:47]
	v_mfma_f32_16x16x32_bf16 v[40:43], v[178:181], v[186:189], v[40:43]
	v_mfma_f32_16x16x32_bf16 v[36:39], v[170:173], v[194:197], v[36:39]
	v_mfma_f32_16x16x32_bf16 v[32:35], v[178:181], v[194:197], v[32:35]
	v_mfma_f32_16x16x32_bf16 v[12:15], v[170:173], v[202:205], v[12:15]
	v_mfma_f32_16x16x32_bf16 v[8:11], v[178:181], v[202:205], v[8:11]
	v_mfma_f32_16x16x32_bf16 v[4:7], v[170:173], v[210:213], v[4:7]
	v_mfma_f32_16x16x32_bf16 v[0:3], v[178:181], v[210:213], v[0:3]
	s_setprio 0
	s_barrier
	s_add_i32 s46, 0, 0x18000
	s_add_i32 s47, 0, 0x1c000
	v_add_u32_e32 v162, s46, v153
	v_add_u32_e32 v178, s47, v153
	ds_read_b128 v[144:147], v162
	ds_read_b128 v[148:151], v162 offset:1024
	ds_read_b128 v[158:161], v162 offset:2048
	ds_read_b128 v[162:165], v162 offset:3072
	ds_read_b128 v[166:169], v178
	ds_read_b128 v[170:173], v178 offset:1024
	ds_read_b128 v[174:177], v178 offset:2048
	ds_read_b128 v[178:181], v178 offset:3072
	s_add_u32 s22, s22, 0x160000
	s_addc_u32 s23, s23, 0
	s_mov_b32 m0, s33
	v_lshl_add_u64 v[222:223], s[22:23], 0, v[128:129]
	ds_read_b128 v[182:185], v157 offset:32768
	ds_read_b128 v[186:189], v157 offset:33792
	ds_read_b128 v[190:193], v157 offset:34816
	ds_read_b128 v[194:197], v157 offset:35840
	ds_read_b128 v[198:201], v157 offset:36864
	ds_read_b128 v[202:205], v157 offset:37888
	ds_read_b128 v[206:209], v157 offset:38912
	ds_read_b128 v[210:213], v157 offset:39936
	global_load_lds_dwordx4 v[222:223], off
	v_lshl_add_u64 v[222:223], s[22:23], 0, v[132:133]
	s_mov_b32 m0, s34
	s_nop 0
	global_load_lds_dwordx4 v[222:223], off
	s_waitcnt vmcnt(8)
	s_waitcnt lgkmcnt(0)
	s_barrier
	s_setprio 1
	s_waitcnt lgkmcnt(0)
	v_mfma_f32_16x16x32_bf16 v[124:127], v[144:147], v[182:185], v[124:127]
	v_mfma_f32_16x16x32_bf16 v[120:123], v[158:161], v[182:185], v[120:123]
	v_mfma_f32_16x16x32_bf16 v[116:119], v[144:147], v[190:193], v[116:119]
	v_mfma_f32_16x16x32_bf16 v[112:115], v[158:161], v[190:193], v[112:115]
	v_mfma_f32_16x16x32_bf16 v[92:95], v[144:147], v[198:201], v[92:95]
	v_mfma_f32_16x16x32_bf16 v[88:91], v[158:161], v[198:201], v[88:91]
	v_mfma_f32_16x16x32_bf16 v[84:87], v[144:147], v[206:209], v[84:87]
	v_mfma_f32_16x16x32_bf16 v[80:83], v[158:161], v[206:209], v[80:83]
	v_mfma_f32_16x16x32_bf16 v[124:127], v[148:151], v[186:189], v[124:127]
	v_mfma_f32_16x16x32_bf16 v[120:123], v[162:165], v[186:189], v[120:123]
	v_mfma_f32_16x16x32_bf16 v[116:119], v[148:151], v[194:197], v[116:119]
	v_mfma_f32_16x16x32_bf16 v[112:115], v[162:165], v[194:197], v[112:115]
	v_mfma_f32_16x16x32_bf16 v[92:95], v[148:151], v[202:205], v[92:95]
	v_mfma_f32_16x16x32_bf16 v[88:91], v[162:165], v[202:205], v[88:91]
	v_mfma_f32_16x16x32_bf16 v[84:87], v[148:151], v[210:213], v[84:87]
	v_mfma_f32_16x16x32_bf16 v[80:83], v[162:165], v[210:213], v[80:83]
	s_setprio 0
	s_setprio 1
	v_mfma_f32_16x16x32_bf16 v[108:111], v[166:169], v[182:185], v[108:111]
	v_mfma_f32_16x16x32_bf16 v[104:107], v[174:177], v[182:185], v[104:107]
	v_mfma_f32_16x16x32_bf16 v[100:103], v[166:169], v[190:193], v[100:103]
	v_mfma_f32_16x16x32_bf16 v[96:99], v[174:177], v[190:193], v[96:99]
	v_mfma_f32_16x16x32_bf16 v[76:79], v[166:169], v[198:201], v[76:79]
	v_mfma_f32_16x16x32_bf16 v[72:75], v[174:177], v[198:201], v[72:75]
	v_mfma_f32_16x16x32_bf16 v[68:71], v[166:169], v[206:209], v[68:71]
	v_mfma_f32_16x16x32_bf16 v[64:67], v[174:177], v[206:209], v[64:67]
	v_mfma_f32_16x16x32_bf16 v[108:111], v[170:173], v[186:189], v[108:111]
	v_mfma_f32_16x16x32_bf16 v[104:107], v[178:181], v[186:189], v[104:107]
	v_mfma_f32_16x16x32_bf16 v[100:103], v[170:173], v[194:197], v[100:103]
	v_mfma_f32_16x16x32_bf16 v[96:99], v[178:181], v[194:197], v[96:99]
	v_mfma_f32_16x16x32_bf16 v[76:79], v[170:173], v[202:205], v[76:79]
	v_mfma_f32_16x16x32_bf16 v[72:75], v[178:181], v[202:205], v[72:75]
	v_mfma_f32_16x16x32_bf16 v[68:71], v[170:173], v[210:213], v[68:71]
	v_mfma_f32_16x16x32_bf16 v[64:67], v[178:181], v[210:213], v[64:67]
	s_setprio 0
	s_barrier
	s_add_i32 s22, s46, s27
	v_lshl_add_u64 v[214:215], v[214:215], 0, s[12:13]
	s_mov_b32 m0, s22
	ds_read_b128 v[182:185], v157 offset:49152
	ds_read_b128 v[186:189], v157 offset:50176
	ds_read_b128 v[190:193], v157 offset:51200
	ds_read_b128 v[194:197], v157 offset:52224
	ds_read_b128 v[198:201], v157 offset:53248
	ds_read_b128 v[202:205], v157 offset:54272
	ds_read_b128 v[206:209], v157 offset:55296
	ds_read_b128 v[210:213], v157 offset:56320
	global_load_lds_dwordx4 v[214:215], off
	s_add_i32 m0, s22, 0x2000
	s_add_u32 s20, s20, 0x160080
	v_lshl_add_u64 v[214:215], v[216:217], 0, s[12:13]
	s_addc_u32 s21, s21, 0
	s_add_i32 s22, s47, s27
	global_load_lds_dwordx4 v[214:215], off
	v_lshl_add_u64 v[214:215], s[20:21], 0, v[130:131]
	s_mov_b32 m0, s22
	s_nop 0
	global_load_lds_dwordx4 v[214:215], off
	v_lshl_add_u64 v[214:215], s[20:21], 0, v[134:135]
	s_add_i32 m0, s22, 0x2000
	s_nop 0
	global_load_lds_dwordx4 v[214:215], off
	v_lshl_add_u64 v[214:215], v[218:219], 0, s[12:13]
	s_mov_b32 m0, s36
	s_nop 0
	global_load_lds_dwordx4 v[214:215], off
	v_lshl_add_u64 v[214:215], v[220:221], 0, s[12:13]
	s_mov_b32 m0, s37
	s_nop 0
	global_load_lds_dwordx4 v[214:215], off
	s_waitcnt vmcnt(8)
	s_waitcnt lgkmcnt(0)
	s_barrier
	s_setprio 1
	s_waitcnt lgkmcnt(0)
	v_mfma_f32_16x16x32_bf16 v[60:63], v[144:147], v[182:185], v[60:63]
	v_mfma_f32_16x16x32_bf16 v[56:59], v[158:161], v[182:185], v[56:59]
	v_mfma_f32_16x16x32_bf16 v[52:55], v[144:147], v[190:193], v[52:55]
	v_mfma_f32_16x16x32_bf16 v[48:51], v[158:161], v[190:193], v[48:51]
	v_mfma_f32_16x16x32_bf16 v[28:31], v[144:147], v[198:201], v[28:31]
	v_mfma_f32_16x16x32_bf16 v[24:27], v[158:161], v[198:201], v[24:27]
	v_mfma_f32_16x16x32_bf16 v[20:23], v[144:147], v[206:209], v[20:23]
	v_mfma_f32_16x16x32_bf16 v[16:19], v[158:161], v[206:209], v[16:19]
	v_mfma_f32_16x16x32_bf16 v[60:63], v[148:151], v[186:189], v[60:63]
	v_mfma_f32_16x16x32_bf16 v[56:59], v[162:165], v[186:189], v[56:59]
	v_mfma_f32_16x16x32_bf16 v[52:55], v[148:151], v[194:197], v[52:55]
	v_mfma_f32_16x16x32_bf16 v[48:51], v[162:165], v[194:197], v[48:51]
	v_mfma_f32_16x16x32_bf16 v[28:31], v[148:151], v[202:205], v[28:31]
	v_mfma_f32_16x16x32_bf16 v[24:27], v[162:165], v[202:205], v[24:27]
	v_mfma_f32_16x16x32_bf16 v[20:23], v[148:151], v[210:213], v[20:23]
	v_mfma_f32_16x16x32_bf16 v[16:19], v[162:165], v[210:213], v[16:19]
	s_setprio 0
	s_setprio 1
	v_mfma_f32_16x16x32_bf16 v[44:47], v[166:169], v[182:185], v[44:47]
	v_mfma_f32_16x16x32_bf16 v[40:43], v[174:177], v[182:185], v[40:43]
	v_mfma_f32_16x16x32_bf16 v[36:39], v[166:169], v[190:193], v[36:39]
	v_mfma_f32_16x16x32_bf16 v[32:35], v[174:177], v[190:193], v[32:35]
	v_mfma_f32_16x16x32_bf16 v[12:15], v[166:169], v[198:201], v[12:15]
	v_mfma_f32_16x16x32_bf16 v[8:11], v[174:177], v[198:201], v[8:11]
	v_mfma_f32_16x16x32_bf16 v[4:7], v[166:169], v[206:209], v[4:7]
	v_mfma_f32_16x16x32_bf16 v[0:3], v[174:177], v[206:209], v[0:3]
	v_mfma_f32_16x16x32_bf16 v[44:47], v[170:173], v[186:189], v[44:47]
	v_mfma_f32_16x16x32_bf16 v[40:43], v[178:181], v[186:189], v[40:43]
	v_mfma_f32_16x16x32_bf16 v[36:39], v[170:173], v[194:197], v[36:39]
	v_mfma_f32_16x16x32_bf16 v[32:35], v[178:181], v[194:197], v[32:35]
	v_mfma_f32_16x16x32_bf16 v[12:15], v[170:173], v[202:205], v[12:15]
	v_mfma_f32_16x16x32_bf16 v[8:11], v[178:181], v[202:205], v[8:11]
	v_mfma_f32_16x16x32_bf16 v[4:7], v[170:173], v[210:213], v[4:7]
	v_mfma_f32_16x16x32_bf16 v[0:3], v[178:181], v[210:213], v[0:3]
	s_setprio 0
	s_barrier
	s_add_i32 s45, s45, 2
	s_add_u32 s18, s18, 0x100
	s_addc_u32 s19, s19, 0
	s_add_u32 s0, s0, 0x100
	s_addc_u32 s1, s1, 0
